# s_setprio: all 512 per-phase flips of the GEMM template deleted, one static priority raise for waves 4-7 at kernel entry
# speedup vs baseline: 1.0020x; 1.0020x over previous
_Z6k_mega6Params:
	s_load_dwordx16 s[40:55], s[0:1], 0x240
	s_load_dword s3, s[0:1], 0x288
	s_load_dwordx2 s[38:39], s[0:1], 0x280
	s_add_u32 s8, s0, 0x280
	s_addc_u32 s9, s1, 0
	v_and_b32_e32 v136, 0x3ff, v0
	s_waitcnt lgkmcnt(0)
	v_writelane_b32 v253, s3, 0
	v_readfirstlane_b32 s4, v136
	s_nop 3
	s_lshr_b32 s4, s4, 6
	s_cmp_ge_u32 s4, 4
	s_cbranch_scc0 .Lprio_done
	s_setprio 1
.Lprio_done:
	v_cmp_eq_u32_e64 s[6:7], 0, v136
	s_mov_b64 s[4:5], exec
	s_nop 0
	v_writelane_b32 v253, s6, 1
	s_nop 1
	v_writelane_b32 v253, s7, 2
	s_and_b64 s[6:7], s[4:5], s[6:7]
	s_mov_b64 exec, s[6:7]
	s_cbranch_execz .LBB0_2
	s_add_i32 s3, 0, 0x20000
	v_mov_b32_e32 v1, 0
	v_mov_b32_e32 v2, s3
	s_add_i32 s3, 0, 0x20004
	ds_write_b32 v2, v1
	v_mov_b32_e32 v2, s3
	s_add_i32 s3, 0, 0x20008
	ds_write_b32 v2, v1
	v_mov_b32_e32 v2, s3
	s_add_i32 s3, 0, 0x2000c
	ds_write_b32 v2, v1
	v_mov_b32_e32 v2, s3
	ds_write_b32 v2, v1

.LBB0_208:
	s_add_i32 s23, 0, 0x10000
	v_add_u32_e32 v157, s23, v143
	ds_read_b128 v[144:147], v157
	ds_read_b128 v[148:151], v157 offset:1024
	ds_read_b128 v[152:155], v157 offset:2048
	ds_read_b128 v[158:161], v157 offset:3072
	v_lshl_add_u64 v[210:211], v[130:131], 0, s[18:19]
	s_add_i32 s22, s52, 0xc000
	v_lshl_add_u64 v[194:195], v[210:211], 0, s[8:9]
	s_mov_b32 m0, s22
	v_lshl_add_u64 v[212:213], v[132:133], 0, s[18:19]
	s_add_i32 s21, s52, 0xe000
	ds_read_b128 v[162:165], v142
	ds_read_b128 v[166:169], v142 offset:1024
	ds_read_b128 v[170:173], v142 offset:2048
	ds_read_b128 v[174:177], v142 offset:3072
	ds_read_b128 v[178:181], v142 offset:4096
	ds_read_b128 v[182:185], v142 offset:5120
	ds_read_b128 v[186:189], v142 offset:6144
	ds_read_b128 v[190:193], v142 offset:7168
	global_load_lds_dwordx4 v[194:195], off
	v_lshl_add_u64 v[194:195], v[212:213], 0, s[8:9]
	s_mov_b32 m0, s21
	s_nop 0
	global_load_lds_dwordx4 v[194:195], off
	s_waitcnt lgkmcnt(8)
	s_barrier
	s_waitcnt lgkmcnt(0)
	s_waitcnt lgkmcnt(0)
	v_mfma_f32_16x16x32_bf16 v[124:127], v[144:147], v[162:165], v[124:127]
	v_mfma_f32_16x16x32_bf16 v[120:123], v[152:155], v[162:165], v[120:123]
	v_mfma_f32_16x16x32_bf16 v[116:119], v[144:147], v[170:173], v[116:119]
	v_mfma_f32_16x16x32_bf16 v[112:115], v[152:155], v[170:173], v[112:115]
	v_mfma_f32_16x16x32_bf16 v[108:111], v[144:147], v[178:181], v[108:111]
	v_mfma_f32_16x16x32_bf16 v[104:107], v[152:155], v[178:181], v[104:107]
	v_mfma_f32_16x16x32_bf16 v[100:103], v[144:147], v[186:189], v[100:103]
	v_mfma_f32_16x16x32_bf16 v[96:99], v[152:155], v[186:189], v[96:99]
	v_mfma_f32_16x16x32_bf16 v[124:127], v[148:151], v[166:169], v[124:127]
	v_mfma_f32_16x16x32_bf16 v[120:123], v[158:161], v[166:169], v[120:123]
	v_mfma_f32_16x16x32_bf16 v[116:119], v[148:151], v[174:177], v[116:119]
	v_mfma_f32_16x16x32_bf16 v[112:115], v[158:161], v[174:177], v[112:115]
	v_mfma_f32_16x16x32_bf16 v[108:111], v[148:151], v[182:185], v[108:111]
	v_mfma_f32_16x16x32_bf16 v[104:107], v[158:161], v[182:185], v[104:107]
	v_mfma_f32_16x16x32_bf16 v[100:103], v[148:151], v[190:193], v[100:103]
	v_mfma_f32_16x16x32_bf16 v[96:99], v[158:161], v[190:193], v[96:99]
	s_barrier
	s_add_i32 s92, 0, 0x14000
	v_lshl_add_u64 v[214:215], v[134:135], 0, s[18:19]
	s_add_i32 s23, s23, s33
	v_add_u32_e32 v157, s92, v143
	v_lshl_add_u64 v[216:217], v[214:215], 0, s[10:11]
	s_mov_b32 m0, s23
	ds_read_b128 v[194:197], v157
	ds_read_b128 v[198:201], v157 offset:1024
	ds_read_b128 v[202:205], v157 offset:2048
	ds_read_b128 v[206:209], v157 offset:3072
	global_load_lds_dwordx4 v[216:217], off
	v_lshl_add_u64 v[216:217], v[140:141], 0, s[18:19]
	v_lshl_add_u64 v[218:219], v[216:217], 0, s[10:11]
	s_add_i32 m0, s23, 0x2000
	s_nop 0
	global_load_lds_dwordx4 v[218:219], off
	s_barrier
	s_waitcnt lgkmcnt(0)
	s_waitcnt lgkmcnt(0)
	v_mfma_f32_16x16x32_bf16 v[92:95], v[194:197], v[162:165], v[92:95]
	v_mfma_f32_16x16x32_bf16 v[88:91], v[202:205], v[162:165], v[88:91]
	v_mfma_f32_16x16x32_bf16 v[84:87], v[194:197], v[170:173], v[84:87]
	v_mfma_f32_16x16x32_bf16 v[80:83], v[202:205], v[170:173], v[80:83]
	v_mfma_f32_16x16x32_bf16 v[76:79], v[194:197], v[178:181], v[76:79]
	v_mfma_f32_16x16x32_bf16 v[72:75], v[202:205], v[178:181], v[72:75]
	v_mfma_f32_16x16x32_bf16 v[68:71], v[194:197], v[186:189], v[68:71]
	v_mfma_f32_16x16x32_bf16 v[64:67], v[202:205], v[186:189], v[64:67]
	v_mfma_f32_16x16x32_bf16 v[92:95], v[198:201], v[166:169], v[92:95]
	v_mfma_f32_16x16x32_bf16 v[88:91], v[206:209], v[166:169], v[88:91]
	v_mfma_f32_16x16x32_bf16 v[84:87], v[198:201], v[174:177], v[84:87]
	v_mfma_f32_16x16x32_bf16 v[80:83], v[206:209], v[174:177], v[80:83]
	v_mfma_f32_16x16x32_bf16 v[76:79], v[198:201], v[182:185], v[76:79]
	v_mfma_f32_16x16x32_bf16 v[72:75], v[206:209], v[182:185], v[72:75]
	v_mfma_f32_16x16x32_bf16 v[68:71], v[198:201], v[190:193], v[68:71]
	v_mfma_f32_16x16x32_bf16 v[64:67], v[206:209], v[190:193], v[64:67]
	s_mov_b32 m0, s52
	v_lshl_add_u64 v[218:219], v[210:211], 0, s[10:11]
	s_barrier
	ds_read_b128 v[162:165], v142 offset:16384
	ds_read_b128 v[166:169], v142 offset:17408
	ds_read_b128 v[170:173], v142 offset:18432
	ds_read_b128 v[174:177], v142 offset:19456
	ds_read_b128 v[178:181], v142 offset:20480
	ds_read_b128 v[182:185], v142 offset:21504
	ds_read_b128 v[186:189], v142 offset:22528
	ds_read_b128 v[190:193], v142 offset:23552
	global_load_lds_dwordx4 v[218:219], off
	v_lshl_add_u64 v[218:219], v[212:213], 0, s[10:11]
	s_mov_b32 m0, s53
	s_nop 0
	global_load_lds_dwordx4 v[218:219], off
	s_barrier
	s_waitcnt lgkmcnt(0)
	s_waitcnt lgkmcnt(0)
	v_mfma_f32_16x16x32_bf16 v[60:63], v[144:147], v[162:165], v[60:63]
	v_mfma_f32_16x16x32_bf16 v[56:59], v[152:155], v[162:165], v[56:59]
	v_mfma_f32_16x16x32_bf16 v[52:55], v[144:147], v[170:173], v[52:55]
	v_mfma_f32_16x16x32_bf16 v[48:51], v[152:155], v[170:173], v[48:51]
	v_mfma_f32_16x16x32_bf16 v[44:47], v[144:147], v[178:181], v[44:47]
	v_mfma_f32_16x16x32_bf16 v[40:43], v[152:155], v[178:181], v[40:43]
	v_mfma_f32_16x16x32_bf16 v[36:39], v[144:147], v[186:189], v[36:39]
	v_mfma_f32_16x16x32_bf16 v[32:35], v[152:155], v[186:189], v[32:35]
	v_mfma_f32_16x16x32_bf16 v[60:63], v[148:151], v[166:169], v[60:63]
	v_mfma_f32_16x16x32_bf16 v[56:59], v[158:161], v[166:169], v[56:59]
	v_mfma_f32_16x16x32_bf16 v[52:55], v[148:151], v[174:177], v[52:55]
	v_mfma_f32_16x16x32_bf16 v[48:51], v[158:161], v[174:177], v[48:51]
	v_mfma_f32_16x16x32_bf16 v[44:47], v[148:151], v[182:185], v[44:47]
	v_mfma_f32_16x16x32_bf16 v[40:43], v[158:161], v[182:185], v[40:43]
	v_mfma_f32_16x16x32_bf16 v[36:39], v[148:151], v[190:193], v[36:39]
	v_mfma_f32_16x16x32_bf16 v[32:35], v[158:161], v[190:193], v[32:35]
	s_barrier
	s_add_i32 s23, s92, s33
	v_lshl_add_u64 v[144:145], v[214:215], 0, s[12:13]
	s_mov_b32 m0, s23
	s_nop 0
	global_load_lds_dwordx4 v[144:145], off
	v_lshl_add_u64 v[144:145], v[216:217], 0, s[12:13]
	s_add_i32 m0, s23, 0x2000
	s_nop 0
	global_load_lds_dwordx4 v[144:145], off
	s_waitcnt vmcnt(6)
	s_barrier
	v_mfma_f32_16x16x32_bf16 v[28:31], v[194:197], v[162:165], v[28:31]
	v_mfma_f32_16x16x32_bf16 v[24:27], v[202:205], v[162:165], v[24:27]
	v_mfma_f32_16x16x32_bf16 v[20:23], v[194:197], v[170:173], v[20:23]
	v_mfma_f32_16x16x32_bf16 v[16:19], v[202:205], v[170:173], v[16:19]
	v_mfma_f32_16x16x32_bf16 v[12:15], v[194:197], v[178:181], v[12:15]
	v_mfma_f32_16x16x32_bf16 v[8:11], v[202:205], v[178:181], v[8:11]
	v_mfma_f32_16x16x32_bf16 v[4:7], v[194:197], v[186:189], v[4:7]
	v_mfma_f32_16x16x32_bf16 v[0:3], v[202:205], v[186:189], v[0:3]
	v_mfma_f32_16x16x32_bf16 v[28:31], v[198:201], v[166:169], v[28:31]
	v_mfma_f32_16x16x32_bf16 v[24:27], v[206:209], v[166:169], v[24:27]
	v_mfma_f32_16x16x32_bf16 v[20:23], v[198:201], v[174:177], v[20:23]
	v_mfma_f32_16x16x32_bf16 v[16:19], v[206:209], v[174:177], v[16:19]
	v_mfma_f32_16x16x32_bf16 v[12:15], v[198:201], v[182:185], v[12:15]
	v_mfma_f32_16x16x32_bf16 v[8:11], v[206:209], v[182:185], v[8:11]
	v_mfma_f32_16x16x32_bf16 v[4:7], v[198:201], v[190:193], v[4:7]
	v_mfma_f32_16x16x32_bf16 v[0:3], v[206:209], v[190:193], v[0:3]
	s_add_i32 s23, 0, 0x18000
	v_add_u32_e32 v157, s23, v143
	s_barrier
	ds_read_b128 v[144:147], v157
	ds_read_b128 v[148:151], v157 offset:1024
	ds_read_b128 v[152:155], v157 offset:2048
	ds_read_b128 v[158:161], v157 offset:3072
	s_mov_b32 m0, s88
	v_lshl_add_u64 v[194:195], v[210:211], 0, s[12:13]
	ds_read_b128 v[162:165], v142 offset:32768
	ds_read_b128 v[166:169], v142 offset:33792
	ds_read_b128 v[170:173], v142 offset:34816
	ds_read_b128 v[174:177], v142 offset:35840
	ds_read_b128 v[178:181], v142 offset:36864
	ds_read_b128 v[182:185], v142 offset:37888
	ds_read_b128 v[186:189], v142 offset:38912
	ds_read_b128 v[190:193], v142 offset:39936
	global_load_lds_dwordx4 v[194:195], off
	v_lshl_add_u64 v[194:195], v[212:213], 0, s[12:13]
	s_mov_b32 m0, s89
	s_nop 0
	global_load_lds_dwordx4 v[194:195], off
	s_waitcnt lgkmcnt(8)
	s_barrier
	s_waitcnt lgkmcnt(0)
	s_waitcnt lgkmcnt(0)
	v_mfma_f32_16x16x32_bf16 v[124:127], v[144:147], v[162:165], v[124:127]
	v_mfma_f32_16x16x32_bf16 v[120:123], v[152:155], v[162:165], v[120:123]
	v_mfma_f32_16x16x32_bf16 v[116:119], v[144:147], v[170:173], v[116:119]
	v_mfma_f32_16x16x32_bf16 v[112:115], v[152:155], v[170:173], v[112:115]
	v_mfma_f32_16x16x32_bf16 v[108:111], v[144:147], v[178:181], v[108:111]
	v_mfma_f32_16x16x32_bf16 v[104:107], v[152:155], v[178:181], v[104:107]
	v_mfma_f32_16x16x32_bf16 v[100:103], v[144:147], v[186:189], v[100:103]
	v_mfma_f32_16x16x32_bf16 v[96:99], v[152:155], v[186:189], v[96:99]
	v_mfma_f32_16x16x32_bf16 v[124:127], v[148:151], v[166:169], v[124:127]
	v_mfma_f32_16x16x32_bf16 v[120:123], v[158:161], v[166:169], v[120:123]
	v_mfma_f32_16x16x32_bf16 v[116:119], v[148:151], v[174:177], v[116:119]
	v_mfma_f32_16x16x32_bf16 v[112:115], v[158:161], v[174:177], v[112:115]
	v_mfma_f32_16x16x32_bf16 v[108:111], v[148:151], v[182:185], v[108:111]
	v_mfma_f32_16x16x32_bf16 v[104:107], v[158:161], v[182:185], v[104:107]
	v_mfma_f32_16x16x32_bf16 v[100:103], v[148:151], v[190:193], v[100:103]
	v_mfma_f32_16x16x32_bf16 v[96:99], v[158:161], v[190:193], v[96:99]
	s_barrier
	s_add_i32 s92, 0, 0x1c000
	s_add_i32 s23, s23, s33
	v_add_u32_e32 v157, s92, v143
	v_lshl_add_u64 v[218:219], v[214:215], 0, s[14:15]
	s_mov_b32 m0, s23
	ds_read_b128 v[194:197], v157
	ds_read_b128 v[198:201], v157 offset:1024
	ds_read_b128 v[202:205], v157 offset:2048
	ds_read_b128 v[206:209], v157 offset:3072
	global_load_lds_dwordx4 v[218:219], off
	v_lshl_add_u64 v[218:219], v[216:217], 0, s[14:15]
	s_add_i32 m0, s23, 0x2000
	s_nop 0
	global_load_lds_dwordx4 v[218:219], off
	s_barrier
	s_waitcnt lgkmcnt(0)
	s_waitcnt lgkmcnt(0)
	v_mfma_f32_16x16x32_bf16 v[92:95], v[194:197], v[162:165], v[92:95]
	v_mfma_f32_16x16x32_bf16 v[88:91], v[202:205], v[162:165], v[88:91]
	v_mfma_f32_16x16x32_bf16 v[84:87], v[194:197], v[170:173], v[84:87]
	v_mfma_f32_16x16x32_bf16 v[80:83], v[202:205], v[170:173], v[80:83]
	v_mfma_f32_16x16x32_bf16 v[76:79], v[194:197], v[178:181], v[76:79]
	v_mfma_f32_16x16x32_bf16 v[72:75], v[202:205], v[178:181], v[72:75]
	v_mfma_f32_16x16x32_bf16 v[68:71], v[194:197], v[186:189], v[68:71]
	v_mfma_f32_16x16x32_bf16 v[64:67], v[202:205], v[186:189], v[64:67]
	v_mfma_f32_16x16x32_bf16 v[92:95], v[198:201], v[166:169], v[92:95]
	v_mfma_f32_16x16x32_bf16 v[88:91], v[206:209], v[166:169], v[88:91]
	v_mfma_f32_16x16x32_bf16 v[84:87], v[198:201], v[174:177], v[84:87]
	v_mfma_f32_16x16x32_bf16 v[80:83], v[206:209], v[174:177], v[80:83]
	v_mfma_f32_16x16x32_bf16 v[76:79], v[198:201], v[182:185], v[76:79]
	v_mfma_f32_16x16x32_bf16 v[72:75], v[206:209], v[182:185], v[72:75]
	v_mfma_f32_16x16x32_bf16 v[68:71], v[198:201], v[190:193], v[68:71]
	v_mfma_f32_16x16x32_bf16 v[64:67], v[206:209], v[190:193], v[64:67]
	s_mov_b32 m0, s90
	v_lshl_add_u64 v[210:211], v[210:211], 0, s[14:15]
	s_barrier
	ds_read_b128 v[162:165], v142 offset:49152
	ds_read_b128 v[166:169], v142 offset:50176
	ds_read_b128 v[170:173], v142 offset:51200
	ds_read_b128 v[174:177], v142 offset:52224
	ds_read_b128 v[178:181], v142 offset:53248
	ds_read_b128 v[182:185], v142 offset:54272
	ds_read_b128 v[186:189], v142 offset:55296
	ds_read_b128 v[190:193], v142 offset:56320
	global_load_lds_dwordx4 v[210:211], off
	v_lshl_add_u64 v[210:211], v[212:213], 0, s[14:15]
	s_mov_b32 m0, s91
	s_nop 0
	global_load_lds_dwordx4 v[210:211], off
	s_barrier
	s_waitcnt lgkmcnt(0)
	s_waitcnt lgkmcnt(0)
	v_mfma_f32_16x16x32_bf16 v[60:63], v[144:147], v[162:165], v[60:63]
	v_mfma_f32_16x16x32_bf16 v[56:59], v[152:155], v[162:165], v[56:59]
	v_mfma_f32_16x16x32_bf16 v[52:55], v[144:147], v[170:173], v[52:55]
	v_mfma_f32_16x16x32_bf16 v[48:51], v[152:155], v[170:173], v[48:51]
	v_mfma_f32_16x16x32_bf16 v[44:47], v[144:147], v[178:181], v[44:47]
	v_mfma_f32_16x16x32_bf16 v[40:43], v[152:155], v[178:181], v[40:43]
	v_mfma_f32_16x16x32_bf16 v[36:39], v[144:147], v[186:189], v[36:39]
	v_mfma_f32_16x16x32_bf16 v[32:35], v[152:155], v[186:189], v[32:35]
	v_mfma_f32_16x16x32_bf16 v[60:63], v[148:151], v[166:169], v[60:63]
	v_mfma_f32_16x16x32_bf16 v[56:59], v[158:161], v[166:169], v[56:59]
	v_mfma_f32_16x16x32_bf16 v[52:55], v[148:151], v[174:177], v[52:55]
	v_mfma_f32_16x16x32_bf16 v[48:51], v[158:161], v[174:177], v[48:51]
	v_mfma_f32_16x16x32_bf16 v[44:47], v[148:151], v[182:185], v[44:47]
	v_mfma_f32_16x16x32_bf16 v[40:43], v[158:161], v[182:185], v[40:43]
	v_mfma_f32_16x16x32_bf16 v[36:39], v[148:151], v[190:193], v[36:39]
	v_mfma_f32_16x16x32_bf16 v[32:35], v[158:161], v[190:193], v[32:35]
	s_barrier
	s_add_i32 s23, s92, s33
	v_lshl_add_u64 v[144:145], v[214:215], 0, s[16:17]
	s_mov_b32 m0, s23
	s_nop 0
	global_load_lds_dwordx4 v[144:145], off
	v_lshl_add_u64 v[144:145], v[216:217], 0, s[16:17]
	s_add_i32 m0, s23, 0x2000
	s_nop 0
	global_load_lds_dwordx4 v[144:145], off
	s_waitcnt vmcnt(6)
	s_barrier
	v_mfma_f32_16x16x32_bf16 v[28:31], v[194:197], v[162:165], v[28:31]
	v_mfma_f32_16x16x32_bf16 v[24:27], v[202:205], v[162:165], v[24:27]
	v_mfma_f32_16x16x32_bf16 v[20:23], v[194:197], v[170:173], v[20:23]
	v_mfma_f32_16x16x32_bf16 v[16:19], v[202:205], v[170:173], v[16:19]
	v_mfma_f32_16x16x32_bf16 v[12:15], v[194:197], v[178:181], v[12:15]
	v_mfma_f32_16x16x32_bf16 v[8:11], v[202:205], v[178:181], v[8:11]
	v_mfma_f32_16x16x32_bf16 v[4:7], v[194:197], v[186:189], v[4:7]
	v_mfma_f32_16x16x32_bf16 v[0:3], v[202:205], v[186:189], v[0:3]
	v_mfma_f32_16x16x32_bf16 v[28:31], v[198:201], v[166:169], v[28:31]
	v_mfma_f32_16x16x32_bf16 v[24:27], v[206:209], v[166:169], v[24:27]
	v_mfma_f32_16x16x32_bf16 v[20:23], v[198:201], v[174:177], v[20:23]
	v_mfma_f32_16x16x32_bf16 v[16:19], v[206:209], v[174:177], v[16:19]
	v_mfma_f32_16x16x32_bf16 v[12:15], v[198:201], v[182:185], v[12:15]
	v_mfma_f32_16x16x32_bf16 v[8:11], v[206:209], v[182:185], v[8:11]
	v_mfma_f32_16x16x32_bf16 v[4:7], v[198:201], v[190:193], v[4:7]
	v_mfma_f32_16x16x32_bf16 v[0:3], v[206:209], v[190:193], v[0:3]
	s_add_i32 s20, s20, 2
	s_add_u32 s18, s18, 0x100
	s_addc_u32 s19, s19, 0
	s_cmp_gt_u32 s20, 11
	s_barrier
	s_cbranch_scc0 .LBB0_208
	v_add_u32_e32 v140, 0, v143
	s_add_u32 s4, s4, 0x40780
	v_add_u32_e32 v134, 0x10000, v140
	s_addc_u32 s5, s5, 0
	s_mov_b32 m0, s22
	ds_read_b128 v[130:133], v134
	ds_read_b128 v[144:147], v134 offset:1024
	ds_read_b128 v[148:151], v134 offset:2048
	ds_read_b128 v[152:155], v134 offset:3072
	ds_read_b128 v[158:161], v142
	ds_read_b128 v[162:165], v142 offset:1024
	ds_read_b128 v[166:169], v142 offset:2048
	ds_read_b128 v[170:173], v142 offset:3072
	ds_read_b128 v[174:177], v142 offset:4096
	ds_read_b128 v[178:181], v142 offset:5120
	ds_read_b128 v[182:185], v142 offset:6144
	ds_read_b128 v[186:189], v142 offset:7168
	v_lshl_add_u64 v[134:135], s[4:5], 0, v[138:139]
	global_load_lds_dwordx4 v[134:135], off
	v_lshl_add_u64 v[128:129], s[4:5], 0, v[128:129]
	s_mov_b32 m0, s21
	s_nop 0
	global_load_lds_dwordx4 v[128:129], off
	s_barrier
	s_waitcnt lgkmcnt(0)
	s_waitcnt lgkmcnt(0)
	v_mfma_f32_16x16x32_bf16 v[124:127], v[130:133], v[158:161], v[124:127]
	v_mfma_f32_16x16x32_bf16 v[120:123], v[148:151], v[158:161], v[120:123]
	v_mfma_f32_16x16x32_bf16 v[116:119], v[130:133], v[166:169], v[116:119]
	v_mfma_f32_16x16x32_bf16 v[112:115], v[148:151], v[166:169], v[112:115]
	v_mfma_f32_16x16x32_bf16 v[100:103], v[130:133], v[182:185], v[100:103]
	v_mfma_f32_16x16x32_bf16 v[96:99], v[148:151], v[182:185], v[96:99]
	v_mfma_f32_16x16x32_bf16 v[124:127], v[144:147], v[162:165], v[124:127]
	v_mfma_f32_16x16x32_bf16 v[120:123], v[152:155], v[162:165], v[120:123]
	v_mfma_f32_16x16x32_bf16 v[116:119], v[144:147], v[170:173], v[116:119]
	v_mfma_f32_16x16x32_bf16 v[112:115], v[152:155], v[170:173], v[112:115]
	v_mfma_f32_16x16x32_bf16 v[108:111], v[130:133], v[174:177], v[108:111]
	v_mfma_f32_16x16x32_bf16 v[104:107], v[148:151], v[174:177], v[104:107]
	v_mfma_f32_16x16x32_bf16 v[100:103], v[144:147], v[186:189], v[100:103]
	v_mfma_f32_16x16x32_bf16 v[96:99], v[152:155], v[186:189], v[96:99]
	v_mfma_f32_16x16x32_bf16 v[190:193], v[144:147], v[178:181], v[108:111]
	v_mfma_f32_16x16x32_bf16 v[194:197], v[152:155], v[178:181], v[104:107]
	v_add_u32_e32 v128, 0x14000, v140
	s_barrier
	s_nop 0
	ds_read_b128 v[104:107], v128
	ds_read_b128 v[108:111], v128 offset:1024
	ds_read_b128 v[198:201], v128 offset:2048
	ds_read_b128 v[202:205], v128 offset:3072
	s_barrier
	s_waitcnt lgkmcnt(0)
	s_waitcnt lgkmcnt(0)
	v_mfma_f32_16x16x32_bf16 v[84:87], v[104:107], v[166:169], v[84:87]
	v_mfma_f32_16x16x32_bf16 v[80:83], v[198:201], v[166:169], v[80:83]
	v_mfma_f32_16x16x32_bf16 v[68:71], v[104:107], v[182:185], v[68:71]
	v_mfma_f32_16x16x32_bf16 v[64:67], v[198:201], v[182:185], v[64:67]
	v_mfma_f32_16x16x32_bf16 v[92:95], v[104:107], v[158:161], v[92:95]
	v_mfma_f32_16x16x32_bf16 v[88:91], v[198:201], v[158:161], v[88:91]
	v_mfma_f32_16x16x32_bf16 v[84:87], v[108:111], v[170:173], v[84:87]
	v_mfma_f32_16x16x32_bf16 v[80:83], v[202:205], v[170:173], v[80:83]
	v_mfma_f32_16x16x32_bf16 v[76:79], v[104:107], v[174:177], v[76:79]
	v_mfma_f32_16x16x32_bf16 v[72:75], v[198:201], v[174:177], v[72:75]
	v_mfma_f32_16x16x32_bf16 v[68:71], v[108:111], v[186:189], v[68:71]
	v_mfma_f32_16x16x32_bf16 v[64:67], v[202:205], v[186:189], v[64:67]
	v_mfma_f32_16x16x32_bf16 v[206:209], v[108:111], v[162:165], v[92:95]
	v_mfma_f32_16x16x32_bf16 v[158:161], v[202:205], v[162:165], v[88:91]
	v_mfma_f32_16x16x32_bf16 v[162:165], v[108:111], v[178:181], v[76:79]
	v_mfma_f32_16x16x32_bf16 v[166:169], v[202:205], v[178:181], v[72:75]
	s_barrier
	s_nop 0
	ds_read_b128 v[72:75], v142 offset:16384
	ds_read_b128 v[76:79], v142 offset:17408
	ds_read_b128 v[88:91], v142 offset:18432
	ds_read_b128 v[92:95], v142 offset:19456
	ds_read_b128 v[170:173], v142 offset:20480
	ds_read_b128 v[174:177], v142 offset:21504
	ds_read_b128 v[178:181], v142 offset:22528
	ds_read_b128 v[182:185], v142 offset:23552
	s_waitcnt vmcnt(4)
	s_barrier
	s_waitcnt lgkmcnt(0)
	s_waitcnt lgkmcnt(0)
	v_mfma_f32_16x16x32_bf16 v[60:63], v[130:133], v[72:75], v[60:63]
	v_mfma_f32_16x16x32_bf16 v[56:59], v[148:151], v[72:75], v[56:59]
	v_mfma_f32_16x16x32_bf16 v[52:55], v[130:133], v[88:91], v[52:55]
	v_mfma_f32_16x16x32_bf16 v[48:51], v[148:151], v[88:91], v[48:51]
	v_mfma_f32_16x16x32_bf16 v[36:39], v[130:133], v[178:181], v[36:39]
	v_mfma_f32_16x16x32_bf16 v[32:35], v[148:151], v[178:181], v[32:35]
	v_mfma_f32_16x16x32_bf16 v[60:63], v[144:147], v[76:79], v[60:63]
	v_mfma_f32_16x16x32_bf16 v[56:59], v[152:155], v[76:79], v[56:59]
	v_mfma_f32_16x16x32_bf16 v[52:55], v[144:147], v[92:95], v[52:55]
	v_mfma_f32_16x16x32_bf16 v[48:51], v[152:155], v[92:95], v[48:51]
	v_mfma_f32_16x16x32_bf16 v[44:47], v[130:133], v[170:173], v[44:47]
	v_mfma_f32_16x16x32_bf16 v[40:43], v[148:151], v[170:173], v[40:43]
	v_mfma_f32_16x16x32_bf16 v[36:39], v[144:147], v[182:185], v[36:39]
	v_mfma_f32_16x16x32_bf16 v[32:35], v[152:155], v[182:185], v[32:35]
	v_mfma_f32_16x16x32_bf16 v[186:189], v[144:147], v[174:177], v[44:47]
	v_mfma_f32_16x16x32_bf16 v[210:213], v[152:155], v[174:177], v[40:43]
	v_mfma_f32_16x16x32_bf16 v[20:23], v[104:107], v[88:91], v[20:23]
	v_mfma_f32_16x16x32_bf16 v[16:19], v[198:201], v[88:91], v[16:19]
	v_mfma_f32_16x16x32_bf16 v[4:7], v[104:107], v[178:181], v[4:7]
	v_mfma_f32_16x16x32_bf16 v[0:3], v[198:201], v[178:181], v[0:3]
	v_mfma_f32_16x16x32_bf16 v[28:31], v[104:107], v[72:75], v[28:31]
	v_mfma_f32_16x16x32_bf16 v[24:27], v[198:201], v[72:75], v[24:27]
	v_mfma_f32_16x16x32_bf16 v[20:23], v[108:111], v[92:95], v[20:23]
	v_mfma_f32_16x16x32_bf16 v[16:19], v[202:205], v[92:95], v[16:19]
	v_mfma_f32_16x16x32_bf16 v[12:15], v[104:107], v[170:173], v[12:15]
	v_mfma_f32_16x16x32_bf16 v[8:11], v[198:201], v[170:173], v[8:11]
	v_mfma_f32_16x16x32_bf16 v[4:7], v[108:111], v[182:185], v[4:7]
	v_mfma_f32_16x16x32_bf16 v[0:3], v[202:205], v[182:185], v[0:3]
	v_mfma_f32_16x16x32_bf16 v[128:131], v[108:111], v[76:79], v[28:31]
	v_mfma_f32_16x16x32_bf16 v[132:135], v[202:205], v[76:79], v[24:27]
	v_mfma_f32_16x16x32_bf16 v[144:147], v[108:111], v[174:177], v[12:15]
	v_mfma_f32_16x16x32_bf16 v[148:151], v[202:205], v[174:177], v[8:11]
	v_add_u32_e32 v24, 0x18000, v140
	s_barrier
	ds_read_b128 v[8:11], v24
	ds_read_b128 v[12:15], v24 offset:1024
	ds_read_b128 v[152:155], v24 offset:2048
	ds_read_b128 v[170:173], v24 offset:3072
	ds_read_b128 v[24:27], v142 offset:32768
	ds_read_b128 v[28:31], v142 offset:33792
	ds_read_b128 v[40:43], v142 offset:34816
	ds_read_b128 v[44:47], v142 offset:35840
	ds_read_b128 v[174:177], v142 offset:36864
	ds_read_b128 v[178:181], v142 offset:37888
	ds_read_b128 v[182:185], v142 offset:38912
	ds_read_b128 v[198:201], v142 offset:39936
	s_waitcnt vmcnt(2)
	s_barrier
	s_waitcnt lgkmcnt(0)
	s_waitcnt lgkmcnt(0)
	v_mfma_f32_16x16x32_bf16 v[72:75], v[8:11], v[24:27], v[124:127]
	v_mfma_f32_16x16x32_bf16 v[124:127], v[12:15], v[28:31], v[72:75]
	v_mfma_f32_16x16x32_bf16 v[72:75], v[152:155], v[24:27], v[120:123]
	v_mfma_f32_16x16x32_bf16 v[120:123], v[170:173], v[28:31], v[72:75]
	v_mfma_f32_16x16x32_bf16 v[72:75], v[8:11], v[40:43], v[116:119]
	v_mfma_f32_16x16x32_bf16 v[108:111], v[12:15], v[44:47], v[72:75]
	v_mfma_f32_16x16x32_bf16 v[72:75], v[152:155], v[40:43], v[112:115]
	v_mfma_f32_16x16x32_bf16 v[104:107], v[170:173], v[44:47], v[72:75]
	v_mfma_f32_16x16x32_bf16 v[72:75], v[8:11], v[174:177], v[190:193]
	v_mfma_f32_16x16x32_bf16 v[92:95], v[12:15], v[178:181], v[72:75]
	v_mfma_f32_16x16x32_bf16 v[72:75], v[152:155], v[174:177], v[194:197]
	v_mfma_f32_16x16x32_bf16 v[88:91], v[170:173], v[178:181], v[72:75]
	v_mfma_f32_16x16x32_bf16 v[72:75], v[8:11], v[182:185], v[100:103]
	v_mfma_f32_16x16x32_bf16 v[76:79], v[12:15], v[198:201], v[72:75]
	v_mfma_f32_16x16x32_bf16 v[72:75], v[152:155], v[182:185], v[96:99]
	v_mfma_f32_16x16x32_bf16 v[72:75], v[170:173], v[198:201], v[72:75]
	s_nop 0
	v_add_u32_e32 v96, 0x1c000, v140
	s_barrier
	ds_read_b128 v[190:193], v96
	ds_read_b128 v[194:197], v96 offset:1024
	ds_read_b128 v[202:205], v96 offset:2048
	ds_read_b128 v[214:217], v96 offset:3072
	s_waitcnt vmcnt(0)
	s_barrier
	s_waitcnt lgkmcnt(0)
	s_waitcnt lgkmcnt(0)
	v_mfma_f32_16x16x32_bf16 v[96:99], v[190:193], v[24:27], v[206:209]
	v_mfma_f32_16x16x32_bf16 v[24:27], v[202:205], v[24:27], v[158:161]
	v_mfma_f32_16x16x32_bf16 v[112:115], v[214:217], v[28:31], v[24:27]
	v_mfma_f32_16x16x32_bf16 v[24:27], v[190:193], v[40:43], v[84:87]
	v_mfma_f32_16x16x32_bf16 v[100:103], v[194:197], v[44:47], v[24:27]
	v_mfma_f32_16x16x32_bf16 v[24:27], v[202:205], v[40:43], v[80:83]
	v_mfma_f32_16x16x32_bf16 v[116:119], v[194:197], v[28:31], v[96:99]
	v_mfma_f32_16x16x32_bf16 v[96:99], v[214:217], v[44:47], v[24:27]
	v_mfma_f32_16x16x32_bf16 v[24:27], v[190:193], v[174:177], v[162:165]
	v_mfma_f32_16x16x32_bf16 v[84:87], v[194:197], v[178:181], v[24:27]
	v_mfma_f32_16x16x32_bf16 v[24:27], v[202:205], v[174:177], v[166:169]
	v_mfma_f32_16x16x32_bf16 v[80:83], v[214:217], v[178:181], v[24:27]
	v_mfma_f32_16x16x32_bf16 v[24:27], v[190:193], v[182:185], v[68:71]
	v_mfma_f32_16x16x32_bf16 v[68:71], v[194:197], v[198:201], v[24:27]
	v_mfma_f32_16x16x32_bf16 v[24:27], v[202:205], v[182:185], v[64:67]
	v_mfma_f32_16x16x32_bf16 v[64:67], v[214:217], v[198:201], v[24:27]
	s_barrier
	ds_read_b128 v[158:161], v142 offset:49152
	ds_read_b128 v[162:165], v142 offset:50176
	ds_read_b128 v[166:169], v142 offset:51200
	ds_read_b128 v[174:177], v142 offset:52224
	ds_read_b128 v[178:181], v142 offset:53248
	ds_read_b128 v[182:185], v142 offset:54272
	ds_read_b128 v[198:201], v142 offset:55296
	ds_read_b128 v[140:143], v142 offset:56320
	s_barrier
	s_waitcnt lgkmcnt(0)
	s_waitcnt lgkmcnt(0)
	v_mfma_f32_16x16x32_bf16 v[24:27], v[8:11], v[158:161], v[60:63]
	v_mfma_f32_16x16x32_bf16 v[60:63], v[12:15], v[162:165], v[24:27]
	v_mfma_f32_16x16x32_bf16 v[24:27], v[152:155], v[158:161], v[56:59]
	v_mfma_f32_16x16x32_bf16 v[56:59], v[170:173], v[162:165], v[24:27]
	v_mfma_f32_16x16x32_bf16 v[24:27], v[8:11], v[166:169], v[52:55]
	v_mfma_f32_16x16x32_bf16 v[44:47], v[12:15], v[174:177], v[24:27]
	v_mfma_f32_16x16x32_bf16 v[24:27], v[152:155], v[166:169], v[48:51]
	v_mfma_f32_16x16x32_bf16 v[40:43], v[170:173], v[174:177], v[24:27]
	v_mfma_f32_16x16x32_bf16 v[24:27], v[8:11], v[178:181], v[186:189]
	v_mfma_f32_16x16x32_bf16 v[8:11], v[8:11], v[198:201], v[36:39]
	v_mfma_f32_16x16x32_bf16 v[28:31], v[12:15], v[182:185], v[24:27]
	v_mfma_f32_16x16x32_bf16 v[24:27], v[152:155], v[178:181], v[210:213]
	v_mfma_f32_16x16x32_bf16 v[12:15], v[12:15], v[140:143], v[8:11]
	v_mfma_f32_16x16x32_bf16 v[8:11], v[152:155], v[198:201], v[32:35]
	v_mfma_f32_16x16x32_bf16 v[24:27], v[170:173], v[182:185], v[24:27]
	v_mfma_f32_16x16x32_bf16 v[8:11], v[170:173], v[140:143], v[8:11]
	v_mfma_f32_16x16x32_bf16 v[32:35], v[190:193], v[158:161], v[128:131]
	v_mfma_f32_16x16x32_bf16 v[52:55], v[194:197], v[162:165], v[32:35]
	v_mfma_f32_16x16x32_bf16 v[32:35], v[202:205], v[158:161], v[132:135]
	v_mfma_f32_16x16x32_bf16 v[16:19], v[202:205], v[166:169], v[16:19]
	v_mfma_f32_16x16x32_bf16 v[48:51], v[214:217], v[162:165], v[32:35]
	v_mfma_f32_16x16x32_bf16 v[20:23], v[190:193], v[166:169], v[20:23]
	v_mfma_f32_16x16x32_bf16 v[32:35], v[214:217], v[174:177], v[16:19]
	v_mfma_f32_16x16x32_bf16 v[16:19], v[190:193], v[178:181], v[144:147]
	v_mfma_f32_16x16x32_bf16 v[36:39], v[194:197], v[174:177], v[20:23]
	v_mfma_f32_16x16x32_bf16 v[20:23], v[194:197], v[182:185], v[16:19]
	v_mfma_f32_16x16x32_bf16 v[16:19], v[202:205], v[178:181], v[148:151]
	v_mfma_f32_16x16x32_bf16 v[4:7], v[190:193], v[198:201], v[4:7]
	v_mfma_f32_16x16x32_bf16 v[0:3], v[202:205], v[198:201], v[0:3]
	v_mfma_f32_16x16x32_bf16 v[16:19], v[214:217], v[182:185], v[16:19]
	v_mfma_f32_16x16x32_bf16 v[4:7], v[194:197], v[140:143], v[4:7]
	v_mfma_f32_16x16x32_bf16 v[0:3], v[214:217], v[140:143], v[0:3]
	s_cmpk_lt_u32 s1, 0x100
	s_barrier
	s_cbranch_scc0 .LBB0_211
	s_barrier

.LBB0_280:
	s_add_i32 s91, 0, 0x10000
	v_add_u32_e32 v157, s91, v143
	ds_read_b128 v[144:147], v157
	ds_read_b128 v[148:151], v157 offset:1024
	ds_read_b128 v[152:155], v157 offset:2048
	ds_read_b128 v[158:161], v157 offset:3072
	v_lshl_add_u64 v[210:211], v[130:131], 0, s[20:21]
	s_add_i32 s90, s33, 0xc000
	v_lshl_add_u64 v[194:195], v[210:211], 0, s[8:9]
	s_mov_b32 m0, s90
	v_lshl_add_u64 v[212:213], v[132:133], 0, s[20:21]
	s_add_i32 s23, s33, 0xe000
	ds_read_b128 v[162:165], v142
	ds_read_b128 v[166:169], v142 offset:1024
	ds_read_b128 v[170:173], v142 offset:2048
	ds_read_b128 v[174:177], v142 offset:3072
	ds_read_b128 v[178:181], v142 offset:4096
	ds_read_b128 v[182:185], v142 offset:5120
	ds_read_b128 v[186:189], v142 offset:6144
	ds_read_b128 v[190:193], v142 offset:7168
	global_load_lds_dwordx4 v[194:195], off
	v_lshl_add_u64 v[194:195], v[212:213], 0, s[8:9]
	s_mov_b32 m0, s23
	s_nop 0
	global_load_lds_dwordx4 v[194:195], off
	s_waitcnt lgkmcnt(8)
	s_barrier
	s_waitcnt lgkmcnt(0)
	s_waitcnt lgkmcnt(0)
	v_mfma_f32_16x16x32_bf16 v[124:127], v[144:147], v[162:165], v[124:127]
	v_mfma_f32_16x16x32_bf16 v[120:123], v[152:155], v[162:165], v[120:123]
	v_mfma_f32_16x16x32_bf16 v[116:119], v[144:147], v[170:173], v[116:119]
	v_mfma_f32_16x16x32_bf16 v[112:115], v[152:155], v[170:173], v[112:115]
	v_mfma_f32_16x16x32_bf16 v[108:111], v[144:147], v[178:181], v[108:111]
	v_mfma_f32_16x16x32_bf16 v[104:107], v[152:155], v[178:181], v[104:107]
	v_mfma_f32_16x16x32_bf16 v[100:103], v[144:147], v[186:189], v[100:103]
	v_mfma_f32_16x16x32_bf16 v[96:99], v[152:155], v[186:189], v[96:99]
	v_mfma_f32_16x16x32_bf16 v[124:127], v[148:151], v[166:169], v[124:127]
	v_mfma_f32_16x16x32_bf16 v[120:123], v[158:161], v[166:169], v[120:123]
	v_mfma_f32_16x16x32_bf16 v[116:119], v[148:151], v[174:177], v[116:119]
	v_mfma_f32_16x16x32_bf16 v[112:115], v[158:161], v[174:177], v[112:115]
	v_mfma_f32_16x16x32_bf16 v[108:111], v[148:151], v[182:185], v[108:111]
	v_mfma_f32_16x16x32_bf16 v[104:107], v[158:161], v[182:185], v[104:107]
	v_mfma_f32_16x16x32_bf16 v[100:103], v[148:151], v[190:193], v[100:103]
	v_mfma_f32_16x16x32_bf16 v[96:99], v[158:161], v[190:193], v[96:99]
	s_barrier
	s_add_i32 s92, 0, 0x14000
	v_lshl_add_u64 v[214:215], v[134:135], 0, s[20:21]
	s_add_i32 s91, s91, s5
	v_add_u32_e32 v157, s92, v143
	v_lshl_add_u64 v[216:217], v[214:215], 0, s[10:11]
	s_mov_b32 m0, s91
	ds_read_b128 v[194:197], v157
	ds_read_b128 v[198:201], v157 offset:1024
	ds_read_b128 v[202:205], v157 offset:2048
	ds_read_b128 v[206:209], v157 offset:3072
	global_load_lds_dwordx4 v[216:217], off
	v_lshl_add_u64 v[216:217], v[140:141], 0, s[20:21]
	v_lshl_add_u64 v[218:219], v[216:217], 0, s[10:11]
	s_add_i32 m0, s91, 0x2000
	s_nop 0
	global_load_lds_dwordx4 v[218:219], off
	s_barrier
	s_waitcnt lgkmcnt(0)
	s_waitcnt lgkmcnt(0)
	v_mfma_f32_16x16x32_bf16 v[92:95], v[194:197], v[162:165], v[92:95]
	v_mfma_f32_16x16x32_bf16 v[88:91], v[202:205], v[162:165], v[88:91]
	v_mfma_f32_16x16x32_bf16 v[84:87], v[194:197], v[170:173], v[84:87]
	v_mfma_f32_16x16x32_bf16 v[80:83], v[202:205], v[170:173], v[80:83]
	v_mfma_f32_16x16x32_bf16 v[76:79], v[194:197], v[178:181], v[76:79]
	v_mfma_f32_16x16x32_bf16 v[72:75], v[202:205], v[178:181], v[72:75]
	v_mfma_f32_16x16x32_bf16 v[68:71], v[194:197], v[186:189], v[68:71]
	v_mfma_f32_16x16x32_bf16 v[64:67], v[202:205], v[186:189], v[64:67]
	v_mfma_f32_16x16x32_bf16 v[92:95], v[198:201], v[166:169], v[92:95]
	v_mfma_f32_16x16x32_bf16 v[88:91], v[206:209], v[166:169], v[88:91]
	v_mfma_f32_16x16x32_bf16 v[84:87], v[198:201], v[174:177], v[84:87]
	v_mfma_f32_16x16x32_bf16 v[80:83], v[206:209], v[174:177], v[80:83]
	v_mfma_f32_16x16x32_bf16 v[76:79], v[198:201], v[182:185], v[76:79]
	v_mfma_f32_16x16x32_bf16 v[72:75], v[206:209], v[182:185], v[72:75]
	v_mfma_f32_16x16x32_bf16 v[68:71], v[198:201], v[190:193], v[68:71]
	v_mfma_f32_16x16x32_bf16 v[64:67], v[206:209], v[190:193], v[64:67]
	s_mov_b32 m0, s33
	v_lshl_add_u64 v[218:219], v[210:211], 0, s[10:11]
	s_barrier
	ds_read_b128 v[162:165], v142 offset:16384
	ds_read_b128 v[166:169], v142 offset:17408
	ds_read_b128 v[170:173], v142 offset:18432
	ds_read_b128 v[174:177], v142 offset:19456
	ds_read_b128 v[178:181], v142 offset:20480
	ds_read_b128 v[182:185], v142 offset:21504
	ds_read_b128 v[186:189], v142 offset:22528
	ds_read_b128 v[190:193], v142 offset:23552
	global_load_lds_dwordx4 v[218:219], off
	v_lshl_add_u64 v[218:219], v[212:213], 0, s[10:11]
	s_mov_b32 m0, s51
	s_nop 0
	global_load_lds_dwordx4 v[218:219], off
	s_barrier
	s_waitcnt lgkmcnt(0)
	s_waitcnt lgkmcnt(0)
	v_mfma_f32_16x16x32_bf16 v[60:63], v[144:147], v[162:165], v[60:63]
	v_mfma_f32_16x16x32_bf16 v[56:59], v[152:155], v[162:165], v[56:59]
	v_mfma_f32_16x16x32_bf16 v[52:55], v[144:147], v[170:173], v[52:55]
	v_mfma_f32_16x16x32_bf16 v[48:51], v[152:155], v[170:173], v[48:51]
	v_mfma_f32_16x16x32_bf16 v[44:47], v[144:147], v[178:181], v[44:47]
	v_mfma_f32_16x16x32_bf16 v[40:43], v[152:155], v[178:181], v[40:43]
	v_mfma_f32_16x16x32_bf16 v[36:39], v[144:147], v[186:189], v[36:39]
	v_mfma_f32_16x16x32_bf16 v[32:35], v[152:155], v[186:189], v[32:35]
	v_mfma_f32_16x16x32_bf16 v[60:63], v[148:151], v[166:169], v[60:63]
	v_mfma_f32_16x16x32_bf16 v[56:59], v[158:161], v[166:169], v[56:59]
	v_mfma_f32_16x16x32_bf16 v[52:55], v[148:151], v[174:177], v[52:55]
	v_mfma_f32_16x16x32_bf16 v[48:51], v[158:161], v[174:177], v[48:51]
	v_mfma_f32_16x16x32_bf16 v[44:47], v[148:151], v[182:185], v[44:47]
	v_mfma_f32_16x16x32_bf16 v[40:43], v[158:161], v[182:185], v[40:43]
	v_mfma_f32_16x16x32_bf16 v[36:39], v[148:151], v[190:193], v[36:39]
	v_mfma_f32_16x16x32_bf16 v[32:35], v[158:161], v[190:193], v[32:35]
	s_barrier
	s_add_i32 s91, s92, s5
	v_lshl_add_u64 v[144:145], v[214:215], 0, s[12:13]
	s_mov_b32 m0, s91
	s_nop 0
	global_load_lds_dwordx4 v[144:145], off
	v_lshl_add_u64 v[144:145], v[216:217], 0, s[12:13]
	s_add_i32 m0, s91, 0x2000
	s_nop 0
	global_load_lds_dwordx4 v[144:145], off
	s_waitcnt vmcnt(6)
	s_barrier
	v_mfma_f32_16x16x32_bf16 v[28:31], v[194:197], v[162:165], v[28:31]
	v_mfma_f32_16x16x32_bf16 v[24:27], v[202:205], v[162:165], v[24:27]
	v_mfma_f32_16x16x32_bf16 v[20:23], v[194:197], v[170:173], v[20:23]
	v_mfma_f32_16x16x32_bf16 v[16:19], v[202:205], v[170:173], v[16:19]
	v_mfma_f32_16x16x32_bf16 v[12:15], v[194:197], v[178:181], v[12:15]
	v_mfma_f32_16x16x32_bf16 v[8:11], v[202:205], v[178:181], v[8:11]
	v_mfma_f32_16x16x32_bf16 v[4:7], v[194:197], v[186:189], v[4:7]
	v_mfma_f32_16x16x32_bf16 v[0:3], v[202:205], v[186:189], v[0:3]
	v_mfma_f32_16x16x32_bf16 v[28:31], v[198:201], v[166:169], v[28:31]
	v_mfma_f32_16x16x32_bf16 v[24:27], v[206:209], v[166:169], v[24:27]
	v_mfma_f32_16x16x32_bf16 v[20:23], v[198:201], v[174:177], v[20:23]
	v_mfma_f32_16x16x32_bf16 v[16:19], v[206:209], v[174:177], v[16:19]
	v_mfma_f32_16x16x32_bf16 v[12:15], v[198:201], v[182:185], v[12:15]
	v_mfma_f32_16x16x32_bf16 v[8:11], v[206:209], v[182:185], v[8:11]
	v_mfma_f32_16x16x32_bf16 v[4:7], v[198:201], v[190:193], v[4:7]
	v_mfma_f32_16x16x32_bf16 v[0:3], v[206:209], v[190:193], v[0:3]
	s_add_i32 s91, 0, 0x18000
	v_add_u32_e32 v157, s91, v143
	s_barrier
	ds_read_b128 v[144:147], v157
	ds_read_b128 v[148:151], v157 offset:1024
	ds_read_b128 v[152:155], v157 offset:2048
	ds_read_b128 v[158:161], v157 offset:3072
	s_mov_b32 m0, s52
	v_lshl_add_u64 v[194:195], v[210:211], 0, s[12:13]
	ds_read_b128 v[162:165], v142 offset:32768
	ds_read_b128 v[166:169], v142 offset:33792
	ds_read_b128 v[170:173], v142 offset:34816
	ds_read_b128 v[174:177], v142 offset:35840
	ds_read_b128 v[178:181], v142 offset:36864
	ds_read_b128 v[182:185], v142 offset:37888
	ds_read_b128 v[186:189], v142 offset:38912
	ds_read_b128 v[190:193], v142 offset:39936
	global_load_lds_dwordx4 v[194:195], off
	v_lshl_add_u64 v[194:195], v[212:213], 0, s[12:13]
	s_mov_b32 m0, s53
	s_nop 0
	global_load_lds_dwordx4 v[194:195], off
	s_waitcnt lgkmcnt(8)
	s_barrier
	s_waitcnt lgkmcnt(0)
	s_waitcnt lgkmcnt(0)
	v_mfma_f32_16x16x32_bf16 v[124:127], v[144:147], v[162:165], v[124:127]
	v_mfma_f32_16x16x32_bf16 v[120:123], v[152:155], v[162:165], v[120:123]
	v_mfma_f32_16x16x32_bf16 v[116:119], v[144:147], v[170:173], v[116:119]
	v_mfma_f32_16x16x32_bf16 v[112:115], v[152:155], v[170:173], v[112:115]
	v_mfma_f32_16x16x32_bf16 v[108:111], v[144:147], v[178:181], v[108:111]
	v_mfma_f32_16x16x32_bf16 v[104:107], v[152:155], v[178:181], v[104:107]
	v_mfma_f32_16x16x32_bf16 v[100:103], v[144:147], v[186:189], v[100:103]
	v_mfma_f32_16x16x32_bf16 v[96:99], v[152:155], v[186:189], v[96:99]
	v_mfma_f32_16x16x32_bf16 v[124:127], v[148:151], v[166:169], v[124:127]
	v_mfma_f32_16x16x32_bf16 v[120:123], v[158:161], v[166:169], v[120:123]
	v_mfma_f32_16x16x32_bf16 v[116:119], v[148:151], v[174:177], v[116:119]
	v_mfma_f32_16x16x32_bf16 v[112:115], v[158:161], v[174:177], v[112:115]
	v_mfma_f32_16x16x32_bf16 v[108:111], v[148:151], v[182:185], v[108:111]
	v_mfma_f32_16x16x32_bf16 v[104:107], v[158:161], v[182:185], v[104:107]
	v_mfma_f32_16x16x32_bf16 v[100:103], v[148:151], v[190:193], v[100:103]
	v_mfma_f32_16x16x32_bf16 v[96:99], v[158:161], v[190:193], v[96:99]
	s_barrier
	s_add_i32 s92, 0, 0x1c000
	s_add_i32 s91, s91, s5
	v_add_u32_e32 v157, s92, v143
	v_lshl_add_u64 v[218:219], v[214:215], 0, s[14:15]
	s_mov_b32 m0, s91
	ds_read_b128 v[194:197], v157
	ds_read_b128 v[198:201], v157 offset:1024
	ds_read_b128 v[202:205], v157 offset:2048
	ds_read_b128 v[206:209], v157 offset:3072
	global_load_lds_dwordx4 v[218:219], off
	v_lshl_add_u64 v[218:219], v[216:217], 0, s[14:15]
	s_add_i32 m0, s91, 0x2000
	s_nop 0
	global_load_lds_dwordx4 v[218:219], off
	s_barrier
	s_waitcnt lgkmcnt(0)
	s_waitcnt lgkmcnt(0)
	v_mfma_f32_16x16x32_bf16 v[92:95], v[194:197], v[162:165], v[92:95]
	v_mfma_f32_16x16x32_bf16 v[88:91], v[202:205], v[162:165], v[88:91]
	v_mfma_f32_16x16x32_bf16 v[84:87], v[194:197], v[170:173], v[84:87]
	v_mfma_f32_16x16x32_bf16 v[80:83], v[202:205], v[170:173], v[80:83]
	v_mfma_f32_16x16x32_bf16 v[76:79], v[194:197], v[178:181], v[76:79]
	v_mfma_f32_16x16x32_bf16 v[72:75], v[202:205], v[178:181], v[72:75]
	v_mfma_f32_16x16x32_bf16 v[68:71], v[194:197], v[186:189], v[68:71]
	v_mfma_f32_16x16x32_bf16 v[64:67], v[202:205], v[186:189], v[64:67]
	v_mfma_f32_16x16x32_bf16 v[92:95], v[198:201], v[166:169], v[92:95]
	v_mfma_f32_16x16x32_bf16 v[88:91], v[206:209], v[166:169], v[88:91]
	v_mfma_f32_16x16x32_bf16 v[84:87], v[198:201], v[174:177], v[84:87]
	v_mfma_f32_16x16x32_bf16 v[80:83], v[206:209], v[174:177], v[80:83]
	v_mfma_f32_16x16x32_bf16 v[76:79], v[198:201], v[182:185], v[76:79]
	v_mfma_f32_16x16x32_bf16 v[72:75], v[206:209], v[182:185], v[72:75]
	v_mfma_f32_16x16x32_bf16 v[68:71], v[198:201], v[190:193], v[68:71]
	v_mfma_f32_16x16x32_bf16 v[64:67], v[206:209], v[190:193], v[64:67]
	s_mov_b32 m0, s88
	v_lshl_add_u64 v[210:211], v[210:211], 0, s[14:15]
	s_barrier
	ds_read_b128 v[162:165], v142 offset:49152
	ds_read_b128 v[166:169], v142 offset:50176
	ds_read_b128 v[170:173], v142 offset:51200
	ds_read_b128 v[174:177], v142 offset:52224
	ds_read_b128 v[178:181], v142 offset:53248
	ds_read_b128 v[182:185], v142 offset:54272
	ds_read_b128 v[186:189], v142 offset:55296
	ds_read_b128 v[190:193], v142 offset:56320
	global_load_lds_dwordx4 v[210:211], off
	v_lshl_add_u64 v[210:211], v[212:213], 0, s[14:15]
	s_mov_b32 m0, s89
	s_nop 0
	global_load_lds_dwordx4 v[210:211], off
	s_barrier
	s_waitcnt lgkmcnt(0)
	s_waitcnt lgkmcnt(0)
	v_mfma_f32_16x16x32_bf16 v[60:63], v[144:147], v[162:165], v[60:63]
	v_mfma_f32_16x16x32_bf16 v[56:59], v[152:155], v[162:165], v[56:59]
	v_mfma_f32_16x16x32_bf16 v[52:55], v[144:147], v[170:173], v[52:55]
	v_mfma_f32_16x16x32_bf16 v[48:51], v[152:155], v[170:173], v[48:51]
	v_mfma_f32_16x16x32_bf16 v[44:47], v[144:147], v[178:181], v[44:47]
	v_mfma_f32_16x16x32_bf16 v[40:43], v[152:155], v[178:181], v[40:43]
	v_mfma_f32_16x16x32_bf16 v[36:39], v[144:147], v[186:189], v[36:39]
	v_mfma_f32_16x16x32_bf16 v[32:35], v[152:155], v[186:189], v[32:35]
	v_mfma_f32_16x16x32_bf16 v[60:63], v[148:151], v[166:169], v[60:63]
	v_mfma_f32_16x16x32_bf16 v[56:59], v[158:161], v[166:169], v[56:59]
	v_mfma_f32_16x16x32_bf16 v[52:55], v[148:151], v[174:177], v[52:55]
	v_mfma_f32_16x16x32_bf16 v[48:51], v[158:161], v[174:177], v[48:51]
	v_mfma_f32_16x16x32_bf16 v[44:47], v[148:151], v[182:185], v[44:47]
	v_mfma_f32_16x16x32_bf16 v[40:43], v[158:161], v[182:185], v[40:43]
	v_mfma_f32_16x16x32_bf16 v[36:39], v[148:151], v[190:193], v[36:39]
	v_mfma_f32_16x16x32_bf16 v[32:35], v[158:161], v[190:193], v[32:35]
	s_barrier
	s_add_i32 s91, s92, s5
	v_lshl_add_u64 v[144:145], v[214:215], 0, s[16:17]
	s_mov_b32 m0, s91
	s_nop 0
	global_load_lds_dwordx4 v[144:145], off
	v_lshl_add_u64 v[144:145], v[216:217], 0, s[16:17]
	s_add_i32 m0, s91, 0x2000
	s_nop 0
	global_load_lds_dwordx4 v[144:145], off
	s_waitcnt vmcnt(6)
	s_barrier
	v_mfma_f32_16x16x32_bf16 v[28:31], v[194:197], v[162:165], v[28:31]
	v_mfma_f32_16x16x32_bf16 v[24:27], v[202:205], v[162:165], v[24:27]
	v_mfma_f32_16x16x32_bf16 v[20:23], v[194:197], v[170:173], v[20:23]
	v_mfma_f32_16x16x32_bf16 v[16:19], v[202:205], v[170:173], v[16:19]
	v_mfma_f32_16x16x32_bf16 v[12:15], v[194:197], v[178:181], v[12:15]
	v_mfma_f32_16x16x32_bf16 v[8:11], v[202:205], v[178:181], v[8:11]
	v_mfma_f32_16x16x32_bf16 v[4:7], v[194:197], v[186:189], v[4:7]
	v_mfma_f32_16x16x32_bf16 v[0:3], v[202:205], v[186:189], v[0:3]
	v_mfma_f32_16x16x32_bf16 v[28:31], v[198:201], v[166:169], v[28:31]
	v_mfma_f32_16x16x32_bf16 v[24:27], v[206:209], v[166:169], v[24:27]
	v_mfma_f32_16x16x32_bf16 v[20:23], v[198:201], v[174:177], v[20:23]
	v_mfma_f32_16x16x32_bf16 v[16:19], v[206:209], v[174:177], v[16:19]
	v_mfma_f32_16x16x32_bf16 v[12:15], v[198:201], v[182:185], v[12:15]
	v_mfma_f32_16x16x32_bf16 v[8:11], v[206:209], v[182:185], v[8:11]
	v_mfma_f32_16x16x32_bf16 v[4:7], v[198:201], v[190:193], v[4:7]
	v_mfma_f32_16x16x32_bf16 v[0:3], v[206:209], v[190:193], v[0:3]
	s_add_i32 s22, s22, 2
	s_add_u32 s20, s20, 0x100
	s_addc_u32 s21, s21, 0
	s_cmp_gt_u32 s22, 11
	s_barrier
	s_cbranch_scc0 .LBB0_280
	v_add_u32_e32 v140, 0, v143
	s_add_u32 s18, s18, 0x40780
	v_add_u32_e32 v134, 0x10000, v140
	s_addc_u32 s19, s19, 0
	s_mov_b32 m0, s90
	ds_read_b128 v[130:133], v134
	ds_read_b128 v[144:147], v134 offset:1024
	ds_read_b128 v[148:151], v134 offset:2048
	ds_read_b128 v[152:155], v134 offset:3072
	ds_read_b128 v[158:161], v142
	ds_read_b128 v[162:165], v142 offset:1024
	ds_read_b128 v[166:169], v142 offset:2048
	ds_read_b128 v[170:173], v142 offset:3072
	ds_read_b128 v[174:177], v142 offset:4096
	ds_read_b128 v[178:181], v142 offset:5120
	ds_read_b128 v[182:185], v142 offset:6144
	ds_read_b128 v[186:189], v142 offset:7168
	v_lshl_add_u64 v[134:135], s[18:19], 0, v[138:139]
	global_load_lds_dwordx4 v[134:135], off
	v_lshl_add_u64 v[128:129], s[18:19], 0, v[128:129]
	s_mov_b32 m0, s23
	s_nop 0
	global_load_lds_dwordx4 v[128:129], off
	s_barrier
	s_waitcnt lgkmcnt(0)
	s_waitcnt lgkmcnt(0)
	v_mfma_f32_16x16x32_bf16 v[124:127], v[130:133], v[158:161], v[124:127]
	v_mfma_f32_16x16x32_bf16 v[120:123], v[148:151], v[158:161], v[120:123]
	v_mfma_f32_16x16x32_bf16 v[108:111], v[130:133], v[174:177], v[108:111]
	v_mfma_f32_16x16x32_bf16 v[104:107], v[148:151], v[174:177], v[104:107]
	v_mfma_f32_16x16x32_bf16 v[124:127], v[144:147], v[162:165], v[124:127]
	v_mfma_f32_16x16x32_bf16 v[120:123], v[152:155], v[162:165], v[120:123]
	v_mfma_f32_16x16x32_bf16 v[116:119], v[130:133], v[166:169], v[116:119]
	v_mfma_f32_16x16x32_bf16 v[112:115], v[148:151], v[166:169], v[112:115]
	v_mfma_f32_16x16x32_bf16 v[108:111], v[144:147], v[178:181], v[108:111]
	v_mfma_f32_16x16x32_bf16 v[104:107], v[152:155], v[178:181], v[104:107]
	v_mfma_f32_16x16x32_bf16 v[100:103], v[130:133], v[182:185], v[100:103]
	v_mfma_f32_16x16x32_bf16 v[96:99], v[148:151], v[182:185], v[96:99]
	v_mfma_f32_16x16x32_bf16 v[190:193], v[144:147], v[170:173], v[116:119]
	v_mfma_f32_16x16x32_bf16 v[194:197], v[152:155], v[170:173], v[112:115]
	v_mfma_f32_16x16x32_bf16 v[198:201], v[144:147], v[186:189], v[100:103]
	v_mfma_f32_16x16x32_bf16 v[202:205], v[152:155], v[186:189], v[96:99]
	v_add_u32_e32 v116, 0x14000, v140
	s_barrier
	s_nop 0
	ds_read_b128 v[96:99], v116
	ds_read_b128 v[100:103], v116 offset:1024
	ds_read_b128 v[112:115], v116 offset:2048
	ds_read_b128 v[116:119], v116 offset:3072
	s_barrier
	s_waitcnt lgkmcnt(0)
	s_waitcnt lgkmcnt(0)
	v_mfma_f32_16x16x32_bf16 v[92:95], v[96:99], v[158:161], v[92:95]
	v_mfma_f32_16x16x32_bf16 v[88:91], v[112:115], v[158:161], v[88:91]
	v_mfma_f32_16x16x32_bf16 v[76:79], v[96:99], v[174:177], v[76:79]
	v_mfma_f32_16x16x32_bf16 v[72:75], v[112:115], v[174:177], v[72:75]
	v_mfma_f32_16x16x32_bf16 v[92:95], v[100:103], v[162:165], v[92:95]
	v_mfma_f32_16x16x32_bf16 v[88:91], v[116:119], v[162:165], v[88:91]
	v_mfma_f32_16x16x32_bf16 v[84:87], v[96:99], v[166:169], v[84:87]
	v_mfma_f32_16x16x32_bf16 v[80:83], v[112:115], v[166:169], v[80:83]
	v_mfma_f32_16x16x32_bf16 v[76:79], v[100:103], v[178:181], v[76:79]
	v_mfma_f32_16x16x32_bf16 v[72:75], v[116:119], v[178:181], v[72:75]
	v_mfma_f32_16x16x32_bf16 v[68:71], v[96:99], v[182:185], v[68:71]
	v_mfma_f32_16x16x32_bf16 v[64:67], v[112:115], v[182:185], v[64:67]
	v_mfma_f32_16x16x32_bf16 v[158:161], v[100:103], v[170:173], v[84:87]
	v_mfma_f32_16x16x32_bf16 v[162:165], v[116:119], v[170:173], v[80:83]
	v_mfma_f32_16x16x32_bf16 v[166:169], v[100:103], v[186:189], v[68:71]
	v_mfma_f32_16x16x32_bf16 v[170:173], v[116:119], v[186:189], v[64:67]
	s_barrier
	s_nop 1
	ds_read_b128 v[64:67], v142 offset:16384
	ds_read_b128 v[68:71], v142 offset:17408
	ds_read_b128 v[80:83], v142 offset:18432
	ds_read_b128 v[84:87], v142 offset:19456
	ds_read_b128 v[174:177], v142 offset:20480
	ds_read_b128 v[178:181], v142 offset:21504
	ds_read_b128 v[182:185], v142 offset:22528
	ds_read_b128 v[186:189], v142 offset:23552
	s_waitcnt vmcnt(4)
	s_barrier
	s_waitcnt lgkmcnt(0)
	s_waitcnt lgkmcnt(0)
	v_mfma_f32_16x16x32_bf16 v[60:63], v[130:133], v[64:67], v[60:63]
	v_mfma_f32_16x16x32_bf16 v[56:59], v[148:151], v[64:67], v[56:59]
	v_mfma_f32_16x16x32_bf16 v[44:47], v[130:133], v[174:177], v[44:47]
	v_mfma_f32_16x16x32_bf16 v[40:43], v[148:151], v[174:177], v[40:43]
	v_mfma_f32_16x16x32_bf16 v[60:63], v[144:147], v[68:71], v[60:63]
	v_mfma_f32_16x16x32_bf16 v[56:59], v[152:155], v[68:71], v[56:59]
	v_mfma_f32_16x16x32_bf16 v[52:55], v[130:133], v[80:83], v[52:55]
	v_mfma_f32_16x16x32_bf16 v[48:51], v[148:151], v[80:83], v[48:51]
	v_mfma_f32_16x16x32_bf16 v[44:47], v[144:147], v[178:181], v[44:47]
	v_mfma_f32_16x16x32_bf16 v[40:43], v[152:155], v[178:181], v[40:43]
	v_mfma_f32_16x16x32_bf16 v[36:39], v[130:133], v[182:185], v[36:39]
	v_mfma_f32_16x16x32_bf16 v[32:35], v[148:151], v[182:185], v[32:35]
	v_mfma_f32_16x16x32_bf16 v[206:209], v[144:147], v[84:87], v[52:55]
	v_mfma_f32_16x16x32_bf16 v[210:213], v[152:155], v[84:87], v[48:51]
	v_mfma_f32_16x16x32_bf16 v[128:131], v[144:147], v[186:189], v[36:39]
	v_mfma_f32_16x16x32_bf16 v[132:135], v[152:155], v[186:189], v[32:35]
	v_mfma_f32_16x16x32_bf16 v[28:31], v[96:99], v[64:67], v[28:31]
	v_mfma_f32_16x16x32_bf16 v[24:27], v[112:115], v[64:67], v[24:27]
	v_mfma_f32_16x16x32_bf16 v[12:15], v[96:99], v[174:177], v[12:15]
	v_mfma_f32_16x16x32_bf16 v[8:11], v[112:115], v[174:177], v[8:11]
	v_mfma_f32_16x16x32_bf16 v[28:31], v[100:103], v[68:71], v[28:31]
	v_mfma_f32_16x16x32_bf16 v[24:27], v[116:119], v[68:71], v[24:27]
	v_mfma_f32_16x16x32_bf16 v[20:23], v[96:99], v[80:83], v[20:23]
	v_mfma_f32_16x16x32_bf16 v[16:19], v[112:115], v[80:83], v[16:19]
	v_mfma_f32_16x16x32_bf16 v[12:15], v[100:103], v[178:181], v[12:15]
	v_mfma_f32_16x16x32_bf16 v[8:11], v[116:119], v[178:181], v[8:11]
	v_mfma_f32_16x16x32_bf16 v[4:7], v[96:99], v[182:185], v[4:7]
	v_mfma_f32_16x16x32_bf16 v[0:3], v[112:115], v[182:185], v[0:3]
	v_mfma_f32_16x16x32_bf16 v[144:147], v[100:103], v[84:87], v[20:23]
	v_mfma_f32_16x16x32_bf16 v[148:151], v[116:119], v[84:87], v[16:19]
	v_mfma_f32_16x16x32_bf16 v[152:155], v[100:103], v[186:189], v[4:7]
	v_mfma_f32_16x16x32_bf16 v[174:177], v[116:119], v[186:189], v[0:3]
	v_add_u32_e32 v16, 0x18000, v140
	s_barrier
	s_nop 0
	ds_read_b128 v[0:3], v16
	ds_read_b128 v[4:7], v16 offset:1024
	ds_read_b128 v[178:181], v16 offset:2048
	ds_read_b128 v[182:185], v16 offset:3072
	ds_read_b128 v[16:19], v142 offset:32768
	ds_read_b128 v[20:23], v142 offset:33792
	ds_read_b128 v[32:35], v142 offset:34816
	ds_read_b128 v[36:39], v142 offset:35840
	ds_read_b128 v[48:51], v142 offset:36864
	ds_read_b128 v[52:55], v142 offset:37888
	ds_read_b128 v[186:189], v142 offset:38912
	ds_read_b128 v[214:217], v142 offset:39936
	s_waitcnt vmcnt(2)
	s_barrier
	s_waitcnt lgkmcnt(0)
	s_waitcnt lgkmcnt(0)
	v_mfma_f32_16x16x32_bf16 v[64:67], v[0:3], v[16:19], v[124:127]
	v_mfma_f32_16x16x32_bf16 v[116:119], v[4:7], v[20:23], v[64:67]
	v_mfma_f32_16x16x32_bf16 v[64:67], v[178:181], v[16:19], v[120:123]
	v_mfma_f32_16x16x32_bf16 v[112:115], v[182:185], v[20:23], v[64:67]
	v_mfma_f32_16x16x32_bf16 v[64:67], v[0:3], v[32:35], v[190:193]
	v_mfma_f32_16x16x32_bf16 v[100:103], v[4:7], v[36:39], v[64:67]
	v_mfma_f32_16x16x32_bf16 v[64:67], v[178:181], v[32:35], v[194:197]
	v_mfma_f32_16x16x32_bf16 v[96:99], v[182:185], v[36:39], v[64:67]
	v_mfma_f32_16x16x32_bf16 v[64:67], v[0:3], v[48:51], v[108:111]
	v_mfma_f32_16x16x32_bf16 v[84:87], v[4:7], v[52:55], v[64:67]
	v_mfma_f32_16x16x32_bf16 v[64:67], v[178:181], v[48:51], v[104:107]
	v_mfma_f32_16x16x32_bf16 v[80:83], v[182:185], v[52:55], v[64:67]
	v_mfma_f32_16x16x32_bf16 v[64:67], v[0:3], v[186:189], v[198:201]
	v_mfma_f32_16x16x32_bf16 v[68:71], v[4:7], v[214:217], v[64:67]
	v_mfma_f32_16x16x32_bf16 v[64:67], v[178:181], v[186:189], v[202:205]
	v_mfma_f32_16x16x32_bf16 v[64:67], v[182:185], v[214:217], v[64:67]
	v_add_u32_e32 v104, 0x1c000, v140
	s_barrier
	ds_read_b128 v[190:193], v104
	ds_read_b128 v[194:197], v104 offset:1024
	ds_read_b128 v[198:201], v104 offset:2048
	ds_read_b128 v[202:205], v104 offset:3072
	s_waitcnt vmcnt(0)
	s_barrier
	s_waitcnt lgkmcnt(0)
	s_waitcnt lgkmcnt(0)
	v_mfma_f32_16x16x32_bf16 v[92:95], v[190:193], v[16:19], v[92:95]
	v_mfma_f32_16x16x32_bf16 v[16:19], v[198:201], v[16:19], v[88:91]
	v_mfma_f32_16x16x32_bf16 v[120:123], v[202:205], v[20:23], v[16:19]
	v_mfma_f32_16x16x32_bf16 v[16:19], v[190:193], v[32:35], v[158:161]
	v_mfma_f32_16x16x32_bf16 v[108:111], v[194:197], v[36:39], v[16:19]
	v_mfma_f32_16x16x32_bf16 v[16:19], v[198:201], v[32:35], v[162:165]
	v_mfma_f32_16x16x32_bf16 v[104:107], v[202:205], v[36:39], v[16:19]
	v_mfma_f32_16x16x32_bf16 v[16:19], v[190:193], v[48:51], v[76:79]
	v_mfma_f32_16x16x32_bf16 v[124:127], v[194:197], v[20:23], v[92:95]
	v_mfma_f32_16x16x32_bf16 v[92:95], v[194:197], v[52:55], v[16:19]
	v_mfma_f32_16x16x32_bf16 v[16:19], v[198:201], v[48:51], v[72:75]
	v_mfma_f32_16x16x32_bf16 v[88:91], v[202:205], v[52:55], v[16:19]
	v_mfma_f32_16x16x32_bf16 v[16:19], v[190:193], v[186:189], v[166:169]
	v_mfma_f32_16x16x32_bf16 v[76:79], v[194:197], v[214:217], v[16:19]
	v_mfma_f32_16x16x32_bf16 v[16:19], v[198:201], v[186:189], v[170:173]
	v_mfma_f32_16x16x32_bf16 v[72:75], v[202:205], v[214:217], v[16:19]
	s_barrier
	ds_read_b128 v[158:161], v142 offset:49152
	ds_read_b128 v[162:165], v142 offset:50176
	ds_read_b128 v[166:169], v142 offset:51200
	ds_read_b128 v[170:173], v142 offset:52224
	ds_read_b128 v[186:189], v142 offset:53248
	ds_read_b128 v[214:217], v142 offset:54272
	ds_read_b128 v[218:221], v142 offset:55296
	ds_read_b128 v[140:143], v142 offset:56320
	s_barrier
	s_waitcnt lgkmcnt(0)
	s_waitcnt lgkmcnt(0)
	v_mfma_f32_16x16x32_bf16 v[16:19], v[0:3], v[158:161], v[60:63]
	v_mfma_f32_16x16x32_bf16 v[52:55], v[4:7], v[162:165], v[16:19]
	v_mfma_f32_16x16x32_bf16 v[16:19], v[178:181], v[158:161], v[56:59]
	v_mfma_f32_16x16x32_bf16 v[48:51], v[182:185], v[162:165], v[16:19]
	v_mfma_f32_16x16x32_bf16 v[16:19], v[0:3], v[166:169], v[206:209]
	v_mfma_f32_16x16x32_bf16 v[36:39], v[4:7], v[170:173], v[16:19]
	v_mfma_f32_16x16x32_bf16 v[16:19], v[178:181], v[166:169], v[210:213]
	v_mfma_f32_16x16x32_bf16 v[32:35], v[182:185], v[170:173], v[16:19]
	v_mfma_f32_16x16x32_bf16 v[16:19], v[0:3], v[186:189], v[44:47]
	v_mfma_f32_16x16x32_bf16 v[0:3], v[0:3], v[218:221], v[128:131]
	v_mfma_f32_16x16x32_bf16 v[20:23], v[4:7], v[214:217], v[16:19]
	v_mfma_f32_16x16x32_bf16 v[16:19], v[178:181], v[186:189], v[40:43]
	v_mfma_f32_16x16x32_bf16 v[4:7], v[4:7], v[140:143], v[0:3]
	v_mfma_f32_16x16x32_bf16 v[0:3], v[178:181], v[218:221], v[132:135]
	v_mfma_f32_16x16x32_bf16 v[16:19], v[182:185], v[214:217], v[16:19]
	v_mfma_f32_16x16x32_bf16 v[0:3], v[182:185], v[140:143], v[0:3]
	v_mfma_f32_16x16x32_bf16 v[24:27], v[198:201], v[158:161], v[24:27]
	v_mfma_f32_16x16x32_bf16 v[56:59], v[202:205], v[162:165], v[24:27]
	v_mfma_f32_16x16x32_bf16 v[24:27], v[190:193], v[166:169], v[144:147]
	v_mfma_f32_16x16x32_bf16 v[44:47], v[194:197], v[170:173], v[24:27]
	v_mfma_f32_16x16x32_bf16 v[24:27], v[198:201], v[166:169], v[148:151]
	v_mfma_f32_16x16x32_bf16 v[8:11], v[198:201], v[186:189], v[8:11]
	v_mfma_f32_16x16x32_bf16 v[28:31], v[190:193], v[158:161], v[28:31]
	v_mfma_f32_16x16x32_bf16 v[40:43], v[202:205], v[170:173], v[24:27]
	v_mfma_f32_16x16x32_bf16 v[12:15], v[190:193], v[186:189], v[12:15]
	v_mfma_f32_16x16x32_bf16 v[24:27], v[202:205], v[214:217], v[8:11]
	v_mfma_f32_16x16x32_bf16 v[8:11], v[190:193], v[218:221], v[152:155]
	v_mfma_f32_16x16x32_bf16 v[60:63], v[194:197], v[162:165], v[28:31]
	v_mfma_f32_16x16x32_bf16 v[28:31], v[194:197], v[214:217], v[12:15]
	v_mfma_f32_16x16x32_bf16 v[12:15], v[194:197], v[140:143], v[8:11]
	v_mfma_f32_16x16x32_bf16 v[8:11], v[198:201], v[218:221], v[174:177]
	v_mfma_f32_16x16x32_bf16 v[8:11], v[202:205], v[140:143], v[8:11]
	s_cmpk_lt_u32 s1, 0x100
	s_barrier
	s_cbranch_scc0 .LBB0_283
	s_barrier

.LBB0_416:
	s_add_i32 s91, 0, 0x10000
	v_add_u32_e32 v157, s91, v143
	ds_read_b128 v[144:147], v157
	ds_read_b128 v[148:151], v157 offset:1024
	ds_read_b128 v[152:155], v157 offset:2048
	ds_read_b128 v[158:161], v157 offset:3072
	v_lshl_add_u64 v[210:211], v[130:131], 0, s[18:19]
	s_add_i32 s90, s22, 0xc000
	v_lshl_add_u64 v[194:195], v[210:211], 0, s[8:9]
	s_mov_b32 m0, s90
	v_lshl_add_u64 v[212:213], v[132:133], 0, s[18:19]
	s_add_i32 s89, s22, 0xe000
	ds_read_b128 v[162:165], v142
	ds_read_b128 v[166:169], v142 offset:1024
	ds_read_b128 v[170:173], v142 offset:2048
	ds_read_b128 v[174:177], v142 offset:3072
	ds_read_b128 v[178:181], v142 offset:4096
	ds_read_b128 v[182:185], v142 offset:5120
	ds_read_b128 v[186:189], v142 offset:6144
	ds_read_b128 v[190:193], v142 offset:7168
	global_load_lds_dwordx4 v[194:195], off
	v_lshl_add_u64 v[194:195], v[212:213], 0, s[8:9]
	s_mov_b32 m0, s89
	s_nop 0
	global_load_lds_dwordx4 v[194:195], off
	s_waitcnt lgkmcnt(8)
	s_barrier
	s_waitcnt lgkmcnt(0)
	s_waitcnt lgkmcnt(0)
	v_mfma_f32_16x16x32_bf16 v[124:127], v[144:147], v[162:165], v[124:127]
	v_mfma_f32_16x16x32_bf16 v[120:123], v[152:155], v[162:165], v[120:123]
	v_mfma_f32_16x16x32_bf16 v[116:119], v[144:147], v[170:173], v[116:119]
	v_mfma_f32_16x16x32_bf16 v[112:115], v[152:155], v[170:173], v[112:115]
	v_mfma_f32_16x16x32_bf16 v[108:111], v[144:147], v[178:181], v[108:111]
	v_mfma_f32_16x16x32_bf16 v[104:107], v[152:155], v[178:181], v[104:107]
	v_mfma_f32_16x16x32_bf16 v[100:103], v[144:147], v[186:189], v[100:103]
	v_mfma_f32_16x16x32_bf16 v[96:99], v[152:155], v[186:189], v[96:99]
	v_mfma_f32_16x16x32_bf16 v[124:127], v[148:151], v[166:169], v[124:127]
	v_mfma_f32_16x16x32_bf16 v[120:123], v[158:161], v[166:169], v[120:123]
	v_mfma_f32_16x16x32_bf16 v[116:119], v[148:151], v[174:177], v[116:119]
	v_mfma_f32_16x16x32_bf16 v[112:115], v[158:161], v[174:177], v[112:115]
	v_mfma_f32_16x16x32_bf16 v[108:111], v[148:151], v[182:185], v[108:111]
	v_mfma_f32_16x16x32_bf16 v[104:107], v[158:161], v[182:185], v[104:107]
	v_mfma_f32_16x16x32_bf16 v[100:103], v[148:151], v[190:193], v[100:103]
	v_mfma_f32_16x16x32_bf16 v[96:99], v[158:161], v[190:193], v[96:99]
	s_barrier
	s_add_i32 s92, 0, 0x14000
	v_lshl_add_u64 v[214:215], v[134:135], 0, s[18:19]
	s_add_i32 s91, s91, s21
	v_add_u32_e32 v157, s92, v143
	v_lshl_add_u64 v[216:217], v[214:215], 0, s[10:11]
	s_mov_b32 m0, s91
	ds_read_b128 v[194:197], v157
	ds_read_b128 v[198:201], v157 offset:1024
	ds_read_b128 v[202:205], v157 offset:2048
	ds_read_b128 v[206:209], v157 offset:3072
	global_load_lds_dwordx4 v[216:217], off
	v_lshl_add_u64 v[216:217], v[140:141], 0, s[18:19]
	v_lshl_add_u64 v[218:219], v[216:217], 0, s[10:11]
	s_add_i32 m0, s91, 0x2000
	s_nop 0
	global_load_lds_dwordx4 v[218:219], off
	s_barrier
	s_waitcnt lgkmcnt(0)
	s_waitcnt lgkmcnt(0)
	v_mfma_f32_16x16x32_bf16 v[92:95], v[194:197], v[162:165], v[92:95]
	v_mfma_f32_16x16x32_bf16 v[88:91], v[202:205], v[162:165], v[88:91]
	v_mfma_f32_16x16x32_bf16 v[84:87], v[194:197], v[170:173], v[84:87]
	v_mfma_f32_16x16x32_bf16 v[80:83], v[202:205], v[170:173], v[80:83]
	v_mfma_f32_16x16x32_bf16 v[76:79], v[194:197], v[178:181], v[76:79]
	v_mfma_f32_16x16x32_bf16 v[72:75], v[202:205], v[178:181], v[72:75]
	v_mfma_f32_16x16x32_bf16 v[68:71], v[194:197], v[186:189], v[68:71]
	v_mfma_f32_16x16x32_bf16 v[64:67], v[202:205], v[186:189], v[64:67]
	v_mfma_f32_16x16x32_bf16 v[92:95], v[198:201], v[166:169], v[92:95]
	v_mfma_f32_16x16x32_bf16 v[88:91], v[206:209], v[166:169], v[88:91]
	v_mfma_f32_16x16x32_bf16 v[84:87], v[198:201], v[174:177], v[84:87]
	v_mfma_f32_16x16x32_bf16 v[80:83], v[206:209], v[174:177], v[80:83]
	v_mfma_f32_16x16x32_bf16 v[76:79], v[198:201], v[182:185], v[76:79]
	v_mfma_f32_16x16x32_bf16 v[72:75], v[206:209], v[182:185], v[72:75]
	v_mfma_f32_16x16x32_bf16 v[68:71], v[198:201], v[190:193], v[68:71]
	v_mfma_f32_16x16x32_bf16 v[64:67], v[206:209], v[190:193], v[64:67]
	s_mov_b32 m0, s22
	v_lshl_add_u64 v[218:219], v[210:211], 0, s[10:11]
	s_barrier
	ds_read_b128 v[162:165], v142 offset:16384
	ds_read_b128 v[166:169], v142 offset:17408
	ds_read_b128 v[170:173], v142 offset:18432
	ds_read_b128 v[174:177], v142 offset:19456
	ds_read_b128 v[178:181], v142 offset:20480
	ds_read_b128 v[182:185], v142 offset:21504
	ds_read_b128 v[186:189], v142 offset:22528
	ds_read_b128 v[190:193], v142 offset:23552
	global_load_lds_dwordx4 v[218:219], off
	v_lshl_add_u64 v[218:219], v[212:213], 0, s[10:11]
	s_mov_b32 m0, s23
	s_nop 0
	global_load_lds_dwordx4 v[218:219], off
	s_barrier
	s_waitcnt lgkmcnt(0)
	s_waitcnt lgkmcnt(0)
	v_mfma_f32_16x16x32_bf16 v[60:63], v[144:147], v[162:165], v[60:63]
	v_mfma_f32_16x16x32_bf16 v[56:59], v[152:155], v[162:165], v[56:59]
	v_mfma_f32_16x16x32_bf16 v[52:55], v[144:147], v[170:173], v[52:55]
	v_mfma_f32_16x16x32_bf16 v[48:51], v[152:155], v[170:173], v[48:51]
	v_mfma_f32_16x16x32_bf16 v[44:47], v[144:147], v[178:181], v[44:47]
	v_mfma_f32_16x16x32_bf16 v[40:43], v[152:155], v[178:181], v[40:43]
	v_mfma_f32_16x16x32_bf16 v[36:39], v[144:147], v[186:189], v[36:39]
	v_mfma_f32_16x16x32_bf16 v[32:35], v[152:155], v[186:189], v[32:35]
	v_mfma_f32_16x16x32_bf16 v[60:63], v[148:151], v[166:169], v[60:63]
	v_mfma_f32_16x16x32_bf16 v[56:59], v[158:161], v[166:169], v[56:59]
	v_mfma_f32_16x16x32_bf16 v[52:55], v[148:151], v[174:177], v[52:55]
	v_mfma_f32_16x16x32_bf16 v[48:51], v[158:161], v[174:177], v[48:51]
	v_mfma_f32_16x16x32_bf16 v[44:47], v[148:151], v[182:185], v[44:47]
	v_mfma_f32_16x16x32_bf16 v[40:43], v[158:161], v[182:185], v[40:43]
	v_mfma_f32_16x16x32_bf16 v[36:39], v[148:151], v[190:193], v[36:39]
	v_mfma_f32_16x16x32_bf16 v[32:35], v[158:161], v[190:193], v[32:35]
	s_barrier
	s_add_i32 s91, s92, s21
	v_lshl_add_u64 v[144:145], v[214:215], 0, s[12:13]
	s_mov_b32 m0, s91
	s_nop 0
	global_load_lds_dwordx4 v[144:145], off
	v_lshl_add_u64 v[144:145], v[216:217], 0, s[12:13]
	s_add_i32 m0, s91, 0x2000
	s_nop 0
	global_load_lds_dwordx4 v[144:145], off
	s_waitcnt vmcnt(6)
	s_barrier
	v_mfma_f32_16x16x32_bf16 v[28:31], v[194:197], v[162:165], v[28:31]
	v_mfma_f32_16x16x32_bf16 v[24:27], v[202:205], v[162:165], v[24:27]
	v_mfma_f32_16x16x32_bf16 v[20:23], v[194:197], v[170:173], v[20:23]
	v_mfma_f32_16x16x32_bf16 v[16:19], v[202:205], v[170:173], v[16:19]
	v_mfma_f32_16x16x32_bf16 v[12:15], v[194:197], v[178:181], v[12:15]
	v_mfma_f32_16x16x32_bf16 v[8:11], v[202:205], v[178:181], v[8:11]
	v_mfma_f32_16x16x32_bf16 v[4:7], v[194:197], v[186:189], v[4:7]
	v_mfma_f32_16x16x32_bf16 v[0:3], v[202:205], v[186:189], v[0:3]
	v_mfma_f32_16x16x32_bf16 v[28:31], v[198:201], v[166:169], v[28:31]
	v_mfma_f32_16x16x32_bf16 v[24:27], v[206:209], v[166:169], v[24:27]
	v_mfma_f32_16x16x32_bf16 v[20:23], v[198:201], v[174:177], v[20:23]
	v_mfma_f32_16x16x32_bf16 v[16:19], v[206:209], v[174:177], v[16:19]
	v_mfma_f32_16x16x32_bf16 v[12:15], v[198:201], v[182:185], v[12:15]
	v_mfma_f32_16x16x32_bf16 v[8:11], v[206:209], v[182:185], v[8:11]
	v_mfma_f32_16x16x32_bf16 v[4:7], v[198:201], v[190:193], v[4:7]
	v_mfma_f32_16x16x32_bf16 v[0:3], v[206:209], v[190:193], v[0:3]
	s_add_i32 s91, 0, 0x18000
	v_add_u32_e32 v157, s91, v143
	s_barrier
	ds_read_b128 v[144:147], v157
	ds_read_b128 v[148:151], v157 offset:1024
	ds_read_b128 v[152:155], v157 offset:2048
	ds_read_b128 v[158:161], v157 offset:3072
	s_mov_b32 m0, s33
	v_lshl_add_u64 v[194:195], v[210:211], 0, s[12:13]
	ds_read_b128 v[162:165], v142 offset:32768
	ds_read_b128 v[166:169], v142 offset:33792
	ds_read_b128 v[170:173], v142 offset:34816
	ds_read_b128 v[174:177], v142 offset:35840
	ds_read_b128 v[178:181], v142 offset:36864
	ds_read_b128 v[182:185], v142 offset:37888
	ds_read_b128 v[186:189], v142 offset:38912
	ds_read_b128 v[190:193], v142 offset:39936
	global_load_lds_dwordx4 v[194:195], off
	v_lshl_add_u64 v[194:195], v[212:213], 0, s[12:13]
	s_mov_b32 m0, s51
	s_nop 0
	global_load_lds_dwordx4 v[194:195], off
	s_waitcnt lgkmcnt(8)
	s_barrier
	s_waitcnt lgkmcnt(0)
	s_waitcnt lgkmcnt(0)
	v_mfma_f32_16x16x32_bf16 v[124:127], v[144:147], v[162:165], v[124:127]
	v_mfma_f32_16x16x32_bf16 v[120:123], v[152:155], v[162:165], v[120:123]
	v_mfma_f32_16x16x32_bf16 v[116:119], v[144:147], v[170:173], v[116:119]
	v_mfma_f32_16x16x32_bf16 v[112:115], v[152:155], v[170:173], v[112:115]
	v_mfma_f32_16x16x32_bf16 v[108:111], v[144:147], v[178:181], v[108:111]
	v_mfma_f32_16x16x32_bf16 v[104:107], v[152:155], v[178:181], v[104:107]
	v_mfma_f32_16x16x32_bf16 v[100:103], v[144:147], v[186:189], v[100:103]
	v_mfma_f32_16x16x32_bf16 v[96:99], v[152:155], v[186:189], v[96:99]
	v_mfma_f32_16x16x32_bf16 v[124:127], v[148:151], v[166:169], v[124:127]
	v_mfma_f32_16x16x32_bf16 v[120:123], v[158:161], v[166:169], v[120:123]
	v_mfma_f32_16x16x32_bf16 v[116:119], v[148:151], v[174:177], v[116:119]
	v_mfma_f32_16x16x32_bf16 v[112:115], v[158:161], v[174:177], v[112:115]
	v_mfma_f32_16x16x32_bf16 v[108:111], v[148:151], v[182:185], v[108:111]
	v_mfma_f32_16x16x32_bf16 v[104:107], v[158:161], v[182:185], v[104:107]
	v_mfma_f32_16x16x32_bf16 v[100:103], v[148:151], v[190:193], v[100:103]
	v_mfma_f32_16x16x32_bf16 v[96:99], v[158:161], v[190:193], v[96:99]
	s_barrier
	s_add_i32 s92, 0, 0x1c000
	s_add_i32 s91, s91, s21
	v_add_u32_e32 v157, s92, v143
	v_lshl_add_u64 v[218:219], v[214:215], 0, s[14:15]
	s_mov_b32 m0, s91
	ds_read_b128 v[194:197], v157
	ds_read_b128 v[198:201], v157 offset:1024
	ds_read_b128 v[202:205], v157 offset:2048
	ds_read_b128 v[206:209], v157 offset:3072
	global_load_lds_dwordx4 v[218:219], off
	v_lshl_add_u64 v[218:219], v[216:217], 0, s[14:15]
	s_add_i32 m0, s91, 0x2000
	s_nop 0
	global_load_lds_dwordx4 v[218:219], off
	s_barrier
	s_waitcnt lgkmcnt(0)
	s_waitcnt lgkmcnt(0)
	v_mfma_f32_16x16x32_bf16 v[92:95], v[194:197], v[162:165], v[92:95]
	v_mfma_f32_16x16x32_bf16 v[88:91], v[202:205], v[162:165], v[88:91]
	v_mfma_f32_16x16x32_bf16 v[84:87], v[194:197], v[170:173], v[84:87]
	v_mfma_f32_16x16x32_bf16 v[80:83], v[202:205], v[170:173], v[80:83]
	v_mfma_f32_16x16x32_bf16 v[76:79], v[194:197], v[178:181], v[76:79]
	v_mfma_f32_16x16x32_bf16 v[72:75], v[202:205], v[178:181], v[72:75]
	v_mfma_f32_16x16x32_bf16 v[68:71], v[194:197], v[186:189], v[68:71]
	v_mfma_f32_16x16x32_bf16 v[64:67], v[202:205], v[186:189], v[64:67]
	v_mfma_f32_16x16x32_bf16 v[92:95], v[198:201], v[166:169], v[92:95]
	v_mfma_f32_16x16x32_bf16 v[88:91], v[206:209], v[166:169], v[88:91]
	v_mfma_f32_16x16x32_bf16 v[84:87], v[198:201], v[174:177], v[84:87]
	v_mfma_f32_16x16x32_bf16 v[80:83], v[206:209], v[174:177], v[80:83]
	v_mfma_f32_16x16x32_bf16 v[76:79], v[198:201], v[182:185], v[76:79]
	v_mfma_f32_16x16x32_bf16 v[72:75], v[206:209], v[182:185], v[72:75]
	v_mfma_f32_16x16x32_bf16 v[68:71], v[198:201], v[190:193], v[68:71]
	v_mfma_f32_16x16x32_bf16 v[64:67], v[206:209], v[190:193], v[64:67]
	s_mov_b32 m0, s52
	v_lshl_add_u64 v[210:211], v[210:211], 0, s[14:15]
	s_barrier
	ds_read_b128 v[162:165], v142 offset:49152
	ds_read_b128 v[166:169], v142 offset:50176
	ds_read_b128 v[170:173], v142 offset:51200
	ds_read_b128 v[174:177], v142 offset:52224
	ds_read_b128 v[178:181], v142 offset:53248
	ds_read_b128 v[182:185], v142 offset:54272
	ds_read_b128 v[186:189], v142 offset:55296
	ds_read_b128 v[190:193], v142 offset:56320
	global_load_lds_dwordx4 v[210:211], off
	v_lshl_add_u64 v[210:211], v[212:213], 0, s[14:15]
	s_mov_b32 m0, s53
	s_nop 0
	global_load_lds_dwordx4 v[210:211], off
	s_barrier
	s_waitcnt lgkmcnt(0)
	s_waitcnt lgkmcnt(0)
	v_mfma_f32_16x16x32_bf16 v[60:63], v[144:147], v[162:165], v[60:63]
	v_mfma_f32_16x16x32_bf16 v[56:59], v[152:155], v[162:165], v[56:59]
	v_mfma_f32_16x16x32_bf16 v[52:55], v[144:147], v[170:173], v[52:55]
	v_mfma_f32_16x16x32_bf16 v[48:51], v[152:155], v[170:173], v[48:51]
	v_mfma_f32_16x16x32_bf16 v[44:47], v[144:147], v[178:181], v[44:47]
	v_mfma_f32_16x16x32_bf16 v[40:43], v[152:155], v[178:181], v[40:43]
	v_mfma_f32_16x16x32_bf16 v[36:39], v[144:147], v[186:189], v[36:39]
	v_mfma_f32_16x16x32_bf16 v[32:35], v[152:155], v[186:189], v[32:35]
	v_mfma_f32_16x16x32_bf16 v[60:63], v[148:151], v[166:169], v[60:63]
	v_mfma_f32_16x16x32_bf16 v[56:59], v[158:161], v[166:169], v[56:59]
	v_mfma_f32_16x16x32_bf16 v[52:55], v[148:151], v[174:177], v[52:55]
	v_mfma_f32_16x16x32_bf16 v[48:51], v[158:161], v[174:177], v[48:51]
	v_mfma_f32_16x16x32_bf16 v[44:47], v[148:151], v[182:185], v[44:47]
	v_mfma_f32_16x16x32_bf16 v[40:43], v[158:161], v[182:185], v[40:43]
	v_mfma_f32_16x16x32_bf16 v[36:39], v[148:151], v[190:193], v[36:39]
	v_mfma_f32_16x16x32_bf16 v[32:35], v[158:161], v[190:193], v[32:35]
	s_barrier
	s_add_i32 s91, s92, s21
	v_lshl_add_u64 v[144:145], v[214:215], 0, s[16:17]
	s_mov_b32 m0, s91
	s_nop 0
	global_load_lds_dwordx4 v[144:145], off
	v_lshl_add_u64 v[144:145], v[216:217], 0, s[16:17]
	s_add_i32 m0, s91, 0x2000
	s_nop 0
	global_load_lds_dwordx4 v[144:145], off
	s_waitcnt vmcnt(6)
	s_barrier
	v_mfma_f32_16x16x32_bf16 v[28:31], v[194:197], v[162:165], v[28:31]
	v_mfma_f32_16x16x32_bf16 v[24:27], v[202:205], v[162:165], v[24:27]
	v_mfma_f32_16x16x32_bf16 v[20:23], v[194:197], v[170:173], v[20:23]
	v_mfma_f32_16x16x32_bf16 v[16:19], v[202:205], v[170:173], v[16:19]
	v_mfma_f32_16x16x32_bf16 v[12:15], v[194:197], v[178:181], v[12:15]
	v_mfma_f32_16x16x32_bf16 v[8:11], v[202:205], v[178:181], v[8:11]
	v_mfma_f32_16x16x32_bf16 v[4:7], v[194:197], v[186:189], v[4:7]
	v_mfma_f32_16x16x32_bf16 v[0:3], v[202:205], v[186:189], v[0:3]
	v_mfma_f32_16x16x32_bf16 v[28:31], v[198:201], v[166:169], v[28:31]
	v_mfma_f32_16x16x32_bf16 v[24:27], v[206:209], v[166:169], v[24:27]
	v_mfma_f32_16x16x32_bf16 v[20:23], v[198:201], v[174:177], v[20:23]
	v_mfma_f32_16x16x32_bf16 v[16:19], v[206:209], v[174:177], v[16:19]
	v_mfma_f32_16x16x32_bf16 v[12:15], v[198:201], v[182:185], v[12:15]
	v_mfma_f32_16x16x32_bf16 v[8:11], v[206:209], v[182:185], v[8:11]
	v_mfma_f32_16x16x32_bf16 v[4:7], v[198:201], v[190:193], v[4:7]
	v_mfma_f32_16x16x32_bf16 v[0:3], v[206:209], v[190:193], v[0:3]
	s_add_i32 s88, s88, 2
	s_add_u32 s18, s18, 0x100
	s_addc_u32 s19, s19, 0
	s_cmp_gt_u32 s88, 11
	s_barrier
	s_cbranch_scc0 .LBB0_416
	v_add_u32_e32 v140, 0, v143
	s_add_u32 s4, s4, 0x40780
	v_add_u32_e32 v134, 0x10000, v140
	s_addc_u32 s5, s5, 0
	s_mov_b32 m0, s90
	ds_read_b128 v[130:133], v134
	ds_read_b128 v[144:147], v134 offset:1024
	ds_read_b128 v[148:151], v134 offset:2048
	ds_read_b128 v[152:155], v134 offset:3072
	ds_read_b128 v[158:161], v142
	ds_read_b128 v[162:165], v142 offset:1024
	ds_read_b128 v[166:169], v142 offset:2048
	ds_read_b128 v[170:173], v142 offset:3072
	ds_read_b128 v[174:177], v142 offset:4096
	ds_read_b128 v[178:181], v142 offset:5120
	ds_read_b128 v[182:185], v142 offset:6144
	ds_read_b128 v[186:189], v142 offset:7168
	v_lshl_add_u64 v[134:135], s[4:5], 0, v[138:139]
	global_load_lds_dwordx4 v[134:135], off
	v_lshl_add_u64 v[128:129], s[4:5], 0, v[128:129]
	s_mov_b32 m0, s89
	s_nop 0
	global_load_lds_dwordx4 v[128:129], off
	s_barrier
	s_waitcnt lgkmcnt(0)
	s_waitcnt lgkmcnt(0)
	v_mfma_f32_16x16x32_bf16 v[124:127], v[130:133], v[158:161], v[124:127]
	v_mfma_f32_16x16x32_bf16 v[116:119], v[130:133], v[166:169], v[116:119]
	v_mfma_f32_16x16x32_bf16 v[108:111], v[130:133], v[174:177], v[108:111]
	v_mfma_f32_16x16x32_bf16 v[100:103], v[130:133], v[182:185], v[100:103]
	v_mfma_f32_16x16x32_bf16 v[124:127], v[144:147], v[162:165], v[124:127]
	v_mfma_f32_16x16x32_bf16 v[120:123], v[148:151], v[158:161], v[120:123]
	v_mfma_f32_16x16x32_bf16 v[116:119], v[144:147], v[170:173], v[116:119]
	v_mfma_f32_16x16x32_bf16 v[112:115], v[148:151], v[166:169], v[112:115]
	v_mfma_f32_16x16x32_bf16 v[108:111], v[144:147], v[178:181], v[108:111]
	v_mfma_f32_16x16x32_bf16 v[104:107], v[148:151], v[174:177], v[104:107]
	v_mfma_f32_16x16x32_bf16 v[100:103], v[144:147], v[186:189], v[100:103]
	v_mfma_f32_16x16x32_bf16 v[96:99], v[148:151], v[182:185], v[96:99]
	v_mfma_f32_16x16x32_bf16 v[190:193], v[152:155], v[162:165], v[120:123]
	v_mfma_f32_16x16x32_bf16 v[194:197], v[152:155], v[170:173], v[112:115]
	v_mfma_f32_16x16x32_bf16 v[198:201], v[152:155], v[178:181], v[104:107]
	v_mfma_f32_16x16x32_bf16 v[202:205], v[152:155], v[186:189], v[96:99]
	v_add_u32_e32 v120, 0x14000, v140
	s_barrier
	s_nop 0
	ds_read_b128 v[96:99], v120
	ds_read_b128 v[104:107], v120 offset:1024
	ds_read_b128 v[112:115], v120 offset:2048
	ds_read_b128 v[120:123], v120 offset:3072
	s_barrier
	s_waitcnt lgkmcnt(0)
	s_waitcnt lgkmcnt(0)
	v_mfma_f32_16x16x32_bf16 v[92:95], v[96:99], v[158:161], v[92:95]
	v_mfma_f32_16x16x32_bf16 v[84:87], v[96:99], v[166:169], v[84:87]
	v_mfma_f32_16x16x32_bf16 v[76:79], v[96:99], v[174:177], v[76:79]
	v_mfma_f32_16x16x32_bf16 v[68:71], v[96:99], v[182:185], v[68:71]
	v_mfma_f32_16x16x32_bf16 v[92:95], v[104:107], v[162:165], v[92:95]
	v_mfma_f32_16x16x32_bf16 v[88:91], v[112:115], v[158:161], v[88:91]
	v_mfma_f32_16x16x32_bf16 v[84:87], v[104:107], v[170:173], v[84:87]
	v_mfma_f32_16x16x32_bf16 v[80:83], v[112:115], v[166:169], v[80:83]
	v_mfma_f32_16x16x32_bf16 v[76:79], v[104:107], v[178:181], v[76:79]
	v_mfma_f32_16x16x32_bf16 v[72:75], v[112:115], v[174:177], v[72:75]
	v_mfma_f32_16x16x32_bf16 v[68:71], v[104:107], v[186:189], v[68:71]
	v_mfma_f32_16x16x32_bf16 v[64:67], v[112:115], v[182:185], v[64:67]
	v_mfma_f32_16x16x32_bf16 v[158:161], v[120:123], v[162:165], v[88:91]
	v_mfma_f32_16x16x32_bf16 v[162:165], v[120:123], v[170:173], v[80:83]
	v_mfma_f32_16x16x32_bf16 v[166:169], v[120:123], v[178:181], v[72:75]
	v_mfma_f32_16x16x32_bf16 v[170:173], v[120:123], v[186:189], v[64:67]
	s_barrier
	s_nop 1
	ds_read_b128 v[64:67], v142 offset:16384
	ds_read_b128 v[72:75], v142 offset:17408
	ds_read_b128 v[80:83], v142 offset:18432
	ds_read_b128 v[88:91], v142 offset:19456
	ds_read_b128 v[174:177], v142 offset:20480
	ds_read_b128 v[178:181], v142 offset:21504
	ds_read_b128 v[182:185], v142 offset:22528
	ds_read_b128 v[186:189], v142 offset:23552
	s_waitcnt vmcnt(4)
	s_barrier
	s_waitcnt lgkmcnt(0)
	s_waitcnt lgkmcnt(0)
	v_mfma_f32_16x16x32_bf16 v[60:63], v[130:133], v[64:67], v[60:63]
	v_mfma_f32_16x16x32_bf16 v[52:55], v[130:133], v[80:83], v[52:55]
	v_mfma_f32_16x16x32_bf16 v[44:47], v[130:133], v[174:177], v[44:47]
	v_mfma_f32_16x16x32_bf16 v[36:39], v[130:133], v[182:185], v[36:39]
	v_mfma_f32_16x16x32_bf16 v[60:63], v[144:147], v[72:75], v[60:63]
	v_mfma_f32_16x16x32_bf16 v[56:59], v[148:151], v[64:67], v[56:59]
	v_mfma_f32_16x16x32_bf16 v[52:55], v[144:147], v[88:91], v[52:55]
	v_mfma_f32_16x16x32_bf16 v[48:51], v[148:151], v[80:83], v[48:51]
	v_mfma_f32_16x16x32_bf16 v[44:47], v[144:147], v[178:181], v[44:47]
	v_mfma_f32_16x16x32_bf16 v[40:43], v[148:151], v[174:177], v[40:43]
	v_mfma_f32_16x16x32_bf16 v[36:39], v[144:147], v[186:189], v[36:39]
	v_mfma_f32_16x16x32_bf16 v[32:35], v[148:151], v[182:185], v[32:35]
	v_mfma_f32_16x16x32_bf16 v[206:209], v[152:155], v[72:75], v[56:59]
	v_mfma_f32_16x16x32_bf16 v[210:213], v[152:155], v[88:91], v[48:51]
	v_mfma_f32_16x16x32_bf16 v[214:217], v[152:155], v[178:181], v[40:43]
	v_mfma_f32_16x16x32_bf16 v[128:131], v[152:155], v[186:189], v[32:35]
	v_mfma_f32_16x16x32_bf16 v[28:31], v[96:99], v[64:67], v[28:31]
	v_mfma_f32_16x16x32_bf16 v[20:23], v[96:99], v[80:83], v[20:23]
	v_mfma_f32_16x16x32_bf16 v[12:15], v[96:99], v[174:177], v[12:15]
	v_mfma_f32_16x16x32_bf16 v[4:7], v[96:99], v[182:185], v[4:7]
	v_mfma_f32_16x16x32_bf16 v[28:31], v[104:107], v[72:75], v[28:31]
	v_mfma_f32_16x16x32_bf16 v[24:27], v[112:115], v[64:67], v[24:27]
	v_mfma_f32_16x16x32_bf16 v[20:23], v[104:107], v[88:91], v[20:23]
	v_mfma_f32_16x16x32_bf16 v[16:19], v[112:115], v[80:83], v[16:19]
	v_mfma_f32_16x16x32_bf16 v[12:15], v[104:107], v[178:181], v[12:15]
	v_mfma_f32_16x16x32_bf16 v[8:11], v[112:115], v[174:177], v[8:11]
	v_mfma_f32_16x16x32_bf16 v[4:7], v[104:107], v[186:189], v[4:7]
	v_mfma_f32_16x16x32_bf16 v[0:3], v[112:115], v[182:185], v[0:3]
	v_mfma_f32_16x16x32_bf16 v[132:135], v[120:123], v[72:75], v[24:27]
	v_mfma_f32_16x16x32_bf16 v[144:147], v[120:123], v[88:91], v[16:19]
	v_mfma_f32_16x16x32_bf16 v[148:151], v[120:123], v[178:181], v[8:11]
	v_mfma_f32_16x16x32_bf16 v[152:155], v[120:123], v[186:189], v[0:3]
	v_add_u32_e32 v16, 0x18000, v140
	s_barrier
	s_nop 0
	ds_read_b128 v[0:3], v16
	ds_read_b128 v[8:11], v16 offset:1024
	ds_read_b128 v[174:177], v16 offset:2048
	ds_read_b128 v[178:181], v16 offset:3072
	ds_read_b128 v[16:19], v142 offset:32768
	ds_read_b128 v[24:27], v142 offset:33792
	ds_read_b128 v[32:35], v142 offset:34816
	ds_read_b128 v[40:43], v142 offset:35840
	ds_read_b128 v[48:51], v142 offset:36864
	ds_read_b128 v[56:59], v142 offset:37888
	ds_read_b128 v[182:185], v142 offset:38912
	ds_read_b128 v[186:189], v142 offset:39936
	s_waitcnt vmcnt(2)
	s_barrier
	s_waitcnt lgkmcnt(0)
	s_waitcnt lgkmcnt(0)
	v_mfma_f32_16x16x32_bf16 v[64:67], v[0:3], v[16:19], v[124:127]
	v_mfma_f32_16x16x32_bf16 v[120:123], v[8:11], v[24:27], v[64:67]
	v_mfma_f32_16x16x32_bf16 v[64:67], v[174:177], v[16:19], v[190:193]
	v_mfma_f32_16x16x32_bf16 v[112:115], v[178:181], v[24:27], v[64:67]
	v_mfma_f32_16x16x32_bf16 v[64:67], v[0:3], v[32:35], v[116:119]
	v_mfma_f32_16x16x32_bf16 v[104:107], v[8:11], v[40:43], v[64:67]
	v_mfma_f32_16x16x32_bf16 v[64:67], v[174:177], v[32:35], v[194:197]
	v_mfma_f32_16x16x32_bf16 v[96:99], v[178:181], v[40:43], v[64:67]
	v_mfma_f32_16x16x32_bf16 v[64:67], v[0:3], v[48:51], v[108:111]
	v_mfma_f32_16x16x32_bf16 v[88:91], v[8:11], v[56:59], v[64:67]
	v_mfma_f32_16x16x32_bf16 v[64:67], v[174:177], v[48:51], v[198:201]
	v_mfma_f32_16x16x32_bf16 v[80:83], v[178:181], v[56:59], v[64:67]
	v_mfma_f32_16x16x32_bf16 v[64:67], v[0:3], v[182:185], v[100:103]
	v_mfma_f32_16x16x32_bf16 v[72:75], v[8:11], v[186:189], v[64:67]
	v_mfma_f32_16x16x32_bf16 v[64:67], v[174:177], v[182:185], v[202:205]
	v_mfma_f32_16x16x32_bf16 v[64:67], v[178:181], v[186:189], v[64:67]
	v_add_u32_e32 v100, 0x1c000, v140
	s_barrier
	ds_read_b128 v[190:193], v100
	ds_read_b128 v[194:197], v100 offset:1024
	ds_read_b128 v[198:201], v100 offset:2048
	ds_read_b128 v[202:205], v100 offset:3072
	s_waitcnt vmcnt(0)
	s_barrier
	s_waitcnt lgkmcnt(0)
	s_waitcnt lgkmcnt(0)
	v_mfma_f32_16x16x32_bf16 v[92:95], v[190:193], v[16:19], v[92:95]
	v_mfma_f32_16x16x32_bf16 v[16:19], v[198:201], v[16:19], v[158:161]
	v_mfma_f32_16x16x32_bf16 v[116:119], v[202:205], v[24:27], v[16:19]
	v_mfma_f32_16x16x32_bf16 v[16:19], v[190:193], v[32:35], v[84:87]
	v_mfma_f32_16x16x32_bf16 v[108:111], v[194:197], v[40:43], v[16:19]
	v_mfma_f32_16x16x32_bf16 v[16:19], v[198:201], v[32:35], v[162:165]
	v_mfma_f32_16x16x32_bf16 v[100:103], v[202:205], v[40:43], v[16:19]
	v_mfma_f32_16x16x32_bf16 v[16:19], v[190:193], v[48:51], v[76:79]
	v_mfma_f32_16x16x32_bf16 v[124:127], v[194:197], v[24:27], v[92:95]
	v_mfma_f32_16x16x32_bf16 v[92:95], v[194:197], v[56:59], v[16:19]
	v_mfma_f32_16x16x32_bf16 v[16:19], v[198:201], v[48:51], v[166:169]
	v_mfma_f32_16x16x32_bf16 v[84:87], v[202:205], v[56:59], v[16:19]
	v_mfma_f32_16x16x32_bf16 v[16:19], v[190:193], v[182:185], v[68:71]
	v_mfma_f32_16x16x32_bf16 v[76:79], v[194:197], v[186:189], v[16:19]
	v_mfma_f32_16x16x32_bf16 v[16:19], v[198:201], v[182:185], v[170:173]
	v_mfma_f32_16x16x32_bf16 v[68:71], v[202:205], v[186:189], v[16:19]
	s_barrier
	ds_read_b128 v[158:161], v142 offset:49152
	ds_read_b128 v[162:165], v142 offset:50176
	ds_read_b128 v[166:169], v142 offset:51200
	ds_read_b128 v[170:173], v142 offset:52224
	ds_read_b128 v[182:185], v142 offset:53248
	ds_read_b128 v[186:189], v142 offset:54272
	ds_read_b128 v[218:221], v142 offset:55296
	ds_read_b128 v[140:143], v142 offset:56320
	s_barrier
	s_waitcnt lgkmcnt(0)
	s_waitcnt lgkmcnt(0)
	v_mfma_f32_16x16x32_bf16 v[16:19], v[0:3], v[158:161], v[60:63]
	v_mfma_f32_16x16x32_bf16 v[56:59], v[8:11], v[162:165], v[16:19]
	v_mfma_f32_16x16x32_bf16 v[16:19], v[174:177], v[158:161], v[206:209]
	v_mfma_f32_16x16x32_bf16 v[48:51], v[178:181], v[162:165], v[16:19]
	v_mfma_f32_16x16x32_bf16 v[16:19], v[0:3], v[166:169], v[52:55]
	v_mfma_f32_16x16x32_bf16 v[40:43], v[8:11], v[170:173], v[16:19]
	v_mfma_f32_16x16x32_bf16 v[16:19], v[174:177], v[166:169], v[210:213]
	v_mfma_f32_16x16x32_bf16 v[32:35], v[178:181], v[170:173], v[16:19]
	v_mfma_f32_16x16x32_bf16 v[16:19], v[0:3], v[182:185], v[44:47]
	v_mfma_f32_16x16x32_bf16 v[0:3], v[0:3], v[218:221], v[36:39]
	v_mfma_f32_16x16x32_bf16 v[24:27], v[8:11], v[186:189], v[16:19]
	v_mfma_f32_16x16x32_bf16 v[16:19], v[174:177], v[182:185], v[214:217]
	v_mfma_f32_16x16x32_bf16 v[8:11], v[8:11], v[140:143], v[0:3]
	v_mfma_f32_16x16x32_bf16 v[0:3], v[174:177], v[218:221], v[128:131]
	v_mfma_f32_16x16x32_bf16 v[16:19], v[178:181], v[186:189], v[16:19]
	v_mfma_f32_16x16x32_bf16 v[0:3], v[178:181], v[140:143], v[0:3]
	v_mfma_f32_16x16x32_bf16 v[28:31], v[190:193], v[158:161], v[28:31]
	v_mfma_f32_16x16x32_bf16 v[60:63], v[194:197], v[162:165], v[28:31]
	v_mfma_f32_16x16x32_bf16 v[28:31], v[198:201], v[158:161], v[132:135]
	v_mfma_f32_16x16x32_bf16 v[20:23], v[190:193], v[166:169], v[20:23]
	v_mfma_f32_16x16x32_bf16 v[12:15], v[190:193], v[182:185], v[12:15]
	v_mfma_f32_16x16x32_bf16 v[52:55], v[202:205], v[162:165], v[28:31]
	v_mfma_f32_16x16x32_bf16 v[44:47], v[194:197], v[170:173], v[20:23]
	v_mfma_f32_16x16x32_bf16 v[20:23], v[198:201], v[166:169], v[144:147]
	v_mfma_f32_16x16x32_bf16 v[28:31], v[194:197], v[186:189], v[12:15]
	v_mfma_f32_16x16x32_bf16 v[12:15], v[198:201], v[182:185], v[148:151]
	v_mfma_f32_16x16x32_bf16 v[4:7], v[190:193], v[218:221], v[4:7]
	v_mfma_f32_16x16x32_bf16 v[36:39], v[202:205], v[170:173], v[20:23]
	v_mfma_f32_16x16x32_bf16 v[20:23], v[202:205], v[186:189], v[12:15]
	v_mfma_f32_16x16x32_bf16 v[12:15], v[194:197], v[140:143], v[4:7]
	v_mfma_f32_16x16x32_bf16 v[4:7], v[198:201], v[218:221], v[152:155]
	v_mfma_f32_16x16x32_bf16 v[4:7], v[202:205], v[140:143], v[4:7]
	s_cmpk_lt_u32 s1, 0x100
	s_barrier
	s_cbranch_scc0 .LBB0_200
	s_barrier
	s_branch .LBB0_200

.LBB0_475:
	v_and_b32_e32 v17, 15, v16
	v_and_b32_e32 v18, 48, v16
	v_lshlrev_b32_e32 v16, 2, v16
	v_lshlrev_b32_e32 v17, 6, v17
	v_and_b32_e32 v16, 32, v16
	s_lshl_b32 s16, s16, 12
	v_or_b32_e32 v19, v17, v18
	v_bitop3_b32 v17, v17, v16, v18 bitop3:0x36
	s_and_b32 s16, s16, 0x3000
	v_or_b32_e32 v18, s16, v17
	s_add_i32 s16, 0, 0x18000
	s_lshl_b32 s14, s14, 13
	s_add_i32 s27, s16, s25
	s_mov_b64 s[30:31], 0x80
	v_bitop3_b32 v19, v19, s14, v16 bitop3:0xde
	v_lshl_add_u64 v[16:17], v[14:15], 0, s[30:31]
	s_mov_b32 m0, s27
	s_add_i32 s28, s27, 0x2000
	s_waitcnt vmcnt(4)
	s_barrier
	global_load_lds_dwordx4 v[16:17], off
	v_lshl_add_u64 v[16:17], v[12:13], 0, s[30:31]
	s_mov_b32 m0, s28
	s_add_i32 s26, s22, 0x8000
	global_load_lds_dwordx4 v[16:17], off
	v_lshl_add_u64 v[16:17], v[8:9], 0, s[30:31]
	s_mov_b32 m0, s26
	s_add_i32 s23, s22, 0xa000
	global_load_lds_dwordx4 v[16:17], off
	v_lshl_add_u64 v[16:17], v[10:11], 0, s[30:31]
	s_add_u32 s30, s10, 0x10080
	s_mov_b32 m0, s23
	s_addc_u32 s31, s11, 0
	s_add_i32 s20, s22, 0x1c000
	global_load_lds_dwordx4 v[16:17], off
	v_lshl_add_u64 v[16:17], s[30:31], 0, v[4:5]
	s_mov_b32 m0, s20
	s_add_i32 s18, s22, 0x1e000
	global_load_lds_dwordx4 v[16:17], off
	v_lshl_add_u64 v[16:17], s[30:31], 0, v[6:7]
	s_mov_b32 m0, s18
	s_add_i32 s14, 0, 0x10000
	global_load_lds_dwordx4 v[16:17], off
	v_add_u32_e32 v64, s14, v18
	s_waitcnt vmcnt(6)
	s_barrier
	v_add_u32_e32 v134, 0, v19
	v_add_u32_e32 v132, s16, v18
	ds_read_b128 v[16:19], v64
	ds_read_b128 v[20:23], v64 offset:1024
	ds_read_b128 v[24:27], v64 offset:2048
	ds_read_b128 v[28:31], v64 offset:3072
	s_add_u32 s34, s4, 0x18080
	s_addc_u32 s35, s5, 0
	s_add_i32 s30, s22, 0xc000
	v_lshl_add_u64 v[66:67], s[34:35], 0, v[0:1]
	s_mov_b32 m0, s30
	s_add_i32 s29, s22, 0xe000
	ds_read_b128 v[32:35], v134
	ds_read_b128 v[36:39], v134 offset:1024
	ds_read_b128 v[40:43], v134 offset:2048
	ds_read_b128 v[44:47], v134 offset:3072
	ds_read_b128 v[48:51], v134 offset:4096
	ds_read_b128 v[52:55], v134 offset:5120
	ds_read_b128 v[56:59], v134 offset:6144
	ds_read_b128 v[60:63], v134 offset:7168
	global_load_lds_dwordx4 v[66:67], off
	v_lshl_add_u64 v[66:67], s[34:35], 0, v[2:3]
	s_mov_b32 m0, s29
	s_nop 0
	global_load_lds_dwordx4 v[66:67], off
	s_waitcnt lgkmcnt(8)
	s_barrier
	s_waitcnt lgkmcnt(0)
	s_waitcnt lgkmcnt(0)
	v_mfma_f32_16x16x32_bf16 v[66:69], v[16:19], v[32:35], 0
	v_mfma_f32_16x16x32_bf16 v[32:35], v[24:27], v[32:35], 0
	v_mfma_f32_16x16x32_bf16 v[66:69], v[20:23], v[36:39], v[66:69]
	v_mfma_f32_16x16x32_bf16 v[32:35], v[28:31], v[36:39], v[32:35]
	v_mfma_f32_16x16x32_bf16 v[36:39], v[16:19], v[40:43], 0
	v_mfma_f32_16x16x32_bf16 v[40:43], v[24:27], v[40:43], 0
	v_mfma_f32_16x16x32_bf16 v[36:39], v[20:23], v[44:47], v[36:39]
	v_mfma_f32_16x16x32_bf16 v[40:43], v[28:31], v[44:47], v[40:43]
	v_mfma_f32_16x16x32_bf16 v[44:47], v[16:19], v[48:51], 0
	v_mfma_f32_16x16x32_bf16 v[48:51], v[24:27], v[48:51], 0
	v_mfma_f32_16x16x32_bf16 v[44:47], v[20:23], v[52:55], v[44:47]
	v_mfma_f32_16x16x32_bf16 v[48:51], v[28:31], v[52:55], v[48:51]
	v_mfma_f32_16x16x32_bf16 v[52:55], v[16:19], v[56:59], 0
	v_mfma_f32_16x16x32_bf16 v[56:59], v[24:27], v[56:59], 0
	v_mfma_f32_16x16x32_bf16 v[52:55], v[20:23], v[60:63], v[52:55]
	v_mfma_f32_16x16x32_bf16 v[56:59], v[28:31], v[60:63], v[56:59]
	s_barrier
	s_mov_b64 s[34:35], 0x100
	s_add_i32 s25, s14, s25
	v_lshl_add_u64 v[60:61], v[14:15], 0, s[34:35]
	s_mov_b32 m0, s25
	s_nop 0
	global_load_lds_dwordx4 v[60:61], off
	v_lshl_add_u64 v[60:61], v[12:13], 0, s[34:35]
	s_add_i32 m0, s25, 0x2000
	s_nop 0
	global_load_lds_dwordx4 v[60:61], off
	s_barrier
	s_waitcnt lgkmcnt(0)
	s_mov_b32 m0, s22
	v_lshl_add_u64 v[98:99], v[8:9], 0, s[34:35]
	s_barrier
	ds_read_b128 v[60:63], v134 offset:16384
	ds_read_b128 v[70:73], v134 offset:17408
	ds_read_b128 v[74:77], v134 offset:18432
	ds_read_b128 v[78:81], v134 offset:19456
	ds_read_b128 v[82:85], v134 offset:20480
	ds_read_b128 v[86:89], v134 offset:21504
	ds_read_b128 v[90:93], v134 offset:22528
	ds_read_b128 v[94:97], v134 offset:23552
	global_load_lds_dwordx4 v[98:99], off
	v_lshl_add_u64 v[98:99], v[10:11], 0, s[34:35]
	s_mov_b32 m0, s24
	s_nop 0
	global_load_lds_dwordx4 v[98:99], off
	s_barrier
	s_waitcnt lgkmcnt(0)
	s_waitcnt lgkmcnt(0)
	v_mfma_f32_16x16x32_bf16 v[98:101], v[16:19], v[60:63], 0
	v_mfma_f32_16x16x32_bf16 v[60:63], v[24:27], v[60:63], 0
	v_mfma_f32_16x16x32_bf16 v[98:101], v[20:23], v[70:73], v[98:101]
	v_mfma_f32_16x16x32_bf16 v[60:63], v[28:31], v[70:73], v[60:63]
	v_mfma_f32_16x16x32_bf16 v[70:73], v[16:19], v[74:77], 0
	v_mfma_f32_16x16x32_bf16 v[74:77], v[24:27], v[74:77], 0
	v_mfma_f32_16x16x32_bf16 v[70:73], v[20:23], v[78:81], v[70:73]
	v_mfma_f32_16x16x32_bf16 v[74:77], v[28:31], v[78:81], v[74:77]
	v_mfma_f32_16x16x32_bf16 v[78:81], v[16:19], v[82:85], 0
	v_mfma_f32_16x16x32_bf16 v[16:19], v[16:19], v[90:93], 0
	v_mfma_f32_16x16x32_bf16 v[78:81], v[20:23], v[86:89], v[78:81]
	v_mfma_f32_16x16x32_bf16 v[16:19], v[20:23], v[94:97], v[16:19]
	v_mfma_f32_16x16x32_bf16 v[20:23], v[24:27], v[90:93], 0
	v_mfma_f32_16x16x32_bf16 v[82:85], v[24:27], v[82:85], 0
	v_mfma_f32_16x16x32_bf16 v[20:23], v[28:31], v[94:97], v[20:23]
	v_mfma_f32_16x16x32_bf16 v[82:85], v[28:31], v[86:89], v[82:85]
	s_barrier
	s_add_u32 s24, s10, 0x10100
	s_addc_u32 s25, s11, 0
	s_mov_b32 m0, s21
	v_lshl_add_u64 v[24:25], s[24:25], 0, v[4:5]
	global_load_lds_dwordx4 v[24:25], off
	v_lshl_add_u64 v[24:25], s[24:25], 0, v[6:7]
	s_mov_b32 m0, s19
	s_nop 0
	global_load_lds_dwordx4 v[24:25], off
	s_waitcnt vmcnt(6)
	s_barrier
	s_barrier
	ds_read_b128 v[24:27], v132
	ds_read_b128 v[28:31], v132 offset:1024
	ds_read_b128 v[86:89], v132 offset:2048
	ds_read_b128 v[90:93], v132 offset:3072
	s_add_u32 s24, s4, 0x18100
	s_addc_u32 s25, s5, 0
	s_mov_b32 m0, s17
	v_lshl_add_u64 v[130:131], s[24:25], 0, v[0:1]
	ds_read_b128 v[94:97], v134 offset:32768
	ds_read_b128 v[102:105], v134 offset:33792
	ds_read_b128 v[106:109], v134 offset:34816
	ds_read_b128 v[110:113], v134 offset:35840
	ds_read_b128 v[114:117], v134 offset:36864
	ds_read_b128 v[118:121], v134 offset:37888
	ds_read_b128 v[122:125], v134 offset:38912
	ds_read_b128 v[126:129], v134 offset:39936
	global_load_lds_dwordx4 v[130:131], off
	v_lshl_add_u64 v[130:131], s[24:25], 0, v[2:3]
	s_mov_b32 m0, s15
	s_nop 0
	global_load_lds_dwordx4 v[130:131], off
	s_waitcnt lgkmcnt(8)
	s_barrier
	s_waitcnt lgkmcnt(0)
	s_waitcnt lgkmcnt(0)
	v_mfma_f32_16x16x32_bf16 v[32:35], v[86:89], v[94:97], v[32:35]
	v_mfma_f32_16x16x32_bf16 v[36:39], v[24:27], v[106:109], v[36:39]
	v_mfma_f32_16x16x32_bf16 v[40:43], v[86:89], v[106:109], v[40:43]
	v_mfma_f32_16x16x32_bf16 v[44:47], v[24:27], v[114:117], v[44:47]
	v_mfma_f32_16x16x32_bf16 v[48:51], v[86:89], v[114:117], v[48:51]
	v_mfma_f32_16x16x32_bf16 v[52:55], v[24:27], v[122:125], v[52:55]
	v_mfma_f32_16x16x32_bf16 v[56:59], v[86:89], v[122:125], v[56:59]
	v_mfma_f32_16x16x32_bf16 v[66:69], v[24:27], v[94:97], v[66:69]
	v_mfma_f32_16x16x32_bf16 v[32:35], v[90:93], v[102:105], v[32:35]
	v_mfma_f32_16x16x32_bf16 v[36:39], v[28:31], v[110:113], v[36:39]
	v_mfma_f32_16x16x32_bf16 v[40:43], v[90:93], v[110:113], v[40:43]
	v_mfma_f32_16x16x32_bf16 v[44:47], v[28:31], v[118:121], v[44:47]
	v_mfma_f32_16x16x32_bf16 v[48:51], v[90:93], v[118:121], v[48:51]
	v_mfma_f32_16x16x32_bf16 v[52:55], v[28:31], v[126:129], v[52:55]
	v_mfma_f32_16x16x32_bf16 v[56:59], v[90:93], v[126:129], v[56:59]
	v_mfma_f32_16x16x32_bf16 v[66:69], v[28:31], v[102:105], v[66:69]
	s_barrier
	s_mov_b64 s[24:25], 0x180
	s_mov_b32 m0, s27
	v_lshl_add_u64 v[14:15], v[14:15], 0, s[24:25]
	global_load_lds_dwordx4 v[14:15], off
	v_lshl_add_u64 v[12:13], v[12:13], 0, s[24:25]
	s_mov_b32 m0, s28
	s_nop 0
	global_load_lds_dwordx4 v[12:13], off
	s_barrier
	s_waitcnt lgkmcnt(0)
	s_mov_b32 m0, s26
	v_lshl_add_u64 v[8:9], v[8:9], 0, s[24:25]
	s_barrier
	ds_read_b128 v[12:15], v134 offset:49152
	ds_read_b128 v[94:97], v134 offset:50176
	ds_read_b128 v[102:105], v134 offset:51200
	ds_read_b128 v[106:109], v134 offset:52224
	ds_read_b128 v[110:113], v134 offset:53248
	ds_read_b128 v[114:117], v134 offset:54272
	ds_read_b128 v[118:121], v134 offset:55296
	ds_read_b128 v[122:125], v134 offset:56320
	global_load_lds_dwordx4 v[8:9], off
	v_lshl_add_u64 v[8:9], v[10:11], 0, s[24:25]
	s_mov_b32 m0, s23
	s_nop 0
	global_load_lds_dwordx4 v[8:9], off
	s_barrier
	s_waitcnt lgkmcnt(0)
	s_waitcnt lgkmcnt(0)
	v_mfma_f32_16x16x32_bf16 v[8:11], v[24:27], v[12:15], v[98:101]
	v_mfma_f32_16x16x32_bf16 v[12:15], v[86:89], v[12:15], v[60:63]
	v_mfma_f32_16x16x32_bf16 v[60:63], v[24:27], v[102:105], v[70:73]
	v_mfma_f32_16x16x32_bf16 v[16:19], v[24:27], v[118:121], v[16:19]
	v_mfma_f32_16x16x32_bf16 v[20:23], v[86:89], v[118:121], v[20:23]
	v_mfma_f32_16x16x32_bf16 v[8:11], v[28:31], v[94:97], v[8:11]
	v_mfma_f32_16x16x32_bf16 v[12:15], v[90:93], v[94:97], v[12:15]
	v_mfma_f32_16x16x32_bf16 v[60:63], v[28:31], v[106:109], v[60:63]
	v_mfma_f32_16x16x32_bf16 v[70:73], v[86:89], v[102:105], v[74:77]
	v_mfma_f32_16x16x32_bf16 v[74:77], v[24:27], v[110:113], v[78:81]
	v_mfma_f32_16x16x32_bf16 v[78:81], v[86:89], v[110:113], v[82:85]
	v_mfma_f32_16x16x32_bf16 v[16:19], v[28:31], v[122:125], v[16:19]
	v_mfma_f32_16x16x32_bf16 v[20:23], v[90:93], v[122:125], v[20:23]
	v_mfma_f32_16x16x32_bf16 v[70:73], v[90:93], v[106:109], v[70:73]
	v_mfma_f32_16x16x32_bf16 v[74:77], v[28:31], v[114:117], v[74:77]
	v_mfma_f32_16x16x32_bf16 v[78:81], v[90:93], v[114:117], v[78:81]
	s_barrier
	s_add_u32 s10, s10, 0x10180
	s_addc_u32 s11, s11, 0
	s_mov_b32 m0, s20
	v_lshl_add_u64 v[4:5], s[10:11], 0, v[4:5]
	global_load_lds_dwordx4 v[4:5], off
	v_lshl_add_u64 v[4:5], s[10:11], 0, v[6:7]
	s_mov_b32 m0, s18
	s_nop 0
	global_load_lds_dwordx4 v[4:5], off
	s_waitcnt vmcnt(6)
	s_barrier
	s_add_u32 s10, s4, 0x18180
	s_addc_u32 s11, s5, 0
	s_mov_b32 m0, s30
	v_lshl_add_u64 v[0:1], s[10:11], 0, v[0:1]
	s_barrier
	ds_read_b128 v[4:7], v64
	ds_read_b128 v[24:27], v64 offset:1024
	ds_read_b128 v[28:31], v64 offset:2048
	ds_read_b128 v[82:85], v64 offset:3072
	ds_read_b128 v[86:89], v134
	ds_read_b128 v[90:93], v134 offset:1024
	ds_read_b128 v[94:97], v134 offset:2048
	ds_read_b128 v[98:101], v134 offset:3072
	ds_read_b128 v[102:105], v134 offset:4096
	ds_read_b128 v[106:109], v134 offset:5120
	ds_read_b128 v[110:113], v134 offset:6144
	ds_read_b128 v[114:117], v134 offset:7168
	global_load_lds_dwordx4 v[0:1], off
	v_lshl_add_u64 v[0:1], s[10:11], 0, v[2:3]
	s_mov_b32 m0, s29
	s_nop 0
	global_load_lds_dwordx4 v[0:1], off
	s_barrier
	s_waitcnt lgkmcnt(0)
	s_waitcnt lgkmcnt(0)
	v_mfma_f32_16x16x32_bf16 v[40:43], v[28:31], v[94:97], v[40:43]
	v_mfma_f32_16x16x32_bf16 v[0:3], v[4:7], v[86:89], v[66:69]
	v_mfma_f32_16x16x32_bf16 v[66:69], v[82:85], v[98:101], v[40:43]
	v_mfma_f32_16x16x32_bf16 v[40:43], v[4:7], v[102:105], v[44:47]
	v_mfma_f32_16x16x32_bf16 v[32:35], v[28:31], v[86:89], v[32:35]
	v_mfma_f32_16x16x32_bf16 v[86:89], v[24:27], v[106:109], v[40:43]
	v_mfma_f32_16x16x32_bf16 v[40:43], v[28:31], v[102:105], v[48:51]
	v_mfma_f32_16x16x32_bf16 v[36:39], v[4:7], v[94:97], v[36:39]
	v_mfma_f32_16x16x32_bf16 v[48:51], v[82:85], v[106:109], v[40:43]
	v_mfma_f32_16x16x32_bf16 v[40:43], v[4:7], v[110:113], v[52:55]
	v_mfma_f32_16x16x32_bf16 v[0:3], v[24:27], v[90:93], v[0:3]
	v_mfma_f32_16x16x32_bf16 v[32:35], v[82:85], v[90:93], v[32:35]
	v_mfma_f32_16x16x32_bf16 v[36:39], v[24:27], v[98:101], v[36:39]
	v_mfma_f32_16x16x32_bf16 v[52:55], v[24:27], v[114:117], v[40:43]
	v_mfma_f32_16x16x32_bf16 v[40:43], v[28:31], v[110:113], v[56:59]
	v_mfma_f32_16x16x32_bf16 v[90:93], v[82:85], v[114:117], v[40:43]
	s_barrier
	s_barrier
	s_waitcnt lgkmcnt(0)
	s_barrier
	s_nop 0
	ds_read_b128 v[40:43], v134 offset:16384
	ds_read_b128 v[44:47], v134 offset:17408
	ds_read_b128 v[56:59], v134 offset:18432
	ds_read_b128 v[94:97], v134 offset:19456
	ds_read_b128 v[98:101], v134 offset:20480
	ds_read_b128 v[102:105], v134 offset:21504
	ds_read_b128 v[106:109], v134 offset:22528
	ds_read_b128 v[110:113], v134 offset:23552
	s_waitcnt vmcnt(4)
	s_barrier
	s_waitcnt lgkmcnt(0)
	s_waitcnt lgkmcnt(0)
	v_mfma_f32_16x16x32_bf16 v[8:11], v[4:7], v[40:43], v[8:11]
	v_mfma_f32_16x16x32_bf16 v[114:117], v[24:27], v[44:47], v[8:11]
	v_mfma_f32_16x16x32_bf16 v[8:11], v[28:31], v[40:43], v[12:15]
	v_mfma_f32_16x16x32_bf16 v[118:121], v[82:85], v[44:47], v[8:11]
	v_mfma_f32_16x16x32_bf16 v[8:11], v[4:7], v[56:59], v[60:63]
	v_mfma_f32_16x16x32_bf16 v[122:125], v[24:27], v[94:97], v[8:11]
	v_mfma_f32_16x16x32_bf16 v[8:11], v[28:31], v[56:59], v[70:73]
	v_mfma_f32_16x16x32_bf16 v[70:73], v[82:85], v[94:97], v[8:11]
	v_mfma_f32_16x16x32_bf16 v[8:11], v[4:7], v[98:101], v[74:77]
	v_mfma_f32_16x16x32_bf16 v[74:77], v[24:27], v[102:105], v[8:11]
	v_mfma_f32_16x16x32_bf16 v[8:11], v[28:31], v[98:101], v[78:81]
	v_mfma_f32_16x16x32_bf16 v[4:7], v[4:7], v[106:109], v[16:19]
	v_mfma_f32_16x16x32_bf16 v[78:81], v[82:85], v[102:105], v[8:11]
	v_mfma_f32_16x16x32_bf16 v[4:7], v[24:27], v[110:113], v[4:7]
	v_mfma_f32_16x16x32_bf16 v[8:11], v[28:31], v[106:109], v[20:23]
	v_mfma_f32_16x16x32_bf16 v[82:85], v[82:85], v[110:113], v[8:11]
	s_barrier
	ds_read_b128 v[94:97], v132
	ds_read_b128 v[98:101], v132 offset:1024
	ds_read_b128 v[102:105], v132 offset:2048
	ds_read_b128 v[106:109], v132 offset:3072
	ds_read_b128 v[8:11], v134 offset:32768
	ds_read_b128 v[12:15], v134 offset:33792
	ds_read_b128 v[16:19], v134 offset:34816
	ds_read_b128 v[20:23], v134 offset:35840
	ds_read_b128 v[28:31], v134 offset:36864
	ds_read_b128 v[110:113], v134 offset:37888
	ds_read_b128 v[126:129], v134 offset:38912
	ds_read_b128 v[130:133], v134 offset:39936
	s_waitcnt vmcnt(2)
	s_barrier
	s_waitcnt lgkmcnt(0)
	s_waitcnt lgkmcnt(0)
	v_mfma_f32_16x16x32_bf16 v[0:3], v[94:97], v[8:11], v[0:3]
	v_mfma_f32_16x16x32_bf16 v[56:59], v[98:101], v[12:15], v[0:3]
	v_mfma_f32_16x16x32_bf16 v[0:3], v[102:105], v[8:11], v[32:35]
	v_mfma_f32_16x16x32_bf16 v[60:63], v[106:109], v[12:15], v[0:3]
	v_mfma_f32_16x16x32_bf16 v[0:3], v[94:97], v[16:19], v[36:39]
	v_mfma_f32_16x16x32_bf16 v[40:43], v[98:101], v[20:23], v[0:3]
	v_mfma_f32_16x16x32_bf16 v[0:3], v[102:105], v[16:19], v[66:69]
	v_mfma_f32_16x16x32_bf16 v[44:47], v[106:109], v[20:23], v[0:3]
	v_mfma_f32_16x16x32_bf16 v[0:3], v[94:97], v[28:31], v[86:89]
	v_mfma_f32_16x16x32_bf16 v[24:27], v[98:101], v[110:113], v[0:3]
	v_mfma_f32_16x16x32_bf16 v[0:3], v[102:105], v[28:31], v[48:51]
	v_mfma_f32_16x16x32_bf16 v[28:31], v[106:109], v[110:113], v[0:3]
	v_mfma_f32_16x16x32_bf16 v[0:3], v[94:97], v[126:129], v[52:55]
	v_mfma_f32_16x16x32_bf16 v[8:11], v[98:101], v[130:133], v[0:3]
	v_mfma_f32_16x16x32_bf16 v[0:3], v[102:105], v[126:129], v[90:93]
	v_mfma_f32_16x16x32_bf16 v[12:15], v[106:109], v[130:133], v[0:3]
	s_barrier
	s_waitcnt vmcnt(0)
	s_barrier
	s_waitcnt lgkmcnt(0)
	s_barrier
	s_nop 0
	ds_read_b128 v[0:3], v134 offset:49152
	ds_read_b128 v[16:19], v134 offset:50176
	ds_read_b128 v[20:23], v134 offset:51200
	ds_read_b128 v[36:39], v134 offset:52224
	ds_read_b128 v[66:69], v134 offset:53248
	ds_read_b128 v[86:89], v134 offset:54272
	ds_read_b128 v[90:93], v134 offset:55296
	ds_read_b128 v[110:113], v134 offset:56320
	s_barrier
	s_waitcnt lgkmcnt(0)
	s_waitcnt lgkmcnt(0)
	v_mfma_f32_16x16x32_bf16 v[32:35], v[94:97], v[0:3], v[114:117]
	v_mfma_f32_16x16x32_bf16 v[0:3], v[102:105], v[0:3], v[118:121]
	v_mfma_f32_16x16x32_bf16 v[52:55], v[106:109], v[16:19], v[0:3]
	v_mfma_f32_16x16x32_bf16 v[0:3], v[94:97], v[20:23], v[122:125]
	v_mfma_f32_16x16x32_bf16 v[48:51], v[98:101], v[16:19], v[32:35]
	v_mfma_f32_16x16x32_bf16 v[32:35], v[98:101], v[36:39], v[0:3]
	v_mfma_f32_16x16x32_bf16 v[0:3], v[102:105], v[20:23], v[70:73]
	v_mfma_f32_16x16x32_bf16 v[36:39], v[106:109], v[36:39], v[0:3]
	v_mfma_f32_16x16x32_bf16 v[0:3], v[94:97], v[66:69], v[74:77]
	v_mfma_f32_16x16x32_bf16 v[16:19], v[98:101], v[86:89], v[0:3]
	v_mfma_f32_16x16x32_bf16 v[0:3], v[102:105], v[66:69], v[78:81]
	v_mfma_f32_16x16x32_bf16 v[20:23], v[106:109], v[86:89], v[0:3]
	v_mfma_f32_16x16x32_bf16 v[0:3], v[94:97], v[90:93], v[4:7]
	v_mfma_f32_16x16x32_bf16 v[4:7], v[102:105], v[90:93], v[82:85]
	v_mfma_f32_16x16x32_bf16 v[0:3], v[98:101], v[110:113], v[0:3]
	v_mfma_f32_16x16x32_bf16 v[4:7], v[106:109], v[110:113], v[4:7]
	s_cmpk_gt_u32 s13, 0xff
	s_barrier
	s_cbranch_scc1 .LBB0_477
	s_barrier

.LBB0_492:
	s_add_u32 s24, s4, s18
	s_addc_u32 s25, s5, 0
	s_add_u32 s26, s8, s18
	s_addc_u32 s27, s9, 0
	s_add_u32 s28, s6, s18
	ds_read_b128 v[140:143], v134
	ds_read_b128 v[144:147], v134 offset:1024
	ds_read_b128 v[148:151], v134 offset:2048
	ds_read_b128 v[152:155], v134 offset:3072
	s_addc_u32 s29, s7, 0
	s_add_u32 s22, s26, 0x18100
	s_addc_u32 s23, s27, 0
	s_add_u32 s20, s24, 0x18100
	s_addc_u32 s21, s25, 0
	s_add_u32 s18, s26, 0x18180
	s_addc_u32 s19, s27, 0
	v_lshl_add_u64 v[188:189], s[28:29], 0, v[128:129]
	s_mov_b32 m0, s42
	v_lshl_add_u64 v[188:189], v[188:189], 0, s[10:11]
	ds_read_b128 v[156:159], v132
	ds_read_b128 v[160:163], v132 offset:1024
	ds_read_b128 v[164:167], v132 offset:2048
	ds_read_b128 v[168:171], v132 offset:3072
	ds_read_b128 v[172:175], v132 offset:4096
	ds_read_b128 v[176:179], v132 offset:5120
	ds_read_b128 v[180:183], v132 offset:6144
	ds_read_b128 v[184:187], v132 offset:7168
	global_load_lds_dwordx4 v[188:189], off
	v_lshl_add_u64 v[188:189], s[28:29], 0, v[130:131]
	v_lshl_add_u64 v[188:189], v[188:189], 0, s[10:11]
	s_mov_b32 m0, s35
	s_nop 0
	global_load_lds_dwordx4 v[188:189], off
	s_waitcnt lgkmcnt(8)
	s_barrier
	s_waitcnt lgkmcnt(0)
	s_waitcnt lgkmcnt(0)
	v_mfma_f32_16x16x32_bf16 v[124:127], v[140:143], v[156:159], v[124:127]
	v_mfma_f32_16x16x32_bf16 v[120:123], v[148:151], v[156:159], v[120:123]
	v_mfma_f32_16x16x32_bf16 v[116:119], v[140:143], v[164:167], v[116:119]
	v_mfma_f32_16x16x32_bf16 v[112:115], v[148:151], v[164:167], v[112:115]
	v_mfma_f32_16x16x32_bf16 v[108:111], v[140:143], v[172:175], v[108:111]
	v_mfma_f32_16x16x32_bf16 v[104:107], v[148:151], v[172:175], v[104:107]
	v_mfma_f32_16x16x32_bf16 v[100:103], v[140:143], v[180:183], v[100:103]
	v_mfma_f32_16x16x32_bf16 v[96:99], v[148:151], v[180:183], v[96:99]
	v_mfma_f32_16x16x32_bf16 v[124:127], v[144:147], v[160:163], v[124:127]
	v_mfma_f32_16x16x32_bf16 v[120:123], v[152:155], v[160:163], v[120:123]
	v_mfma_f32_16x16x32_bf16 v[116:119], v[144:147], v[168:171], v[116:119]
	v_mfma_f32_16x16x32_bf16 v[112:115], v[152:155], v[168:171], v[112:115]
	v_mfma_f32_16x16x32_bf16 v[108:111], v[144:147], v[176:179], v[108:111]
	v_mfma_f32_16x16x32_bf16 v[104:107], v[152:155], v[176:179], v[104:107]
	v_mfma_f32_16x16x32_bf16 v[100:103], v[144:147], v[184:187], v[100:103]
	v_mfma_f32_16x16x32_bf16 v[96:99], v[152:155], v[184:187], v[96:99]
	s_barrier
	v_lshl_add_u64 v[204:205], s[26:27], 0, v[128:129]
	s_mov_b32 m0, s43
	v_lshl_add_u64 v[206:207], v[204:205], 0, s[14:15]
	ds_read_b128 v[188:191], v135
	ds_read_b128 v[192:195], v135 offset:1024
	ds_read_b128 v[196:199], v135 offset:2048
	ds_read_b128 v[200:203], v135 offset:3072
	global_load_lds_dwordx4 v[206:207], off
	v_lshl_add_u64 v[206:207], s[26:27], 0, v[130:131]
	v_lshl_add_u64 v[208:209], v[206:207], 0, s[14:15]
	s_mov_b32 m0, s50
	s_nop 0
	global_load_lds_dwordx4 v[208:209], off
	s_barrier
	s_waitcnt lgkmcnt(0)
	s_waitcnt lgkmcnt(0)
	v_mfma_f32_16x16x32_bf16 v[92:95], v[188:191], v[156:159], v[92:95]
	v_mfma_f32_16x16x32_bf16 v[88:91], v[196:199], v[156:159], v[88:91]
	v_mfma_f32_16x16x32_bf16 v[84:87], v[188:191], v[164:167], v[84:87]
	v_mfma_f32_16x16x32_bf16 v[80:83], v[196:199], v[164:167], v[80:83]
	v_mfma_f32_16x16x32_bf16 v[76:79], v[188:191], v[172:175], v[76:79]
	v_mfma_f32_16x16x32_bf16 v[72:75], v[196:199], v[172:175], v[72:75]
	v_mfma_f32_16x16x32_bf16 v[68:71], v[188:191], v[180:183], v[68:71]
	v_mfma_f32_16x16x32_bf16 v[64:67], v[196:199], v[180:183], v[64:67]
	v_mfma_f32_16x16x32_bf16 v[92:95], v[192:195], v[160:163], v[92:95]
	v_mfma_f32_16x16x32_bf16 v[88:91], v[200:203], v[160:163], v[88:91]
	v_mfma_f32_16x16x32_bf16 v[84:87], v[192:195], v[168:171], v[84:87]
	v_mfma_f32_16x16x32_bf16 v[80:83], v[200:203], v[168:171], v[80:83]
	v_mfma_f32_16x16x32_bf16 v[76:79], v[192:195], v[176:179], v[76:79]
	v_mfma_f32_16x16x32_bf16 v[72:75], v[200:203], v[176:179], v[72:75]
	v_mfma_f32_16x16x32_bf16 v[68:71], v[192:195], v[184:187], v[68:71]
	v_mfma_f32_16x16x32_bf16 v[64:67], v[200:203], v[184:187], v[64:67]
	v_lshl_add_u64 v[208:209], s[24:25], 0, v[128:129]
	s_mov_b32 m0, s30
	v_lshl_add_u64 v[210:211], v[208:209], 0, s[14:15]
	s_barrier
	ds_read_b128 v[156:159], v132 offset:16384
	ds_read_b128 v[160:163], v132 offset:17408
	ds_read_b128 v[164:167], v132 offset:18432
	ds_read_b128 v[168:171], v132 offset:19456
	ds_read_b128 v[172:175], v132 offset:20480
	ds_read_b128 v[176:179], v132 offset:21504
	ds_read_b128 v[180:183], v132 offset:22528
	ds_read_b128 v[184:187], v132 offset:23552
	global_load_lds_dwordx4 v[210:211], off
	v_lshl_add_u64 v[210:211], s[24:25], 0, v[130:131]
	v_lshl_add_u64 v[212:213], v[210:211], 0, s[14:15]
	s_mov_b32 m0, s31
	s_nop 0
	global_load_lds_dwordx4 v[212:213], off
	s_barrier
	s_waitcnt lgkmcnt(0)
	s_waitcnt lgkmcnt(0)
	v_mfma_f32_16x16x32_bf16 v[60:63], v[140:143], v[156:159], v[60:63]
	v_mfma_f32_16x16x32_bf16 v[56:59], v[148:151], v[156:159], v[56:59]
	v_mfma_f32_16x16x32_bf16 v[52:55], v[140:143], v[164:167], v[52:55]
	v_mfma_f32_16x16x32_bf16 v[48:51], v[148:151], v[164:167], v[48:51]
	v_mfma_f32_16x16x32_bf16 v[44:47], v[140:143], v[172:175], v[44:47]
	v_mfma_f32_16x16x32_bf16 v[40:43], v[148:151], v[172:175], v[40:43]
	v_mfma_f32_16x16x32_bf16 v[36:39], v[140:143], v[180:183], v[36:39]
	v_mfma_f32_16x16x32_bf16 v[32:35], v[148:151], v[180:183], v[32:35]
	v_mfma_f32_16x16x32_bf16 v[60:63], v[144:147], v[160:163], v[60:63]
	v_mfma_f32_16x16x32_bf16 v[56:59], v[152:155], v[160:163], v[56:59]
	v_mfma_f32_16x16x32_bf16 v[52:55], v[144:147], v[168:171], v[52:55]
	v_mfma_f32_16x16x32_bf16 v[48:51], v[152:155], v[168:171], v[48:51]
	v_mfma_f32_16x16x32_bf16 v[44:47], v[144:147], v[176:179], v[44:47]
	v_mfma_f32_16x16x32_bf16 v[40:43], v[152:155], v[176:179], v[40:43]
	v_mfma_f32_16x16x32_bf16 v[36:39], v[144:147], v[184:187], v[36:39]
	v_mfma_f32_16x16x32_bf16 v[32:35], v[152:155], v[184:187], v[32:35]
	s_barrier
	s_mov_b32 m0, s51
	v_lshl_add_u64 v[140:141], s[22:23], 0, v[128:129]
	global_load_lds_dwordx4 v[140:141], off
	v_lshl_add_u64 v[140:141], s[22:23], 0, v[130:131]
	s_mov_b32 m0, s52
	s_nop 0
	global_load_lds_dwordx4 v[140:141], off
	s_waitcnt vmcnt(6)
	s_barrier
	v_mfma_f32_16x16x32_bf16 v[28:31], v[188:191], v[156:159], v[28:31]
	v_mfma_f32_16x16x32_bf16 v[24:27], v[196:199], v[156:159], v[24:27]
	v_mfma_f32_16x16x32_bf16 v[20:23], v[188:191], v[164:167], v[20:23]
	v_mfma_f32_16x16x32_bf16 v[16:19], v[196:199], v[164:167], v[16:19]
	v_mfma_f32_16x16x32_bf16 v[12:15], v[188:191], v[172:175], v[12:15]
	v_mfma_f32_16x16x32_bf16 v[8:11], v[196:199], v[172:175], v[8:11]
	v_mfma_f32_16x16x32_bf16 v[4:7], v[188:191], v[180:183], v[4:7]
	v_mfma_f32_16x16x32_bf16 v[0:3], v[196:199], v[180:183], v[0:3]
	v_mfma_f32_16x16x32_bf16 v[28:31], v[192:195], v[160:163], v[28:31]
	v_mfma_f32_16x16x32_bf16 v[24:27], v[200:203], v[160:163], v[24:27]
	v_mfma_f32_16x16x32_bf16 v[20:23], v[192:195], v[168:171], v[20:23]
	v_mfma_f32_16x16x32_bf16 v[16:19], v[200:203], v[168:171], v[16:19]
	v_mfma_f32_16x16x32_bf16 v[12:15], v[192:195], v[176:179], v[12:15]
	v_mfma_f32_16x16x32_bf16 v[8:11], v[200:203], v[176:179], v[8:11]
	v_mfma_f32_16x16x32_bf16 v[4:7], v[192:195], v[184:187], v[4:7]
	v_mfma_f32_16x16x32_bf16 v[0:3], v[200:203], v[184:187], v[0:3]
	s_barrier
	ds_read_b128 v[140:143], v137
	ds_read_b128 v[144:147], v137 offset:1024
	ds_read_b128 v[148:151], v137 offset:2048
	ds_read_b128 v[152:155], v137 offset:3072
	s_mov_b32 m0, s33
	v_lshl_add_u64 v[188:189], s[20:21], 0, v[128:129]
	ds_read_b128 v[156:159], v132 offset:32768
	ds_read_b128 v[160:163], v132 offset:33792
	ds_read_b128 v[164:167], v132 offset:34816
	ds_read_b128 v[168:171], v132 offset:35840
	ds_read_b128 v[172:175], v132 offset:36864
	ds_read_b128 v[176:179], v132 offset:37888
	ds_read_b128 v[180:183], v132 offset:38912
	ds_read_b128 v[184:187], v132 offset:39936
	global_load_lds_dwordx4 v[188:189], off
	v_lshl_add_u64 v[188:189], s[20:21], 0, v[130:131]
	s_mov_b32 m0, s34
	s_nop 0
	global_load_lds_dwordx4 v[188:189], off
	s_waitcnt lgkmcnt(8)
	s_barrier
	s_waitcnt lgkmcnt(0)
	s_waitcnt lgkmcnt(0)
	v_mfma_f32_16x16x32_bf16 v[124:127], v[140:143], v[156:159], v[124:127]
	v_mfma_f32_16x16x32_bf16 v[120:123], v[148:151], v[156:159], v[120:123]
	v_mfma_f32_16x16x32_bf16 v[116:119], v[140:143], v[164:167], v[116:119]
	v_mfma_f32_16x16x32_bf16 v[112:115], v[148:151], v[164:167], v[112:115]
	v_mfma_f32_16x16x32_bf16 v[108:111], v[140:143], v[172:175], v[108:111]
	v_mfma_f32_16x16x32_bf16 v[104:107], v[148:151], v[172:175], v[104:107]
	v_mfma_f32_16x16x32_bf16 v[100:103], v[140:143], v[180:183], v[100:103]
	v_mfma_f32_16x16x32_bf16 v[96:99], v[148:151], v[180:183], v[96:99]
	v_mfma_f32_16x16x32_bf16 v[124:127], v[144:147], v[160:163], v[124:127]
	v_mfma_f32_16x16x32_bf16 v[120:123], v[152:155], v[160:163], v[120:123]
	v_mfma_f32_16x16x32_bf16 v[116:119], v[144:147], v[168:171], v[116:119]
	v_mfma_f32_16x16x32_bf16 v[112:115], v[152:155], v[168:171], v[112:115]
	v_mfma_f32_16x16x32_bf16 v[108:111], v[144:147], v[176:179], v[108:111]
	v_mfma_f32_16x16x32_bf16 v[104:107], v[152:155], v[176:179], v[104:107]
	v_mfma_f32_16x16x32_bf16 v[100:103], v[144:147], v[184:187], v[100:103]
	v_mfma_f32_16x16x32_bf16 v[96:99], v[152:155], v[184:187], v[96:99]
	s_barrier
	s_mov_b32 m0, s53
	v_lshl_add_u64 v[204:205], v[204:205], 0, s[16:17]
	ds_read_b128 v[188:191], v138
	ds_read_b128 v[192:195], v138 offset:1024
	ds_read_b128 v[196:199], v138 offset:2048
	ds_read_b128 v[200:203], v138 offset:3072
	global_load_lds_dwordx4 v[204:205], off
	v_lshl_add_u64 v[204:205], v[206:207], 0, s[16:17]
	s_mov_b32 m0, s76
	s_nop 0
	global_load_lds_dwordx4 v[204:205], off
	s_barrier
	s_waitcnt lgkmcnt(0)
	s_waitcnt lgkmcnt(0)
	v_mfma_f32_16x16x32_bf16 v[92:95], v[188:191], v[156:159], v[92:95]
	v_mfma_f32_16x16x32_bf16 v[88:91], v[196:199], v[156:159], v[88:91]
	v_mfma_f32_16x16x32_bf16 v[84:87], v[188:191], v[164:167], v[84:87]
	v_mfma_f32_16x16x32_bf16 v[80:83], v[196:199], v[164:167], v[80:83]
	v_mfma_f32_16x16x32_bf16 v[76:79], v[188:191], v[172:175], v[76:79]
	v_mfma_f32_16x16x32_bf16 v[72:75], v[196:199], v[172:175], v[72:75]
	v_mfma_f32_16x16x32_bf16 v[68:71], v[188:191], v[180:183], v[68:71]
	v_mfma_f32_16x16x32_bf16 v[64:67], v[196:199], v[180:183], v[64:67]
	v_mfma_f32_16x16x32_bf16 v[92:95], v[192:195], v[160:163], v[92:95]
	v_mfma_f32_16x16x32_bf16 v[88:91], v[200:203], v[160:163], v[88:91]
	v_mfma_f32_16x16x32_bf16 v[84:87], v[192:195], v[168:171], v[84:87]
	v_mfma_f32_16x16x32_bf16 v[80:83], v[200:203], v[168:171], v[80:83]
	v_mfma_f32_16x16x32_bf16 v[76:79], v[192:195], v[176:179], v[76:79]
	v_mfma_f32_16x16x32_bf16 v[72:75], v[200:203], v[176:179], v[72:75]
	v_mfma_f32_16x16x32_bf16 v[68:71], v[192:195], v[184:187], v[68:71]
	v_mfma_f32_16x16x32_bf16 v[64:67], v[200:203], v[184:187], v[64:67]
	s_mov_b32 m0, s36
	v_lshl_add_u64 v[204:205], v[208:209], 0, s[16:17]
	s_barrier
	ds_read_b128 v[156:159], v132 offset:49152
	ds_read_b128 v[160:163], v132 offset:50176
	ds_read_b128 v[164:167], v132 offset:51200
	ds_read_b128 v[168:171], v132 offset:52224
	ds_read_b128 v[172:175], v132 offset:53248
	ds_read_b128 v[176:179], v132 offset:54272
	ds_read_b128 v[180:183], v132 offset:55296
	ds_read_b128 v[184:187], v132 offset:56320
	global_load_lds_dwordx4 v[204:205], off
	v_lshl_add_u64 v[204:205], v[210:211], 0, s[16:17]
	s_mov_b32 m0, s37
	s_nop 0
	global_load_lds_dwordx4 v[204:205], off
	s_barrier
	s_waitcnt lgkmcnt(0)
	s_waitcnt lgkmcnt(0)
	v_mfma_f32_16x16x32_bf16 v[60:63], v[140:143], v[156:159], v[60:63]
	v_mfma_f32_16x16x32_bf16 v[56:59], v[148:151], v[156:159], v[56:59]
	v_mfma_f32_16x16x32_bf16 v[52:55], v[140:143], v[164:167], v[52:55]
	v_mfma_f32_16x16x32_bf16 v[48:51], v[148:151], v[164:167], v[48:51]
	v_mfma_f32_16x16x32_bf16 v[44:47], v[140:143], v[172:175], v[44:47]
	v_mfma_f32_16x16x32_bf16 v[40:43], v[148:151], v[172:175], v[40:43]
	v_mfma_f32_16x16x32_bf16 v[36:39], v[140:143], v[180:183], v[36:39]
	v_mfma_f32_16x16x32_bf16 v[32:35], v[148:151], v[180:183], v[32:35]
	v_mfma_f32_16x16x32_bf16 v[60:63], v[144:147], v[160:163], v[60:63]
	v_mfma_f32_16x16x32_bf16 v[56:59], v[152:155], v[160:163], v[56:59]
	v_mfma_f32_16x16x32_bf16 v[52:55], v[144:147], v[168:171], v[52:55]
	v_mfma_f32_16x16x32_bf16 v[48:51], v[152:155], v[168:171], v[48:51]
	v_mfma_f32_16x16x32_bf16 v[44:47], v[144:147], v[176:179], v[44:47]
	v_mfma_f32_16x16x32_bf16 v[40:43], v[152:155], v[176:179], v[40:43]
	v_mfma_f32_16x16x32_bf16 v[36:39], v[144:147], v[184:187], v[36:39]
	v_mfma_f32_16x16x32_bf16 v[32:35], v[152:155], v[184:187], v[32:35]
	s_barrier
	s_mov_b32 m0, s77
	v_lshl_add_u64 v[140:141], s[18:19], 0, v[128:129]
	global_load_lds_dwordx4 v[140:141], off
	v_lshl_add_u64 v[140:141], s[18:19], 0, v[130:131]
	s_mov_b32 m0, s88
	s_nop 0
	global_load_lds_dwordx4 v[140:141], off
	s_waitcnt vmcnt(6)
	s_barrier
	v_mfma_f32_16x16x32_bf16 v[28:31], v[188:191], v[156:159], v[28:31]
	v_mfma_f32_16x16x32_bf16 v[24:27], v[196:199], v[156:159], v[24:27]
	v_mfma_f32_16x16x32_bf16 v[20:23], v[188:191], v[164:167], v[20:23]
	v_mfma_f32_16x16x32_bf16 v[16:19], v[196:199], v[164:167], v[16:19]
	v_mfma_f32_16x16x32_bf16 v[12:15], v[188:191], v[172:175], v[12:15]
	v_mfma_f32_16x16x32_bf16 v[8:11], v[196:199], v[172:175], v[8:11]
	v_mfma_f32_16x16x32_bf16 v[4:7], v[188:191], v[180:183], v[4:7]
	v_mfma_f32_16x16x32_bf16 v[0:3], v[196:199], v[180:183], v[0:3]
	v_mfma_f32_16x16x32_bf16 v[28:31], v[192:195], v[160:163], v[28:31]
	v_mfma_f32_16x16x32_bf16 v[24:27], v[200:203], v[160:163], v[24:27]
	v_mfma_f32_16x16x32_bf16 v[20:23], v[192:195], v[168:171], v[20:23]
	v_mfma_f32_16x16x32_bf16 v[16:19], v[200:203], v[168:171], v[16:19]
	v_mfma_f32_16x16x32_bf16 v[12:15], v[192:195], v[176:179], v[12:15]
	v_mfma_f32_16x16x32_bf16 v[8:11], v[200:203], v[176:179], v[8:11]
	v_mfma_f32_16x16x32_bf16 v[4:7], v[192:195], v[184:187], v[4:7]
	v_mfma_f32_16x16x32_bf16 v[0:3], v[200:203], v[184:187], v[0:3]
	s_movk_i32 s18, 0x100
	s_andn2_b64 vcc, exec, s[12:13]
	s_mov_b64 s[12:13], 0
	s_barrier
	s_cbranch_vccz .LBB0_492
	s_add_u32 s4, s4, 0x18280
	v_add_u32_e32 v133, 0, v133
	s_addc_u32 s5, s5, 0
	s_mov_b32 m0, s42
	v_add_u32_e32 v134, 0x10000, v133
	v_lshl_add_u64 v[128:129], s[4:5], 0, v[128:129]
	ds_read_b128 v[138:141], v134
	ds_read_b128 v[142:145], v134 offset:1024
	ds_read_b128 v[146:149], v134 offset:2048
	ds_read_b128 v[150:153], v134 offset:3072
	ds_read_b128 v[154:157], v132
	ds_read_b128 v[158:161], v132 offset:1024
	ds_read_b128 v[162:165], v132 offset:2048
	ds_read_b128 v[166:169], v132 offset:3072
	ds_read_b128 v[170:173], v132 offset:4096
	ds_read_b128 v[174:177], v132 offset:5120
	ds_read_b128 v[178:181], v132 offset:6144
	ds_read_b128 v[182:185], v132 offset:7168
	global_load_lds_dwordx4 v[128:129], off
	v_lshl_add_u64 v[128:129], s[4:5], 0, v[130:131]
	s_mov_b32 m0, s35
	s_nop 0
	global_load_lds_dwordx4 v[128:129], off
	s_barrier
	s_waitcnt lgkmcnt(0)
	s_waitcnt lgkmcnt(0)
	v_mfma_f32_16x16x32_bf16 v[124:127], v[138:141], v[154:157], v[124:127]
	v_mfma_f32_16x16x32_bf16 v[120:123], v[146:149], v[154:157], v[120:123]
	v_mfma_f32_16x16x32_bf16 v[112:115], v[146:149], v[162:165], v[112:115]
	v_mfma_f32_16x16x32_bf16 v[104:107], v[146:149], v[170:173], v[104:107]
	v_mfma_f32_16x16x32_bf16 v[96:99], v[146:149], v[178:181], v[96:99]
	v_mfma_f32_16x16x32_bf16 v[124:127], v[142:145], v[158:161], v[124:127]
	v_mfma_f32_16x16x32_bf16 v[120:123], v[150:153], v[158:161], v[120:123]
	v_mfma_f32_16x16x32_bf16 v[116:119], v[138:141], v[162:165], v[116:119]
	v_mfma_f32_16x16x32_bf16 v[112:115], v[150:153], v[166:169], v[112:115]
	v_mfma_f32_16x16x32_bf16 v[108:111], v[138:141], v[170:173], v[108:111]
	v_mfma_f32_16x16x32_bf16 v[104:107], v[150:153], v[174:177], v[104:107]
	v_mfma_f32_16x16x32_bf16 v[100:103], v[138:141], v[178:181], v[100:103]
	v_mfma_f32_16x16x32_bf16 v[96:99], v[150:153], v[182:185], v[96:99]
	v_mfma_f32_16x16x32_bf16 v[128:131], v[142:145], v[166:169], v[116:119]
	v_mfma_f32_16x16x32_bf16 v[186:189], v[142:145], v[174:177], v[108:111]
	v_mfma_f32_16x16x32_bf16 v[190:193], v[142:145], v[182:185], v[100:103]
	v_add_u32_e32 v134, 0x14000, v133
	s_barrier
	s_nop 0
	ds_read_b128 v[100:103], v134
	ds_read_b128 v[108:111], v134 offset:1024
	ds_read_b128 v[116:119], v134 offset:2048
	ds_read_b128 v[194:197], v134 offset:3072
	s_barrier
	s_waitcnt lgkmcnt(0)
	s_waitcnt lgkmcnt(0)
	v_mfma_f32_16x16x32_bf16 v[88:91], v[116:119], v[154:157], v[88:91]
	v_mfma_f32_16x16x32_bf16 v[80:83], v[116:119], v[162:165], v[80:83]
	v_mfma_f32_16x16x32_bf16 v[72:75], v[116:119], v[170:173], v[72:75]
	v_mfma_f32_16x16x32_bf16 v[64:67], v[116:119], v[178:181], v[64:67]
	v_mfma_f32_16x16x32_bf16 v[92:95], v[100:103], v[154:157], v[92:95]
	v_mfma_f32_16x16x32_bf16 v[88:91], v[194:197], v[158:161], v[88:91]
	v_mfma_f32_16x16x32_bf16 v[84:87], v[100:103], v[162:165], v[84:87]
	v_mfma_f32_16x16x32_bf16 v[80:83], v[194:197], v[166:169], v[80:83]
	v_mfma_f32_16x16x32_bf16 v[76:79], v[100:103], v[170:173], v[76:79]
	v_mfma_f32_16x16x32_bf16 v[72:75], v[194:197], v[174:177], v[72:75]
	v_mfma_f32_16x16x32_bf16 v[68:71], v[100:103], v[178:181], v[68:71]
	v_mfma_f32_16x16x32_bf16 v[64:67], v[194:197], v[182:185], v[64:67]
	v_mfma_f32_16x16x32_bf16 v[198:201], v[108:111], v[158:161], v[92:95]
	v_mfma_f32_16x16x32_bf16 v[154:157], v[108:111], v[166:169], v[84:87]
	v_mfma_f32_16x16x32_bf16 v[158:161], v[108:111], v[174:177], v[76:79]
	v_mfma_f32_16x16x32_bf16 v[162:165], v[108:111], v[182:185], v[68:71]
	s_barrier
	s_nop 0
	ds_read_b128 v[68:71], v132 offset:16384
	ds_read_b128 v[76:79], v132 offset:17408
	ds_read_b128 v[84:87], v132 offset:18432
	ds_read_b128 v[92:95], v132 offset:19456
	ds_read_b128 v[166:169], v132 offset:20480
	ds_read_b128 v[170:173], v132 offset:21504
	ds_read_b128 v[174:177], v132 offset:22528
	ds_read_b128 v[178:181], v132 offset:23552
	s_waitcnt vmcnt(4)
	s_barrier
	s_waitcnt lgkmcnt(0)
	s_waitcnt lgkmcnt(0)
	v_mfma_f32_16x16x32_bf16 v[60:63], v[138:141], v[68:71], v[60:63]
	v_mfma_f32_16x16x32_bf16 v[56:59], v[146:149], v[68:71], v[56:59]
	v_mfma_f32_16x16x32_bf16 v[48:51], v[146:149], v[84:87], v[48:51]
	v_mfma_f32_16x16x32_bf16 v[40:43], v[146:149], v[166:169], v[40:43]
	v_mfma_f32_16x16x32_bf16 v[32:35], v[146:149], v[174:177], v[32:35]
	v_mfma_f32_16x16x32_bf16 v[60:63], v[142:145], v[76:79], v[60:63]
	v_mfma_f32_16x16x32_bf16 v[56:59], v[150:153], v[76:79], v[56:59]
	v_mfma_f32_16x16x32_bf16 v[52:55], v[138:141], v[84:87], v[52:55]
	v_mfma_f32_16x16x32_bf16 v[48:51], v[150:153], v[92:95], v[48:51]
	v_mfma_f32_16x16x32_bf16 v[44:47], v[138:141], v[166:169], v[44:47]
	v_mfma_f32_16x16x32_bf16 v[40:43], v[150:153], v[170:173], v[40:43]
	v_mfma_f32_16x16x32_bf16 v[36:39], v[138:141], v[174:177], v[36:39]
	v_mfma_f32_16x16x32_bf16 v[32:35], v[150:153], v[178:181], v[32:35]
	v_mfma_f32_16x16x32_bf16 v[182:185], v[142:145], v[92:95], v[52:55]
	v_mfma_f32_16x16x32_bf16 v[202:205], v[142:145], v[170:173], v[44:47]
	v_mfma_f32_16x16x32_bf16 v[138:141], v[142:145], v[178:181], v[36:39]
	v_mfma_f32_16x16x32_bf16 v[24:27], v[116:119], v[68:71], v[24:27]
	v_mfma_f32_16x16x32_bf16 v[16:19], v[116:119], v[84:87], v[16:19]
	v_mfma_f32_16x16x32_bf16 v[8:11], v[116:119], v[166:169], v[8:11]
	v_mfma_f32_16x16x32_bf16 v[0:3], v[116:119], v[174:177], v[0:3]
	v_mfma_f32_16x16x32_bf16 v[28:31], v[100:103], v[68:71], v[28:31]
	v_mfma_f32_16x16x32_bf16 v[24:27], v[194:197], v[76:79], v[24:27]
	v_mfma_f32_16x16x32_bf16 v[20:23], v[100:103], v[84:87], v[20:23]
	v_mfma_f32_16x16x32_bf16 v[16:19], v[194:197], v[92:95], v[16:19]
	v_mfma_f32_16x16x32_bf16 v[12:15], v[100:103], v[166:169], v[12:15]
	v_mfma_f32_16x16x32_bf16 v[8:11], v[194:197], v[170:173], v[8:11]
	v_mfma_f32_16x16x32_bf16 v[4:7], v[100:103], v[174:177], v[4:7]
	v_mfma_f32_16x16x32_bf16 v[0:3], v[194:197], v[178:181], v[0:3]
	v_mfma_f32_16x16x32_bf16 v[142:145], v[108:111], v[76:79], v[28:31]
	v_mfma_f32_16x16x32_bf16 v[146:149], v[108:111], v[92:95], v[20:23]
	v_mfma_f32_16x16x32_bf16 v[150:153], v[108:111], v[170:173], v[12:15]
	v_mfma_f32_16x16x32_bf16 v[166:169], v[108:111], v[178:181], v[4:7]
	v_add_u32_e32 v20, 0x18000, v133
	s_barrier
	ds_read_b128 v[4:7], v20
	ds_read_b128 v[12:15], v20 offset:1024
	ds_read_b128 v[170:173], v20 offset:2048
	ds_read_b128 v[174:177], v20 offset:3072
	ds_read_b128 v[20:23], v132 offset:32768
	ds_read_b128 v[28:31], v132 offset:33792
	ds_read_b128 v[36:39], v132 offset:34816
	ds_read_b128 v[44:47], v132 offset:35840
	ds_read_b128 v[52:55], v132 offset:36864
	ds_read_b128 v[178:181], v132 offset:37888
	ds_read_b128 v[194:197], v132 offset:38912
	ds_read_b128 v[206:209], v132 offset:39936
	s_waitcnt vmcnt(2)
	s_barrier
	s_waitcnt lgkmcnt(0)
	s_waitcnt lgkmcnt(0)
	v_mfma_f32_16x16x32_bf16 v[68:71], v[4:7], v[20:23], v[124:127]
	v_mfma_f32_16x16x32_bf16 v[124:127], v[12:15], v[28:31], v[68:71]
	v_mfma_f32_16x16x32_bf16 v[68:71], v[170:173], v[20:23], v[120:123]
	v_mfma_f32_16x16x32_bf16 v[116:119], v[174:177], v[28:31], v[68:71]
	v_mfma_f32_16x16x32_bf16 v[68:71], v[4:7], v[36:39], v[128:131]
	v_mfma_f32_16x16x32_bf16 v[108:111], v[12:15], v[44:47], v[68:71]
	v_mfma_f32_16x16x32_bf16 v[68:71], v[170:173], v[36:39], v[112:115]
	v_mfma_f32_16x16x32_bf16 v[100:103], v[174:177], v[44:47], v[68:71]
	v_mfma_f32_16x16x32_bf16 v[68:71], v[4:7], v[52:55], v[186:189]
	v_mfma_f32_16x16x32_bf16 v[92:95], v[12:15], v[178:181], v[68:71]
	v_mfma_f32_16x16x32_bf16 v[68:71], v[170:173], v[52:55], v[104:107]
	v_mfma_f32_16x16x32_bf16 v[84:87], v[174:177], v[178:181], v[68:71]
	v_mfma_f32_16x16x32_bf16 v[68:71], v[4:7], v[194:197], v[190:193]
	v_mfma_f32_16x16x32_bf16 v[76:79], v[12:15], v[206:209], v[68:71]
	v_mfma_f32_16x16x32_bf16 v[68:71], v[170:173], v[194:197], v[96:99]
	v_mfma_f32_16x16x32_bf16 v[68:71], v[174:177], v[206:209], v[68:71]
	s_nop 0
	v_add_u32_e32 v96, 0x1c000, v133
	s_barrier
	ds_read_b128 v[128:131], v96
	ds_read_b128 v[186:189], v96 offset:1024
	ds_read_b128 v[190:193], v96 offset:2048
	ds_read_b128 v[210:213], v96 offset:3072
	s_waitcnt vmcnt(0)
	s_barrier
	s_waitcnt lgkmcnt(0)
	s_waitcnt lgkmcnt(0)
	v_mfma_f32_16x16x32_bf16 v[96:99], v[128:131], v[20:23], v[198:201]
	v_mfma_f32_16x16x32_bf16 v[20:23], v[190:193], v[20:23], v[88:91]
	v_mfma_f32_16x16x32_bf16 v[112:115], v[210:213], v[28:31], v[20:23]
	v_mfma_f32_16x16x32_bf16 v[20:23], v[128:131], v[36:39], v[154:157]
	v_mfma_f32_16x16x32_bf16 v[104:107], v[186:189], v[44:47], v[20:23]
	v_mfma_f32_16x16x32_bf16 v[20:23], v[190:193], v[36:39], v[80:83]
	v_mfma_f32_16x16x32_bf16 v[120:123], v[186:189], v[28:31], v[96:99]
	v_mfma_f32_16x16x32_bf16 v[96:99], v[210:213], v[44:47], v[20:23]
	v_mfma_f32_16x16x32_bf16 v[20:23], v[128:131], v[52:55], v[158:161]
	v_mfma_f32_16x16x32_bf16 v[88:91], v[186:189], v[178:181], v[20:23]
	v_mfma_f32_16x16x32_bf16 v[20:23], v[190:193], v[52:55], v[72:75]
	v_mfma_f32_16x16x32_bf16 v[80:83], v[210:213], v[178:181], v[20:23]
	v_mfma_f32_16x16x32_bf16 v[20:23], v[128:131], v[194:197], v[162:165]
	v_mfma_f32_16x16x32_bf16 v[72:75], v[186:189], v[206:209], v[20:23]
	v_mfma_f32_16x16x32_bf16 v[20:23], v[190:193], v[194:197], v[64:67]
	v_mfma_f32_16x16x32_bf16 v[64:67], v[210:213], v[206:209], v[20:23]
	s_barrier
	ds_read_b128 v[154:157], v132 offset:49152
	ds_read_b128 v[158:161], v132 offset:50176
	ds_read_b128 v[162:165], v132 offset:51200
	ds_read_b128 v[178:181], v132 offset:52224
	ds_read_b128 v[194:197], v132 offset:53248
	ds_read_b128 v[198:201], v132 offset:54272
	ds_read_b128 v[206:209], v132 offset:55296
	ds_read_b128 v[132:135], v132 offset:56320
	s_barrier
	s_waitcnt lgkmcnt(0)
	s_waitcnt lgkmcnt(0)
	v_mfma_f32_16x16x32_bf16 v[20:23], v[4:7], v[154:157], v[60:63]
	v_mfma_f32_16x16x32_bf16 v[60:63], v[12:15], v[158:161], v[20:23]
	v_mfma_f32_16x16x32_bf16 v[20:23], v[170:173], v[154:157], v[56:59]
	v_mfma_f32_16x16x32_bf16 v[52:55], v[174:177], v[158:161], v[20:23]
	v_mfma_f32_16x16x32_bf16 v[20:23], v[4:7], v[162:165], v[182:185]
	v_mfma_f32_16x16x32_bf16 v[44:47], v[12:15], v[178:181], v[20:23]
	v_mfma_f32_16x16x32_bf16 v[20:23], v[170:173], v[162:165], v[48:51]
	v_mfma_f32_16x16x32_bf16 v[36:39], v[174:177], v[178:181], v[20:23]
	v_mfma_f32_16x16x32_bf16 v[20:23], v[4:7], v[194:197], v[202:205]
	v_mfma_f32_16x16x32_bf16 v[4:7], v[4:7], v[206:209], v[138:141]
	v_mfma_f32_16x16x32_bf16 v[28:31], v[12:15], v[198:201], v[20:23]
	v_mfma_f32_16x16x32_bf16 v[20:23], v[170:173], v[194:197], v[40:43]
	v_mfma_f32_16x16x32_bf16 v[12:15], v[12:15], v[132:135], v[4:7]
	v_mfma_f32_16x16x32_bf16 v[4:7], v[170:173], v[206:209], v[32:35]
	v_mfma_f32_16x16x32_bf16 v[20:23], v[174:177], v[198:201], v[20:23]
	v_mfma_f32_16x16x32_bf16 v[4:7], v[174:177], v[132:135], v[4:7]
	v_mfma_f32_16x16x32_bf16 v[32:35], v[128:131], v[154:157], v[142:145]
	v_mfma_f32_16x16x32_bf16 v[24:27], v[190:193], v[154:157], v[24:27]
	v_mfma_f32_16x16x32_bf16 v[16:19], v[190:193], v[162:165], v[16:19]
	v_mfma_f32_16x16x32_bf16 v[56:59], v[186:189], v[158:161], v[32:35]
	v_mfma_f32_16x16x32_bf16 v[48:51], v[210:213], v[158:161], v[24:27]
	v_mfma_f32_16x16x32_bf16 v[24:27], v[128:131], v[162:165], v[146:149]
	v_mfma_f32_16x16x32_bf16 v[32:35], v[210:213], v[178:181], v[16:19]
	v_mfma_f32_16x16x32_bf16 v[16:19], v[128:131], v[194:197], v[150:153]
	v_mfma_f32_16x16x32_bf16 v[8:11], v[190:193], v[194:197], v[8:11]
	v_mfma_f32_16x16x32_bf16 v[40:43], v[186:189], v[178:181], v[24:27]
	v_mfma_f32_16x16x32_bf16 v[24:27], v[186:189], v[198:201], v[16:19]
	v_mfma_f32_16x16x32_bf16 v[16:19], v[210:213], v[198:201], v[8:11]
	v_mfma_f32_16x16x32_bf16 v[8:11], v[128:131], v[206:209], v[166:169]
	v_mfma_f32_16x16x32_bf16 v[0:3], v[190:193], v[206:209], v[0:3]
	v_mfma_f32_16x16x32_bf16 v[8:11], v[186:189], v[132:135], v[8:11]
	v_mfma_f32_16x16x32_bf16 v[0:3], v[210:213], v[132:135], v[0:3]
	s_cmpk_lt_u32 s1, 0x100
	s_barrier
	s_cbranch_scc0 .LBB0_495
	s_barrier

.LBB0_713:
	ds_read_b128 v[146:149], v145
	ds_read_b128 v[150:153], v145 offset:1024
	ds_read_b128 v[154:157], v145 offset:2048
	ds_read_b128 v[158:161], v145 offset:3072
	v_lshl_add_u64 v[210:211], v[132:133], 0, s[20:21]
	s_add_i32 s33, s26, 0xc000
	v_lshl_add_u64 v[194:195], v[210:211], 0, s[4:5]
	s_mov_b32 m0, s33
	v_lshl_add_u64 v[212:213], v[134:135], 0, s[20:21]
	s_add_i32 s23, s26, 0xe000
	ds_read_b128 v[162:165], v143
	ds_read_b128 v[166:169], v143 offset:1024
	ds_read_b128 v[170:173], v143 offset:2048
	ds_read_b128 v[174:177], v143 offset:3072
	ds_read_b128 v[178:181], v143 offset:4096
	ds_read_b128 v[182:185], v143 offset:5120
	ds_read_b128 v[186:189], v143 offset:6144
	ds_read_b128 v[190:193], v143 offset:7168
	global_load_lds_dwordx4 v[194:195], off
	v_lshl_add_u64 v[194:195], v[212:213], 0, s[4:5]
	s_mov_b32 m0, s23
	s_nop 0
	global_load_lds_dwordx4 v[194:195], off
	s_waitcnt lgkmcnt(8)
	s_barrier
	s_waitcnt lgkmcnt(0)
	s_waitcnt lgkmcnt(0)
	v_mfma_f32_16x16x32_bf16 v[124:127], v[146:149], v[162:165], v[124:127]
	v_mfma_f32_16x16x32_bf16 v[120:123], v[154:157], v[162:165], v[120:123]
	v_mfma_f32_16x16x32_bf16 v[116:119], v[146:149], v[170:173], v[116:119]
	v_mfma_f32_16x16x32_bf16 v[112:115], v[154:157], v[170:173], v[112:115]
	v_mfma_f32_16x16x32_bf16 v[108:111], v[146:149], v[178:181], v[108:111]
	v_mfma_f32_16x16x32_bf16 v[104:107], v[154:157], v[178:181], v[104:107]
	v_mfma_f32_16x16x32_bf16 v[100:103], v[146:149], v[186:189], v[100:103]
	v_mfma_f32_16x16x32_bf16 v[96:99], v[154:157], v[186:189], v[96:99]
	v_mfma_f32_16x16x32_bf16 v[124:127], v[150:153], v[166:169], v[124:127]
	v_mfma_f32_16x16x32_bf16 v[120:123], v[158:161], v[166:169], v[120:123]
	v_mfma_f32_16x16x32_bf16 v[116:119], v[150:153], v[174:177], v[116:119]
	v_mfma_f32_16x16x32_bf16 v[112:115], v[158:161], v[174:177], v[112:115]
	v_mfma_f32_16x16x32_bf16 v[108:111], v[150:153], v[182:185], v[108:111]
	v_mfma_f32_16x16x32_bf16 v[104:107], v[158:161], v[182:185], v[104:107]
	v_mfma_f32_16x16x32_bf16 v[100:103], v[150:153], v[190:193], v[100:103]
	v_mfma_f32_16x16x32_bf16 v[96:99], v[158:161], v[190:193], v[96:99]
	s_barrier
	s_add_i32 s34, 0, 0x14000
	v_lshl_add_u64 v[214:215], v[138:139], 0, s[20:21]
	s_add_i32 s35, s24, s17
	v_add_u32_e32 v206, s34, v144
	v_lshl_add_u64 v[216:217], v[214:215], 0, s[6:7]
	s_mov_b32 m0, s35
	ds_read_b128 v[194:197], v206
	ds_read_b128 v[198:201], v206 offset:1024
	ds_read_b128 v[202:205], v206 offset:2048
	ds_read_b128 v[206:209], v206 offset:3072
	global_load_lds_dwordx4 v[216:217], off
	v_lshl_add_u64 v[216:217], v[140:141], 0, s[20:21]
	v_lshl_add_u64 v[218:219], v[216:217], 0, s[6:7]
	s_add_i32 m0, s35, 0x2000
	s_nop 0
	global_load_lds_dwordx4 v[218:219], off
	s_barrier
	s_waitcnt lgkmcnt(0)
	s_waitcnt lgkmcnt(0)
	v_mfma_f32_16x16x32_bf16 v[92:95], v[194:197], v[162:165], v[92:95]
	v_mfma_f32_16x16x32_bf16 v[88:91], v[202:205], v[162:165], v[88:91]
	v_mfma_f32_16x16x32_bf16 v[84:87], v[194:197], v[170:173], v[84:87]
	v_mfma_f32_16x16x32_bf16 v[80:83], v[202:205], v[170:173], v[80:83]
	v_mfma_f32_16x16x32_bf16 v[76:79], v[194:197], v[178:181], v[76:79]
	v_mfma_f32_16x16x32_bf16 v[72:75], v[202:205], v[178:181], v[72:75]
	v_mfma_f32_16x16x32_bf16 v[68:71], v[194:197], v[186:189], v[68:71]
	v_mfma_f32_16x16x32_bf16 v[64:67], v[202:205], v[186:189], v[64:67]
	v_mfma_f32_16x16x32_bf16 v[92:95], v[198:201], v[166:169], v[92:95]
	v_mfma_f32_16x16x32_bf16 v[88:91], v[206:209], v[166:169], v[88:91]
	v_mfma_f32_16x16x32_bf16 v[84:87], v[198:201], v[174:177], v[84:87]
	v_mfma_f32_16x16x32_bf16 v[80:83], v[206:209], v[174:177], v[80:83]
	v_mfma_f32_16x16x32_bf16 v[76:79], v[198:201], v[182:185], v[76:79]
	v_mfma_f32_16x16x32_bf16 v[72:75], v[206:209], v[182:185], v[72:75]
	v_mfma_f32_16x16x32_bf16 v[68:71], v[198:201], v[190:193], v[68:71]
	v_mfma_f32_16x16x32_bf16 v[64:67], v[206:209], v[190:193], v[64:67]
	s_mov_b32 m0, s26
	v_lshl_add_u64 v[218:219], v[210:211], 0, s[6:7]
	s_barrier
	ds_read_b128 v[162:165], v143 offset:16384
	ds_read_b128 v[166:169], v143 offset:17408
	ds_read_b128 v[170:173], v143 offset:18432
	ds_read_b128 v[174:177], v143 offset:19456
	ds_read_b128 v[178:181], v143 offset:20480
	ds_read_b128 v[182:185], v143 offset:21504
	ds_read_b128 v[186:189], v143 offset:22528
	ds_read_b128 v[190:193], v143 offset:23552
	global_load_lds_dwordx4 v[218:219], off
	v_lshl_add_u64 v[218:219], v[212:213], 0, s[6:7]
	s_mov_b32 m0, s27
	s_nop 0
	global_load_lds_dwordx4 v[218:219], off
	s_barrier
	s_waitcnt lgkmcnt(0)
	s_waitcnt lgkmcnt(0)
	v_mfma_f32_16x16x32_bf16 v[60:63], v[146:149], v[162:165], v[60:63]
	v_mfma_f32_16x16x32_bf16 v[56:59], v[154:157], v[162:165], v[56:59]
	v_mfma_f32_16x16x32_bf16 v[52:55], v[146:149], v[170:173], v[52:55]
	v_mfma_f32_16x16x32_bf16 v[48:51], v[154:157], v[170:173], v[48:51]
	v_mfma_f32_16x16x32_bf16 v[44:47], v[146:149], v[178:181], v[44:47]
	v_mfma_f32_16x16x32_bf16 v[40:43], v[154:157], v[178:181], v[40:43]
	v_mfma_f32_16x16x32_bf16 v[36:39], v[146:149], v[186:189], v[36:39]
	v_mfma_f32_16x16x32_bf16 v[32:35], v[154:157], v[186:189], v[32:35]
	v_mfma_f32_16x16x32_bf16 v[60:63], v[150:153], v[166:169], v[60:63]
	v_mfma_f32_16x16x32_bf16 v[56:59], v[158:161], v[166:169], v[56:59]
	v_mfma_f32_16x16x32_bf16 v[52:55], v[150:153], v[174:177], v[52:55]
	v_mfma_f32_16x16x32_bf16 v[48:51], v[158:161], v[174:177], v[48:51]
	v_mfma_f32_16x16x32_bf16 v[44:47], v[150:153], v[182:185], v[44:47]
	v_mfma_f32_16x16x32_bf16 v[40:43], v[158:161], v[182:185], v[40:43]
	v_mfma_f32_16x16x32_bf16 v[36:39], v[150:153], v[190:193], v[36:39]
	v_mfma_f32_16x16x32_bf16 v[32:35], v[158:161], v[190:193], v[32:35]
	s_barrier
	s_add_i32 s34, s34, s17
	v_lshl_add_u64 v[146:147], v[214:215], 0, s[8:9]
	s_mov_b32 m0, s34
	s_nop 0
	global_load_lds_dwordx4 v[146:147], off
	v_lshl_add_u64 v[146:147], v[216:217], 0, s[8:9]
	s_add_i32 m0, s34, 0x2000
	s_nop 0
	global_load_lds_dwordx4 v[146:147], off
	s_waitcnt vmcnt(6)
	s_barrier
	v_mfma_f32_16x16x32_bf16 v[28:31], v[194:197], v[162:165], v[28:31]
	v_mfma_f32_16x16x32_bf16 v[24:27], v[202:205], v[162:165], v[24:27]
	v_mfma_f32_16x16x32_bf16 v[20:23], v[194:197], v[170:173], v[20:23]
	v_mfma_f32_16x16x32_bf16 v[16:19], v[202:205], v[170:173], v[16:19]
	v_mfma_f32_16x16x32_bf16 v[12:15], v[194:197], v[178:181], v[12:15]
	v_mfma_f32_16x16x32_bf16 v[8:11], v[202:205], v[178:181], v[8:11]
	v_mfma_f32_16x16x32_bf16 v[4:7], v[194:197], v[186:189], v[4:7]
	v_mfma_f32_16x16x32_bf16 v[0:3], v[202:205], v[186:189], v[0:3]
	v_mfma_f32_16x16x32_bf16 v[28:31], v[198:201], v[166:169], v[28:31]
	v_mfma_f32_16x16x32_bf16 v[24:27], v[206:209], v[166:169], v[24:27]
	v_mfma_f32_16x16x32_bf16 v[20:23], v[198:201], v[174:177], v[20:23]
	v_mfma_f32_16x16x32_bf16 v[16:19], v[206:209], v[174:177], v[16:19]
	v_mfma_f32_16x16x32_bf16 v[12:15], v[198:201], v[182:185], v[12:15]
	v_mfma_f32_16x16x32_bf16 v[8:11], v[206:209], v[182:185], v[8:11]
	v_mfma_f32_16x16x32_bf16 v[4:7], v[198:201], v[190:193], v[4:7]
	v_mfma_f32_16x16x32_bf16 v[0:3], v[206:209], v[190:193], v[0:3]
	s_add_i32 s34, 0, 0x18000
	v_add_u32_e32 v158, s34, v144
	s_barrier
	ds_read_b128 v[146:149], v158
	ds_read_b128 v[150:153], v158 offset:1024
	ds_read_b128 v[154:157], v158 offset:2048
	ds_read_b128 v[158:161], v158 offset:3072
	s_mov_b32 m0, s28
	v_lshl_add_u64 v[194:195], v[210:211], 0, s[8:9]
	ds_read_b128 v[162:165], v143 offset:32768
	ds_read_b128 v[166:169], v143 offset:33792
	ds_read_b128 v[170:173], v143 offset:34816
	ds_read_b128 v[174:177], v143 offset:35840
	ds_read_b128 v[178:181], v143 offset:36864
	ds_read_b128 v[182:185], v143 offset:37888
	ds_read_b128 v[186:189], v143 offset:38912
	ds_read_b128 v[190:193], v143 offset:39936
	global_load_lds_dwordx4 v[194:195], off
	v_lshl_add_u64 v[194:195], v[212:213], 0, s[8:9]
	s_mov_b32 m0, s29
	s_nop 0
	global_load_lds_dwordx4 v[194:195], off
	s_waitcnt lgkmcnt(8)
	s_barrier
	s_waitcnt lgkmcnt(0)
	s_waitcnt lgkmcnt(0)
	v_mfma_f32_16x16x32_bf16 v[124:127], v[146:149], v[162:165], v[124:127]
	v_mfma_f32_16x16x32_bf16 v[120:123], v[154:157], v[162:165], v[120:123]
	v_mfma_f32_16x16x32_bf16 v[116:119], v[146:149], v[170:173], v[116:119]
	v_mfma_f32_16x16x32_bf16 v[112:115], v[154:157], v[170:173], v[112:115]
	v_mfma_f32_16x16x32_bf16 v[108:111], v[146:149], v[178:181], v[108:111]
	v_mfma_f32_16x16x32_bf16 v[104:107], v[154:157], v[178:181], v[104:107]
	v_mfma_f32_16x16x32_bf16 v[100:103], v[146:149], v[186:189], v[100:103]
	v_mfma_f32_16x16x32_bf16 v[96:99], v[154:157], v[186:189], v[96:99]
	v_mfma_f32_16x16x32_bf16 v[124:127], v[150:153], v[166:169], v[124:127]
	v_mfma_f32_16x16x32_bf16 v[120:123], v[158:161], v[166:169], v[120:123]
	v_mfma_f32_16x16x32_bf16 v[116:119], v[150:153], v[174:177], v[116:119]
	v_mfma_f32_16x16x32_bf16 v[112:115], v[158:161], v[174:177], v[112:115]
	v_mfma_f32_16x16x32_bf16 v[108:111], v[150:153], v[182:185], v[108:111]
	v_mfma_f32_16x16x32_bf16 v[104:107], v[158:161], v[182:185], v[104:107]
	v_mfma_f32_16x16x32_bf16 v[100:103], v[150:153], v[190:193], v[100:103]
	v_mfma_f32_16x16x32_bf16 v[96:99], v[158:161], v[190:193], v[96:99]
	s_barrier
	s_add_i32 s35, 0, 0x1c000
	s_add_i32 s34, s34, s17
	v_add_u32_e32 v206, s35, v144
	v_lshl_add_u64 v[218:219], v[214:215], 0, s[10:11]
	s_mov_b32 m0, s34
	ds_read_b128 v[194:197], v206
	ds_read_b128 v[198:201], v206 offset:1024
	ds_read_b128 v[202:205], v206 offset:2048
	ds_read_b128 v[206:209], v206 offset:3072
	global_load_lds_dwordx4 v[218:219], off
	v_lshl_add_u64 v[218:219], v[216:217], 0, s[10:11]
	s_add_i32 m0, s34, 0x2000
	s_nop 0
	global_load_lds_dwordx4 v[218:219], off
	s_barrier
	s_waitcnt lgkmcnt(0)
	s_waitcnt lgkmcnt(0)
	v_mfma_f32_16x16x32_bf16 v[92:95], v[194:197], v[162:165], v[92:95]
	v_mfma_f32_16x16x32_bf16 v[88:91], v[202:205], v[162:165], v[88:91]
	v_mfma_f32_16x16x32_bf16 v[84:87], v[194:197], v[170:173], v[84:87]
	v_mfma_f32_16x16x32_bf16 v[80:83], v[202:205], v[170:173], v[80:83]
	v_mfma_f32_16x16x32_bf16 v[76:79], v[194:197], v[178:181], v[76:79]
	v_mfma_f32_16x16x32_bf16 v[72:75], v[202:205], v[178:181], v[72:75]
	v_mfma_f32_16x16x32_bf16 v[68:71], v[194:197], v[186:189], v[68:71]
	v_mfma_f32_16x16x32_bf16 v[64:67], v[202:205], v[186:189], v[64:67]
	v_mfma_f32_16x16x32_bf16 v[92:95], v[198:201], v[166:169], v[92:95]
	v_mfma_f32_16x16x32_bf16 v[88:91], v[206:209], v[166:169], v[88:91]
	v_mfma_f32_16x16x32_bf16 v[84:87], v[198:201], v[174:177], v[84:87]
	v_mfma_f32_16x16x32_bf16 v[80:83], v[206:209], v[174:177], v[80:83]
	v_mfma_f32_16x16x32_bf16 v[76:79], v[198:201], v[182:185], v[76:79]
	v_mfma_f32_16x16x32_bf16 v[72:75], v[206:209], v[182:185], v[72:75]
	v_mfma_f32_16x16x32_bf16 v[68:71], v[198:201], v[190:193], v[68:71]
	v_mfma_f32_16x16x32_bf16 v[64:67], v[206:209], v[190:193], v[64:67]
	s_mov_b32 m0, s30
	v_lshl_add_u64 v[210:211], v[210:211], 0, s[10:11]
	s_barrier
	ds_read_b128 v[162:165], v143 offset:49152
	ds_read_b128 v[166:169], v143 offset:50176
	ds_read_b128 v[170:173], v143 offset:51200
	ds_read_b128 v[174:177], v143 offset:52224
	ds_read_b128 v[178:181], v143 offset:53248
	ds_read_b128 v[182:185], v143 offset:54272
	ds_read_b128 v[186:189], v143 offset:55296
	ds_read_b128 v[190:193], v143 offset:56320
	global_load_lds_dwordx4 v[210:211], off
	v_lshl_add_u64 v[210:211], v[212:213], 0, s[10:11]
	s_mov_b32 m0, s31
	s_nop 0
	global_load_lds_dwordx4 v[210:211], off
	s_barrier
	s_waitcnt lgkmcnt(0)
	s_waitcnt lgkmcnt(0)
	v_mfma_f32_16x16x32_bf16 v[60:63], v[146:149], v[162:165], v[60:63]
	v_mfma_f32_16x16x32_bf16 v[56:59], v[154:157], v[162:165], v[56:59]
	v_mfma_f32_16x16x32_bf16 v[52:55], v[146:149], v[170:173], v[52:55]
	v_mfma_f32_16x16x32_bf16 v[48:51], v[154:157], v[170:173], v[48:51]
	v_mfma_f32_16x16x32_bf16 v[44:47], v[146:149], v[178:181], v[44:47]
	v_mfma_f32_16x16x32_bf16 v[40:43], v[154:157], v[178:181], v[40:43]
	v_mfma_f32_16x16x32_bf16 v[36:39], v[146:149], v[186:189], v[36:39]
	v_mfma_f32_16x16x32_bf16 v[32:35], v[154:157], v[186:189], v[32:35]
	v_mfma_f32_16x16x32_bf16 v[60:63], v[150:153], v[166:169], v[60:63]
	v_mfma_f32_16x16x32_bf16 v[56:59], v[158:161], v[166:169], v[56:59]
	v_mfma_f32_16x16x32_bf16 v[52:55], v[150:153], v[174:177], v[52:55]
	v_mfma_f32_16x16x32_bf16 v[48:51], v[158:161], v[174:177], v[48:51]
	v_mfma_f32_16x16x32_bf16 v[44:47], v[150:153], v[182:185], v[44:47]
	v_mfma_f32_16x16x32_bf16 v[40:43], v[158:161], v[182:185], v[40:43]
	v_mfma_f32_16x16x32_bf16 v[36:39], v[150:153], v[190:193], v[36:39]
	v_mfma_f32_16x16x32_bf16 v[32:35], v[158:161], v[190:193], v[32:35]
	s_barrier
	s_add_i32 s34, s35, s17
	v_lshl_add_u64 v[146:147], v[214:215], 0, s[12:13]
	s_mov_b32 m0, s34
	s_nop 0
	global_load_lds_dwordx4 v[146:147], off
	v_lshl_add_u64 v[146:147], v[216:217], 0, s[12:13]
	s_add_i32 m0, s34, 0x2000
	s_nop 0
	global_load_lds_dwordx4 v[146:147], off
	s_waitcnt vmcnt(6)
	s_barrier
	v_mfma_f32_16x16x32_bf16 v[28:31], v[194:197], v[162:165], v[28:31]
	v_mfma_f32_16x16x32_bf16 v[24:27], v[202:205], v[162:165], v[24:27]
	v_mfma_f32_16x16x32_bf16 v[20:23], v[194:197], v[170:173], v[20:23]
	v_mfma_f32_16x16x32_bf16 v[16:19], v[202:205], v[170:173], v[16:19]
	v_mfma_f32_16x16x32_bf16 v[12:15], v[194:197], v[178:181], v[12:15]
	v_mfma_f32_16x16x32_bf16 v[8:11], v[202:205], v[178:181], v[8:11]
	v_mfma_f32_16x16x32_bf16 v[4:7], v[194:197], v[186:189], v[4:7]
	v_mfma_f32_16x16x32_bf16 v[0:3], v[202:205], v[186:189], v[0:3]
	v_mfma_f32_16x16x32_bf16 v[28:31], v[198:201], v[166:169], v[28:31]
	v_mfma_f32_16x16x32_bf16 v[24:27], v[206:209], v[166:169], v[24:27]
	v_mfma_f32_16x16x32_bf16 v[20:23], v[198:201], v[174:177], v[20:23]
	v_mfma_f32_16x16x32_bf16 v[16:19], v[206:209], v[174:177], v[16:19]
	v_mfma_f32_16x16x32_bf16 v[12:15], v[198:201], v[182:185], v[12:15]
	v_mfma_f32_16x16x32_bf16 v[8:11], v[206:209], v[182:185], v[8:11]
	v_mfma_f32_16x16x32_bf16 v[4:7], v[198:201], v[190:193], v[4:7]
	v_mfma_f32_16x16x32_bf16 v[0:3], v[206:209], v[190:193], v[0:3]
	s_add_i32 s22, s22, 2
	s_add_u32 s20, s20, 0x100
	s_addc_u32 s21, s21, 0
	s_cmp_gt_u32 s22, 3
	s_barrier
	s_cbranch_scc0 .LBB0_713
	s_add_u32 s18, s18, 0x20380
	v_add_u32_e32 v208, 0, v144
	s_addc_u32 s19, s19, 0
	s_mov_b32 m0, s33
	v_add_u32_e32 v148, 0x10000, v208
	v_lshl_add_u64 v[184:185], s[18:19], 0, v[128:129]
	ds_read_b128 v[132:135], v148
	ds_read_b128 v[138:141], v148 offset:1024
	ds_read_b128 v[144:147], v148 offset:2048
	ds_read_b128 v[148:151], v148 offset:3072
	ds_read_b128 v[152:155], v143
	ds_read_b128 v[156:159], v143 offset:1024
	ds_read_b128 v[160:163], v143 offset:2048
	ds_read_b128 v[164:167], v143 offset:3072
	ds_read_b128 v[168:171], v143 offset:4096
	ds_read_b128 v[172:175], v143 offset:5120
	ds_read_b128 v[176:179], v143 offset:6144
	ds_read_b128 v[180:183], v143 offset:7168
	global_load_lds_dwordx4 v[184:185], off
	v_lshl_add_u64 v[130:131], s[18:19], 0, v[130:131]
	s_mov_b32 m0, s23
	s_nop 0
	global_load_lds_dwordx4 v[130:131], off
	s_barrier
	s_waitcnt lgkmcnt(0)
	s_waitcnt lgkmcnt(0)
	v_mfma_f32_16x16x32_bf16 v[124:127], v[132:135], v[152:155], v[124:127]
	v_mfma_f32_16x16x32_bf16 v[120:123], v[144:147], v[152:155], v[120:123]
	v_mfma_f32_16x16x32_bf16 v[116:119], v[132:135], v[160:163], v[116:119]
	v_mfma_f32_16x16x32_bf16 v[112:115], v[144:147], v[160:163], v[112:115]
	v_mfma_f32_16x16x32_bf16 v[100:103], v[132:135], v[176:179], v[100:103]
	v_mfma_f32_16x16x32_bf16 v[96:99], v[144:147], v[176:179], v[96:99]
	v_mfma_f32_16x16x32_bf16 v[124:127], v[138:141], v[156:159], v[124:127]
	v_mfma_f32_16x16x32_bf16 v[120:123], v[148:151], v[156:159], v[120:123]
	v_mfma_f32_16x16x32_bf16 v[116:119], v[138:141], v[164:167], v[116:119]
	v_mfma_f32_16x16x32_bf16 v[112:115], v[148:151], v[164:167], v[112:115]
	v_mfma_f32_16x16x32_bf16 v[108:111], v[132:135], v[168:171], v[108:111]
	v_mfma_f32_16x16x32_bf16 v[104:107], v[144:147], v[168:171], v[104:107]
	v_mfma_f32_16x16x32_bf16 v[100:103], v[138:141], v[180:183], v[100:103]
	v_mfma_f32_16x16x32_bf16 v[96:99], v[148:151], v[180:183], v[96:99]
	v_mfma_f32_16x16x32_bf16 v[184:187], v[138:141], v[172:175], v[108:111]
	v_mfma_f32_16x16x32_bf16 v[188:191], v[148:151], v[172:175], v[104:107]
	v_add_u32_e32 v128, 0x14000, v208
	s_barrier
	s_nop 0
	ds_read_b128 v[104:107], v128
	ds_read_b128 v[108:111], v128 offset:1024
	ds_read_b128 v[192:195], v128 offset:2048
	ds_read_b128 v[196:199], v128 offset:3072
	s_barrier
	s_waitcnt lgkmcnt(0)
	s_waitcnt lgkmcnt(0)
	v_mfma_f32_16x16x32_bf16 v[84:87], v[104:107], v[160:163], v[84:87]
	v_mfma_f32_16x16x32_bf16 v[80:83], v[192:195], v[160:163], v[80:83]
	v_mfma_f32_16x16x32_bf16 v[68:71], v[104:107], v[176:179], v[68:71]
	v_mfma_f32_16x16x32_bf16 v[64:67], v[192:195], v[176:179], v[64:67]
	v_mfma_f32_16x16x32_bf16 v[92:95], v[104:107], v[152:155], v[92:95]
	v_mfma_f32_16x16x32_bf16 v[88:91], v[192:195], v[152:155], v[88:91]
	v_mfma_f32_16x16x32_bf16 v[84:87], v[108:111], v[164:167], v[84:87]
	v_mfma_f32_16x16x32_bf16 v[80:83], v[196:199], v[164:167], v[80:83]
	v_mfma_f32_16x16x32_bf16 v[76:79], v[104:107], v[168:171], v[76:79]
	v_mfma_f32_16x16x32_bf16 v[72:75], v[192:195], v[168:171], v[72:75]
	v_mfma_f32_16x16x32_bf16 v[68:71], v[108:111], v[180:183], v[68:71]
	v_mfma_f32_16x16x32_bf16 v[64:67], v[196:199], v[180:183], v[64:67]
	v_mfma_f32_16x16x32_bf16 v[200:203], v[108:111], v[156:159], v[92:95]
	v_mfma_f32_16x16x32_bf16 v[152:155], v[196:199], v[156:159], v[88:91]
	v_mfma_f32_16x16x32_bf16 v[156:159], v[108:111], v[172:175], v[76:79]
	v_mfma_f32_16x16x32_bf16 v[160:163], v[196:199], v[172:175], v[72:75]
	s_barrier
	s_nop 0
	ds_read_b128 v[72:75], v143 offset:16384
	ds_read_b128 v[76:79], v143 offset:17408
	ds_read_b128 v[88:91], v143 offset:18432
	ds_read_b128 v[92:95], v143 offset:19456
	ds_read_b128 v[164:167], v143 offset:20480
	ds_read_b128 v[168:171], v143 offset:21504
	ds_read_b128 v[172:175], v143 offset:22528
	ds_read_b128 v[176:179], v143 offset:23552
	s_waitcnt vmcnt(4)
	s_barrier
	s_waitcnt lgkmcnt(0)
	s_waitcnt lgkmcnt(0)
	v_mfma_f32_16x16x32_bf16 v[60:63], v[132:135], v[72:75], v[60:63]
	v_mfma_f32_16x16x32_bf16 v[56:59], v[144:147], v[72:75], v[56:59]
	v_mfma_f32_16x16x32_bf16 v[52:55], v[132:135], v[88:91], v[52:55]
	v_mfma_f32_16x16x32_bf16 v[48:51], v[144:147], v[88:91], v[48:51]
	v_mfma_f32_16x16x32_bf16 v[36:39], v[132:135], v[172:175], v[36:39]
	v_mfma_f32_16x16x32_bf16 v[32:35], v[144:147], v[172:175], v[32:35]
	v_mfma_f32_16x16x32_bf16 v[60:63], v[138:141], v[76:79], v[60:63]
	v_mfma_f32_16x16x32_bf16 v[56:59], v[148:151], v[76:79], v[56:59]
	v_mfma_f32_16x16x32_bf16 v[52:55], v[138:141], v[92:95], v[52:55]
	v_mfma_f32_16x16x32_bf16 v[48:51], v[148:151], v[92:95], v[48:51]
	v_mfma_f32_16x16x32_bf16 v[44:47], v[132:135], v[164:167], v[44:47]
	v_mfma_f32_16x16x32_bf16 v[40:43], v[144:147], v[164:167], v[40:43]
	v_mfma_f32_16x16x32_bf16 v[36:39], v[138:141], v[176:179], v[36:39]
	v_mfma_f32_16x16x32_bf16 v[32:35], v[148:151], v[176:179], v[32:35]
	v_mfma_f32_16x16x32_bf16 v[180:183], v[138:141], v[168:171], v[44:47]
	v_mfma_f32_16x16x32_bf16 v[204:207], v[148:151], v[168:171], v[40:43]
	v_mfma_f32_16x16x32_bf16 v[20:23], v[104:107], v[88:91], v[20:23]
	v_mfma_f32_16x16x32_bf16 v[16:19], v[192:195], v[88:91], v[16:19]
	v_mfma_f32_16x16x32_bf16 v[4:7], v[104:107], v[172:175], v[4:7]
	v_mfma_f32_16x16x32_bf16 v[0:3], v[192:195], v[172:175], v[0:3]
	v_mfma_f32_16x16x32_bf16 v[28:31], v[104:107], v[72:75], v[28:31]
	v_mfma_f32_16x16x32_bf16 v[24:27], v[192:195], v[72:75], v[24:27]
	v_mfma_f32_16x16x32_bf16 v[20:23], v[108:111], v[92:95], v[20:23]
	v_mfma_f32_16x16x32_bf16 v[16:19], v[196:199], v[92:95], v[16:19]
	v_mfma_f32_16x16x32_bf16 v[12:15], v[104:107], v[164:167], v[12:15]
	v_mfma_f32_16x16x32_bf16 v[8:11], v[192:195], v[164:167], v[8:11]
	v_mfma_f32_16x16x32_bf16 v[4:7], v[108:111], v[176:179], v[4:7]
	v_mfma_f32_16x16x32_bf16 v[0:3], v[196:199], v[176:179], v[0:3]
	v_mfma_f32_16x16x32_bf16 v[130:133], v[108:111], v[76:79], v[28:31]
	v_mfma_f32_16x16x32_bf16 v[138:141], v[196:199], v[76:79], v[24:27]
	v_mfma_f32_16x16x32_bf16 v[144:147], v[108:111], v[168:171], v[12:15]
	v_mfma_f32_16x16x32_bf16 v[148:151], v[196:199], v[168:171], v[8:11]
	v_add_u32_e32 v24, 0x18000, v208
	s_barrier
	ds_read_b128 v[8:11], v24
	ds_read_b128 v[12:15], v24 offset:1024
	ds_read_b128 v[164:167], v24 offset:2048
	ds_read_b128 v[168:171], v24 offset:3072
	ds_read_b128 v[24:27], v143 offset:32768
	ds_read_b128 v[28:31], v143 offset:33792
	ds_read_b128 v[40:43], v143 offset:34816
	ds_read_b128 v[44:47], v143 offset:35840
	ds_read_b128 v[172:175], v143 offset:36864
	ds_read_b128 v[176:179], v143 offset:37888
	ds_read_b128 v[192:195], v143 offset:38912
	ds_read_b128 v[196:199], v143 offset:39936
	s_waitcnt vmcnt(2)
	s_barrier
	s_waitcnt lgkmcnt(0)
	s_waitcnt lgkmcnt(0)
	v_mfma_f32_16x16x32_bf16 v[72:75], v[8:11], v[24:27], v[124:127]
	v_mfma_f32_16x16x32_bf16 v[124:127], v[12:15], v[28:31], v[72:75]
	v_mfma_f32_16x16x32_bf16 v[72:75], v[164:167], v[24:27], v[120:123]
	v_mfma_f32_16x16x32_bf16 v[120:123], v[168:171], v[28:31], v[72:75]
	v_mfma_f32_16x16x32_bf16 v[72:75], v[8:11], v[40:43], v[116:119]
	v_mfma_f32_16x16x32_bf16 v[108:111], v[12:15], v[44:47], v[72:75]
	v_mfma_f32_16x16x32_bf16 v[72:75], v[164:167], v[40:43], v[112:115]
	v_mfma_f32_16x16x32_bf16 v[104:107], v[168:171], v[44:47], v[72:75]
	v_mfma_f32_16x16x32_bf16 v[72:75], v[8:11], v[172:175], v[184:187]
	v_mfma_f32_16x16x32_bf16 v[92:95], v[12:15], v[176:179], v[72:75]
	v_mfma_f32_16x16x32_bf16 v[72:75], v[164:167], v[172:175], v[188:191]
	v_mfma_f32_16x16x32_bf16 v[88:91], v[168:171], v[176:179], v[72:75]
	v_mfma_f32_16x16x32_bf16 v[72:75], v[8:11], v[192:195], v[100:103]
	v_mfma_f32_16x16x32_bf16 v[76:79], v[12:15], v[196:199], v[72:75]
	v_mfma_f32_16x16x32_bf16 v[72:75], v[164:167], v[192:195], v[96:99]
	v_mfma_f32_16x16x32_bf16 v[72:75], v[168:171], v[196:199], v[72:75]
	s_nop 0
	v_add_u32_e32 v96, 0x1c000, v208
	s_barrier
	ds_read_b128 v[184:187], v96
	ds_read_b128 v[188:191], v96 offset:1024
	ds_read_b128 v[208:211], v96 offset:2048
	ds_read_b128 v[212:215], v96 offset:3072
	s_waitcnt vmcnt(0)
	s_barrier
	s_waitcnt lgkmcnt(0)
	s_waitcnt lgkmcnt(0)
	v_mfma_f32_16x16x32_bf16 v[96:99], v[184:187], v[24:27], v[200:203]
	v_mfma_f32_16x16x32_bf16 v[24:27], v[208:211], v[24:27], v[152:155]
	v_mfma_f32_16x16x32_bf16 v[112:115], v[212:215], v[28:31], v[24:27]
	v_mfma_f32_16x16x32_bf16 v[24:27], v[184:187], v[40:43], v[84:87]
	v_mfma_f32_16x16x32_bf16 v[100:103], v[188:191], v[44:47], v[24:27]
	v_mfma_f32_16x16x32_bf16 v[24:27], v[208:211], v[40:43], v[80:83]
	v_mfma_f32_16x16x32_bf16 v[116:119], v[188:191], v[28:31], v[96:99]
	v_mfma_f32_16x16x32_bf16 v[96:99], v[212:215], v[44:47], v[24:27]
	v_mfma_f32_16x16x32_bf16 v[24:27], v[184:187], v[172:175], v[156:159]
	v_mfma_f32_16x16x32_bf16 v[84:87], v[188:191], v[176:179], v[24:27]
	v_mfma_f32_16x16x32_bf16 v[24:27], v[208:211], v[172:175], v[160:163]
	v_mfma_f32_16x16x32_bf16 v[80:83], v[212:215], v[176:179], v[24:27]
	v_mfma_f32_16x16x32_bf16 v[24:27], v[184:187], v[192:195], v[68:71]
	v_mfma_f32_16x16x32_bf16 v[68:71], v[188:191], v[196:199], v[24:27]
	v_mfma_f32_16x16x32_bf16 v[24:27], v[208:211], v[192:195], v[64:67]
	v_mfma_f32_16x16x32_bf16 v[64:67], v[212:215], v[196:199], v[24:27]
	s_barrier
	ds_read_b128 v[152:155], v143 offset:49152
	ds_read_b128 v[156:159], v143 offset:50176
	ds_read_b128 v[160:163], v143 offset:51200
	ds_read_b128 v[172:175], v143 offset:52224
	ds_read_b128 v[176:179], v143 offset:53248
	ds_read_b128 v[192:195], v143 offset:54272
	ds_read_b128 v[196:199], v143 offset:55296
	ds_read_b128 v[200:203], v143 offset:56320
	s_barrier
	s_waitcnt lgkmcnt(0)
	s_waitcnt lgkmcnt(0)
	v_mfma_f32_16x16x32_bf16 v[24:27], v[8:11], v[152:155], v[60:63]
	v_mfma_f32_16x16x32_bf16 v[60:63], v[12:15], v[156:159], v[24:27]
	v_mfma_f32_16x16x32_bf16 v[24:27], v[164:167], v[152:155], v[56:59]
	v_mfma_f32_16x16x32_bf16 v[56:59], v[168:171], v[156:159], v[24:27]
	v_mfma_f32_16x16x32_bf16 v[24:27], v[8:11], v[160:163], v[52:55]
	v_mfma_f32_16x16x32_bf16 v[44:47], v[12:15], v[172:175], v[24:27]
	v_mfma_f32_16x16x32_bf16 v[24:27], v[164:167], v[160:163], v[48:51]
	v_mfma_f32_16x16x32_bf16 v[40:43], v[168:171], v[172:175], v[24:27]
	v_mfma_f32_16x16x32_bf16 v[24:27], v[8:11], v[176:179], v[180:183]
	v_mfma_f32_16x16x32_bf16 v[8:11], v[8:11], v[196:199], v[36:39]
	v_mfma_f32_16x16x32_bf16 v[28:31], v[12:15], v[192:195], v[24:27]
	v_mfma_f32_16x16x32_bf16 v[24:27], v[164:167], v[176:179], v[204:207]
	v_mfma_f32_16x16x32_bf16 v[12:15], v[12:15], v[200:203], v[8:11]
	v_mfma_f32_16x16x32_bf16 v[8:11], v[164:167], v[196:199], v[32:35]
	v_mfma_f32_16x16x32_bf16 v[24:27], v[168:171], v[192:195], v[24:27]
	v_mfma_f32_16x16x32_bf16 v[8:11], v[168:171], v[200:203], v[8:11]
	v_mfma_f32_16x16x32_bf16 v[32:35], v[184:187], v[152:155], v[130:133]
	v_mfma_f32_16x16x32_bf16 v[52:55], v[188:191], v[156:159], v[32:35]
	v_mfma_f32_16x16x32_bf16 v[32:35], v[208:211], v[152:155], v[138:141]
	v_mfma_f32_16x16x32_bf16 v[16:19], v[208:211], v[160:163], v[16:19]
	v_mfma_f32_16x16x32_bf16 v[48:51], v[212:215], v[156:159], v[32:35]
	v_mfma_f32_16x16x32_bf16 v[20:23], v[184:187], v[160:163], v[20:23]
	v_mfma_f32_16x16x32_bf16 v[32:35], v[212:215], v[172:175], v[16:19]
	v_mfma_f32_16x16x32_bf16 v[16:19], v[184:187], v[176:179], v[144:147]
	v_mfma_f32_16x16x32_bf16 v[36:39], v[188:191], v[172:175], v[20:23]
	v_mfma_f32_16x16x32_bf16 v[20:23], v[188:191], v[192:195], v[16:19]
	v_mfma_f32_16x16x32_bf16 v[16:19], v[208:211], v[176:179], v[148:151]
	v_mfma_f32_16x16x32_bf16 v[4:7], v[184:187], v[196:199], v[4:7]
	v_mfma_f32_16x16x32_bf16 v[0:3], v[208:211], v[196:199], v[0:3]
	v_mfma_f32_16x16x32_bf16 v[16:19], v[212:215], v[192:195], v[16:19]
	v_mfma_f32_16x16x32_bf16 v[4:7], v[188:191], v[200:203], v[4:7]
	v_mfma_f32_16x16x32_bf16 v[0:3], v[212:215], v[200:203], v[0:3]
	s_cmpk_lt_u32 s15, 0x100
	s_barrier
	s_cbranch_scc0 .LBB0_707
	s_barrier
	s_branch .LBB0_707

.LBB0_781:
	ds_read_b128 v[148:151], v146
	ds_read_b128 v[152:155], v146 offset:1024
	ds_read_b128 v[156:159], v146 offset:2048
	ds_read_b128 v[160:163], v146 offset:3072
	v_lshl_add_u64 v[180:181], v[134:135], 0, s[22:23]
	s_mov_b32 m0, s34
	v_lshl_add_u64 v[208:209], v[180:181], 0, s[6:7]
	v_lshl_add_u64 v[224:225], v[138:139], 0, s[22:23]
	ds_read_b128 v[164:167], v144
	ds_read_b128 v[168:171], v144 offset:1024
	ds_read_b128 v[172:175], v144 offset:2048
	ds_read_b128 v[176:179], v144 offset:3072
	ds_read_b128 v[192:195], v144 offset:4096
	ds_read_b128 v[196:199], v144 offset:5120
	ds_read_b128 v[200:203], v144 offset:6144
	ds_read_b128 v[204:207], v144 offset:7168
	global_load_lds_dwordx4 v[208:209], off
	v_lshl_add_u64 v[208:209], v[224:225], 0, s[6:7]
	s_mov_b32 m0, s24
	s_nop 0
	global_load_lds_dwordx4 v[208:209], off
	s_waitcnt lgkmcnt(8)
	s_barrier
	s_waitcnt lgkmcnt(0)
	s_waitcnt lgkmcnt(0)
	v_mfma_f32_16x16x32_bf16 v[124:127], v[148:151], v[164:167], v[124:127]
	v_mfma_f32_16x16x32_bf16 v[120:123], v[156:159], v[164:167], v[120:123]
	v_mfma_f32_16x16x32_bf16 v[116:119], v[148:151], v[172:175], v[116:119]
	v_mfma_f32_16x16x32_bf16 v[112:115], v[156:159], v[172:175], v[112:115]
	v_mfma_f32_16x16x32_bf16 v[108:111], v[148:151], v[192:195], v[108:111]
	v_mfma_f32_16x16x32_bf16 v[104:107], v[156:159], v[192:195], v[104:107]
	v_mfma_f32_16x16x32_bf16 v[100:103], v[148:151], v[200:203], v[100:103]
	v_mfma_f32_16x16x32_bf16 v[96:99], v[156:159], v[200:203], v[96:99]
	v_mfma_f32_16x16x32_bf16 v[124:127], v[152:155], v[168:171], v[124:127]
	v_mfma_f32_16x16x32_bf16 v[120:123], v[160:163], v[168:171], v[120:123]
	v_mfma_f32_16x16x32_bf16 v[116:119], v[152:155], v[176:179], v[116:119]
	v_mfma_f32_16x16x32_bf16 v[112:115], v[160:163], v[176:179], v[112:115]
	v_mfma_f32_16x16x32_bf16 v[108:111], v[152:155], v[196:199], v[108:111]
	v_mfma_f32_16x16x32_bf16 v[104:107], v[160:163], v[196:199], v[104:107]
	v_mfma_f32_16x16x32_bf16 v[100:103], v[152:155], v[204:207], v[100:103]
	v_mfma_f32_16x16x32_bf16 v[96:99], v[160:163], v[204:207], v[96:99]
	s_barrier
	v_lshl_add_u64 v[226:227], v[140:141], 0, s[22:23]
	s_add_i32 s35, s42, s19
	v_lshl_add_u64 v[228:229], v[226:227], 0, s[8:9]
	s_mov_b32 m0, s35
	ds_read_b128 v[208:211], v147
	ds_read_b128 v[212:215], v147 offset:1024
	ds_read_b128 v[216:219], v147 offset:2048
	ds_read_b128 v[220:223], v147 offset:3072
	global_load_lds_dwordx4 v[228:229], off
	v_lshl_add_u64 v[228:229], v[142:143], 0, s[22:23]
	v_lshl_add_u64 v[230:231], v[228:229], 0, s[8:9]
	s_add_i32 m0, s35, 0x2000
	s_nop 0
	global_load_lds_dwordx4 v[230:231], off
	s_barrier
	s_waitcnt lgkmcnt(0)
	s_waitcnt lgkmcnt(0)
	v_mfma_f32_16x16x32_bf16 v[92:95], v[208:211], v[164:167], v[92:95]
	v_mfma_f32_16x16x32_bf16 v[88:91], v[216:219], v[164:167], v[88:91]
	v_mfma_f32_16x16x32_bf16 v[84:87], v[208:211], v[172:175], v[84:87]
	v_mfma_f32_16x16x32_bf16 v[80:83], v[216:219], v[172:175], v[80:83]
	v_mfma_f32_16x16x32_bf16 v[76:79], v[208:211], v[192:195], v[76:79]
	v_mfma_f32_16x16x32_bf16 v[72:75], v[216:219], v[192:195], v[72:75]
	v_mfma_f32_16x16x32_bf16 v[68:71], v[208:211], v[200:203], v[68:71]
	v_mfma_f32_16x16x32_bf16 v[64:67], v[216:219], v[200:203], v[64:67]
	v_mfma_f32_16x16x32_bf16 v[92:95], v[212:215], v[168:171], v[92:95]
	v_mfma_f32_16x16x32_bf16 v[88:91], v[220:223], v[168:171], v[88:91]
	v_mfma_f32_16x16x32_bf16 v[84:87], v[212:215], v[176:179], v[84:87]
	v_mfma_f32_16x16x32_bf16 v[80:83], v[220:223], v[176:179], v[80:83]
	v_mfma_f32_16x16x32_bf16 v[76:79], v[212:215], v[196:199], v[76:79]
	v_mfma_f32_16x16x32_bf16 v[72:75], v[220:223], v[196:199], v[72:75]
	v_mfma_f32_16x16x32_bf16 v[68:71], v[212:215], v[204:207], v[68:71]
	v_mfma_f32_16x16x32_bf16 v[64:67], v[220:223], v[204:207], v[64:67]
	s_mov_b32 m0, s27
	v_lshl_add_u64 v[230:231], v[180:181], 0, s[8:9]
	s_barrier
	ds_read_b128 v[164:167], v144 offset:16384
	ds_read_b128 v[168:171], v144 offset:17408
	ds_read_b128 v[172:175], v144 offset:18432
	ds_read_b128 v[176:179], v144 offset:19456
	ds_read_b128 v[192:195], v144 offset:20480
	ds_read_b128 v[196:199], v144 offset:21504
	ds_read_b128 v[200:203], v144 offset:22528
	ds_read_b128 v[204:207], v144 offset:23552
	global_load_lds_dwordx4 v[230:231], off
	v_lshl_add_u64 v[230:231], v[224:225], 0, s[8:9]
	s_mov_b32 m0, s28
	s_nop 0
	global_load_lds_dwordx4 v[230:231], off
	s_barrier
	s_waitcnt lgkmcnt(0)
	s_waitcnt lgkmcnt(0)
	v_mfma_f32_16x16x32_bf16 v[60:63], v[148:151], v[164:167], v[60:63]
	v_mfma_f32_16x16x32_bf16 v[56:59], v[156:159], v[164:167], v[56:59]
	v_mfma_f32_16x16x32_bf16 v[52:55], v[148:151], v[172:175], v[52:55]
	v_mfma_f32_16x16x32_bf16 v[48:51], v[156:159], v[172:175], v[48:51]
	v_mfma_f32_16x16x32_bf16 v[44:47], v[148:151], v[192:195], v[44:47]
	v_mfma_f32_16x16x32_bf16 v[40:43], v[156:159], v[192:195], v[40:43]
	v_mfma_f32_16x16x32_bf16 v[36:39], v[148:151], v[200:203], v[36:39]
	v_mfma_f32_16x16x32_bf16 v[32:35], v[156:159], v[200:203], v[32:35]
	v_mfma_f32_16x16x32_bf16 v[60:63], v[152:155], v[168:171], v[60:63]
	v_mfma_f32_16x16x32_bf16 v[56:59], v[160:163], v[168:171], v[56:59]
	v_mfma_f32_16x16x32_bf16 v[52:55], v[152:155], v[176:179], v[52:55]
	v_mfma_f32_16x16x32_bf16 v[48:51], v[160:163], v[176:179], v[48:51]
	v_mfma_f32_16x16x32_bf16 v[44:47], v[152:155], v[196:199], v[44:47]
	v_mfma_f32_16x16x32_bf16 v[40:43], v[160:163], v[196:199], v[40:43]
	v_mfma_f32_16x16x32_bf16 v[36:39], v[152:155], v[204:207], v[36:39]
	v_mfma_f32_16x16x32_bf16 v[32:35], v[160:163], v[204:207], v[32:35]
	s_barrier
	s_add_i32 s35, s43, s19
	v_lshl_add_u64 v[148:149], v[226:227], 0, s[12:13]
	s_mov_b32 m0, s35
	s_nop 0
	global_load_lds_dwordx4 v[148:149], off
	v_lshl_add_u64 v[148:149], v[228:229], 0, s[12:13]
	s_add_i32 m0, s35, 0x2000
	s_nop 0
	global_load_lds_dwordx4 v[148:149], off
	s_waitcnt vmcnt(6)
	s_barrier
	v_mfma_f32_16x16x32_bf16 v[28:31], v[208:211], v[164:167], v[28:31]
	v_mfma_f32_16x16x32_bf16 v[24:27], v[216:219], v[164:167], v[24:27]
	v_mfma_f32_16x16x32_bf16 v[20:23], v[208:211], v[172:175], v[20:23]
	v_mfma_f32_16x16x32_bf16 v[16:19], v[216:219], v[172:175], v[16:19]
	v_mfma_f32_16x16x32_bf16 v[12:15], v[208:211], v[192:195], v[12:15]
	v_mfma_f32_16x16x32_bf16 v[8:11], v[216:219], v[192:195], v[8:11]
	v_mfma_f32_16x16x32_bf16 v[4:7], v[208:211], v[200:203], v[4:7]
	v_mfma_f32_16x16x32_bf16 v[0:3], v[216:219], v[200:203], v[0:3]
	v_mfma_f32_16x16x32_bf16 v[28:31], v[212:215], v[168:171], v[28:31]
	v_mfma_f32_16x16x32_bf16 v[24:27], v[220:223], v[168:171], v[24:27]
	v_mfma_f32_16x16x32_bf16 v[20:23], v[212:215], v[176:179], v[20:23]
	v_mfma_f32_16x16x32_bf16 v[16:19], v[220:223], v[176:179], v[16:19]
	v_mfma_f32_16x16x32_bf16 v[12:15], v[212:215], v[196:199], v[12:15]
	v_mfma_f32_16x16x32_bf16 v[8:11], v[220:223], v[196:199], v[8:11]
	v_mfma_f32_16x16x32_bf16 v[4:7], v[212:215], v[204:207], v[4:7]
	v_mfma_f32_16x16x32_bf16 v[0:3], v[220:223], v[204:207], v[0:3]
	s_add_i32 s35, 0, 0x18000
	v_add_u32_e32 v160, s35, v145
	s_barrier
	ds_read_b128 v[148:151], v160
	ds_read_b128 v[152:155], v160 offset:1024
	ds_read_b128 v[156:159], v160 offset:2048
	ds_read_b128 v[160:163], v160 offset:3072
	s_mov_b32 m0, s29
	v_lshl_add_u64 v[208:209], v[180:181], 0, s[12:13]
	ds_read_b128 v[164:167], v144 offset:32768
	ds_read_b128 v[168:171], v144 offset:33792
	ds_read_b128 v[172:175], v144 offset:34816
	ds_read_b128 v[176:179], v144 offset:35840
	ds_read_b128 v[192:195], v144 offset:36864
	ds_read_b128 v[196:199], v144 offset:37888
	ds_read_b128 v[200:203], v144 offset:38912
	ds_read_b128 v[204:207], v144 offset:39936
	global_load_lds_dwordx4 v[208:209], off
	v_lshl_add_u64 v[208:209], v[224:225], 0, s[12:13]
	s_mov_b32 m0, s30
	s_nop 0
	global_load_lds_dwordx4 v[208:209], off
	s_waitcnt lgkmcnt(8)
	s_barrier
	s_waitcnt lgkmcnt(0)
	s_waitcnt lgkmcnt(0)
	v_mfma_f32_16x16x32_bf16 v[124:127], v[148:151], v[164:167], v[124:127]
	v_mfma_f32_16x16x32_bf16 v[120:123], v[156:159], v[164:167], v[120:123]
	v_mfma_f32_16x16x32_bf16 v[116:119], v[148:151], v[172:175], v[116:119]
	v_mfma_f32_16x16x32_bf16 v[112:115], v[156:159], v[172:175], v[112:115]
	v_mfma_f32_16x16x32_bf16 v[108:111], v[148:151], v[192:195], v[108:111]
	v_mfma_f32_16x16x32_bf16 v[104:107], v[156:159], v[192:195], v[104:107]
	v_mfma_f32_16x16x32_bf16 v[100:103], v[148:151], v[200:203], v[100:103]
	v_mfma_f32_16x16x32_bf16 v[96:99], v[156:159], v[200:203], v[96:99]
	v_mfma_f32_16x16x32_bf16 v[124:127], v[152:155], v[168:171], v[124:127]
	v_mfma_f32_16x16x32_bf16 v[120:123], v[160:163], v[168:171], v[120:123]
	v_mfma_f32_16x16x32_bf16 v[116:119], v[152:155], v[176:179], v[116:119]
	v_mfma_f32_16x16x32_bf16 v[112:115], v[160:163], v[176:179], v[112:115]
	v_mfma_f32_16x16x32_bf16 v[108:111], v[152:155], v[196:199], v[108:111]
	v_mfma_f32_16x16x32_bf16 v[104:107], v[160:163], v[196:199], v[104:107]
	v_mfma_f32_16x16x32_bf16 v[100:103], v[152:155], v[204:207], v[100:103]
	v_mfma_f32_16x16x32_bf16 v[96:99], v[160:163], v[204:207], v[96:99]
	s_barrier
	s_add_i32 s36, 0, 0x1c000
	s_add_i32 s35, s35, s19
	v_add_u32_e32 v184, s36, v145
	v_lshl_add_u64 v[230:231], v[226:227], 0, s[14:15]
	s_mov_b32 m0, s35
	ds_read_b128 v[208:211], v184
	ds_read_b128 v[212:215], v184 offset:1024
	ds_read_b128 v[216:219], v184 offset:2048
	ds_read_b128 v[220:223], v184 offset:3072
	global_load_lds_dwordx4 v[230:231], off
	v_lshl_add_u64 v[230:231], v[228:229], 0, s[14:15]
	s_add_i32 m0, s35, 0x2000
	s_nop 0
	global_load_lds_dwordx4 v[230:231], off
	s_barrier
	s_waitcnt lgkmcnt(0)
	s_waitcnt lgkmcnt(0)
	v_mfma_f32_16x16x32_bf16 v[92:95], v[208:211], v[164:167], v[92:95]
	v_mfma_f32_16x16x32_bf16 v[88:91], v[216:219], v[164:167], v[88:91]
	v_mfma_f32_16x16x32_bf16 v[84:87], v[208:211], v[172:175], v[84:87]
	v_mfma_f32_16x16x32_bf16 v[80:83], v[216:219], v[172:175], v[80:83]
	v_mfma_f32_16x16x32_bf16 v[76:79], v[208:211], v[192:195], v[76:79]
	v_mfma_f32_16x16x32_bf16 v[72:75], v[216:219], v[192:195], v[72:75]
	v_mfma_f32_16x16x32_bf16 v[68:71], v[208:211], v[200:203], v[68:71]
	v_mfma_f32_16x16x32_bf16 v[64:67], v[216:219], v[200:203], v[64:67]
	v_mfma_f32_16x16x32_bf16 v[92:95], v[212:215], v[168:171], v[92:95]
	v_mfma_f32_16x16x32_bf16 v[88:91], v[220:223], v[168:171], v[88:91]
	v_mfma_f32_16x16x32_bf16 v[84:87], v[212:215], v[176:179], v[84:87]
	v_mfma_f32_16x16x32_bf16 v[80:83], v[220:223], v[176:179], v[80:83]
	v_mfma_f32_16x16x32_bf16 v[76:79], v[212:215], v[196:199], v[76:79]
	v_mfma_f32_16x16x32_bf16 v[72:75], v[220:223], v[196:199], v[72:75]
	v_mfma_f32_16x16x32_bf16 v[68:71], v[212:215], v[204:207], v[68:71]
	v_mfma_f32_16x16x32_bf16 v[64:67], v[220:223], v[204:207], v[64:67]
	s_mov_b32 m0, s31
	v_lshl_add_u64 v[180:181], v[180:181], 0, s[14:15]
	s_barrier
	ds_read_b128 v[164:167], v144 offset:49152
	ds_read_b128 v[168:171], v144 offset:50176
	ds_read_b128 v[172:175], v144 offset:51200
	ds_read_b128 v[176:179], v144 offset:52224
	ds_read_b128 v[192:195], v144 offset:53248
	ds_read_b128 v[196:199], v144 offset:54272
	ds_read_b128 v[200:203], v144 offset:55296
	ds_read_b128 v[204:207], v144 offset:56320
	global_load_lds_dwordx4 v[180:181], off
	v_lshl_add_u64 v[180:181], v[224:225], 0, s[14:15]
	s_mov_b32 m0, s33
	s_nop 0
	global_load_lds_dwordx4 v[180:181], off
	s_barrier
	s_waitcnt lgkmcnt(0)
	s_waitcnt lgkmcnt(0)
	v_mfma_f32_16x16x32_bf16 v[60:63], v[148:151], v[164:167], v[60:63]
	v_mfma_f32_16x16x32_bf16 v[56:59], v[156:159], v[164:167], v[56:59]
	v_mfma_f32_16x16x32_bf16 v[52:55], v[148:151], v[172:175], v[52:55]
	v_mfma_f32_16x16x32_bf16 v[48:51], v[156:159], v[172:175], v[48:51]
	v_mfma_f32_16x16x32_bf16 v[44:47], v[148:151], v[192:195], v[44:47]
	v_mfma_f32_16x16x32_bf16 v[40:43], v[156:159], v[192:195], v[40:43]
	v_mfma_f32_16x16x32_bf16 v[36:39], v[148:151], v[200:203], v[36:39]
	v_mfma_f32_16x16x32_bf16 v[32:35], v[156:159], v[200:203], v[32:35]
	v_mfma_f32_16x16x32_bf16 v[60:63], v[152:155], v[168:171], v[60:63]
	v_mfma_f32_16x16x32_bf16 v[56:59], v[160:163], v[168:171], v[56:59]
	v_mfma_f32_16x16x32_bf16 v[52:55], v[152:155], v[176:179], v[52:55]
	v_mfma_f32_16x16x32_bf16 v[48:51], v[160:163], v[176:179], v[48:51]
	v_mfma_f32_16x16x32_bf16 v[44:47], v[152:155], v[196:199], v[44:47]
	v_mfma_f32_16x16x32_bf16 v[40:43], v[160:163], v[196:199], v[40:43]
	v_mfma_f32_16x16x32_bf16 v[36:39], v[152:155], v[204:207], v[36:39]
	v_mfma_f32_16x16x32_bf16 v[32:35], v[160:163], v[204:207], v[32:35]
	s_barrier
	s_add_i32 s35, s36, s19
	v_lshl_add_u64 v[148:149], v[226:227], 0, s[16:17]
	s_mov_b32 m0, s35
	s_nop 0
	global_load_lds_dwordx4 v[148:149], off
	v_lshl_add_u64 v[148:149], v[228:229], 0, s[16:17]
	s_add_i32 m0, s35, 0x2000
	s_nop 0
	global_load_lds_dwordx4 v[148:149], off
	s_waitcnt vmcnt(6)
	s_barrier
	v_mfma_f32_16x16x32_bf16 v[28:31], v[208:211], v[164:167], v[28:31]
	v_mfma_f32_16x16x32_bf16 v[24:27], v[216:219], v[164:167], v[24:27]
	v_mfma_f32_16x16x32_bf16 v[20:23], v[208:211], v[172:175], v[20:23]
	v_mfma_f32_16x16x32_bf16 v[16:19], v[216:219], v[172:175], v[16:19]
	v_mfma_f32_16x16x32_bf16 v[12:15], v[208:211], v[192:195], v[12:15]
	v_mfma_f32_16x16x32_bf16 v[8:11], v[216:219], v[192:195], v[8:11]
	v_mfma_f32_16x16x32_bf16 v[4:7], v[208:211], v[200:203], v[4:7]
	v_mfma_f32_16x16x32_bf16 v[0:3], v[216:219], v[200:203], v[0:3]
	v_mfma_f32_16x16x32_bf16 v[28:31], v[212:215], v[168:171], v[28:31]
	v_mfma_f32_16x16x32_bf16 v[24:27], v[220:223], v[168:171], v[24:27]
	v_mfma_f32_16x16x32_bf16 v[20:23], v[212:215], v[176:179], v[20:23]
	v_mfma_f32_16x16x32_bf16 v[16:19], v[220:223], v[176:179], v[16:19]
	v_mfma_f32_16x16x32_bf16 v[12:15], v[212:215], v[196:199], v[12:15]
	v_mfma_f32_16x16x32_bf16 v[8:11], v[220:223], v[196:199], v[8:11]
	v_mfma_f32_16x16x32_bf16 v[4:7], v[212:215], v[204:207], v[4:7]
	v_mfma_f32_16x16x32_bf16 v[0:3], v[220:223], v[204:207], v[0:3]
	s_add_i32 s25, s25, 2
	s_add_u32 s22, s22, 0x100
	s_addc_u32 s23, s23, 0
	s_cmp_gt_u32 s25, 11
	s_barrier
	s_cbranch_scc0 .LBB0_781
	v_add_u32_e32 v142, 0, v145
	s_add_u32 s20, s20, 0x40780
	v_add_u32_e32 v134, 0x10000, v142
	s_addc_u32 s21, s21, 0
	s_mov_b32 m0, s34
	ds_read_b128 v[138:141], v134
	ds_read_b128 v[146:149], v134 offset:1024
	ds_read_b128 v[150:153], v134 offset:2048
	ds_read_b128 v[154:157], v134 offset:3072
	ds_read_b128 v[158:161], v144
	ds_read_b128 v[162:165], v144 offset:1024
	ds_read_b128 v[166:169], v144 offset:2048
	ds_read_b128 v[170:173], v144 offset:3072
	ds_read_b128 v[174:177], v144 offset:4096
	ds_read_b128 v[178:181], v144 offset:5120
	ds_read_b128 v[192:195], v144 offset:6144
	ds_read_b128 v[196:199], v144 offset:7168
	v_lshl_add_u64 v[134:135], s[20:21], 0, v[128:129]
	global_load_lds_dwordx4 v[134:135], off
	v_lshl_add_u64 v[130:131], s[20:21], 0, v[130:131]
	s_mov_b32 m0, s24
	s_nop 0
	global_load_lds_dwordx4 v[130:131], off
	s_barrier
	s_waitcnt lgkmcnt(0)
	s_waitcnt lgkmcnt(0)
	v_mfma_f32_16x16x32_bf16 v[124:127], v[138:141], v[158:161], v[124:127]
	v_mfma_f32_16x16x32_bf16 v[120:123], v[150:153], v[158:161], v[120:123]
	v_mfma_f32_16x16x32_bf16 v[116:119], v[138:141], v[166:169], v[116:119]
	v_mfma_f32_16x16x32_bf16 v[104:107], v[150:153], v[174:177], v[104:107]
	v_mfma_f32_16x16x32_bf16 v[100:103], v[138:141], v[192:195], v[100:103]
	v_mfma_f32_16x16x32_bf16 v[124:127], v[146:149], v[162:165], v[124:127]
	v_mfma_f32_16x16x32_bf16 v[120:123], v[154:157], v[162:165], v[120:123]
	v_mfma_f32_16x16x32_bf16 v[116:119], v[146:149], v[170:173], v[116:119]
	v_mfma_f32_16x16x32_bf16 v[112:115], v[150:153], v[166:169], v[112:115]
	v_mfma_f32_16x16x32_bf16 v[108:111], v[138:141], v[174:177], v[108:111]
	v_mfma_f32_16x16x32_bf16 v[104:107], v[154:157], v[178:181], v[104:107]
	v_mfma_f32_16x16x32_bf16 v[100:103], v[146:149], v[196:199], v[100:103]
	v_mfma_f32_16x16x32_bf16 v[96:99], v[150:153], v[192:195], v[96:99]
	v_mfma_f32_16x16x32_bf16 v[200:203], v[154:157], v[170:173], v[112:115]
	v_mfma_f32_16x16x32_bf16 v[204:207], v[146:149], v[178:181], v[108:111]
	v_mfma_f32_16x16x32_bf16 v[208:211], v[154:157], v[196:199], v[96:99]
	v_add_u32_e32 v128, 0x14000, v142
	s_barrier
	s_nop 1
	ds_read_b128 v[96:99], v128
	ds_read_b128 v[108:111], v128 offset:1024
	ds_read_b128 v[112:115], v128 offset:2048
	ds_read_b128 v[212:215], v128 offset:3072
	s_barrier
	s_waitcnt lgkmcnt(0)
	s_waitcnt lgkmcnt(0)
	v_mfma_f32_16x16x32_bf16 v[88:91], v[112:115], v[158:161], v[88:91]
	v_mfma_f32_16x16x32_bf16 v[84:87], v[96:99], v[166:169], v[84:87]
	v_mfma_f32_16x16x32_bf16 v[72:75], v[112:115], v[174:177], v[72:75]
	v_mfma_f32_16x16x32_bf16 v[68:71], v[96:99], v[192:195], v[68:71]
	v_mfma_f32_16x16x32_bf16 v[92:95], v[96:99], v[158:161], v[92:95]
	v_mfma_f32_16x16x32_bf16 v[88:91], v[212:215], v[162:165], v[88:91]
	v_mfma_f32_16x16x32_bf16 v[84:87], v[108:111], v[170:173], v[84:87]
	v_mfma_f32_16x16x32_bf16 v[80:83], v[112:115], v[166:169], v[80:83]
	v_mfma_f32_16x16x32_bf16 v[76:79], v[96:99], v[174:177], v[76:79]
	v_mfma_f32_16x16x32_bf16 v[72:75], v[212:215], v[178:181], v[72:75]
	v_mfma_f32_16x16x32_bf16 v[68:71], v[108:111], v[196:199], v[68:71]
	v_mfma_f32_16x16x32_bf16 v[64:67], v[112:115], v[192:195], v[64:67]
	v_mfma_f32_16x16x32_bf16 v[216:219], v[108:111], v[162:165], v[92:95]
	v_mfma_f32_16x16x32_bf16 v[158:161], v[212:215], v[170:173], v[80:83]
	v_mfma_f32_16x16x32_bf16 v[162:165], v[108:111], v[178:181], v[76:79]
	v_mfma_f32_16x16x32_bf16 v[166:169], v[212:215], v[196:199], v[64:67]
	s_barrier
	s_nop 1
	ds_read_b128 v[64:67], v144 offset:16384
	ds_read_b128 v[76:79], v144 offset:17408
	ds_read_b128 v[80:83], v144 offset:18432
	ds_read_b128 v[92:95], v144 offset:19456
	ds_read_b128 v[170:173], v144 offset:20480
	ds_read_b128 v[174:177], v144 offset:21504
	ds_read_b128 v[178:181], v144 offset:22528
	ds_read_b128 v[192:195], v144 offset:23552
	s_waitcnt vmcnt(4)
	s_barrier
	s_waitcnt lgkmcnt(0)
	s_waitcnt lgkmcnt(0)
	v_mfma_f32_16x16x32_bf16 v[60:63], v[138:141], v[64:67], v[60:63]
	v_mfma_f32_16x16x32_bf16 v[56:59], v[150:153], v[64:67], v[56:59]
	v_mfma_f32_16x16x32_bf16 v[52:55], v[138:141], v[80:83], v[52:55]
	v_mfma_f32_16x16x32_bf16 v[40:43], v[150:153], v[170:173], v[40:43]
	v_mfma_f32_16x16x32_bf16 v[36:39], v[138:141], v[178:181], v[36:39]
	v_mfma_f32_16x16x32_bf16 v[60:63], v[146:149], v[76:79], v[60:63]
	v_mfma_f32_16x16x32_bf16 v[56:59], v[154:157], v[76:79], v[56:59]
	v_mfma_f32_16x16x32_bf16 v[52:55], v[146:149], v[92:95], v[52:55]
	v_mfma_f32_16x16x32_bf16 v[48:51], v[150:153], v[80:83], v[48:51]
	v_mfma_f32_16x16x32_bf16 v[44:47], v[138:141], v[170:173], v[44:47]
	v_mfma_f32_16x16x32_bf16 v[40:43], v[154:157], v[174:177], v[40:43]
	v_mfma_f32_16x16x32_bf16 v[36:39], v[146:149], v[192:195], v[36:39]
	v_mfma_f32_16x16x32_bf16 v[32:35], v[150:153], v[178:181], v[32:35]
	v_mfma_f32_16x16x32_bf16 v[196:199], v[154:157], v[92:95], v[48:51]
	v_mfma_f32_16x16x32_bf16 v[220:223], v[146:149], v[174:177], v[44:47]
	v_mfma_f32_16x16x32_bf16 v[138:141], v[154:157], v[192:195], v[32:35]
	v_mfma_f32_16x16x32_bf16 v[24:27], v[112:115], v[64:67], v[24:27]
	v_mfma_f32_16x16x32_bf16 v[20:23], v[96:99], v[80:83], v[20:23]
	v_mfma_f32_16x16x32_bf16 v[8:11], v[112:115], v[170:173], v[8:11]
	v_mfma_f32_16x16x32_bf16 v[4:7], v[96:99], v[178:181], v[4:7]
	v_mfma_f32_16x16x32_bf16 v[28:31], v[96:99], v[64:67], v[28:31]
	v_mfma_f32_16x16x32_bf16 v[24:27], v[212:215], v[76:79], v[24:27]
	v_mfma_f32_16x16x32_bf16 v[20:23], v[108:111], v[92:95], v[20:23]
	v_mfma_f32_16x16x32_bf16 v[16:19], v[112:115], v[80:83], v[16:19]
	v_mfma_f32_16x16x32_bf16 v[12:15], v[96:99], v[170:173], v[12:15]
	v_mfma_f32_16x16x32_bf16 v[8:11], v[212:215], v[174:177], v[8:11]
	v_mfma_f32_16x16x32_bf16 v[4:7], v[108:111], v[192:195], v[4:7]
	v_mfma_f32_16x16x32_bf16 v[0:3], v[112:115], v[178:181], v[0:3]
	v_mfma_f32_16x16x32_bf16 v[146:149], v[108:111], v[76:79], v[28:31]
	v_mfma_f32_16x16x32_bf16 v[150:153], v[212:215], v[92:95], v[16:19]
	v_mfma_f32_16x16x32_bf16 v[154:157], v[108:111], v[174:177], v[12:15]
	v_mfma_f32_16x16x32_bf16 v[170:173], v[212:215], v[192:195], v[0:3]
	v_add_u32_e32 v16, 0x18000, v142
	s_barrier
	s_nop 0
	ds_read_b128 v[0:3], v16
	ds_read_b128 v[12:15], v16 offset:1024
	ds_read_b128 v[174:177], v16 offset:2048
	ds_read_b128 v[178:181], v16 offset:3072
	ds_read_b128 v[16:19], v144 offset:32768
	ds_read_b128 v[28:31], v144 offset:33792
	ds_read_b128 v[32:35], v144 offset:34816
	ds_read_b128 v[44:47], v144 offset:35840
	ds_read_b128 v[48:51], v144 offset:36864
	ds_read_b128 v[192:195], v144 offset:37888
	ds_read_b128 v[212:215], v144 offset:38912
	ds_read_b128 v[224:227], v144 offset:39936
	s_waitcnt vmcnt(2)
	s_barrier
	s_waitcnt lgkmcnt(0)
	s_waitcnt lgkmcnt(0)
	v_mfma_f32_16x16x32_bf16 v[64:67], v[0:3], v[16:19], v[124:127]
	v_mfma_f32_16x16x32_bf16 v[124:127], v[12:15], v[28:31], v[64:67]
	v_mfma_f32_16x16x32_bf16 v[64:67], v[174:177], v[16:19], v[120:123]
	v_mfma_f32_16x16x32_bf16 v[112:115], v[178:181], v[28:31], v[64:67]
	v_mfma_f32_16x16x32_bf16 v[64:67], v[0:3], v[32:35], v[116:119]
	v_mfma_f32_16x16x32_bf16 v[108:111], v[12:15], v[44:47], v[64:67]
	v_mfma_f32_16x16x32_bf16 v[64:67], v[174:177], v[32:35], v[200:203]
	v_mfma_f32_16x16x32_bf16 v[96:99], v[178:181], v[44:47], v[64:67]
	v_mfma_f32_16x16x32_bf16 v[64:67], v[0:3], v[48:51], v[204:207]
	v_mfma_f32_16x16x32_bf16 v[92:95], v[12:15], v[192:195], v[64:67]
	v_mfma_f32_16x16x32_bf16 v[64:67], v[174:177], v[48:51], v[104:107]
	v_mfma_f32_16x16x32_bf16 v[80:83], v[178:181], v[192:195], v[64:67]
	v_mfma_f32_16x16x32_bf16 v[64:67], v[0:3], v[212:215], v[100:103]
	v_mfma_f32_16x16x32_bf16 v[76:79], v[12:15], v[224:227], v[64:67]
	v_mfma_f32_16x16x32_bf16 v[64:67], v[174:177], v[212:215], v[208:211]
	v_mfma_f32_16x16x32_bf16 v[64:67], v[178:181], v[224:227], v[64:67]
	v_add_u32_e32 v100, 0x1c000, v142
	s_barrier
	ds_read_b128 v[200:203], v100
	ds_read_b128 v[204:207], v100 offset:1024
	ds_read_b128 v[208:211], v100 offset:2048
	ds_read_b128 v[228:231], v100 offset:3072
	s_waitcnt vmcnt(0)
	s_barrier
	s_waitcnt lgkmcnt(0)
	s_waitcnt lgkmcnt(0)
	v_mfma_f32_16x16x32_bf16 v[100:103], v[200:203], v[16:19], v[216:219]
	v_mfma_f32_16x16x32_bf16 v[16:19], v[208:211], v[16:19], v[88:91]
	v_mfma_f32_16x16x32_bf16 v[116:119], v[228:231], v[28:31], v[16:19]
	v_mfma_f32_16x16x32_bf16 v[16:19], v[200:203], v[32:35], v[84:87]
	v_mfma_f32_16x16x32_bf16 v[120:123], v[204:207], v[28:31], v[100:103]
	v_mfma_f32_16x16x32_bf16 v[100:103], v[204:207], v[44:47], v[16:19]
	v_mfma_f32_16x16x32_bf16 v[16:19], v[208:211], v[32:35], v[158:161]
	v_mfma_f32_16x16x32_bf16 v[104:107], v[228:231], v[44:47], v[16:19]
	v_mfma_f32_16x16x32_bf16 v[16:19], v[200:203], v[48:51], v[162:165]
	v_mfma_f32_16x16x32_bf16 v[84:87], v[204:207], v[192:195], v[16:19]
	v_mfma_f32_16x16x32_bf16 v[16:19], v[208:211], v[48:51], v[72:75]
	v_mfma_f32_16x16x32_bf16 v[88:91], v[228:231], v[192:195], v[16:19]
	v_mfma_f32_16x16x32_bf16 v[16:19], v[200:203], v[212:215], v[68:71]
	v_mfma_f32_16x16x32_bf16 v[68:71], v[204:207], v[224:227], v[16:19]
	v_mfma_f32_16x16x32_bf16 v[16:19], v[208:211], v[212:215], v[166:169]
	v_mfma_f32_16x16x32_bf16 v[72:75], v[228:231], v[224:227], v[16:19]
	s_barrier
	ds_read_b128 v[158:161], v144 offset:49152
	ds_read_b128 v[162:165], v144 offset:50176
	ds_read_b128 v[166:169], v144 offset:51200
	ds_read_b128 v[192:195], v144 offset:52224
	ds_read_b128 v[212:215], v144 offset:53248
	ds_read_b128 v[216:219], v144 offset:54272
	ds_read_b128 v[224:227], v144 offset:55296
	ds_read_b128 v[142:145], v144 offset:56320
	s_barrier
	s_waitcnt lgkmcnt(0)
	s_waitcnt lgkmcnt(0)
	v_mfma_f32_16x16x32_bf16 v[16:19], v[0:3], v[158:161], v[60:63]
	v_mfma_f32_16x16x32_bf16 v[60:63], v[12:15], v[162:165], v[16:19]
	v_mfma_f32_16x16x32_bf16 v[16:19], v[174:177], v[158:161], v[56:59]
	v_mfma_f32_16x16x32_bf16 v[48:51], v[178:181], v[162:165], v[16:19]
	v_mfma_f32_16x16x32_bf16 v[16:19], v[0:3], v[166:169], v[52:55]
	v_mfma_f32_16x16x32_bf16 v[44:47], v[12:15], v[192:195], v[16:19]
	v_mfma_f32_16x16x32_bf16 v[16:19], v[174:177], v[166:169], v[196:199]
	v_mfma_f32_16x16x32_bf16 v[32:35], v[178:181], v[192:195], v[16:19]
	v_mfma_f32_16x16x32_bf16 v[16:19], v[0:3], v[212:215], v[220:223]
	v_mfma_f32_16x16x32_bf16 v[0:3], v[0:3], v[224:227], v[36:39]
	v_mfma_f32_16x16x32_bf16 v[28:31], v[12:15], v[216:219], v[16:19]
	v_mfma_f32_16x16x32_bf16 v[16:19], v[174:177], v[212:215], v[40:43]
	v_mfma_f32_16x16x32_bf16 v[12:15], v[12:15], v[142:145], v[0:3]
	v_mfma_f32_16x16x32_bf16 v[0:3], v[174:177], v[224:227], v[138:141]
	v_mfma_f32_16x16x32_bf16 v[16:19], v[178:181], v[216:219], v[16:19]
	v_mfma_f32_16x16x32_bf16 v[0:3], v[178:181], v[142:145], v[0:3]
	v_mfma_f32_16x16x32_bf16 v[36:39], v[200:203], v[158:161], v[146:149]
	v_mfma_f32_16x16x32_bf16 v[20:23], v[200:203], v[166:169], v[20:23]
	v_mfma_f32_16x16x32_bf16 v[52:55], v[204:207], v[162:165], v[36:39]
	v_mfma_f32_16x16x32_bf16 v[24:27], v[208:211], v[158:161], v[24:27]
	v_mfma_f32_16x16x32_bf16 v[36:39], v[204:207], v[192:195], v[20:23]
	v_mfma_f32_16x16x32_bf16 v[20:23], v[208:211], v[166:169], v[150:153]
	v_mfma_f32_16x16x32_bf16 v[8:11], v[208:211], v[212:215], v[8:11]
	v_mfma_f32_16x16x32_bf16 v[56:59], v[228:231], v[162:165], v[24:27]
	v_mfma_f32_16x16x32_bf16 v[40:43], v[228:231], v[192:195], v[20:23]
	v_mfma_f32_16x16x32_bf16 v[20:23], v[200:203], v[212:215], v[154:157]
	v_mfma_f32_16x16x32_bf16 v[24:27], v[228:231], v[216:219], v[8:11]
	v_mfma_f32_16x16x32_bf16 v[4:7], v[200:203], v[224:227], v[4:7]
	v_mfma_f32_16x16x32_bf16 v[8:11], v[208:211], v[224:227], v[170:173]
	v_mfma_f32_16x16x32_bf16 v[20:23], v[204:207], v[216:219], v[20:23]
	v_mfma_f32_16x16x32_bf16 v[4:7], v[204:207], v[142:145], v[4:7]
	v_mfma_f32_16x16x32_bf16 v[8:11], v[228:231], v[142:145], v[8:11]
	s_cmpk_lt_u32 s1, 0x100
	s_barrier
	s_cbranch_scc0 .LBB0_784
	s_barrier

.LBB0_927:
	ds_read_b128 v[148:151], v146
	ds_read_b128 v[152:155], v146 offset:1024
	ds_read_b128 v[156:159], v146 offset:2048
	ds_read_b128 v[160:163], v146 offset:3072
	v_lshl_add_u64 v[180:181], v[134:135], 0, s[26:27]
	s_mov_b32 m0, s40
	v_lshl_add_u64 v[208:209], v[180:181], 0, s[6:7]
	v_lshl_add_u64 v[224:225], v[138:139], 0, s[26:27]
	ds_read_b128 v[164:167], v144
	ds_read_b128 v[168:171], v144 offset:1024
	ds_read_b128 v[172:175], v144 offset:2048
	ds_read_b128 v[176:179], v144 offset:3072
	ds_read_b128 v[192:195], v144 offset:4096
	ds_read_b128 v[196:199], v144 offset:5120
	ds_read_b128 v[200:203], v144 offset:6144
	ds_read_b128 v[204:207], v144 offset:7168
	global_load_lds_dwordx4 v[208:209], off
	v_lshl_add_u64 v[208:209], v[224:225], 0, s[6:7]
	s_mov_b32 m0, s28
	s_nop 0
	global_load_lds_dwordx4 v[208:209], off
	s_waitcnt lgkmcnt(8)
	s_barrier
	s_waitcnt lgkmcnt(0)
	s_waitcnt lgkmcnt(0)
	v_mfma_f32_16x16x32_bf16 v[124:127], v[148:151], v[164:167], v[124:127]
	v_mfma_f32_16x16x32_bf16 v[120:123], v[156:159], v[164:167], v[120:123]
	v_mfma_f32_16x16x32_bf16 v[116:119], v[148:151], v[172:175], v[116:119]
	v_mfma_f32_16x16x32_bf16 v[112:115], v[156:159], v[172:175], v[112:115]
	v_mfma_f32_16x16x32_bf16 v[108:111], v[148:151], v[192:195], v[108:111]
	v_mfma_f32_16x16x32_bf16 v[104:107], v[156:159], v[192:195], v[104:107]
	v_mfma_f32_16x16x32_bf16 v[100:103], v[148:151], v[200:203], v[100:103]
	v_mfma_f32_16x16x32_bf16 v[96:99], v[156:159], v[200:203], v[96:99]
	v_mfma_f32_16x16x32_bf16 v[124:127], v[152:155], v[168:171], v[124:127]
	v_mfma_f32_16x16x32_bf16 v[120:123], v[160:163], v[168:171], v[120:123]
	v_mfma_f32_16x16x32_bf16 v[116:119], v[152:155], v[176:179], v[116:119]
	v_mfma_f32_16x16x32_bf16 v[112:115], v[160:163], v[176:179], v[112:115]
	v_mfma_f32_16x16x32_bf16 v[108:111], v[152:155], v[196:199], v[108:111]
	v_mfma_f32_16x16x32_bf16 v[104:107], v[160:163], v[196:199], v[104:107]
	v_mfma_f32_16x16x32_bf16 v[100:103], v[152:155], v[204:207], v[100:103]
	v_mfma_f32_16x16x32_bf16 v[96:99], v[160:163], v[204:207], v[96:99]
	s_barrier
	v_lshl_add_u64 v[226:227], v[140:141], 0, s[26:27]
	s_add_i32 s41, s42, s23
	v_lshl_add_u64 v[228:229], v[226:227], 0, s[12:13]
	s_mov_b32 m0, s41
	ds_read_b128 v[208:211], v147
	ds_read_b128 v[212:215], v147 offset:1024
	ds_read_b128 v[216:219], v147 offset:2048
	ds_read_b128 v[220:223], v147 offset:3072
	global_load_lds_dwordx4 v[228:229], off
	v_lshl_add_u64 v[228:229], v[142:143], 0, s[26:27]
	v_lshl_add_u64 v[230:231], v[228:229], 0, s[12:13]
	s_add_i32 m0, s41, 0x2000
	s_nop 0
	global_load_lds_dwordx4 v[230:231], off
	s_barrier
	s_waitcnt lgkmcnt(0)
	s_waitcnt lgkmcnt(0)
	v_mfma_f32_16x16x32_bf16 v[92:95], v[208:211], v[164:167], v[92:95]
	v_mfma_f32_16x16x32_bf16 v[88:91], v[216:219], v[164:167], v[88:91]
	v_mfma_f32_16x16x32_bf16 v[84:87], v[208:211], v[172:175], v[84:87]
	v_mfma_f32_16x16x32_bf16 v[80:83], v[216:219], v[172:175], v[80:83]
	v_mfma_f32_16x16x32_bf16 v[76:79], v[208:211], v[192:195], v[76:79]
	v_mfma_f32_16x16x32_bf16 v[72:75], v[216:219], v[192:195], v[72:75]
	v_mfma_f32_16x16x32_bf16 v[68:71], v[208:211], v[200:203], v[68:71]
	v_mfma_f32_16x16x32_bf16 v[64:67], v[216:219], v[200:203], v[64:67]
	v_mfma_f32_16x16x32_bf16 v[92:95], v[212:215], v[168:171], v[92:95]
	v_mfma_f32_16x16x32_bf16 v[88:91], v[220:223], v[168:171], v[88:91]
	v_mfma_f32_16x16x32_bf16 v[84:87], v[212:215], v[176:179], v[84:87]
	v_mfma_f32_16x16x32_bf16 v[80:83], v[220:223], v[176:179], v[80:83]
	v_mfma_f32_16x16x32_bf16 v[76:79], v[212:215], v[196:199], v[76:79]
	v_mfma_f32_16x16x32_bf16 v[72:75], v[220:223], v[196:199], v[72:75]
	v_mfma_f32_16x16x32_bf16 v[68:71], v[212:215], v[204:207], v[68:71]
	v_mfma_f32_16x16x32_bf16 v[64:67], v[220:223], v[204:207], v[64:67]
	s_mov_b32 m0, s31
	v_lshl_add_u64 v[230:231], v[180:181], 0, s[12:13]
	s_barrier
	ds_read_b128 v[164:167], v144 offset:16384
	ds_read_b128 v[168:171], v144 offset:17408
	ds_read_b128 v[172:175], v144 offset:18432
	ds_read_b128 v[176:179], v144 offset:19456
	ds_read_b128 v[192:195], v144 offset:20480
	ds_read_b128 v[196:199], v144 offset:21504
	ds_read_b128 v[200:203], v144 offset:22528
	ds_read_b128 v[204:207], v144 offset:23552
	global_load_lds_dwordx4 v[230:231], off
	v_lshl_add_u64 v[230:231], v[224:225], 0, s[12:13]
	s_mov_b32 m0, s33
	s_nop 0
	global_load_lds_dwordx4 v[230:231], off
	s_barrier
	s_waitcnt lgkmcnt(0)
	s_waitcnt lgkmcnt(0)
	v_mfma_f32_16x16x32_bf16 v[60:63], v[148:151], v[164:167], v[60:63]
	v_mfma_f32_16x16x32_bf16 v[56:59], v[156:159], v[164:167], v[56:59]
	v_mfma_f32_16x16x32_bf16 v[52:55], v[148:151], v[172:175], v[52:55]
	v_mfma_f32_16x16x32_bf16 v[48:51], v[156:159], v[172:175], v[48:51]
	v_mfma_f32_16x16x32_bf16 v[44:47], v[148:151], v[192:195], v[44:47]
	v_mfma_f32_16x16x32_bf16 v[40:43], v[156:159], v[192:195], v[40:43]
	v_mfma_f32_16x16x32_bf16 v[36:39], v[148:151], v[200:203], v[36:39]
	v_mfma_f32_16x16x32_bf16 v[32:35], v[156:159], v[200:203], v[32:35]
	v_mfma_f32_16x16x32_bf16 v[60:63], v[152:155], v[168:171], v[60:63]
	v_mfma_f32_16x16x32_bf16 v[56:59], v[160:163], v[168:171], v[56:59]
	v_mfma_f32_16x16x32_bf16 v[52:55], v[152:155], v[176:179], v[52:55]
	v_mfma_f32_16x16x32_bf16 v[48:51], v[160:163], v[176:179], v[48:51]
	v_mfma_f32_16x16x32_bf16 v[44:47], v[152:155], v[196:199], v[44:47]
	v_mfma_f32_16x16x32_bf16 v[40:43], v[160:163], v[196:199], v[40:43]
	v_mfma_f32_16x16x32_bf16 v[36:39], v[152:155], v[204:207], v[36:39]
	v_mfma_f32_16x16x32_bf16 v[32:35], v[160:163], v[204:207], v[32:35]
	s_barrier
	s_add_i32 s41, s43, s23
	v_lshl_add_u64 v[148:149], v[226:227], 0, s[14:15]
	s_mov_b32 m0, s41
	s_nop 0
	global_load_lds_dwordx4 v[148:149], off
	v_lshl_add_u64 v[148:149], v[228:229], 0, s[14:15]
	s_add_i32 m0, s41, 0x2000
	s_nop 0
	global_load_lds_dwordx4 v[148:149], off
	s_waitcnt vmcnt(6)
	s_barrier
	v_mfma_f32_16x16x32_bf16 v[28:31], v[208:211], v[164:167], v[28:31]
	v_mfma_f32_16x16x32_bf16 v[24:27], v[216:219], v[164:167], v[24:27]
	v_mfma_f32_16x16x32_bf16 v[20:23], v[208:211], v[172:175], v[20:23]
	v_mfma_f32_16x16x32_bf16 v[16:19], v[216:219], v[172:175], v[16:19]
	v_mfma_f32_16x16x32_bf16 v[12:15], v[208:211], v[192:195], v[12:15]
	v_mfma_f32_16x16x32_bf16 v[8:11], v[216:219], v[192:195], v[8:11]
	v_mfma_f32_16x16x32_bf16 v[4:7], v[208:211], v[200:203], v[4:7]
	v_mfma_f32_16x16x32_bf16 v[0:3], v[216:219], v[200:203], v[0:3]
	v_mfma_f32_16x16x32_bf16 v[28:31], v[212:215], v[168:171], v[28:31]
	v_mfma_f32_16x16x32_bf16 v[24:27], v[220:223], v[168:171], v[24:27]
	v_mfma_f32_16x16x32_bf16 v[20:23], v[212:215], v[176:179], v[20:23]
	v_mfma_f32_16x16x32_bf16 v[16:19], v[220:223], v[176:179], v[16:19]
	v_mfma_f32_16x16x32_bf16 v[12:15], v[212:215], v[196:199], v[12:15]
	v_mfma_f32_16x16x32_bf16 v[8:11], v[220:223], v[196:199], v[8:11]
	v_mfma_f32_16x16x32_bf16 v[4:7], v[212:215], v[204:207], v[4:7]
	v_mfma_f32_16x16x32_bf16 v[0:3], v[220:223], v[204:207], v[0:3]
	s_add_i32 s41, 0, 0x18000
	v_add_u32_e32 v160, s41, v145
	s_barrier
	ds_read_b128 v[148:151], v160
	ds_read_b128 v[152:155], v160 offset:1024
	ds_read_b128 v[156:159], v160 offset:2048
	ds_read_b128 v[160:163], v160 offset:3072
	s_mov_b32 m0, s34
	v_lshl_add_u64 v[208:209], v[180:181], 0, s[14:15]
	ds_read_b128 v[164:167], v144 offset:32768
	ds_read_b128 v[168:171], v144 offset:33792
	ds_read_b128 v[172:175], v144 offset:34816
	ds_read_b128 v[176:179], v144 offset:35840
	ds_read_b128 v[192:195], v144 offset:36864
	ds_read_b128 v[196:199], v144 offset:37888
	ds_read_b128 v[200:203], v144 offset:38912
	ds_read_b128 v[204:207], v144 offset:39936
	global_load_lds_dwordx4 v[208:209], off
	v_lshl_add_u64 v[208:209], v[224:225], 0, s[14:15]
	s_mov_b32 m0, s35
	s_nop 0
	global_load_lds_dwordx4 v[208:209], off
	s_waitcnt lgkmcnt(8)
	s_barrier
	s_waitcnt lgkmcnt(0)
	s_waitcnt lgkmcnt(0)
	v_mfma_f32_16x16x32_bf16 v[124:127], v[148:151], v[164:167], v[124:127]
	v_mfma_f32_16x16x32_bf16 v[120:123], v[156:159], v[164:167], v[120:123]
	v_mfma_f32_16x16x32_bf16 v[116:119], v[148:151], v[172:175], v[116:119]
	v_mfma_f32_16x16x32_bf16 v[112:115], v[156:159], v[172:175], v[112:115]
	v_mfma_f32_16x16x32_bf16 v[108:111], v[148:151], v[192:195], v[108:111]
	v_mfma_f32_16x16x32_bf16 v[104:107], v[156:159], v[192:195], v[104:107]
	v_mfma_f32_16x16x32_bf16 v[100:103], v[148:151], v[200:203], v[100:103]
	v_mfma_f32_16x16x32_bf16 v[96:99], v[156:159], v[200:203], v[96:99]
	v_mfma_f32_16x16x32_bf16 v[124:127], v[152:155], v[168:171], v[124:127]
	v_mfma_f32_16x16x32_bf16 v[120:123], v[160:163], v[168:171], v[120:123]
	v_mfma_f32_16x16x32_bf16 v[116:119], v[152:155], v[176:179], v[116:119]
	v_mfma_f32_16x16x32_bf16 v[112:115], v[160:163], v[176:179], v[112:115]
	v_mfma_f32_16x16x32_bf16 v[108:111], v[152:155], v[196:199], v[108:111]
	v_mfma_f32_16x16x32_bf16 v[104:107], v[160:163], v[196:199], v[104:107]
	v_mfma_f32_16x16x32_bf16 v[100:103], v[152:155], v[204:207], v[100:103]
	v_mfma_f32_16x16x32_bf16 v[96:99], v[160:163], v[204:207], v[96:99]
	s_barrier
	s_add_i32 s50, 0, 0x1c000
	s_add_i32 s41, s41, s23
	v_add_u32_e32 v184, s50, v145
	v_lshl_add_u64 v[230:231], v[226:227], 0, s[16:17]
	s_mov_b32 m0, s41
	ds_read_b128 v[208:211], v184
	ds_read_b128 v[212:215], v184 offset:1024
	ds_read_b128 v[216:219], v184 offset:2048
	ds_read_b128 v[220:223], v184 offset:3072
	global_load_lds_dwordx4 v[230:231], off
	v_lshl_add_u64 v[230:231], v[228:229], 0, s[16:17]
	s_add_i32 m0, s41, 0x2000
	s_nop 0
	global_load_lds_dwordx4 v[230:231], off
	s_barrier
	s_waitcnt lgkmcnt(0)
	s_waitcnt lgkmcnt(0)
	v_mfma_f32_16x16x32_bf16 v[92:95], v[208:211], v[164:167], v[92:95]
	v_mfma_f32_16x16x32_bf16 v[88:91], v[216:219], v[164:167], v[88:91]
	v_mfma_f32_16x16x32_bf16 v[84:87], v[208:211], v[172:175], v[84:87]
	v_mfma_f32_16x16x32_bf16 v[80:83], v[216:219], v[172:175], v[80:83]
	v_mfma_f32_16x16x32_bf16 v[76:79], v[208:211], v[192:195], v[76:79]
	v_mfma_f32_16x16x32_bf16 v[72:75], v[216:219], v[192:195], v[72:75]
	v_mfma_f32_16x16x32_bf16 v[68:71], v[208:211], v[200:203], v[68:71]
	v_mfma_f32_16x16x32_bf16 v[64:67], v[216:219], v[200:203], v[64:67]
	v_mfma_f32_16x16x32_bf16 v[92:95], v[212:215], v[168:171], v[92:95]
	v_mfma_f32_16x16x32_bf16 v[88:91], v[220:223], v[168:171], v[88:91]
	v_mfma_f32_16x16x32_bf16 v[84:87], v[212:215], v[176:179], v[84:87]
	v_mfma_f32_16x16x32_bf16 v[80:83], v[220:223], v[176:179], v[80:83]
	v_mfma_f32_16x16x32_bf16 v[76:79], v[212:215], v[196:199], v[76:79]
	v_mfma_f32_16x16x32_bf16 v[72:75], v[220:223], v[196:199], v[72:75]
	v_mfma_f32_16x16x32_bf16 v[68:71], v[212:215], v[204:207], v[68:71]
	v_mfma_f32_16x16x32_bf16 v[64:67], v[220:223], v[204:207], v[64:67]
	s_mov_b32 m0, s36
	v_lshl_add_u64 v[180:181], v[180:181], 0, s[16:17]
	s_barrier
	ds_read_b128 v[164:167], v144 offset:49152
	ds_read_b128 v[168:171], v144 offset:50176
	ds_read_b128 v[172:175], v144 offset:51200
	ds_read_b128 v[176:179], v144 offset:52224
	ds_read_b128 v[192:195], v144 offset:53248
	ds_read_b128 v[196:199], v144 offset:54272
	ds_read_b128 v[200:203], v144 offset:55296
	ds_read_b128 v[204:207], v144 offset:56320
	global_load_lds_dwordx4 v[180:181], off
	v_lshl_add_u64 v[180:181], v[224:225], 0, s[16:17]
	s_mov_b32 m0, s37
	s_nop 0
	global_load_lds_dwordx4 v[180:181], off
	s_barrier
	s_waitcnt lgkmcnt(0)
	s_waitcnt lgkmcnt(0)
	v_mfma_f32_16x16x32_bf16 v[60:63], v[148:151], v[164:167], v[60:63]
	v_mfma_f32_16x16x32_bf16 v[56:59], v[156:159], v[164:167], v[56:59]
	v_mfma_f32_16x16x32_bf16 v[52:55], v[148:151], v[172:175], v[52:55]
	v_mfma_f32_16x16x32_bf16 v[48:51], v[156:159], v[172:175], v[48:51]
	v_mfma_f32_16x16x32_bf16 v[44:47], v[148:151], v[192:195], v[44:47]
	v_mfma_f32_16x16x32_bf16 v[40:43], v[156:159], v[192:195], v[40:43]
	v_mfma_f32_16x16x32_bf16 v[36:39], v[148:151], v[200:203], v[36:39]
	v_mfma_f32_16x16x32_bf16 v[32:35], v[156:159], v[200:203], v[32:35]
	v_mfma_f32_16x16x32_bf16 v[60:63], v[152:155], v[168:171], v[60:63]
	v_mfma_f32_16x16x32_bf16 v[56:59], v[160:163], v[168:171], v[56:59]
	v_mfma_f32_16x16x32_bf16 v[52:55], v[152:155], v[176:179], v[52:55]
	v_mfma_f32_16x16x32_bf16 v[48:51], v[160:163], v[176:179], v[48:51]
	v_mfma_f32_16x16x32_bf16 v[44:47], v[152:155], v[196:199], v[44:47]
	v_mfma_f32_16x16x32_bf16 v[40:43], v[160:163], v[196:199], v[40:43]
	v_mfma_f32_16x16x32_bf16 v[36:39], v[152:155], v[204:207], v[36:39]
	v_mfma_f32_16x16x32_bf16 v[32:35], v[160:163], v[204:207], v[32:35]
	s_barrier
	s_add_i32 s41, s50, s23
	v_lshl_add_u64 v[148:149], v[226:227], 0, s[18:19]
	s_mov_b32 m0, s41
	s_nop 0
	global_load_lds_dwordx4 v[148:149], off
	v_lshl_add_u64 v[148:149], v[228:229], 0, s[18:19]
	s_add_i32 m0, s41, 0x2000
	s_nop 0
	global_load_lds_dwordx4 v[148:149], off
	s_waitcnt vmcnt(6)
	s_barrier
	v_mfma_f32_16x16x32_bf16 v[28:31], v[208:211], v[164:167], v[28:31]
	v_mfma_f32_16x16x32_bf16 v[24:27], v[216:219], v[164:167], v[24:27]
	v_mfma_f32_16x16x32_bf16 v[20:23], v[208:211], v[172:175], v[20:23]
	v_mfma_f32_16x16x32_bf16 v[16:19], v[216:219], v[172:175], v[16:19]
	v_mfma_f32_16x16x32_bf16 v[12:15], v[208:211], v[192:195], v[12:15]
	v_mfma_f32_16x16x32_bf16 v[8:11], v[216:219], v[192:195], v[8:11]
	v_mfma_f32_16x16x32_bf16 v[4:7], v[208:211], v[200:203], v[4:7]
	v_mfma_f32_16x16x32_bf16 v[0:3], v[216:219], v[200:203], v[0:3]
	v_mfma_f32_16x16x32_bf16 v[28:31], v[212:215], v[168:171], v[28:31]
	v_mfma_f32_16x16x32_bf16 v[24:27], v[220:223], v[168:171], v[24:27]
	v_mfma_f32_16x16x32_bf16 v[20:23], v[212:215], v[176:179], v[20:23]
	v_mfma_f32_16x16x32_bf16 v[16:19], v[220:223], v[176:179], v[16:19]
	v_mfma_f32_16x16x32_bf16 v[12:15], v[212:215], v[196:199], v[12:15]
	v_mfma_f32_16x16x32_bf16 v[8:11], v[220:223], v[196:199], v[8:11]
	v_mfma_f32_16x16x32_bf16 v[4:7], v[212:215], v[204:207], v[4:7]
	v_mfma_f32_16x16x32_bf16 v[0:3], v[220:223], v[204:207], v[0:3]
	s_add_i32 s29, s29, 2
	s_add_u32 s26, s26, 0x100
	s_addc_u32 s27, s27, 0
	s_cmp_gt_u32 s29, 11
	s_barrier
	s_cbranch_scc0 .LBB0_927
	v_add_u32_e32 v142, 0, v145
	s_add_u32 s24, s24, 0x40780
	v_add_u32_e32 v134, 0x10000, v142
	s_addc_u32 s25, s25, 0
	s_mov_b32 m0, s40
	ds_read_b128 v[138:141], v134
	ds_read_b128 v[146:149], v134 offset:1024
	ds_read_b128 v[150:153], v134 offset:2048
	ds_read_b128 v[154:157], v134 offset:3072
	ds_read_b128 v[158:161], v144
	ds_read_b128 v[162:165], v144 offset:1024
	ds_read_b128 v[166:169], v144 offset:2048
	ds_read_b128 v[170:173], v144 offset:3072
	ds_read_b128 v[174:177], v144 offset:4096
	ds_read_b128 v[178:181], v144 offset:5120
	ds_read_b128 v[192:195], v144 offset:6144
	ds_read_b128 v[196:199], v144 offset:7168
	v_lshl_add_u64 v[134:135], s[24:25], 0, v[128:129]
	global_load_lds_dwordx4 v[134:135], off
	v_lshl_add_u64 v[130:131], s[24:25], 0, v[130:131]
	s_mov_b32 m0, s28
	s_nop 0
	global_load_lds_dwordx4 v[130:131], off
	s_barrier
	s_waitcnt lgkmcnt(0)
	s_waitcnt lgkmcnt(0)
	v_mfma_f32_16x16x32_bf16 v[124:127], v[138:141], v[158:161], v[124:127]
	v_mfma_f32_16x16x32_bf16 v[120:123], v[150:153], v[158:161], v[120:123]
	v_mfma_f32_16x16x32_bf16 v[108:111], v[138:141], v[174:177], v[108:111]
	v_mfma_f32_16x16x32_bf16 v[104:107], v[150:153], v[174:177], v[104:107]
	v_mfma_f32_16x16x32_bf16 v[124:127], v[146:149], v[162:165], v[124:127]
	v_mfma_f32_16x16x32_bf16 v[120:123], v[154:157], v[162:165], v[120:123]
	v_mfma_f32_16x16x32_bf16 v[116:119], v[138:141], v[166:169], v[116:119]
	v_mfma_f32_16x16x32_bf16 v[112:115], v[150:153], v[166:169], v[112:115]
	v_mfma_f32_16x16x32_bf16 v[108:111], v[146:149], v[178:181], v[108:111]
	v_mfma_f32_16x16x32_bf16 v[104:107], v[154:157], v[178:181], v[104:107]
	v_mfma_f32_16x16x32_bf16 v[100:103], v[138:141], v[192:195], v[100:103]
	v_mfma_f32_16x16x32_bf16 v[96:99], v[150:153], v[192:195], v[96:99]
	v_mfma_f32_16x16x32_bf16 v[200:203], v[146:149], v[170:173], v[116:119]
	v_mfma_f32_16x16x32_bf16 v[204:207], v[154:157], v[170:173], v[112:115]
	v_mfma_f32_16x16x32_bf16 v[208:211], v[146:149], v[196:199], v[100:103]
	v_mfma_f32_16x16x32_bf16 v[212:215], v[154:157], v[196:199], v[96:99]
	v_add_u32_e32 v116, 0x14000, v142
	s_barrier
	s_nop 0
	ds_read_b128 v[96:99], v116
	ds_read_b128 v[100:103], v116 offset:1024
	ds_read_b128 v[112:115], v116 offset:2048
	ds_read_b128 v[116:119], v116 offset:3072
	s_barrier
	s_waitcnt lgkmcnt(0)
	s_waitcnt lgkmcnt(0)
	v_mfma_f32_16x16x32_bf16 v[92:95], v[96:99], v[158:161], v[92:95]
	v_mfma_f32_16x16x32_bf16 v[88:91], v[112:115], v[158:161], v[88:91]
	v_mfma_f32_16x16x32_bf16 v[76:79], v[96:99], v[174:177], v[76:79]
	v_mfma_f32_16x16x32_bf16 v[72:75], v[112:115], v[174:177], v[72:75]
	v_mfma_f32_16x16x32_bf16 v[92:95], v[100:103], v[162:165], v[92:95]
	v_mfma_f32_16x16x32_bf16 v[88:91], v[116:119], v[162:165], v[88:91]
	v_mfma_f32_16x16x32_bf16 v[84:87], v[96:99], v[166:169], v[84:87]
	v_mfma_f32_16x16x32_bf16 v[80:83], v[112:115], v[166:169], v[80:83]
	v_mfma_f32_16x16x32_bf16 v[76:79], v[100:103], v[178:181], v[76:79]
	v_mfma_f32_16x16x32_bf16 v[72:75], v[116:119], v[178:181], v[72:75]
	v_mfma_f32_16x16x32_bf16 v[68:71], v[96:99], v[192:195], v[68:71]
	v_mfma_f32_16x16x32_bf16 v[64:67], v[112:115], v[192:195], v[64:67]
	v_mfma_f32_16x16x32_bf16 v[158:161], v[100:103], v[170:173], v[84:87]
	v_mfma_f32_16x16x32_bf16 v[162:165], v[116:119], v[170:173], v[80:83]
	v_mfma_f32_16x16x32_bf16 v[166:169], v[100:103], v[196:199], v[68:71]
	v_mfma_f32_16x16x32_bf16 v[170:173], v[116:119], v[196:199], v[64:67]
	s_barrier
	s_nop 1
	ds_read_b128 v[64:67], v144 offset:16384
	ds_read_b128 v[68:71], v144 offset:17408
	ds_read_b128 v[80:83], v144 offset:18432
	ds_read_b128 v[84:87], v144 offset:19456
	ds_read_b128 v[174:177], v144 offset:20480
	ds_read_b128 v[178:181], v144 offset:21504
	ds_read_b128 v[192:195], v144 offset:22528
	ds_read_b128 v[196:199], v144 offset:23552
	s_waitcnt vmcnt(4)
	s_barrier
	s_waitcnt lgkmcnt(0)
	s_waitcnt lgkmcnt(0)
	v_mfma_f32_16x16x32_bf16 v[60:63], v[138:141], v[64:67], v[60:63]
	v_mfma_f32_16x16x32_bf16 v[56:59], v[150:153], v[64:67], v[56:59]
	v_mfma_f32_16x16x32_bf16 v[52:55], v[138:141], v[80:83], v[52:55]
	v_mfma_f32_16x16x32_bf16 v[48:51], v[150:153], v[80:83], v[48:51]
	v_mfma_f32_16x16x32_bf16 v[36:39], v[138:141], v[192:195], v[36:39]
	v_mfma_f32_16x16x32_bf16 v[32:35], v[150:153], v[192:195], v[32:35]
	v_mfma_f32_16x16x32_bf16 v[60:63], v[146:149], v[68:71], v[60:63]
	v_mfma_f32_16x16x32_bf16 v[56:59], v[154:157], v[68:71], v[56:59]
	v_mfma_f32_16x16x32_bf16 v[52:55], v[146:149], v[84:87], v[52:55]
	v_mfma_f32_16x16x32_bf16 v[48:51], v[154:157], v[84:87], v[48:51]
	v_mfma_f32_16x16x32_bf16 v[44:47], v[138:141], v[174:177], v[44:47]
	v_mfma_f32_16x16x32_bf16 v[40:43], v[150:153], v[174:177], v[40:43]
	v_mfma_f32_16x16x32_bf16 v[36:39], v[146:149], v[196:199], v[36:39]
	v_mfma_f32_16x16x32_bf16 v[32:35], v[154:157], v[196:199], v[32:35]
	v_mfma_f32_16x16x32_bf16 v[216:219], v[146:149], v[178:181], v[44:47]
	v_mfma_f32_16x16x32_bf16 v[220:223], v[154:157], v[178:181], v[40:43]
	v_mfma_f32_16x16x32_bf16 v[20:23], v[96:99], v[80:83], v[20:23]
	v_mfma_f32_16x16x32_bf16 v[16:19], v[112:115], v[80:83], v[16:19]
	v_mfma_f32_16x16x32_bf16 v[4:7], v[96:99], v[192:195], v[4:7]
	v_mfma_f32_16x16x32_bf16 v[0:3], v[112:115], v[192:195], v[0:3]
	v_mfma_f32_16x16x32_bf16 v[28:31], v[96:99], v[64:67], v[28:31]
	v_mfma_f32_16x16x32_bf16 v[24:27], v[112:115], v[64:67], v[24:27]
	v_mfma_f32_16x16x32_bf16 v[20:23], v[100:103], v[84:87], v[20:23]
	v_mfma_f32_16x16x32_bf16 v[16:19], v[116:119], v[84:87], v[16:19]
	v_mfma_f32_16x16x32_bf16 v[12:15], v[96:99], v[174:177], v[12:15]
	v_mfma_f32_16x16x32_bf16 v[8:11], v[112:115], v[174:177], v[8:11]
	v_mfma_f32_16x16x32_bf16 v[4:7], v[100:103], v[196:199], v[4:7]
	v_mfma_f32_16x16x32_bf16 v[0:3], v[116:119], v[196:199], v[0:3]
	v_mfma_f32_16x16x32_bf16 v[138:141], v[100:103], v[68:71], v[28:31]
	v_mfma_f32_16x16x32_bf16 v[146:149], v[116:119], v[68:71], v[24:27]
	v_mfma_f32_16x16x32_bf16 v[150:153], v[100:103], v[178:181], v[12:15]
	v_mfma_f32_16x16x32_bf16 v[154:157], v[116:119], v[178:181], v[8:11]
	v_add_u32_e32 v24, 0x18000, v142
	s_barrier
	ds_read_b128 v[8:11], v24
	ds_read_b128 v[12:15], v24 offset:1024
	ds_read_b128 v[174:177], v24 offset:2048
	ds_read_b128 v[178:181], v24 offset:3072
	ds_read_b128 v[24:27], v144 offset:32768
	ds_read_b128 v[28:31], v144 offset:33792
	ds_read_b128 v[40:43], v144 offset:34816
	ds_read_b128 v[44:47], v144 offset:35840
	ds_read_b128 v[192:195], v144 offset:36864
	ds_read_b128 v[196:199], v144 offset:37888
	ds_read_b128 v[224:227], v144 offset:38912
	ds_read_b128 v[228:231], v144 offset:39936
	s_waitcnt vmcnt(2)
	s_barrier
	s_waitcnt lgkmcnt(0)
	s_waitcnt lgkmcnt(0)
	v_mfma_f32_16x16x32_bf16 v[64:67], v[8:11], v[24:27], v[124:127]
	v_mfma_f32_16x16x32_bf16 v[116:119], v[12:15], v[28:31], v[64:67]
	v_mfma_f32_16x16x32_bf16 v[64:67], v[174:177], v[24:27], v[120:123]
	v_mfma_f32_16x16x32_bf16 v[112:115], v[178:181], v[28:31], v[64:67]
	v_mfma_f32_16x16x32_bf16 v[64:67], v[8:11], v[40:43], v[200:203]
	v_mfma_f32_16x16x32_bf16 v[100:103], v[12:15], v[44:47], v[64:67]
	v_mfma_f32_16x16x32_bf16 v[64:67], v[174:177], v[40:43], v[204:207]
	v_mfma_f32_16x16x32_bf16 v[96:99], v[178:181], v[44:47], v[64:67]
	v_mfma_f32_16x16x32_bf16 v[64:67], v[8:11], v[192:195], v[108:111]
	v_mfma_f32_16x16x32_bf16 v[84:87], v[12:15], v[196:199], v[64:67]
	v_mfma_f32_16x16x32_bf16 v[64:67], v[174:177], v[192:195], v[104:107]
	v_mfma_f32_16x16x32_bf16 v[80:83], v[178:181], v[196:199], v[64:67]
	v_mfma_f32_16x16x32_bf16 v[64:67], v[8:11], v[224:227], v[208:211]
	v_mfma_f32_16x16x32_bf16 v[68:71], v[12:15], v[228:231], v[64:67]
	v_mfma_f32_16x16x32_bf16 v[64:67], v[174:177], v[224:227], v[212:215]
	v_mfma_f32_16x16x32_bf16 v[64:67], v[178:181], v[228:231], v[64:67]
	v_add_u32_e32 v104, 0x1c000, v142
	s_barrier
	ds_read_b128 v[200:203], v104
	ds_read_b128 v[204:207], v104 offset:1024
	ds_read_b128 v[208:211], v104 offset:2048
	ds_read_b128 v[212:215], v104 offset:3072
	s_waitcnt vmcnt(0)
	s_barrier
	s_waitcnt lgkmcnt(0)
	s_waitcnt lgkmcnt(0)
	v_mfma_f32_16x16x32_bf16 v[92:95], v[200:203], v[24:27], v[92:95]
	v_mfma_f32_16x16x32_bf16 v[24:27], v[208:211], v[24:27], v[88:91]
	v_mfma_f32_16x16x32_bf16 v[120:123], v[212:215], v[28:31], v[24:27]
	v_mfma_f32_16x16x32_bf16 v[24:27], v[200:203], v[40:43], v[158:161]
	v_mfma_f32_16x16x32_bf16 v[108:111], v[204:207], v[44:47], v[24:27]
	v_mfma_f32_16x16x32_bf16 v[24:27], v[208:211], v[40:43], v[162:165]
	v_mfma_f32_16x16x32_bf16 v[104:107], v[212:215], v[44:47], v[24:27]
	v_mfma_f32_16x16x32_bf16 v[24:27], v[200:203], v[192:195], v[76:79]
	v_mfma_f32_16x16x32_bf16 v[124:127], v[204:207], v[28:31], v[92:95]
	v_mfma_f32_16x16x32_bf16 v[92:95], v[204:207], v[196:199], v[24:27]
	v_mfma_f32_16x16x32_bf16 v[24:27], v[208:211], v[192:195], v[72:75]
	v_mfma_f32_16x16x32_bf16 v[88:91], v[212:215], v[196:199], v[24:27]
	v_mfma_f32_16x16x32_bf16 v[24:27], v[200:203], v[224:227], v[166:169]
	v_mfma_f32_16x16x32_bf16 v[76:79], v[204:207], v[228:231], v[24:27]
	v_mfma_f32_16x16x32_bf16 v[24:27], v[208:211], v[224:227], v[170:173]
	v_mfma_f32_16x16x32_bf16 v[72:75], v[212:215], v[228:231], v[24:27]
	s_barrier
	ds_read_b128 v[158:161], v144 offset:49152
	ds_read_b128 v[162:165], v144 offset:50176
	ds_read_b128 v[166:169], v144 offset:51200
	ds_read_b128 v[170:173], v144 offset:52224
	ds_read_b128 v[192:195], v144 offset:53248
	ds_read_b128 v[196:199], v144 offset:54272
	ds_read_b128 v[224:227], v144 offset:55296
	ds_read_b128 v[142:145], v144 offset:56320
	s_barrier
	s_waitcnt lgkmcnt(0)
	s_waitcnt lgkmcnt(0)
	v_mfma_f32_16x16x32_bf16 v[24:27], v[8:11], v[158:161], v[60:63]
	v_mfma_f32_16x16x32_bf16 v[60:63], v[12:15], v[162:165], v[24:27]
	v_mfma_f32_16x16x32_bf16 v[24:27], v[174:177], v[158:161], v[56:59]
	v_mfma_f32_16x16x32_bf16 v[56:59], v[178:181], v[162:165], v[24:27]
	v_mfma_f32_16x16x32_bf16 v[24:27], v[8:11], v[166:169], v[52:55]
	v_mfma_f32_16x16x32_bf16 v[44:47], v[12:15], v[170:173], v[24:27]
	v_mfma_f32_16x16x32_bf16 v[24:27], v[174:177], v[166:169], v[48:51]
	v_mfma_f32_16x16x32_bf16 v[40:43], v[178:181], v[170:173], v[24:27]
	v_mfma_f32_16x16x32_bf16 v[24:27], v[8:11], v[192:195], v[216:219]
	v_mfma_f32_16x16x32_bf16 v[8:11], v[8:11], v[224:227], v[36:39]
	v_mfma_f32_16x16x32_bf16 v[28:31], v[12:15], v[196:199], v[24:27]
	v_mfma_f32_16x16x32_bf16 v[24:27], v[174:177], v[192:195], v[220:223]
	v_mfma_f32_16x16x32_bf16 v[12:15], v[12:15], v[142:145], v[8:11]
	v_mfma_f32_16x16x32_bf16 v[8:11], v[174:177], v[224:227], v[32:35]
	v_mfma_f32_16x16x32_bf16 v[24:27], v[178:181], v[196:199], v[24:27]
	v_mfma_f32_16x16x32_bf16 v[8:11], v[178:181], v[142:145], v[8:11]
	v_mfma_f32_16x16x32_bf16 v[32:35], v[200:203], v[158:161], v[138:141]
	v_mfma_f32_16x16x32_bf16 v[52:55], v[204:207], v[162:165], v[32:35]
	v_mfma_f32_16x16x32_bf16 v[32:35], v[208:211], v[158:161], v[146:149]
	v_mfma_f32_16x16x32_bf16 v[16:19], v[208:211], v[166:169], v[16:19]
	v_mfma_f32_16x16x32_bf16 v[48:51], v[212:215], v[162:165], v[32:35]
	v_mfma_f32_16x16x32_bf16 v[20:23], v[200:203], v[166:169], v[20:23]
	v_mfma_f32_16x16x32_bf16 v[32:35], v[212:215], v[170:173], v[16:19]
	v_mfma_f32_16x16x32_bf16 v[16:19], v[200:203], v[192:195], v[150:153]
	v_mfma_f32_16x16x32_bf16 v[36:39], v[204:207], v[170:173], v[20:23]
	v_mfma_f32_16x16x32_bf16 v[20:23], v[204:207], v[196:199], v[16:19]
	v_mfma_f32_16x16x32_bf16 v[16:19], v[208:211], v[192:195], v[154:157]
	v_mfma_f32_16x16x32_bf16 v[4:7], v[200:203], v[224:227], v[4:7]
	v_mfma_f32_16x16x32_bf16 v[0:3], v[208:211], v[224:227], v[0:3]
	v_mfma_f32_16x16x32_bf16 v[16:19], v[212:215], v[196:199], v[16:19]
	v_mfma_f32_16x16x32_bf16 v[4:7], v[204:207], v[142:145], v[4:7]
	v_mfma_f32_16x16x32_bf16 v[0:3], v[212:215], v[142:145], v[0:3]
	s_cmpk_lt_u32 s21, 0x100
	s_barrier
	s_cbranch_scc0 .LBB0_921
	s_barrier
	s_branch .LBB0_921

.LBB0_987:
	v_and_b32_e32 v15, 15, v14
	v_and_b32_e32 v16, 48, v14
	v_lshlrev_b32_e32 v14, 2, v14
	v_lshlrev_b32_e32 v15, 6, v15
	v_and_b32_e32 v14, 32, v14
	s_lshl_b32 s51, s51, 12
	v_or_b32_e32 v17, v15, v16
	v_bitop3_b32 v15, v15, v14, v16 bitop3:0x36
	s_lshl_b32 s33, s33, 13
	s_and_b32 s51, s51, 0x3000
	s_add_i32 s74, s40, s53
	v_or_b32_e32 v16, s51, v15
	v_bitop3_b32 v17, v17, s33, v14 bitop3:0xde
	v_lshl_add_u64 v[14:15], v[12:13], 0, s[20:21]
	s_mov_b32 m0, s74
	s_add_i32 s73, s74, 0x2000
	s_waitcnt vmcnt(4)
	s_barrier
	global_load_lds_dwordx4 v[14:15], off
	v_lshl_add_u64 v[14:15], v[10:11], 0, s[20:21]
	s_mov_b32 m0, s73
	s_add_i32 s72, s76, 0x8000
	s_add_i32 s56, s76, 0xa000
	global_load_lds_dwordx4 v[14:15], off
	v_lshl_add_u64 v[14:15], v[6:7], 0, s[20:21]
	s_mov_b32 m0, s72
	s_add_u32 s78, s34, 0x10080
	global_load_lds_dwordx4 v[14:15], off
	v_lshl_add_u64 v[14:15], v[8:9], 0, s[20:21]
	s_mov_b32 m0, s56
	s_addc_u32 s79, s35, 0
	s_add_i32 s51, s41, s53
	global_load_lds_dwordx4 v[14:15], off
	v_lshl_add_u64 v[14:15], s[78:79], 0, v[128:129]
	s_mov_b32 m0, s51
	s_add_i32 s33, s51, 0x2000
	global_load_lds_dwordx4 v[14:15], off
	v_lshl_add_u64 v[14:15], s[78:79], 0, v[4:5]
	s_mov_b32 m0, s33
	v_add_u32_e32 v134, s43, v16
	global_load_lds_dwordx4 v[14:15], off
	v_add_u32_e32 v15, s42, v16
	s_waitcnt vmcnt(6)
	s_barrier
	v_add_u32_e32 v14, 0, v17
	v_add_u32_e32 v135, s40, v16
	v_add_u32_e32 v184, s41, v16
	ds_read_b128 v[16:19], v15
	ds_read_b128 v[20:23], v15 offset:1024
	ds_read_b128 v[24:27], v15 offset:2048
	ds_read_b128 v[28:31], v15 offset:3072
	s_add_u32 s80, s30, 0x40080
	s_addc_u32 s81, s31, 0
	s_add_i32 s78, s76, 0xc000
	v_lshl_add_u64 v[64:65], s[80:81], 0, v[0:1]
	s_mov_b32 m0, s78
	s_add_i32 s75, s76, 0xe000
	ds_read_b128 v[32:35], v14
	ds_read_b128 v[36:39], v14 offset:1024
	ds_read_b128 v[40:43], v14 offset:2048
	ds_read_b128 v[44:47], v14 offset:3072
	ds_read_b128 v[48:51], v14 offset:4096
	ds_read_b128 v[52:55], v14 offset:5120
	ds_read_b128 v[56:59], v14 offset:6144
	ds_read_b128 v[60:63], v14 offset:7168
	global_load_lds_dwordx4 v[64:65], off
	v_lshl_add_u64 v[64:65], s[80:81], 0, v[2:3]
	s_mov_b32 m0, s75
	s_nop 0
	global_load_lds_dwordx4 v[64:65], off
	s_waitcnt lgkmcnt(8)
	s_barrier
	s_waitcnt lgkmcnt(0)
	s_waitcnt lgkmcnt(0)
	v_mfma_f32_16x16x32_bf16 v[64:67], v[16:19], v[32:35], 0
	v_mfma_f32_16x16x32_bf16 v[68:71], v[24:27], v[32:35], 0
	v_mfma_f32_16x16x32_bf16 v[72:75], v[16:19], v[40:43], 0
	v_mfma_f32_16x16x32_bf16 v[76:79], v[24:27], v[40:43], 0
	v_mfma_f32_16x16x32_bf16 v[80:83], v[16:19], v[48:51], 0
	v_mfma_f32_16x16x32_bf16 v[84:87], v[24:27], v[48:51], 0
	v_mfma_f32_16x16x32_bf16 v[88:91], v[16:19], v[56:59], 0
	v_mfma_f32_16x16x32_bf16 v[92:95], v[24:27], v[56:59], 0
	v_mfma_f32_16x16x32_bf16 v[64:67], v[20:23], v[36:39], v[64:67]
	v_mfma_f32_16x16x32_bf16 v[68:71], v[28:31], v[36:39], v[68:71]
	v_mfma_f32_16x16x32_bf16 v[72:75], v[20:23], v[44:47], v[72:75]
	v_mfma_f32_16x16x32_bf16 v[76:79], v[28:31], v[44:47], v[76:79]
	v_mfma_f32_16x16x32_bf16 v[80:83], v[20:23], v[52:55], v[80:83]
	v_mfma_f32_16x16x32_bf16 v[84:87], v[28:31], v[52:55], v[84:87]
	v_mfma_f32_16x16x32_bf16 v[88:91], v[20:23], v[60:63], v[88:91]
	v_mfma_f32_16x16x32_bf16 v[92:95], v[28:31], v[60:63], v[92:95]
	s_barrier
	s_add_i32 s79, s42, s53
	v_lshl_add_u64 v[112:113], v[12:13], 0, s[22:23]
	s_mov_b32 m0, s79
	ds_read_b128 v[96:99], v134
	ds_read_b128 v[100:103], v134 offset:1024
	ds_read_b128 v[104:107], v134 offset:2048
	ds_read_b128 v[108:111], v134 offset:3072
	global_load_lds_dwordx4 v[112:113], off
	v_lshl_add_u64 v[112:113], v[10:11], 0, s[22:23]
	s_add_i32 m0, s79, 0x2000
	s_nop 0
	global_load_lds_dwordx4 v[112:113], off
	s_barrier
	s_waitcnt lgkmcnt(0)
	s_waitcnt lgkmcnt(0)
	v_mfma_f32_16x16x32_bf16 v[112:115], v[96:99], v[32:35], 0
	v_mfma_f32_16x16x32_bf16 v[32:35], v[104:107], v[32:35], 0
	v_mfma_f32_16x16x32_bf16 v[112:115], v[100:103], v[36:39], v[112:115]
	v_mfma_f32_16x16x32_bf16 v[32:35], v[108:111], v[36:39], v[32:35]
	v_mfma_f32_16x16x32_bf16 v[36:39], v[96:99], v[40:43], 0
	v_mfma_f32_16x16x32_bf16 v[40:43], v[104:107], v[40:43], 0
	v_mfma_f32_16x16x32_bf16 v[36:39], v[100:103], v[44:47], v[36:39]
	v_mfma_f32_16x16x32_bf16 v[40:43], v[108:111], v[44:47], v[40:43]
	v_mfma_f32_16x16x32_bf16 v[44:47], v[96:99], v[48:51], 0
	v_mfma_f32_16x16x32_bf16 v[48:51], v[104:107], v[48:51], 0
	v_mfma_f32_16x16x32_bf16 v[44:47], v[100:103], v[52:55], v[44:47]
	v_mfma_f32_16x16x32_bf16 v[48:51], v[108:111], v[52:55], v[48:51]
	v_mfma_f32_16x16x32_bf16 v[52:55], v[96:99], v[56:59], 0
	v_mfma_f32_16x16x32_bf16 v[56:59], v[104:107], v[56:59], 0
	v_mfma_f32_16x16x32_bf16 v[52:55], v[100:103], v[60:63], v[52:55]
	v_mfma_f32_16x16x32_bf16 v[56:59], v[108:111], v[60:63], v[56:59]
	s_mov_b32 m0, s76
	v_lshl_add_u64 v[130:131], v[6:7], 0, s[22:23]
	s_barrier
	ds_read_b128 v[60:63], v14 offset:16384
	ds_read_b128 v[116:119], v14 offset:17408
	ds_read_b128 v[120:123], v14 offset:18432
	ds_read_b128 v[124:127], v14 offset:19456
	ds_read_b128 v[138:141], v14 offset:20480
	ds_read_b128 v[142:145], v14 offset:21504
	ds_read_b128 v[146:149], v14 offset:22528
	ds_read_b128 v[150:153], v14 offset:23552
	global_load_lds_dwordx4 v[130:131], off
	v_lshl_add_u64 v[130:131], v[8:9], 0, s[22:23]
	s_mov_b32 m0, s77
	s_nop 0
	global_load_lds_dwordx4 v[130:131], off
	s_barrier
	s_waitcnt lgkmcnt(0)
	s_waitcnt lgkmcnt(0)
	v_mfma_f32_16x16x32_bf16 v[154:157], v[16:19], v[60:63], 0
	v_mfma_f32_16x16x32_bf16 v[162:165], v[16:19], v[120:123], 0
	v_mfma_f32_16x16x32_bf16 v[170:173], v[16:19], v[138:141], 0
	v_mfma_f32_16x16x32_bf16 v[16:19], v[16:19], v[146:149], 0
	v_mfma_f32_16x16x32_bf16 v[154:157], v[20:23], v[116:119], v[154:157]
	v_mfma_f32_16x16x32_bf16 v[162:165], v[20:23], v[124:127], v[162:165]
	v_mfma_f32_16x16x32_bf16 v[170:173], v[20:23], v[142:145], v[170:173]
	v_mfma_f32_16x16x32_bf16 v[16:19], v[20:23], v[150:153], v[16:19]
	v_mfma_f32_16x16x32_bf16 v[20:23], v[24:27], v[146:149], 0
	v_mfma_f32_16x16x32_bf16 v[158:161], v[24:27], v[60:63], 0
	v_mfma_f32_16x16x32_bf16 v[166:169], v[24:27], v[120:123], 0
	v_mfma_f32_16x16x32_bf16 v[174:177], v[24:27], v[138:141], 0
	v_mfma_f32_16x16x32_bf16 v[20:23], v[28:31], v[150:153], v[20:23]
	v_mfma_f32_16x16x32_bf16 v[158:161], v[28:31], v[116:119], v[158:161]
	v_mfma_f32_16x16x32_bf16 v[166:169], v[28:31], v[124:127], v[166:169]
	v_mfma_f32_16x16x32_bf16 v[174:177], v[28:31], v[142:145], v[174:177]
	s_barrier
	s_add_u32 s76, s34, 0x10100
	s_addc_u32 s77, s35, 0
	s_add_i32 s53, s43, s53
	v_lshl_add_u64 v[24:25], s[76:77], 0, v[128:129]
	s_mov_b32 m0, s53
	s_nop 0
	global_load_lds_dwordx4 v[24:25], off
	v_lshl_add_u64 v[24:25], s[76:77], 0, v[4:5]
	s_add_i32 m0, s53, 0x2000
	s_nop 0
	global_load_lds_dwordx4 v[24:25], off
	s_waitcnt vmcnt(6)
	s_barrier
	v_mfma_f32_16x16x32_bf16 v[24:27], v[96:99], v[60:63], 0
	v_mfma_f32_16x16x32_bf16 v[28:31], v[104:107], v[60:63], 0
	v_mfma_f32_16x16x32_bf16 v[24:27], v[100:103], v[116:119], v[24:27]
	v_mfma_f32_16x16x32_bf16 v[28:31], v[108:111], v[116:119], v[28:31]
	v_mfma_f32_16x16x32_bf16 v[60:63], v[96:99], v[120:123], 0
	v_mfma_f32_16x16x32_bf16 v[116:119], v[104:107], v[120:123], 0
	v_mfma_f32_16x16x32_bf16 v[120:123], v[96:99], v[138:141], 0
	v_mfma_f32_16x16x32_bf16 v[96:99], v[96:99], v[146:149], 0
	v_mfma_f32_16x16x32_bf16 v[60:63], v[100:103], v[124:127], v[60:63]
	v_mfma_f32_16x16x32_bf16 v[116:119], v[108:111], v[124:127], v[116:119]
	v_mfma_f32_16x16x32_bf16 v[120:123], v[100:103], v[142:145], v[120:123]
	v_mfma_f32_16x16x32_bf16 v[124:127], v[104:107], v[138:141], 0
	v_mfma_f32_16x16x32_bf16 v[96:99], v[100:103], v[150:153], v[96:99]
	v_mfma_f32_16x16x32_bf16 v[100:103], v[104:107], v[146:149], 0
	v_mfma_f32_16x16x32_bf16 v[124:127], v[108:111], v[142:145], v[124:127]
	v_mfma_f32_16x16x32_bf16 v[100:103], v[108:111], v[150:153], v[100:103]
	s_barrier
	ds_read_b128 v[104:107], v135
	ds_read_b128 v[108:111], v135 offset:1024
	ds_read_b128 v[138:141], v135 offset:2048
	ds_read_b128 v[142:145], v135 offset:3072
	s_add_u32 s76, s30, 0x40100
	s_addc_u32 s77, s31, 0
	s_mov_b32 m0, s57
	v_lshl_add_u64 v[130:131], s[76:77], 0, v[0:1]
	ds_read_b128 v[146:149], v14 offset:32768
	ds_read_b128 v[150:153], v14 offset:33792
	ds_read_b128 v[178:181], v14 offset:34816
	ds_read_b128 v[192:195], v14 offset:35840
	ds_read_b128 v[196:199], v14 offset:36864
	ds_read_b128 v[200:203], v14 offset:37888
	ds_read_b128 v[204:207], v14 offset:38912
	ds_read_b128 v[208:211], v14 offset:39936
	global_load_lds_dwordx4 v[130:131], off
	v_lshl_add_u64 v[130:131], s[76:77], 0, v[2:3]
	s_mov_b32 m0, s52
	s_nop 0
	global_load_lds_dwordx4 v[130:131], off
	s_waitcnt lgkmcnt(8)
	s_barrier
	s_waitcnt lgkmcnt(0)
	s_waitcnt lgkmcnt(0)
	v_mfma_f32_16x16x32_bf16 v[64:67], v[104:107], v[146:149], v[64:67]
	v_mfma_f32_16x16x32_bf16 v[68:71], v[138:141], v[146:149], v[68:71]
	v_mfma_f32_16x16x32_bf16 v[72:75], v[104:107], v[178:181], v[72:75]
	v_mfma_f32_16x16x32_bf16 v[76:79], v[138:141], v[178:181], v[76:79]
	v_mfma_f32_16x16x32_bf16 v[80:83], v[104:107], v[196:199], v[80:83]
	v_mfma_f32_16x16x32_bf16 v[84:87], v[138:141], v[196:199], v[84:87]
	v_mfma_f32_16x16x32_bf16 v[88:91], v[104:107], v[204:207], v[88:91]
	v_mfma_f32_16x16x32_bf16 v[92:95], v[138:141], v[204:207], v[92:95]
	v_mfma_f32_16x16x32_bf16 v[64:67], v[108:111], v[150:153], v[64:67]
	v_mfma_f32_16x16x32_bf16 v[68:71], v[142:145], v[150:153], v[68:71]
	v_mfma_f32_16x16x32_bf16 v[72:75], v[108:111], v[192:195], v[72:75]
	v_mfma_f32_16x16x32_bf16 v[76:79], v[142:145], v[192:195], v[76:79]
	v_mfma_f32_16x16x32_bf16 v[80:83], v[108:111], v[200:203], v[80:83]
	v_mfma_f32_16x16x32_bf16 v[84:87], v[142:145], v[200:203], v[84:87]
	v_mfma_f32_16x16x32_bf16 v[88:91], v[108:111], v[208:211], v[88:91]
	v_mfma_f32_16x16x32_bf16 v[92:95], v[142:145], v[208:211], v[92:95]
	s_barrier
	s_mov_b32 m0, s74
	v_lshl_add_u64 v[12:13], v[12:13], 0, s[24:25]
	ds_read_b128 v[212:215], v184
	ds_read_b128 v[216:219], v184 offset:1024
	ds_read_b128 v[220:223], v184 offset:2048
	ds_read_b128 v[224:227], v184 offset:3072
	global_load_lds_dwordx4 v[12:13], off
	v_lshl_add_u64 v[10:11], v[10:11], 0, s[24:25]
	s_mov_b32 m0, s73
	s_nop 0
	global_load_lds_dwordx4 v[10:11], off
	s_barrier
	s_waitcnt lgkmcnt(0)
	s_waitcnt lgkmcnt(0)
	v_mfma_f32_16x16x32_bf16 v[10:13], v[212:215], v[146:149], v[112:115]
	v_mfma_f32_16x16x32_bf16 v[32:35], v[220:223], v[146:149], v[32:35]
	v_mfma_f32_16x16x32_bf16 v[36:39], v[212:215], v[178:181], v[36:39]
	v_mfma_f32_16x16x32_bf16 v[40:43], v[220:223], v[178:181], v[40:43]
	v_mfma_f32_16x16x32_bf16 v[44:47], v[212:215], v[196:199], v[44:47]
	v_mfma_f32_16x16x32_bf16 v[48:51], v[220:223], v[196:199], v[48:51]
	v_mfma_f32_16x16x32_bf16 v[52:55], v[212:215], v[204:207], v[52:55]
	v_mfma_f32_16x16x32_bf16 v[56:59], v[220:223], v[204:207], v[56:59]
	v_mfma_f32_16x16x32_bf16 v[10:13], v[216:219], v[150:153], v[10:13]
	v_mfma_f32_16x16x32_bf16 v[32:35], v[224:227], v[150:153], v[32:35]
	v_mfma_f32_16x16x32_bf16 v[36:39], v[216:219], v[192:195], v[36:39]
	v_mfma_f32_16x16x32_bf16 v[40:43], v[224:227], v[192:195], v[40:43]
	v_mfma_f32_16x16x32_bf16 v[44:47], v[216:219], v[200:203], v[44:47]
	v_mfma_f32_16x16x32_bf16 v[48:51], v[224:227], v[200:203], v[48:51]
	v_mfma_f32_16x16x32_bf16 v[52:55], v[216:219], v[208:211], v[52:55]
	v_mfma_f32_16x16x32_bf16 v[56:59], v[224:227], v[208:211], v[56:59]
	s_mov_b32 m0, s72
	v_lshl_add_u64 v[6:7], v[6:7], 0, s[24:25]
	s_barrier
	ds_read_b128 v[112:115], v14 offset:49152
	ds_read_b128 v[146:149], v14 offset:50176
	ds_read_b128 v[150:153], v14 offset:51200
	ds_read_b128 v[178:181], v14 offset:52224
	ds_read_b128 v[192:195], v14 offset:53248
	ds_read_b128 v[196:199], v14 offset:54272
	ds_read_b128 v[200:203], v14 offset:55296
	ds_read_b128 v[204:207], v14 offset:56320
	global_load_lds_dwordx4 v[6:7], off
	v_lshl_add_u64 v[6:7], v[8:9], 0, s[24:25]
	s_mov_b32 m0, s56
	s_nop 0
	global_load_lds_dwordx4 v[6:7], off
	s_barrier
	s_waitcnt lgkmcnt(0)
	s_waitcnt lgkmcnt(0)
	v_mfma_f32_16x16x32_bf16 v[6:9], v[104:107], v[112:115], v[154:157]
	v_mfma_f32_16x16x32_bf16 v[16:19], v[104:107], v[200:203], v[16:19]
	v_mfma_f32_16x16x32_bf16 v[20:23], v[138:141], v[200:203], v[20:23]
	v_mfma_f32_16x16x32_bf16 v[6:9], v[108:111], v[146:149], v[6:9]
	v_mfma_f32_16x16x32_bf16 v[154:157], v[138:141], v[112:115], v[158:161]
	v_mfma_f32_16x16x32_bf16 v[158:161], v[104:107], v[150:153], v[162:165]
	v_mfma_f32_16x16x32_bf16 v[162:165], v[138:141], v[150:153], v[166:169]
	v_mfma_f32_16x16x32_bf16 v[166:169], v[104:107], v[192:195], v[170:173]
	v_mfma_f32_16x16x32_bf16 v[170:173], v[138:141], v[192:195], v[174:177]
	v_mfma_f32_16x16x32_bf16 v[16:19], v[108:111], v[204:207], v[16:19]
	v_mfma_f32_16x16x32_bf16 v[20:23], v[142:145], v[204:207], v[20:23]
	v_mfma_f32_16x16x32_bf16 v[154:157], v[142:145], v[146:149], v[154:157]
	v_mfma_f32_16x16x32_bf16 v[158:161], v[108:111], v[178:181], v[158:161]
	v_mfma_f32_16x16x32_bf16 v[162:165], v[142:145], v[178:181], v[162:165]
	v_mfma_f32_16x16x32_bf16 v[166:169], v[108:111], v[196:199], v[166:169]
	v_mfma_f32_16x16x32_bf16 v[170:173], v[142:145], v[196:199], v[170:173]
	s_barrier
	s_add_u32 s34, s34, 0x10180
	s_addc_u32 s35, s35, 0
	s_mov_b32 m0, s51
	v_lshl_add_u64 v[104:105], s[34:35], 0, v[128:129]
	global_load_lds_dwordx4 v[104:105], off
	v_lshl_add_u64 v[4:5], s[34:35], 0, v[4:5]
	s_mov_b32 m0, s33
	s_nop 0
	global_load_lds_dwordx4 v[4:5], off
	s_waitcnt vmcnt(6)
	s_barrier
	v_mfma_f32_16x16x32_bf16 v[24:27], v[212:215], v[112:115], v[24:27]
	v_mfma_f32_16x16x32_bf16 v[28:31], v[220:223], v[112:115], v[28:31]
	v_mfma_f32_16x16x32_bf16 v[60:63], v[212:215], v[150:153], v[60:63]
	v_mfma_f32_16x16x32_bf16 v[104:107], v[220:223], v[150:153], v[116:119]
	v_mfma_f32_16x16x32_bf16 v[108:111], v[212:215], v[192:195], v[120:123]
	v_mfma_f32_16x16x32_bf16 v[112:115], v[220:223], v[192:195], v[124:127]
	v_mfma_f32_16x16x32_bf16 v[96:99], v[212:215], v[200:203], v[96:99]
	v_mfma_f32_16x16x32_bf16 v[100:103], v[220:223], v[200:203], v[100:103]
	v_mfma_f32_16x16x32_bf16 v[24:27], v[216:219], v[146:149], v[24:27]
	v_mfma_f32_16x16x32_bf16 v[28:31], v[224:227], v[146:149], v[28:31]
	v_mfma_f32_16x16x32_bf16 v[60:63], v[216:219], v[178:181], v[60:63]
	v_mfma_f32_16x16x32_bf16 v[104:107], v[224:227], v[178:181], v[104:107]
	v_mfma_f32_16x16x32_bf16 v[108:111], v[216:219], v[196:199], v[108:111]
	v_mfma_f32_16x16x32_bf16 v[112:115], v[224:227], v[196:199], v[112:115]
	v_mfma_f32_16x16x32_bf16 v[96:99], v[216:219], v[204:207], v[96:99]
	v_mfma_f32_16x16x32_bf16 v[100:103], v[224:227], v[204:207], v[100:103]
	s_add_u32 s30, s30, 0x40180
	s_addc_u32 s31, s31, 0
	s_mov_b32 m0, s78
	v_lshl_add_u64 v[0:1], s[30:31], 0, v[0:1]
	s_barrier
	ds_read_b128 v[116:119], v15
	ds_read_b128 v[120:123], v15 offset:1024
	ds_read_b128 v[124:127], v15 offset:2048
	ds_read_b128 v[138:141], v15 offset:3072
	ds_read_b128 v[142:145], v14
	ds_read_b128 v[146:149], v14 offset:1024
	ds_read_b128 v[150:153], v14 offset:2048
	ds_read_b128 v[174:177], v14 offset:3072
	ds_read_b128 v[178:181], v14 offset:4096
	ds_read_b128 v[192:195], v14 offset:5120
	ds_read_b128 v[196:199], v14 offset:6144
	ds_read_b128 v[200:203], v14 offset:7168
	global_load_lds_dwordx4 v[0:1], off
	v_lshl_add_u64 v[0:1], s[30:31], 0, v[2:3]
	s_mov_b32 m0, s75
	s_nop 0
	global_load_lds_dwordx4 v[0:1], off
	s_barrier
	s_waitcnt lgkmcnt(0)
	s_waitcnt lgkmcnt(0)
	v_mfma_f32_16x16x32_bf16 v[0:3], v[116:119], v[142:145], v[64:67]
	v_mfma_f32_16x16x32_bf16 v[64:67], v[124:127], v[142:145], v[68:71]
	v_mfma_f32_16x16x32_bf16 v[68:71], v[116:119], v[150:153], v[72:75]
	v_mfma_f32_16x16x32_bf16 v[72:75], v[124:127], v[150:153], v[76:79]
	v_mfma_f32_16x16x32_bf16 v[76:79], v[116:119], v[178:181], v[80:83]
	v_mfma_f32_16x16x32_bf16 v[80:83], v[124:127], v[178:181], v[84:87]
	v_mfma_f32_16x16x32_bf16 v[84:87], v[116:119], v[196:199], v[88:91]
	v_mfma_f32_16x16x32_bf16 v[0:3], v[120:123], v[146:149], v[0:3]
	v_mfma_f32_16x16x32_bf16 v[64:67], v[138:141], v[146:149], v[64:67]
	v_mfma_f32_16x16x32_bf16 v[68:71], v[120:123], v[174:177], v[68:71]
	v_mfma_f32_16x16x32_bf16 v[72:75], v[138:141], v[174:177], v[72:75]
	v_mfma_f32_16x16x32_bf16 v[76:79], v[120:123], v[192:195], v[76:79]
	v_mfma_f32_16x16x32_bf16 v[80:83], v[138:141], v[192:195], v[80:83]
	v_mfma_f32_16x16x32_bf16 v[88:91], v[120:123], v[200:203], v[84:87]
	v_mfma_f32_16x16x32_bf16 v[84:87], v[124:127], v[196:199], v[92:95]
	v_mfma_f32_16x16x32_bf16 v[204:207], v[138:141], v[200:203], v[84:87]
	s_barrier
	s_nop 4
	ds_read_b128 v[84:87], v134
	ds_read_b128 v[92:95], v134 offset:1024
	ds_read_b128 v[208:211], v134 offset:2048
	ds_read_b128 v[212:215], v134 offset:3072
	s_barrier
	s_waitcnt lgkmcnt(0)
	s_waitcnt lgkmcnt(0)
	v_mfma_f32_16x16x32_bf16 v[10:13], v[84:87], v[142:145], v[10:13]
	v_mfma_f32_16x16x32_bf16 v[32:35], v[208:211], v[142:145], v[32:35]
	v_mfma_f32_16x16x32_bf16 v[36:39], v[84:87], v[150:153], v[36:39]
	v_mfma_f32_16x16x32_bf16 v[40:43], v[208:211], v[150:153], v[40:43]
	v_mfma_f32_16x16x32_bf16 v[44:47], v[84:87], v[178:181], v[44:47]
	v_mfma_f32_16x16x32_bf16 v[48:51], v[208:211], v[178:181], v[48:51]
	v_mfma_f32_16x16x32_bf16 v[52:55], v[84:87], v[196:199], v[52:55]
	v_mfma_f32_16x16x32_bf16 v[56:59], v[208:211], v[196:199], v[56:59]
	v_mfma_f32_16x16x32_bf16 v[10:13], v[92:95], v[146:149], v[10:13]
	v_mfma_f32_16x16x32_bf16 v[32:35], v[212:215], v[146:149], v[32:35]
	v_mfma_f32_16x16x32_bf16 v[36:39], v[92:95], v[174:177], v[36:39]
	v_mfma_f32_16x16x32_bf16 v[40:43], v[212:215], v[174:177], v[40:43]
	v_mfma_f32_16x16x32_bf16 v[44:47], v[92:95], v[192:195], v[44:47]
	v_mfma_f32_16x16x32_bf16 v[48:51], v[212:215], v[192:195], v[48:51]
	v_mfma_f32_16x16x32_bf16 v[52:55], v[92:95], v[200:203], v[52:55]
	v_mfma_f32_16x16x32_bf16 v[56:59], v[212:215], v[200:203], v[56:59]
	s_barrier
	ds_read_b128 v[142:145], v14 offset:16384
	ds_read_b128 v[146:149], v14 offset:17408
	ds_read_b128 v[150:153], v14 offset:18432
	ds_read_b128 v[174:177], v14 offset:19456
	ds_read_b128 v[178:181], v14 offset:20480
	ds_read_b128 v[192:195], v14 offset:21504
	ds_read_b128 v[196:199], v14 offset:22528
	ds_read_b128 v[200:203], v14 offset:23552
	s_waitcnt vmcnt(4)
	s_barrier
	s_waitcnt lgkmcnt(0)
	s_waitcnt lgkmcnt(0)
	v_mfma_f32_16x16x32_bf16 v[4:7], v[116:119], v[142:145], v[6:9]
	v_mfma_f32_16x16x32_bf16 v[16:19], v[116:119], v[196:199], v[16:19]
	v_mfma_f32_16x16x32_bf16 v[20:23], v[124:127], v[196:199], v[20:23]
	v_mfma_f32_16x16x32_bf16 v[4:7], v[120:123], v[146:149], v[4:7]
	v_mfma_f32_16x16x32_bf16 v[154:157], v[124:127], v[142:145], v[154:157]
	v_mfma_f32_16x16x32_bf16 v[158:161], v[116:119], v[150:153], v[158:161]
	v_mfma_f32_16x16x32_bf16 v[162:165], v[124:127], v[150:153], v[162:165]
	v_mfma_f32_16x16x32_bf16 v[166:169], v[116:119], v[178:181], v[166:169]
	v_mfma_f32_16x16x32_bf16 v[170:173], v[124:127], v[178:181], v[170:173]
	v_mfma_f32_16x16x32_bf16 v[16:19], v[120:123], v[200:203], v[16:19]
	v_mfma_f32_16x16x32_bf16 v[20:23], v[138:141], v[200:203], v[20:23]
	v_mfma_f32_16x16x32_bf16 v[154:157], v[138:141], v[146:149], v[154:157]
	v_mfma_f32_16x16x32_bf16 v[158:161], v[120:123], v[174:177], v[158:161]
	v_mfma_f32_16x16x32_bf16 v[162:165], v[138:141], v[174:177], v[162:165]
	v_mfma_f32_16x16x32_bf16 v[166:169], v[120:123], v[192:195], v[166:169]
	v_mfma_f32_16x16x32_bf16 v[170:173], v[138:141], v[192:195], v[170:173]
	v_mfma_f32_16x16x32_bf16 v[24:27], v[84:87], v[142:145], v[24:27]
	v_mfma_f32_16x16x32_bf16 v[138:141], v[92:95], v[146:149], v[24:27]
	v_mfma_f32_16x16x32_bf16 v[24:27], v[208:211], v[142:145], v[28:31]
	v_mfma_f32_16x16x32_bf16 v[142:145], v[212:215], v[146:149], v[24:27]
	v_mfma_f32_16x16x32_bf16 v[24:27], v[84:87], v[150:153], v[60:63]
	v_mfma_f32_16x16x32_bf16 v[146:149], v[92:95], v[174:177], v[24:27]
	v_mfma_f32_16x16x32_bf16 v[24:27], v[208:211], v[150:153], v[104:107]
	v_mfma_f32_16x16x32_bf16 v[150:153], v[212:215], v[174:177], v[24:27]
	v_mfma_f32_16x16x32_bf16 v[24:27], v[84:87], v[178:181], v[108:111]
	v_mfma_f32_16x16x32_bf16 v[174:177], v[92:95], v[192:195], v[24:27]
	v_mfma_f32_16x16x32_bf16 v[24:27], v[208:211], v[178:181], v[112:115]
	v_mfma_f32_16x16x32_bf16 v[178:181], v[212:215], v[192:195], v[24:27]
	v_mfma_f32_16x16x32_bf16 v[24:27], v[84:87], v[196:199], v[96:99]
	v_mfma_f32_16x16x32_bf16 v[192:195], v[92:95], v[200:203], v[24:27]
	v_mfma_f32_16x16x32_bf16 v[24:27], v[208:211], v[196:199], v[100:103]
	v_mfma_f32_16x16x32_bf16 v[196:199], v[212:215], v[200:203], v[24:27]
	s_barrier
	ds_read_b128 v[200:203], v135
	ds_read_b128 v[208:211], v135 offset:1024
	ds_read_b128 v[212:215], v135 offset:2048
	ds_read_b128 v[216:219], v135 offset:3072
	s_nop 0
	ds_read_b128 v[24:27], v14 offset:32768
	ds_read_b128 v[28:31], v14 offset:33792
	ds_read_b128 v[60:63], v14 offset:34816
	ds_read_b128 v[96:99], v14 offset:35840
	ds_read_b128 v[220:223], v14 offset:36864
	ds_read_b128 v[224:227], v14 offset:37888
	ds_read_b128 v[228:231], v14 offset:38912
	ds_read_b128 v[232:235], v14 offset:39936
	s_waitcnt vmcnt(2)
	s_barrier
	s_waitcnt lgkmcnt(0)
	s_waitcnt lgkmcnt(0)
	v_mfma_f32_16x16x32_bf16 v[0:3], v[200:203], v[24:27], v[0:3]
	v_mfma_f32_16x16x32_bf16 v[124:127], v[208:211], v[28:31], v[0:3]
	v_mfma_f32_16x16x32_bf16 v[0:3], v[212:215], v[24:27], v[64:67]
	v_mfma_f32_16x16x32_bf16 v[116:119], v[216:219], v[28:31], v[0:3]
	v_mfma_f32_16x16x32_bf16 v[0:3], v[200:203], v[60:63], v[68:71]
	v_mfma_f32_16x16x32_bf16 v[108:111], v[208:211], v[96:99], v[0:3]
	v_mfma_f32_16x16x32_bf16 v[0:3], v[212:215], v[60:63], v[72:75]
	v_mfma_f32_16x16x32_bf16 v[100:103], v[216:219], v[96:99], v[0:3]
	v_mfma_f32_16x16x32_bf16 v[0:3], v[200:203], v[220:223], v[76:79]
	v_mfma_f32_16x16x32_bf16 v[92:95], v[208:211], v[224:227], v[0:3]
	v_mfma_f32_16x16x32_bf16 v[0:3], v[212:215], v[220:223], v[80:83]
	v_mfma_f32_16x16x32_bf16 v[84:87], v[216:219], v[224:227], v[0:3]
	v_mfma_f32_16x16x32_bf16 v[0:3], v[200:203], v[228:231], v[88:91]
	v_mfma_f32_16x16x32_bf16 v[76:79], v[208:211], v[232:235], v[0:3]
	v_mfma_f32_16x16x32_bf16 v[0:3], v[212:215], v[228:231], v[204:207]
	v_mfma_f32_16x16x32_bf16 v[68:71], v[216:219], v[232:235], v[0:3]
	s_barrier
	s_nop 4
	ds_read_b128 v[0:3], v184
	ds_read_b128 v[204:207], v184 offset:1024
	ds_read_b128 v[236:239], v184 offset:2048
	ds_read_b128 v[240:243], v184 offset:3072
	s_waitcnt vmcnt(0)
	s_barrier
	s_waitcnt lgkmcnt(0)
	s_waitcnt lgkmcnt(0)
	v_mfma_f32_16x16x32_bf16 v[8:11], v[0:3], v[24:27], v[10:13]
	v_mfma_f32_16x16x32_bf16 v[120:123], v[204:207], v[28:31], v[8:11]
	v_mfma_f32_16x16x32_bf16 v[8:11], v[236:239], v[24:27], v[32:35]
	v_mfma_f32_16x16x32_bf16 v[112:115], v[240:243], v[28:31], v[8:11]
	v_mfma_f32_16x16x32_bf16 v[8:11], v[0:3], v[60:63], v[36:39]
	v_mfma_f32_16x16x32_bf16 v[104:107], v[204:207], v[96:99], v[8:11]
	v_mfma_f32_16x16x32_bf16 v[8:11], v[236:239], v[60:63], v[40:43]
	v_mfma_f32_16x16x32_bf16 v[96:99], v[240:243], v[96:99], v[8:11]
	v_mfma_f32_16x16x32_bf16 v[8:11], v[0:3], v[220:223], v[44:47]
	v_mfma_f32_16x16x32_bf16 v[88:91], v[204:207], v[224:227], v[8:11]
	v_mfma_f32_16x16x32_bf16 v[8:11], v[236:239], v[220:223], v[48:51]
	v_mfma_f32_16x16x32_bf16 v[80:83], v[240:243], v[224:227], v[8:11]
	v_mfma_f32_16x16x32_bf16 v[8:11], v[0:3], v[228:231], v[52:55]
	v_mfma_f32_16x16x32_bf16 v[72:75], v[204:207], v[232:235], v[8:11]
	v_mfma_f32_16x16x32_bf16 v[8:11], v[236:239], v[228:231], v[56:59]
	v_mfma_f32_16x16x32_bf16 v[64:67], v[240:243], v[232:235], v[8:11]
	s_barrier
	ds_read_b128 v[32:35], v14 offset:49152
	ds_read_b128 v[36:39], v14 offset:50176
	ds_read_b128 v[220:223], v14 offset:51200
	ds_read_b128 v[224:227], v14 offset:52224
	ds_read_b128 v[228:231], v14 offset:53248
	ds_read_b128 v[232:235], v14 offset:54272
	ds_read_b128 v[244:247], v14 offset:55296
	ds_read_b128 v[248:251], v14 offset:56320
	s_barrier
	s_waitcnt lgkmcnt(0)
	s_waitcnt lgkmcnt(0)
	v_mfma_f32_16x16x32_bf16 v[4:7], v[200:203], v[32:35], v[4:7]
	v_mfma_f32_16x16x32_bf16 v[60:63], v[208:211], v[36:39], v[4:7]
	v_mfma_f32_16x16x32_bf16 v[4:7], v[212:215], v[32:35], v[154:157]
	v_mfma_f32_16x16x32_bf16 v[56:59], v[216:219], v[36:39], v[4:7]
	v_mfma_f32_16x16x32_bf16 v[4:7], v[200:203], v[220:223], v[158:161]
	v_mfma_f32_16x16x32_bf16 v[44:47], v[208:211], v[224:227], v[4:7]
	v_mfma_f32_16x16x32_bf16 v[4:7], v[212:215], v[220:223], v[162:165]
	v_mfma_f32_16x16x32_bf16 v[40:43], v[216:219], v[224:227], v[4:7]
	v_mfma_f32_16x16x32_bf16 v[4:7], v[200:203], v[228:231], v[166:169]
	v_mfma_f32_16x16x32_bf16 v[28:31], v[208:211], v[232:235], v[4:7]
	v_mfma_f32_16x16x32_bf16 v[4:7], v[212:215], v[228:231], v[170:173]
	v_mfma_f32_16x16x32_bf16 v[24:27], v[216:219], v[232:235], v[4:7]
	v_mfma_f32_16x16x32_bf16 v[4:7], v[200:203], v[244:247], v[16:19]
	v_mfma_f32_16x16x32_bf16 v[12:15], v[208:211], v[248:251], v[4:7]
	v_mfma_f32_16x16x32_bf16 v[4:7], v[212:215], v[244:247], v[20:23]
	v_mfma_f32_16x16x32_bf16 v[8:11], v[216:219], v[248:251], v[4:7]
	v_mfma_f32_16x16x32_bf16 v[4:7], v[0:3], v[32:35], v[138:141]
	v_mfma_f32_16x16x32_bf16 v[52:55], v[204:207], v[36:39], v[4:7]
	v_mfma_f32_16x16x32_bf16 v[4:7], v[236:239], v[32:35], v[142:145]
	v_mfma_f32_16x16x32_bf16 v[48:51], v[240:243], v[36:39], v[4:7]
	v_mfma_f32_16x16x32_bf16 v[4:7], v[0:3], v[220:223], v[146:149]
	v_mfma_f32_16x16x32_bf16 v[36:39], v[204:207], v[224:227], v[4:7]
	v_mfma_f32_16x16x32_bf16 v[4:7], v[236:239], v[220:223], v[150:153]
	v_mfma_f32_16x16x32_bf16 v[32:35], v[240:243], v[224:227], v[4:7]
	v_mfma_f32_16x16x32_bf16 v[4:7], v[0:3], v[228:231], v[174:177]
	v_mfma_f32_16x16x32_bf16 v[20:23], v[204:207], v[232:235], v[4:7]
	v_mfma_f32_16x16x32_bf16 v[4:7], v[236:239], v[228:231], v[178:181]
	v_mfma_f32_16x16x32_bf16 v[0:3], v[0:3], v[244:247], v[192:195]
	v_mfma_f32_16x16x32_bf16 v[16:19], v[240:243], v[232:235], v[4:7]
	v_mfma_f32_16x16x32_bf16 v[4:7], v[204:207], v[248:251], v[0:3]
	v_mfma_f32_16x16x32_bf16 v[0:3], v[236:239], v[244:247], v[196:199]
	v_mfma_f32_16x16x32_bf16 v[0:3], v[240:243], v[248:251], v[0:3]
	s_cmpk_gt_u32 s27, 0xff
	s_barrier
	s_cbranch_scc1 .LBB0_989
	s_barrier

.LBB0_1023:
	v_and_b32_e32 v11, 15, v10
	v_and_b32_e32 v12, 48, v10
	v_lshlrev_b32_e32 v10, 2, v10
	v_lshlrev_b32_e32 v11, 6, v11
	v_and_b32_e32 v10, 32, v10
	s_lshl_b32 s31, s31, 12
	v_or_b32_e32 v13, v11, v12
	v_bitop3_b32 v11, v11, v10, v12 bitop3:0x36
	s_lshl_b32 s30, s30, 13
	s_and_b32 s31, s31, 0x3000
	s_add_i32 s56, s40, s51
	v_or_b32_e32 v12, s31, v11
	v_bitop3_b32 v13, v13, s30, v10 bitop3:0xde
	v_lshl_add_u64 v[10:11], v[6:7], 0, s[20:21]
	s_mov_b32 m0, s56
	s_add_i32 s53, s56, 0x2000
	v_lshl_add_u64 v[4:5], s[0:1], 0, v[128:129]
	s_waitcnt vmcnt(2)
	s_barrier
	global_load_lds_dwordx4 v[10:11], off
	v_lshl_add_u64 v[10:11], v[8:9], 0, s[20:21]
	s_mov_b32 m0, s53
	s_add_i32 s52, s73, 0x8000
	s_add_i32 s34, s73, 0xa000
	v_lshl_add_u64 v[2:3], s[0:1], 0, v[0:1]
	global_load_lds_dwordx4 v[10:11], off
	v_lshl_add_u64 v[10:11], v[4:5], 0, s[20:21]
	s_mov_b32 m0, s52
	s_add_u32 s76, s28, 0x10080
	v_lshl_add_u64 v[10:11], v[2:3], 0, s[20:21]
	s_mov_b32 m0, s34
	s_addc_u32 s77, s29, 0
	s_add_i32 s31, s41, s51
	v_lshl_add_u64 v[10:11], s[76:77], 0, v[128:129]
	s_mov_b32 m0, s31
	s_add_i32 s30, s31, 0x2000
	global_load_lds_dwordx4 v[10:11], off
	v_lshl_add_u64 v[10:11], s[76:77], 0, v[0:1]
	s_mov_b32 m0, s30
	v_add_u32_e32 v134, s43, v12
	global_load_lds_dwordx4 v[10:11], off
	v_add_u32_e32 v11, s42, v12
	s_waitcnt vmcnt(4)
	s_barrier
	v_add_u32_e32 v10, 0, v13
	v_add_u32_e32 v135, s40, v12
	v_add_u32_e32 v184, s41, v12
	ds_read_b128 v[12:15], v11
	ds_read_b128 v[16:19], v11 offset:1024
	ds_read_b128 v[20:23], v11 offset:2048
	ds_read_b128 v[24:27], v11 offset:3072
	s_add_i32 s72, s73, 0xc000
	v_lshl_add_u64 v[60:61], s[14:15], 0, v[128:129]
	s_mov_b32 m0, s72
	s_add_i32 s57, s73, 0xe000
	ds_read_b128 v[28:31], v10
	ds_read_b128 v[32:35], v10 offset:1024
	ds_read_b128 v[36:39], v10 offset:2048
	ds_read_b128 v[40:43], v10 offset:3072
	ds_read_b128 v[44:47], v10 offset:4096
	ds_read_b128 v[48:51], v10 offset:5120
	ds_read_b128 v[52:55], v10 offset:6144
	ds_read_b128 v[56:59], v10 offset:7168
	v_lshl_add_u64 v[60:61], s[14:15], 0, v[0:1]
	s_mov_b32 m0, s57
	s_nop 0
	s_waitcnt lgkmcnt(8)
	s_barrier
	s_waitcnt lgkmcnt(0)
	s_waitcnt lgkmcnt(0)
	v_mfma_f32_16x16x32_bf16 v[60:63], v[12:15], v[28:31], 0
	v_mfma_f32_16x16x32_bf16 v[64:67], v[20:23], v[28:31], 0
	v_mfma_f32_16x16x32_bf16 v[68:71], v[12:15], v[36:39], 0
	v_mfma_f32_16x16x32_bf16 v[72:75], v[20:23], v[36:39], 0
	v_mfma_f32_16x16x32_bf16 v[76:79], v[12:15], v[44:47], 0
	v_mfma_f32_16x16x32_bf16 v[80:83], v[20:23], v[44:47], 0
	v_mfma_f32_16x16x32_bf16 v[84:87], v[12:15], v[52:55], 0
	v_mfma_f32_16x16x32_bf16 v[88:91], v[20:23], v[52:55], 0
	v_mfma_f32_16x16x32_bf16 v[60:63], v[16:19], v[32:35], v[60:63]
	v_mfma_f32_16x16x32_bf16 v[64:67], v[24:27], v[32:35], v[64:67]
	v_mfma_f32_16x16x32_bf16 v[68:71], v[16:19], v[40:43], v[68:71]
	v_mfma_f32_16x16x32_bf16 v[72:75], v[24:27], v[40:43], v[72:75]
	v_mfma_f32_16x16x32_bf16 v[76:79], v[16:19], v[48:51], v[76:79]
	v_mfma_f32_16x16x32_bf16 v[80:83], v[24:27], v[48:51], v[80:83]
	v_mfma_f32_16x16x32_bf16 v[84:87], v[16:19], v[56:59], v[84:87]
	v_mfma_f32_16x16x32_bf16 v[88:91], v[24:27], v[56:59], v[88:91]
	s_barrier
	s_add_i32 s75, s42, s51
	v_lshl_add_u64 v[108:109], v[6:7], 0, s[22:23]
	s_mov_b32 m0, s75
	ds_read_b128 v[92:95], v134
	ds_read_b128 v[96:99], v134 offset:1024
	ds_read_b128 v[100:103], v134 offset:2048
	ds_read_b128 v[104:107], v134 offset:3072
	global_load_lds_dwordx4 v[108:109], off
	v_lshl_add_u64 v[108:109], v[8:9], 0, s[22:23]
	s_add_i32 m0, s75, 0x2000
	s_nop 0
	global_load_lds_dwordx4 v[108:109], off
	s_barrier
	s_waitcnt lgkmcnt(0)
	s_waitcnt lgkmcnt(0)
	v_mfma_f32_16x16x32_bf16 v[108:111], v[92:95], v[28:31], 0
	v_mfma_f32_16x16x32_bf16 v[28:31], v[100:103], v[28:31], 0
	v_mfma_f32_16x16x32_bf16 v[108:111], v[96:99], v[32:35], v[108:111]
	v_mfma_f32_16x16x32_bf16 v[28:31], v[104:107], v[32:35], v[28:31]
	v_mfma_f32_16x16x32_bf16 v[32:35], v[92:95], v[36:39], 0
	v_mfma_f32_16x16x32_bf16 v[36:39], v[100:103], v[36:39], 0
	v_mfma_f32_16x16x32_bf16 v[32:35], v[96:99], v[40:43], v[32:35]
	v_mfma_f32_16x16x32_bf16 v[36:39], v[104:107], v[40:43], v[36:39]
	v_mfma_f32_16x16x32_bf16 v[40:43], v[92:95], v[44:47], 0
	v_mfma_f32_16x16x32_bf16 v[44:47], v[100:103], v[44:47], 0
	v_mfma_f32_16x16x32_bf16 v[40:43], v[96:99], v[48:51], v[40:43]
	v_mfma_f32_16x16x32_bf16 v[44:47], v[104:107], v[48:51], v[44:47]
	v_mfma_f32_16x16x32_bf16 v[48:51], v[92:95], v[52:55], 0
	v_mfma_f32_16x16x32_bf16 v[52:55], v[100:103], v[52:55], 0
	v_mfma_f32_16x16x32_bf16 v[48:51], v[96:99], v[56:59], v[48:51]
	v_mfma_f32_16x16x32_bf16 v[52:55], v[104:107], v[56:59], v[52:55]
	s_mov_b32 m0, s73
	v_lshl_add_u64 v[130:131], v[4:5], 0, s[22:23]
	s_barrier
	ds_read_b128 v[56:59], v10 offset:16384
	ds_read_b128 v[112:115], v10 offset:17408
	ds_read_b128 v[116:119], v10 offset:18432
	ds_read_b128 v[120:123], v10 offset:19456
	ds_read_b128 v[124:127], v10 offset:20480
	ds_read_b128 v[138:141], v10 offset:21504
	ds_read_b128 v[142:145], v10 offset:22528
	ds_read_b128 v[146:149], v10 offset:23552
	s_bitcmp1_b32 s100, 1
	s_cbranch_scc1 .Lpv1_a
	ds_write_b64 v248, v[224:225]
	ds_write_b64 v249, v[226:227]
	ds_write_b64 v248, v[228:229] offset:2048
	ds_write_b64 v249, v[230:231] offset:2048
	ds_write_b64 v248, v[232:233] offset:4096
	ds_write_b64 v249, v[234:235] offset:4096
	ds_write_b64 v248, v[236:237] offset:6144
	ds_write_b64 v249, v[238:239] offset:6144
.Lpv1_a:
	v_lshl_add_u64 v[130:131], v[2:3], 0, s[22:23]
	s_mov_b32 m0, s74
	s_nop 0
	s_barrier
	s_waitcnt lgkmcnt(0)
	s_waitcnt lgkmcnt(0)
	v_mfma_f32_16x16x32_bf16 v[150:153], v[12:15], v[56:59], 0
	v_mfma_f32_16x16x32_bf16 v[158:161], v[12:15], v[116:119], 0
	v_mfma_f32_16x16x32_bf16 v[166:169], v[12:15], v[124:127], 0
	v_mfma_f32_16x16x32_bf16 v[12:15], v[12:15], v[142:145], 0
	v_mfma_f32_16x16x32_bf16 v[150:153], v[16:19], v[112:115], v[150:153]
	v_mfma_f32_16x16x32_bf16 v[158:161], v[16:19], v[120:123], v[158:161]
	v_mfma_f32_16x16x32_bf16 v[166:169], v[16:19], v[138:141], v[166:169]
	v_mfma_f32_16x16x32_bf16 v[12:15], v[16:19], v[146:149], v[12:15]
	v_mfma_f32_16x16x32_bf16 v[16:19], v[20:23], v[142:145], 0
	v_mfma_f32_16x16x32_bf16 v[154:157], v[20:23], v[56:59], 0
	v_mfma_f32_16x16x32_bf16 v[162:165], v[20:23], v[116:119], 0
	v_mfma_f32_16x16x32_bf16 v[170:173], v[20:23], v[124:127], 0
	v_mfma_f32_16x16x32_bf16 v[16:19], v[24:27], v[146:149], v[16:19]
	v_mfma_f32_16x16x32_bf16 v[154:157], v[24:27], v[112:115], v[154:157]
	v_mfma_f32_16x16x32_bf16 v[162:165], v[24:27], v[120:123], v[162:165]
	v_mfma_f32_16x16x32_bf16 v[170:173], v[24:27], v[138:141], v[170:173]
	s_barrier
	s_add_u32 s74, s28, 0x10100
	s_addc_u32 s75, s29, 0
	s_add_i32 s51, s43, s51
	v_lshl_add_u64 v[20:21], s[74:75], 0, v[128:129]
	s_mov_b32 m0, s51
	s_nop 0
	global_load_lds_dwordx4 v[20:21], off
	v_lshl_add_u64 v[20:21], s[74:75], 0, v[0:1]
	s_add_i32 m0, s51, 0x2000
	s_nop 0
	global_load_lds_dwordx4 v[20:21], off
	s_waitcnt vmcnt(4)
	s_barrier
	v_mfma_f32_16x16x32_bf16 v[20:23], v[92:95], v[56:59], 0
	v_mfma_f32_16x16x32_bf16 v[24:27], v[100:103], v[56:59], 0
	v_mfma_f32_16x16x32_bf16 v[20:23], v[96:99], v[112:115], v[20:23]
	v_mfma_f32_16x16x32_bf16 v[24:27], v[104:107], v[112:115], v[24:27]
	v_mfma_f32_16x16x32_bf16 v[56:59], v[92:95], v[116:119], 0
	v_mfma_f32_16x16x32_bf16 v[112:115], v[100:103], v[116:119], 0
	v_mfma_f32_16x16x32_bf16 v[116:119], v[92:95], v[124:127], 0
	v_mfma_f32_16x16x32_bf16 v[92:95], v[92:95], v[142:145], 0
	v_mfma_f32_16x16x32_bf16 v[56:59], v[96:99], v[120:123], v[56:59]
	v_mfma_f32_16x16x32_bf16 v[112:115], v[104:107], v[120:123], v[112:115]
	v_mfma_f32_16x16x32_bf16 v[116:119], v[96:99], v[138:141], v[116:119]
	v_mfma_f32_16x16x32_bf16 v[120:123], v[100:103], v[124:127], 0
	v_mfma_f32_16x16x32_bf16 v[92:95], v[96:99], v[146:149], v[92:95]
	v_mfma_f32_16x16x32_bf16 v[96:99], v[100:103], v[142:145], 0
	v_mfma_f32_16x16x32_bf16 v[120:123], v[104:107], v[138:141], v[120:123]
	v_mfma_f32_16x16x32_bf16 v[96:99], v[104:107], v[146:149], v[96:99]
	s_barrier
	ds_read_b128 v[100:103], v135
	ds_read_b128 v[104:107], v135 offset:1024
	ds_read_b128 v[124:127], v135 offset:2048
	ds_read_b128 v[138:141], v135 offset:3072
	s_mov_b32 m0, s35
	v_lshl_add_u64 v[130:131], s[16:17], 0, v[128:129]
	ds_read_b128 v[142:145], v10 offset:32768
	ds_read_b128 v[146:149], v10 offset:33792
	ds_read_b128 v[174:177], v10 offset:34816
	ds_read_b128 v[178:181], v10 offset:35840
	ds_read_b128 v[192:195], v10 offset:36864
	ds_read_b128 v[196:199], v10 offset:37888
	ds_read_b128 v[200:203], v10 offset:38912
	ds_read_b128 v[204:207], v10 offset:39936
	s_bitcmp1_b32 s100, 1
	s_cbranch_scc1 .Lpv1_b
	ds_write_b64 v248, v[208:209] offset:16384
	ds_write_b64 v249, v[210:211] offset:16384
	ds_write_b64 v248, v[212:213] offset:18432
	ds_write_b64 v249, v[214:215] offset:18432
	ds_write_b64 v248, v[216:217] offset:20480
	ds_write_b64 v249, v[218:219] offset:20480
	ds_write_b64 v248, v[220:221] offset:22528
	ds_write_b64 v249, v[222:223] offset:22528
.Lpv1_b:
	v_lshl_add_u64 v[130:131], s[16:17], 0, v[0:1]
	s_mov_b32 m0, s33
	s_nop 0
	s_waitcnt lgkmcnt(8)
	s_barrier
	s_waitcnt lgkmcnt(0)
	s_waitcnt lgkmcnt(0)
	v_mfma_f32_16x16x32_bf16 v[60:63], v[100:103], v[142:145], v[60:63]
	v_mfma_f32_16x16x32_bf16 v[64:67], v[124:127], v[142:145], v[64:67]
	v_mfma_f32_16x16x32_bf16 v[68:71], v[100:103], v[174:177], v[68:71]
	v_mfma_f32_16x16x32_bf16 v[72:75], v[124:127], v[174:177], v[72:75]
	v_mfma_f32_16x16x32_bf16 v[76:79], v[100:103], v[192:195], v[76:79]
	v_mfma_f32_16x16x32_bf16 v[80:83], v[124:127], v[192:195], v[80:83]
	v_mfma_f32_16x16x32_bf16 v[84:87], v[100:103], v[200:203], v[84:87]
	v_mfma_f32_16x16x32_bf16 v[88:91], v[124:127], v[200:203], v[88:91]
	v_mfma_f32_16x16x32_bf16 v[60:63], v[104:107], v[146:149], v[60:63]
	v_mfma_f32_16x16x32_bf16 v[64:67], v[138:141], v[146:149], v[64:67]
	v_mfma_f32_16x16x32_bf16 v[68:71], v[104:107], v[178:181], v[68:71]
	v_mfma_f32_16x16x32_bf16 v[72:75], v[138:141], v[178:181], v[72:75]
	v_mfma_f32_16x16x32_bf16 v[76:79], v[104:107], v[196:199], v[76:79]
	v_mfma_f32_16x16x32_bf16 v[80:83], v[138:141], v[196:199], v[80:83]
	v_mfma_f32_16x16x32_bf16 v[84:87], v[104:107], v[204:207], v[84:87]
	v_mfma_f32_16x16x32_bf16 v[88:91], v[138:141], v[204:207], v[88:91]
	s_barrier
	s_mov_b32 m0, s56
	v_lshl_add_u64 v[6:7], v[6:7], 0, s[24:25]
	ds_read_b128 v[208:211], v184
	ds_read_b128 v[212:215], v184 offset:1024
	ds_read_b128 v[216:219], v184 offset:2048
	ds_read_b128 v[220:223], v184 offset:3072
	global_load_lds_dwordx4 v[6:7], off
	v_lshl_add_u64 v[6:7], v[8:9], 0, s[24:25]
	s_mov_b32 m0, s53
	s_nop 0
	global_load_lds_dwordx4 v[6:7], off
	s_barrier
	s_waitcnt lgkmcnt(0)
	s_waitcnt lgkmcnt(0)
	v_mfma_f32_16x16x32_bf16 v[6:9], v[208:211], v[142:145], v[108:111]
	v_mfma_f32_16x16x32_bf16 v[28:31], v[216:219], v[142:145], v[28:31]
	v_mfma_f32_16x16x32_bf16 v[32:35], v[208:211], v[174:177], v[32:35]
	v_mfma_f32_16x16x32_bf16 v[36:39], v[216:219], v[174:177], v[36:39]
	v_mfma_f32_16x16x32_bf16 v[40:43], v[208:211], v[192:195], v[40:43]
	v_mfma_f32_16x16x32_bf16 v[44:47], v[216:219], v[192:195], v[44:47]
	v_mfma_f32_16x16x32_bf16 v[48:51], v[208:211], v[200:203], v[48:51]
	v_mfma_f32_16x16x32_bf16 v[52:55], v[216:219], v[200:203], v[52:55]
	v_mfma_f32_16x16x32_bf16 v[6:9], v[212:215], v[146:149], v[6:9]
	v_mfma_f32_16x16x32_bf16 v[28:31], v[220:223], v[146:149], v[28:31]
	v_mfma_f32_16x16x32_bf16 v[32:35], v[212:215], v[178:181], v[32:35]
	v_mfma_f32_16x16x32_bf16 v[36:39], v[220:223], v[178:181], v[36:39]
	v_mfma_f32_16x16x32_bf16 v[40:43], v[212:215], v[196:199], v[40:43]
	v_mfma_f32_16x16x32_bf16 v[44:47], v[220:223], v[196:199], v[44:47]
	v_mfma_f32_16x16x32_bf16 v[48:51], v[212:215], v[204:207], v[48:51]
	v_mfma_f32_16x16x32_bf16 v[52:55], v[220:223], v[204:207], v[52:55]
	s_mov_b32 m0, s52
	v_lshl_add_u64 v[4:5], v[4:5], 0, s[24:25]
	s_barrier
	ds_read_b128 v[108:111], v10 offset:49152
	ds_read_b128 v[142:145], v10 offset:50176
	ds_read_b128 v[146:149], v10 offset:51200
	ds_read_b128 v[174:177], v10 offset:52224
	ds_read_b128 v[178:181], v10 offset:53248
	ds_read_b128 v[192:195], v10 offset:54272
	ds_read_b128 v[196:199], v10 offset:55296
	ds_read_b128 v[200:203], v10 offset:56320
	s_bitcmp1_b32 s100, 1
	s_cbranch_scc0 .Lpv1_c
	ds_write_b64 v248, v[224:225]
	ds_write_b64 v249, v[226:227]
	ds_write_b64 v248, v[228:229] offset:2048
	ds_write_b64 v249, v[230:231] offset:2048
	ds_write_b64 v248, v[232:233] offset:4096
	ds_write_b64 v249, v[234:235] offset:4096
	ds_write_b64 v248, v[236:237] offset:6144
	ds_write_b64 v249, v[238:239] offset:6144
.Lpv1_c:
	v_lshl_add_u64 v[2:3], v[2:3], 0, s[24:25]
	s_mov_b32 m0, s34
	s_nop 0
	s_barrier
	s_waitcnt lgkmcnt(0)
	s_waitcnt lgkmcnt(0)
	v_mfma_f32_16x16x32_bf16 v[2:5], v[100:103], v[108:111], v[150:153]
	v_mfma_f32_16x16x32_bf16 v[12:15], v[100:103], v[196:199], v[12:15]
	v_mfma_f32_16x16x32_bf16 v[16:19], v[124:127], v[196:199], v[16:19]
	v_mfma_f32_16x16x32_bf16 v[2:5], v[104:107], v[142:145], v[2:5]
	v_mfma_f32_16x16x32_bf16 v[150:153], v[124:127], v[108:111], v[154:157]
	v_mfma_f32_16x16x32_bf16 v[154:157], v[100:103], v[146:149], v[158:161]
	v_mfma_f32_16x16x32_bf16 v[158:161], v[124:127], v[146:149], v[162:165]
	v_mfma_f32_16x16x32_bf16 v[162:165], v[100:103], v[178:181], v[166:169]
	v_mfma_f32_16x16x32_bf16 v[166:169], v[124:127], v[178:181], v[170:173]
	v_mfma_f32_16x16x32_bf16 v[12:15], v[104:107], v[200:203], v[12:15]
	v_mfma_f32_16x16x32_bf16 v[16:19], v[138:141], v[200:203], v[16:19]
	v_mfma_f32_16x16x32_bf16 v[150:153], v[138:141], v[142:145], v[150:153]
	v_mfma_f32_16x16x32_bf16 v[154:157], v[104:107], v[174:177], v[154:157]
	v_mfma_f32_16x16x32_bf16 v[158:161], v[138:141], v[174:177], v[158:161]
	v_mfma_f32_16x16x32_bf16 v[162:165], v[104:107], v[192:195], v[162:165]
	v_mfma_f32_16x16x32_bf16 v[166:169], v[138:141], v[192:195], v[166:169]
	s_barrier
	s_add_u32 s28, s28, 0x10180
	s_addc_u32 s29, s29, 0
	s_mov_b32 m0, s31
	v_lshl_add_u64 v[100:101], s[28:29], 0, v[128:129]
	global_load_lds_dwordx4 v[100:101], off
	v_lshl_add_u64 v[100:101], s[28:29], 0, v[0:1]
	s_mov_b32 m0, s30
	s_nop 0
	global_load_lds_dwordx4 v[100:101], off
	s_waitcnt vmcnt(4)
	s_barrier
	v_mfma_f32_16x16x32_bf16 v[20:23], v[208:211], v[108:111], v[20:23]
	v_mfma_f32_16x16x32_bf16 v[24:27], v[216:219], v[108:111], v[24:27]
	v_mfma_f32_16x16x32_bf16 v[56:59], v[208:211], v[146:149], v[56:59]
	v_mfma_f32_16x16x32_bf16 v[100:103], v[216:219], v[146:149], v[112:115]
	v_mfma_f32_16x16x32_bf16 v[104:107], v[208:211], v[178:181], v[116:119]
	v_mfma_f32_16x16x32_bf16 v[108:111], v[216:219], v[178:181], v[120:123]
	v_mfma_f32_16x16x32_bf16 v[92:95], v[208:211], v[196:199], v[92:95]
	v_mfma_f32_16x16x32_bf16 v[96:99], v[216:219], v[196:199], v[96:99]
	v_mfma_f32_16x16x32_bf16 v[20:23], v[212:215], v[142:145], v[20:23]
	v_mfma_f32_16x16x32_bf16 v[24:27], v[220:223], v[142:145], v[24:27]
	v_mfma_f32_16x16x32_bf16 v[56:59], v[212:215], v[174:177], v[56:59]
	v_mfma_f32_16x16x32_bf16 v[100:103], v[220:223], v[174:177], v[100:103]
	v_mfma_f32_16x16x32_bf16 v[104:107], v[212:215], v[192:195], v[104:107]
	v_mfma_f32_16x16x32_bf16 v[108:111], v[220:223], v[192:195], v[108:111]
	v_mfma_f32_16x16x32_bf16 v[92:95], v[212:215], v[200:203], v[92:95]
	v_mfma_f32_16x16x32_bf16 v[96:99], v[220:223], v[200:203], v[96:99]
	s_mov_b32 m0, s72
	v_lshl_add_u64 v[130:131], s[18:19], 0, v[128:129]
	s_barrier
	ds_read_b128 v[112:115], v11
	ds_read_b128 v[116:119], v11 offset:1024
	ds_read_b128 v[120:123], v11 offset:2048
	ds_read_b128 v[124:127], v11 offset:3072
	ds_read_b128 v[138:141], v10
	ds_read_b128 v[142:145], v10 offset:1024
	ds_read_b128 v[146:149], v10 offset:2048
	ds_read_b128 v[170:173], v10 offset:3072
	ds_read_b128 v[174:177], v10 offset:4096
	ds_read_b128 v[178:181], v10 offset:5120
	ds_read_b128 v[192:195], v10 offset:6144
	ds_read_b128 v[196:199], v10 offset:7168
	v_lshl_add_u64 v[0:1], s[18:19], 0, v[0:1]
	s_mov_b32 m0, s57
	s_nop 0
	s_barrier
	s_waitcnt lgkmcnt(0)
	s_waitcnt lgkmcnt(0)
	v_mfma_f32_16x16x32_bf16 v[84:87], v[112:115], v[192:195], v[84:87]
	v_mfma_f32_16x16x32_bf16 v[60:63], v[112:115], v[138:141], v[60:63]
	v_mfma_f32_16x16x32_bf16 v[64:67], v[120:123], v[138:141], v[64:67]
	v_mfma_f32_16x16x32_bf16 v[68:71], v[112:115], v[146:149], v[68:71]
	v_mfma_f32_16x16x32_bf16 v[72:75], v[120:123], v[146:149], v[72:75]
	v_mfma_f32_16x16x32_bf16 v[76:79], v[112:115], v[174:177], v[76:79]
	v_mfma_f32_16x16x32_bf16 v[80:83], v[120:123], v[174:177], v[80:83]
	v_mfma_f32_16x16x32_bf16 v[200:203], v[116:119], v[196:199], v[84:87]
	v_mfma_f32_16x16x32_bf16 v[84:87], v[120:123], v[192:195], v[88:91]
	v_mfma_f32_16x16x32_bf16 v[60:63], v[116:119], v[142:145], v[60:63]
	v_mfma_f32_16x16x32_bf16 v[64:67], v[124:127], v[142:145], v[64:67]
	v_mfma_f32_16x16x32_bf16 v[68:71], v[116:119], v[170:173], v[68:71]
	v_mfma_f32_16x16x32_bf16 v[72:75], v[124:127], v[170:173], v[72:75]
	v_mfma_f32_16x16x32_bf16 v[76:79], v[116:119], v[178:181], v[76:79]
	v_mfma_f32_16x16x32_bf16 v[80:83], v[124:127], v[178:181], v[80:83]
	v_mfma_f32_16x16x32_bf16 v[88:91], v[124:127], v[196:199], v[84:87]
	s_barrier
	s_nop 0
	ds_read_b128 v[84:87], v134
	ds_read_b128 v[204:207], v134 offset:1024
	ds_read_b128 v[208:211], v134 offset:2048
	ds_read_b128 v[212:215], v134 offset:3072
	s_barrier
	s_waitcnt lgkmcnt(0)
	s_waitcnt lgkmcnt(0)
	v_mfma_f32_16x16x32_bf16 v[6:9], v[84:87], v[138:141], v[6:9]
	v_mfma_f32_16x16x32_bf16 v[28:31], v[208:211], v[138:141], v[28:31]
	v_mfma_f32_16x16x32_bf16 v[32:35], v[84:87], v[146:149], v[32:35]
	v_mfma_f32_16x16x32_bf16 v[36:39], v[208:211], v[146:149], v[36:39]
	v_mfma_f32_16x16x32_bf16 v[40:43], v[84:87], v[174:177], v[40:43]
	v_mfma_f32_16x16x32_bf16 v[44:47], v[208:211], v[174:177], v[44:47]
	v_mfma_f32_16x16x32_bf16 v[48:51], v[84:87], v[192:195], v[48:51]
	v_mfma_f32_16x16x32_bf16 v[6:9], v[204:207], v[142:145], v[6:9]
	v_mfma_f32_16x16x32_bf16 v[28:31], v[212:215], v[142:145], v[28:31]
	v_mfma_f32_16x16x32_bf16 v[32:35], v[204:207], v[170:173], v[32:35]
	v_mfma_f32_16x16x32_bf16 v[36:39], v[212:215], v[170:173], v[36:39]
	v_mfma_f32_16x16x32_bf16 v[40:43], v[204:207], v[178:181], v[40:43]
	v_mfma_f32_16x16x32_bf16 v[44:47], v[212:215], v[178:181], v[44:47]
	v_mfma_f32_16x16x32_bf16 v[48:51], v[204:207], v[196:199], v[48:51]
	v_mfma_f32_16x16x32_bf16 v[52:55], v[208:211], v[192:195], v[52:55]
	v_mfma_f32_16x16x32_bf16 v[138:141], v[212:215], v[196:199], v[52:55]
	s_barrier
	s_nop 4
	ds_read_b128 v[52:55], v10 offset:16384
	ds_read_b128 v[142:145], v10 offset:17408
	ds_read_b128 v[146:149], v10 offset:18432
	ds_read_b128 v[170:173], v10 offset:19456
	ds_read_b128 v[174:177], v10 offset:20480
	ds_read_b128 v[178:181], v10 offset:21504
	ds_read_b128 v[192:195], v10 offset:22528
	ds_read_b128 v[196:199], v10 offset:23552
	s_waitcnt vmcnt(2)
	s_barrier
	s_waitcnt lgkmcnt(0)
	s_waitcnt lgkmcnt(0)
	v_mfma_f32_16x16x32_bf16 v[0:3], v[112:115], v[52:55], v[2:5]
	v_mfma_f32_16x16x32_bf16 v[12:15], v[112:115], v[192:195], v[12:15]
	v_mfma_f32_16x16x32_bf16 v[0:3], v[116:119], v[142:145], v[0:3]
	v_mfma_f32_16x16x32_bf16 v[150:153], v[120:123], v[52:55], v[150:153]
	v_mfma_f32_16x16x32_bf16 v[154:157], v[112:115], v[146:149], v[154:157]
	v_mfma_f32_16x16x32_bf16 v[158:161], v[120:123], v[146:149], v[158:161]
	v_mfma_f32_16x16x32_bf16 v[162:165], v[112:115], v[174:177], v[162:165]
	v_mfma_f32_16x16x32_bf16 v[166:169], v[120:123], v[174:177], v[166:169]
	v_mfma_f32_16x16x32_bf16 v[12:15], v[116:119], v[196:199], v[12:15]
	v_mfma_f32_16x16x32_bf16 v[16:19], v[120:123], v[192:195], v[16:19]
	v_mfma_f32_16x16x32_bf16 v[150:153], v[124:127], v[142:145], v[150:153]
	v_mfma_f32_16x16x32_bf16 v[154:157], v[116:119], v[170:173], v[154:157]
	v_mfma_f32_16x16x32_bf16 v[158:161], v[124:127], v[170:173], v[158:161]
	v_mfma_f32_16x16x32_bf16 v[162:165], v[116:119], v[178:181], v[162:165]
	v_mfma_f32_16x16x32_bf16 v[166:169], v[124:127], v[178:181], v[166:169]
	v_mfma_f32_16x16x32_bf16 v[216:219], v[124:127], v[196:199], v[16:19]
	v_mfma_f32_16x16x32_bf16 v[16:19], v[84:87], v[52:55], v[20:23]
	v_mfma_f32_16x16x32_bf16 v[20:23], v[204:207], v[142:145], v[16:19]
	v_mfma_f32_16x16x32_bf16 v[16:19], v[208:211], v[52:55], v[24:27]
	v_mfma_f32_16x16x32_bf16 v[142:145], v[212:215], v[142:145], v[16:19]
	v_mfma_f32_16x16x32_bf16 v[16:19], v[84:87], v[146:149], v[56:59]
	v_mfma_f32_16x16x32_bf16 v[220:223], v[204:207], v[170:173], v[16:19]
	v_mfma_f32_16x16x32_bf16 v[16:19], v[208:211], v[146:149], v[100:103]
	v_mfma_f32_16x16x32_bf16 v[146:149], v[212:215], v[170:173], v[16:19]
	v_mfma_f32_16x16x32_bf16 v[16:19], v[84:87], v[174:177], v[104:107]
	v_mfma_f32_16x16x32_bf16 v[170:173], v[204:207], v[178:181], v[16:19]
	v_mfma_f32_16x16x32_bf16 v[16:19], v[208:211], v[174:177], v[108:111]
	v_mfma_f32_16x16x32_bf16 v[174:177], v[212:215], v[178:181], v[16:19]
	v_mfma_f32_16x16x32_bf16 v[16:19], v[84:87], v[192:195], v[92:95]
	v_mfma_f32_16x16x32_bf16 v[178:181], v[204:207], v[196:199], v[16:19]
	v_mfma_f32_16x16x32_bf16 v[16:19], v[208:211], v[192:195], v[96:99]
	v_mfma_f32_16x16x32_bf16 v[192:195], v[212:215], v[196:199], v[16:19]
	s_barrier
	ds_read_b128 v[56:59], v135
	ds_read_b128 v[196:199], v135 offset:1024
	ds_read_b128 v[204:207], v135 offset:2048
	ds_read_b128 v[208:211], v135 offset:3072
	s_nop 0
	ds_read_b128 v[16:19], v10 offset:32768
	ds_read_b128 v[24:27], v10 offset:33792
	ds_read_b128 v[92:95], v10 offset:34816
	ds_read_b128 v[104:107], v10 offset:35840
	ds_read_b128 v[212:215], v10 offset:36864
	ds_read_b128 v[224:227], v10 offset:37888
	ds_read_b128 v[228:231], v10 offset:38912
	ds_read_b128 v[232:235], v10 offset:39936
	s_waitcnt vmcnt(0)
	s_barrier
	s_waitcnt lgkmcnt(0)
	s_waitcnt lgkmcnt(0)
	v_mfma_f32_16x16x32_bf16 v[52:55], v[56:59], v[16:19], v[60:63]
	v_mfma_f32_16x16x32_bf16 v[116:119], v[196:199], v[24:27], v[52:55]
	v_mfma_f32_16x16x32_bf16 v[52:55], v[204:207], v[16:19], v[64:67]
	v_mfma_f32_16x16x32_bf16 v[112:115], v[208:211], v[24:27], v[52:55]
	v_mfma_f32_16x16x32_bf16 v[52:55], v[56:59], v[92:95], v[68:71]
	v_mfma_f32_16x16x32_bf16 v[100:103], v[196:199], v[104:107], v[52:55]
	v_mfma_f32_16x16x32_bf16 v[52:55], v[204:207], v[92:95], v[72:75]
	v_mfma_f32_16x16x32_bf16 v[96:99], v[208:211], v[104:107], v[52:55]
	v_mfma_f32_16x16x32_bf16 v[52:55], v[56:59], v[212:215], v[76:79]
	v_mfma_f32_16x16x32_bf16 v[84:87], v[196:199], v[224:227], v[52:55]
	v_mfma_f32_16x16x32_bf16 v[52:55], v[204:207], v[212:215], v[80:83]
	v_mfma_f32_16x16x32_bf16 v[80:83], v[208:211], v[224:227], v[52:55]
	v_mfma_f32_16x16x32_bf16 v[52:55], v[56:59], v[228:231], v[200:203]
	v_mfma_f32_16x16x32_bf16 v[64:67], v[196:199], v[232:235], v[52:55]
	v_mfma_f32_16x16x32_bf16 v[52:55], v[204:207], v[228:231], v[88:91]
	v_mfma_f32_16x16x32_bf16 v[52:55], v[208:211], v[232:235], v[52:55]
	s_barrier
	ds_read_b128 v[200:203], v184
	ds_read_b128 v[236:239], v184 offset:1024
	ds_read_b128 v[240:243], v184 offset:2048
	ds_read_b128 v[244:247], v184 offset:3072
	s_waitcnt vmcnt(0)
	s_barrier
	s_waitcnt lgkmcnt(0)
	s_waitcnt lgkmcnt(0)
	v_mfma_f32_16x16x32_bf16 v[4:7], v[200:203], v[16:19], v[6:9]
	v_mfma_f32_16x16x32_bf16 v[124:127], v[236:239], v[24:27], v[4:7]
	v_mfma_f32_16x16x32_bf16 v[4:7], v[240:243], v[16:19], v[28:31]
	v_mfma_f32_16x16x32_bf16 v[120:123], v[244:247], v[24:27], v[4:7]
	v_mfma_f32_16x16x32_bf16 v[4:7], v[200:203], v[92:95], v[32:35]
	v_mfma_f32_16x16x32_bf16 v[108:111], v[236:239], v[104:107], v[4:7]
	v_mfma_f32_16x16x32_bf16 v[4:7], v[240:243], v[92:95], v[36:39]
	v_mfma_f32_16x16x32_bf16 v[104:107], v[244:247], v[104:107], v[4:7]
	v_mfma_f32_16x16x32_bf16 v[4:7], v[200:203], v[212:215], v[40:43]
	v_mfma_f32_16x16x32_bf16 v[92:95], v[236:239], v[224:227], v[4:7]
	v_mfma_f32_16x16x32_bf16 v[4:7], v[240:243], v[212:215], v[44:47]
	v_mfma_f32_16x16x32_bf16 v[88:91], v[244:247], v[224:227], v[4:7]
	v_mfma_f32_16x16x32_bf16 v[4:7], v[200:203], v[228:231], v[48:51]
	v_mfma_f32_16x16x32_bf16 v[76:79], v[236:239], v[232:235], v[4:7]
	v_mfma_f32_16x16x32_bf16 v[4:7], v[240:243], v[228:231], v[138:141]
	v_mfma_f32_16x16x32_bf16 v[68:71], v[244:247], v[232:235], v[4:7]
	s_barrier
	s_nop 4
	v_add_u32_e32 v10, 0x16000, v10
	ds_read_b128 v[4:7], v10 offset:49152
	ds_read_b128 v[28:31], v10 offset:50176
	ds_read_b128 v[36:39], v10 offset:51200
	ds_read_b128 v[138:141], v10 offset:52224
	ds_read_b128 v[212:215], v10 offset:53248
	ds_read_b128 v[224:227], v10 offset:54272
	ds_read_b128 v[228:231], v10 offset:55296
	ds_read_b128 v[232:235], v10 offset:56320
	s_barrier
	s_waitcnt lgkmcnt(0)
	s_waitcnt lgkmcnt(0)
	v_mfma_f32_16x16x32_bf16 v[0:3], v[56:59], v[4:7], v[0:3]
	v_mfma_f32_16x16x32_bf16 v[60:63], v[196:199], v[28:31], v[0:3]
	v_mfma_f32_16x16x32_bf16 v[0:3], v[204:207], v[4:7], v[150:153]
	v_mfma_f32_16x16x32_bf16 v[48:51], v[208:211], v[28:31], v[0:3]
	v_mfma_f32_16x16x32_bf16 v[0:3], v[56:59], v[36:39], v[154:157]
	v_mfma_f32_16x16x32_bf16 v[40:43], v[196:199], v[138:141], v[0:3]
	v_mfma_f32_16x16x32_bf16 v[0:3], v[204:207], v[36:39], v[158:161]
	v_mfma_f32_16x16x32_bf16 v[32:35], v[208:211], v[138:141], v[0:3]
	v_mfma_f32_16x16x32_bf16 v[0:3], v[56:59], v[212:215], v[162:165]
	v_mfma_f32_16x16x32_bf16 v[24:27], v[196:199], v[224:227], v[0:3]
	v_mfma_f32_16x16x32_bf16 v[0:3], v[204:207], v[212:215], v[166:169]
	v_mfma_f32_16x16x32_bf16 v[16:19], v[208:211], v[224:227], v[0:3]
	v_mfma_f32_16x16x32_bf16 v[0:3], v[56:59], v[228:231], v[12:15]
	v_mfma_f32_16x16x32_bf16 v[8:11], v[196:199], v[232:235], v[0:3]
	v_mfma_f32_16x16x32_bf16 v[0:3], v[204:207], v[228:231], v[216:219]
	v_mfma_f32_16x16x32_bf16 v[0:3], v[208:211], v[232:235], v[0:3]
	v_mfma_f32_16x16x32_bf16 v[12:15], v[200:203], v[4:7], v[20:23]
	v_mfma_f32_16x16x32_bf16 v[4:7], v[240:243], v[4:7], v[142:145]
	v_mfma_f32_16x16x32_bf16 v[56:59], v[244:247], v[28:31], v[4:7]
	v_mfma_f32_16x16x32_bf16 v[4:7], v[200:203], v[36:39], v[220:223]
	v_mfma_f32_16x16x32_bf16 v[44:47], v[236:239], v[138:141], v[4:7]
	v_mfma_f32_16x16x32_bf16 v[4:7], v[240:243], v[36:39], v[146:149]
	v_mfma_f32_16x16x32_bf16 v[36:39], v[244:247], v[138:141], v[4:7]
	v_mfma_f32_16x16x32_bf16 v[4:7], v[200:203], v[212:215], v[170:173]
	v_mfma_f32_16x16x32_bf16 v[72:75], v[236:239], v[28:31], v[12:15]
	v_mfma_f32_16x16x32_bf16 v[28:31], v[236:239], v[224:227], v[4:7]
	v_mfma_f32_16x16x32_bf16 v[4:7], v[240:243], v[212:215], v[174:177]
	v_mfma_f32_16x16x32_bf16 v[20:23], v[244:247], v[224:227], v[4:7]
	v_mfma_f32_16x16x32_bf16 v[4:7], v[200:203], v[228:231], v[178:181]
	v_mfma_f32_16x16x32_bf16 v[12:15], v[236:239], v[232:235], v[4:7]
	v_mfma_f32_16x16x32_bf16 v[4:7], v[240:243], v[228:231], v[192:195]
	v_mfma_f32_16x16x32_bf16 v[4:7], v[244:247], v[232:235], v[4:7]
	s_cmpk_gt_u32 s27, 0xff
	s_barrier
	s_cbranch_scc1 .LBB0_984
	s_barrier
	s_branch .LBB0_984

.LBB0_1069:
	v_and_b32_e32 v15, 15, v14
	v_and_b32_e32 v16, 48, v14
	v_lshlrev_b32_e32 v14, 2, v14
	v_lshlrev_b32_e32 v15, 6, v15
	v_and_b32_e32 v14, 32, v14
	s_lshl_b32 s53, s53, 12
	v_or_b32_e32 v17, v15, v16
	v_bitop3_b32 v15, v15, v14, v16 bitop3:0x36
	s_lshl_b32 s33, s33, 13
	s_and_b32 s53, s53, 0x3000
	s_add_i32 s74, s46, s57
	v_or_b32_e32 v16, s53, v15
	v_bitop3_b32 v17, v17, s33, v14 bitop3:0xde
	v_lshl_add_u64 v[14:15], v[12:13], 0, s[16:17]
	s_mov_b32 m0, s74
	s_add_i32 s73, s74, 0x2000
	s_waitcnt vmcnt(4)
	s_barrier
	global_load_lds_dwordx4 v[14:15], off
	v_lshl_add_u64 v[14:15], v[10:11], 0, s[16:17]
	s_mov_b32 m0, s73
	s_add_i32 s72, s76, 0x8000
	s_add_i32 s68, s76, 0xa000
	global_load_lds_dwordx4 v[14:15], off
	v_lshl_add_u64 v[14:15], v[6:7], 0, s[16:17]
	s_mov_b32 m0, s72
	s_add_u32 s78, s40, 0x10080
	global_load_lds_dwordx4 v[14:15], off
	v_lshl_add_u64 v[14:15], v[8:9], 0, s[16:17]
	s_mov_b32 m0, s68
	s_addc_u32 s79, s41, 0
	s_add_i32 s53, s47, s57
	global_load_lds_dwordx4 v[14:15], off
	v_lshl_add_u64 v[14:15], s[78:79], 0, v[128:129]
	s_mov_b32 m0, s53
	s_add_i32 s33, s53, 0x2000
	global_load_lds_dwordx4 v[14:15], off
	v_lshl_add_u64 v[14:15], s[78:79], 0, v[4:5]
	s_mov_b32 m0, s33
	v_add_u32_e32 v134, s43, v16
	global_load_lds_dwordx4 v[14:15], off
	v_add_u32_e32 v15, s42, v16
	s_waitcnt vmcnt(6)
	s_barrier
	v_add_u32_e32 v14, 0, v17
	v_add_u32_e32 v135, s46, v16
	v_add_u32_e32 v184, s47, v16
	ds_read_b128 v[16:19], v15
	ds_read_b128 v[20:23], v15 offset:1024
	ds_read_b128 v[24:27], v15 offset:2048
	ds_read_b128 v[28:31], v15 offset:3072
	s_add_u32 s80, s34, 0x40080
	s_addc_u32 s81, s35, 0
	s_add_i32 s78, s76, 0xc000
	v_lshl_add_u64 v[64:65], s[80:81], 0, v[0:1]
	s_mov_b32 m0, s78
	s_add_i32 s75, s76, 0xe000
	ds_read_b128 v[32:35], v14
	ds_read_b128 v[36:39], v14 offset:1024
	ds_read_b128 v[40:43], v14 offset:2048
	ds_read_b128 v[44:47], v14 offset:3072
	ds_read_b128 v[48:51], v14 offset:4096
	ds_read_b128 v[52:55], v14 offset:5120
	ds_read_b128 v[56:59], v14 offset:6144
	ds_read_b128 v[60:63], v14 offset:7168
	global_load_lds_dwordx4 v[64:65], off
	v_lshl_add_u64 v[64:65], s[80:81], 0, v[2:3]
	s_mov_b32 m0, s75
	s_nop 0
	global_load_lds_dwordx4 v[64:65], off
	s_waitcnt lgkmcnt(8)
	s_barrier
	s_waitcnt lgkmcnt(0)
	s_waitcnt lgkmcnt(0)
	v_mfma_f32_16x16x32_bf16 v[64:67], v[16:19], v[32:35], 0
	v_mfma_f32_16x16x32_bf16 v[68:71], v[24:27], v[32:35], 0
	v_mfma_f32_16x16x32_bf16 v[72:75], v[16:19], v[40:43], 0
	v_mfma_f32_16x16x32_bf16 v[76:79], v[24:27], v[40:43], 0
	v_mfma_f32_16x16x32_bf16 v[80:83], v[16:19], v[48:51], 0
	v_mfma_f32_16x16x32_bf16 v[84:87], v[24:27], v[48:51], 0
	v_mfma_f32_16x16x32_bf16 v[88:91], v[16:19], v[56:59], 0
	v_mfma_f32_16x16x32_bf16 v[92:95], v[24:27], v[56:59], 0
	v_mfma_f32_16x16x32_bf16 v[64:67], v[20:23], v[36:39], v[64:67]
	v_mfma_f32_16x16x32_bf16 v[68:71], v[28:31], v[36:39], v[68:71]
	v_mfma_f32_16x16x32_bf16 v[72:75], v[20:23], v[44:47], v[72:75]
	v_mfma_f32_16x16x32_bf16 v[76:79], v[28:31], v[44:47], v[76:79]
	v_mfma_f32_16x16x32_bf16 v[80:83], v[20:23], v[52:55], v[80:83]
	v_mfma_f32_16x16x32_bf16 v[84:87], v[28:31], v[52:55], v[84:87]
	v_mfma_f32_16x16x32_bf16 v[88:91], v[20:23], v[60:63], v[88:91]
	v_mfma_f32_16x16x32_bf16 v[92:95], v[28:31], v[60:63], v[92:95]
	s_barrier
	s_add_i32 s79, s42, s57
	v_lshl_add_u64 v[112:113], v[12:13], 0, s[18:19]
	s_mov_b32 m0, s79
	ds_read_b128 v[96:99], v134
	ds_read_b128 v[100:103], v134 offset:1024
	ds_read_b128 v[104:107], v134 offset:2048
	ds_read_b128 v[108:111], v134 offset:3072
	global_load_lds_dwordx4 v[112:113], off
	v_lshl_add_u64 v[112:113], v[10:11], 0, s[18:19]
	s_add_i32 m0, s79, 0x2000
	s_nop 0
	global_load_lds_dwordx4 v[112:113], off
	s_barrier
	s_waitcnt lgkmcnt(0)
	s_waitcnt lgkmcnt(0)
	v_mfma_f32_16x16x32_bf16 v[112:115], v[96:99], v[32:35], 0
	v_mfma_f32_16x16x32_bf16 v[32:35], v[104:107], v[32:35], 0
	v_mfma_f32_16x16x32_bf16 v[112:115], v[100:103], v[36:39], v[112:115]
	v_mfma_f32_16x16x32_bf16 v[32:35], v[108:111], v[36:39], v[32:35]
	v_mfma_f32_16x16x32_bf16 v[36:39], v[96:99], v[40:43], 0
	v_mfma_f32_16x16x32_bf16 v[40:43], v[104:107], v[40:43], 0
	v_mfma_f32_16x16x32_bf16 v[36:39], v[100:103], v[44:47], v[36:39]
	v_mfma_f32_16x16x32_bf16 v[40:43], v[108:111], v[44:47], v[40:43]
	v_mfma_f32_16x16x32_bf16 v[44:47], v[96:99], v[48:51], 0
	v_mfma_f32_16x16x32_bf16 v[48:51], v[104:107], v[48:51], 0
	v_mfma_f32_16x16x32_bf16 v[44:47], v[100:103], v[52:55], v[44:47]
	v_mfma_f32_16x16x32_bf16 v[48:51], v[108:111], v[52:55], v[48:51]
	v_mfma_f32_16x16x32_bf16 v[52:55], v[96:99], v[56:59], 0
	v_mfma_f32_16x16x32_bf16 v[56:59], v[104:107], v[56:59], 0
	v_mfma_f32_16x16x32_bf16 v[52:55], v[100:103], v[60:63], v[52:55]
	v_mfma_f32_16x16x32_bf16 v[56:59], v[108:111], v[60:63], v[56:59]
	s_mov_b32 m0, s76
	v_lshl_add_u64 v[130:131], v[6:7], 0, s[18:19]
	s_barrier
	ds_read_b128 v[60:63], v14 offset:16384
	ds_read_b128 v[116:119], v14 offset:17408
	ds_read_b128 v[120:123], v14 offset:18432
	ds_read_b128 v[124:127], v14 offset:19456
	ds_read_b128 v[138:141], v14 offset:20480
	ds_read_b128 v[142:145], v14 offset:21504
	ds_read_b128 v[146:149], v14 offset:22528
	ds_read_b128 v[150:153], v14 offset:23552
	global_load_lds_dwordx4 v[130:131], off
	v_lshl_add_u64 v[130:131], v[8:9], 0, s[18:19]
	s_mov_b32 m0, s77
	s_nop 0
	global_load_lds_dwordx4 v[130:131], off
	s_barrier
	s_waitcnt lgkmcnt(0)
	s_waitcnt lgkmcnt(0)
	v_mfma_f32_16x16x32_bf16 v[154:157], v[16:19], v[60:63], 0
	v_mfma_f32_16x16x32_bf16 v[162:165], v[16:19], v[120:123], 0
	v_mfma_f32_16x16x32_bf16 v[170:173], v[16:19], v[138:141], 0
	v_mfma_f32_16x16x32_bf16 v[16:19], v[16:19], v[146:149], 0
	v_mfma_f32_16x16x32_bf16 v[154:157], v[20:23], v[116:119], v[154:157]
	v_mfma_f32_16x16x32_bf16 v[162:165], v[20:23], v[124:127], v[162:165]
	v_mfma_f32_16x16x32_bf16 v[170:173], v[20:23], v[142:145], v[170:173]
	v_mfma_f32_16x16x32_bf16 v[16:19], v[20:23], v[150:153], v[16:19]
	v_mfma_f32_16x16x32_bf16 v[20:23], v[24:27], v[146:149], 0
	v_mfma_f32_16x16x32_bf16 v[158:161], v[24:27], v[60:63], 0
	v_mfma_f32_16x16x32_bf16 v[166:169], v[24:27], v[120:123], 0
	v_mfma_f32_16x16x32_bf16 v[174:177], v[24:27], v[138:141], 0
	v_mfma_f32_16x16x32_bf16 v[20:23], v[28:31], v[150:153], v[20:23]
	v_mfma_f32_16x16x32_bf16 v[158:161], v[28:31], v[116:119], v[158:161]
	v_mfma_f32_16x16x32_bf16 v[166:169], v[28:31], v[124:127], v[166:169]
	v_mfma_f32_16x16x32_bf16 v[174:177], v[28:31], v[142:145], v[174:177]
	s_barrier
	s_add_u32 s76, s40, 0x10100
	s_addc_u32 s77, s41, 0
	s_add_i32 s57, s43, s57
	v_lshl_add_u64 v[24:25], s[76:77], 0, v[128:129]
	s_mov_b32 m0, s57
	s_nop 0
	global_load_lds_dwordx4 v[24:25], off
	v_lshl_add_u64 v[24:25], s[76:77], 0, v[4:5]
	s_add_i32 m0, s57, 0x2000
	s_nop 0
	global_load_lds_dwordx4 v[24:25], off
	s_waitcnt vmcnt(6)
	s_barrier
	v_mfma_f32_16x16x32_bf16 v[24:27], v[96:99], v[60:63], 0
	v_mfma_f32_16x16x32_bf16 v[28:31], v[104:107], v[60:63], 0
	v_mfma_f32_16x16x32_bf16 v[24:27], v[100:103], v[116:119], v[24:27]
	v_mfma_f32_16x16x32_bf16 v[28:31], v[108:111], v[116:119], v[28:31]
	v_mfma_f32_16x16x32_bf16 v[60:63], v[96:99], v[120:123], 0
	v_mfma_f32_16x16x32_bf16 v[116:119], v[104:107], v[120:123], 0
	v_mfma_f32_16x16x32_bf16 v[120:123], v[96:99], v[138:141], 0
	v_mfma_f32_16x16x32_bf16 v[96:99], v[96:99], v[146:149], 0
	v_mfma_f32_16x16x32_bf16 v[60:63], v[100:103], v[124:127], v[60:63]
	v_mfma_f32_16x16x32_bf16 v[116:119], v[108:111], v[124:127], v[116:119]
	v_mfma_f32_16x16x32_bf16 v[120:123], v[100:103], v[142:145], v[120:123]
	v_mfma_f32_16x16x32_bf16 v[124:127], v[104:107], v[138:141], 0
	v_mfma_f32_16x16x32_bf16 v[96:99], v[100:103], v[150:153], v[96:99]
	v_mfma_f32_16x16x32_bf16 v[100:103], v[104:107], v[146:149], 0
	v_mfma_f32_16x16x32_bf16 v[124:127], v[108:111], v[142:145], v[124:127]
	v_mfma_f32_16x16x32_bf16 v[100:103], v[108:111], v[150:153], v[100:103]
	s_barrier
	ds_read_b128 v[104:107], v135
	ds_read_b128 v[108:111], v135 offset:1024
	ds_read_b128 v[138:141], v135 offset:2048
	ds_read_b128 v[142:145], v135 offset:3072
	s_add_u32 s76, s34, 0x40100
	s_addc_u32 s77, s35, 0
	s_mov_b32 m0, s69
	v_lshl_add_u64 v[130:131], s[76:77], 0, v[0:1]
	ds_read_b128 v[146:149], v14 offset:32768
	ds_read_b128 v[150:153], v14 offset:33792
	ds_read_b128 v[178:181], v14 offset:34816
	ds_read_b128 v[192:195], v14 offset:35840
	ds_read_b128 v[196:199], v14 offset:36864
	ds_read_b128 v[200:203], v14 offset:37888
	ds_read_b128 v[204:207], v14 offset:38912
	ds_read_b128 v[208:211], v14 offset:39936
	global_load_lds_dwordx4 v[130:131], off
	v_lshl_add_u64 v[130:131], s[76:77], 0, v[2:3]
	s_mov_b32 m0, s56
	s_nop 0
	global_load_lds_dwordx4 v[130:131], off
	s_waitcnt lgkmcnt(8)
	s_barrier
	s_waitcnt lgkmcnt(0)
	s_waitcnt lgkmcnt(0)
	v_mfma_f32_16x16x32_bf16 v[64:67], v[104:107], v[146:149], v[64:67]
	v_mfma_f32_16x16x32_bf16 v[68:71], v[138:141], v[146:149], v[68:71]
	v_mfma_f32_16x16x32_bf16 v[72:75], v[104:107], v[178:181], v[72:75]
	v_mfma_f32_16x16x32_bf16 v[76:79], v[138:141], v[178:181], v[76:79]
	v_mfma_f32_16x16x32_bf16 v[80:83], v[104:107], v[196:199], v[80:83]
	v_mfma_f32_16x16x32_bf16 v[84:87], v[138:141], v[196:199], v[84:87]
	v_mfma_f32_16x16x32_bf16 v[88:91], v[104:107], v[204:207], v[88:91]
	v_mfma_f32_16x16x32_bf16 v[92:95], v[138:141], v[204:207], v[92:95]
	v_mfma_f32_16x16x32_bf16 v[64:67], v[108:111], v[150:153], v[64:67]
	v_mfma_f32_16x16x32_bf16 v[68:71], v[142:145], v[150:153], v[68:71]
	v_mfma_f32_16x16x32_bf16 v[72:75], v[108:111], v[192:195], v[72:75]
	v_mfma_f32_16x16x32_bf16 v[76:79], v[142:145], v[192:195], v[76:79]
	v_mfma_f32_16x16x32_bf16 v[80:83], v[108:111], v[200:203], v[80:83]
	v_mfma_f32_16x16x32_bf16 v[84:87], v[142:145], v[200:203], v[84:87]
	v_mfma_f32_16x16x32_bf16 v[88:91], v[108:111], v[208:211], v[88:91]
	v_mfma_f32_16x16x32_bf16 v[92:95], v[142:145], v[208:211], v[92:95]
	s_barrier
	s_mov_b32 m0, s74
	v_lshl_add_u64 v[12:13], v[12:13], 0, s[20:21]
	ds_read_b128 v[212:215], v184
	ds_read_b128 v[216:219], v184 offset:1024
	ds_read_b128 v[220:223], v184 offset:2048
	ds_read_b128 v[224:227], v184 offset:3072
	global_load_lds_dwordx4 v[12:13], off
	v_lshl_add_u64 v[10:11], v[10:11], 0, s[20:21]
	s_mov_b32 m0, s73
	s_nop 0
	global_load_lds_dwordx4 v[10:11], off
	s_barrier
	s_waitcnt lgkmcnt(0)
	s_waitcnt lgkmcnt(0)
	v_mfma_f32_16x16x32_bf16 v[10:13], v[212:215], v[146:149], v[112:115]
	v_mfma_f32_16x16x32_bf16 v[32:35], v[220:223], v[146:149], v[32:35]
	v_mfma_f32_16x16x32_bf16 v[36:39], v[212:215], v[178:181], v[36:39]
	v_mfma_f32_16x16x32_bf16 v[40:43], v[220:223], v[178:181], v[40:43]
	v_mfma_f32_16x16x32_bf16 v[44:47], v[212:215], v[196:199], v[44:47]
	v_mfma_f32_16x16x32_bf16 v[48:51], v[220:223], v[196:199], v[48:51]
	v_mfma_f32_16x16x32_bf16 v[52:55], v[212:215], v[204:207], v[52:55]
	v_mfma_f32_16x16x32_bf16 v[56:59], v[220:223], v[204:207], v[56:59]
	v_mfma_f32_16x16x32_bf16 v[10:13], v[216:219], v[150:153], v[10:13]
	v_mfma_f32_16x16x32_bf16 v[32:35], v[224:227], v[150:153], v[32:35]
	v_mfma_f32_16x16x32_bf16 v[36:39], v[216:219], v[192:195], v[36:39]
	v_mfma_f32_16x16x32_bf16 v[40:43], v[224:227], v[192:195], v[40:43]
	v_mfma_f32_16x16x32_bf16 v[44:47], v[216:219], v[200:203], v[44:47]
	v_mfma_f32_16x16x32_bf16 v[48:51], v[224:227], v[200:203], v[48:51]
	v_mfma_f32_16x16x32_bf16 v[52:55], v[216:219], v[208:211], v[52:55]
	v_mfma_f32_16x16x32_bf16 v[56:59], v[224:227], v[208:211], v[56:59]
	s_mov_b32 m0, s72
	v_lshl_add_u64 v[6:7], v[6:7], 0, s[20:21]
	s_barrier
	ds_read_b128 v[112:115], v14 offset:49152
	ds_read_b128 v[146:149], v14 offset:50176
	ds_read_b128 v[150:153], v14 offset:51200
	ds_read_b128 v[178:181], v14 offset:52224
	ds_read_b128 v[192:195], v14 offset:53248
	ds_read_b128 v[196:199], v14 offset:54272
	ds_read_b128 v[200:203], v14 offset:55296
	ds_read_b128 v[204:207], v14 offset:56320
	global_load_lds_dwordx4 v[6:7], off
	v_lshl_add_u64 v[6:7], v[8:9], 0, s[20:21]
	s_mov_b32 m0, s68
	s_nop 0
	global_load_lds_dwordx4 v[6:7], off
	s_barrier
	s_waitcnt lgkmcnt(0)
	s_waitcnt lgkmcnt(0)
	v_mfma_f32_16x16x32_bf16 v[6:9], v[104:107], v[112:115], v[154:157]
	v_mfma_f32_16x16x32_bf16 v[16:19], v[104:107], v[200:203], v[16:19]
	v_mfma_f32_16x16x32_bf16 v[20:23], v[138:141], v[200:203], v[20:23]
	v_mfma_f32_16x16x32_bf16 v[6:9], v[108:111], v[146:149], v[6:9]
	v_mfma_f32_16x16x32_bf16 v[154:157], v[138:141], v[112:115], v[158:161]
	v_mfma_f32_16x16x32_bf16 v[158:161], v[104:107], v[150:153], v[162:165]
	v_mfma_f32_16x16x32_bf16 v[162:165], v[138:141], v[150:153], v[166:169]
	v_mfma_f32_16x16x32_bf16 v[166:169], v[104:107], v[192:195], v[170:173]
	v_mfma_f32_16x16x32_bf16 v[170:173], v[138:141], v[192:195], v[174:177]
	v_mfma_f32_16x16x32_bf16 v[16:19], v[108:111], v[204:207], v[16:19]
	v_mfma_f32_16x16x32_bf16 v[20:23], v[142:145], v[204:207], v[20:23]
	v_mfma_f32_16x16x32_bf16 v[154:157], v[142:145], v[146:149], v[154:157]
	v_mfma_f32_16x16x32_bf16 v[158:161], v[108:111], v[178:181], v[158:161]
	v_mfma_f32_16x16x32_bf16 v[162:165], v[142:145], v[178:181], v[162:165]
	v_mfma_f32_16x16x32_bf16 v[166:169], v[108:111], v[196:199], v[166:169]
	v_mfma_f32_16x16x32_bf16 v[170:173], v[142:145], v[196:199], v[170:173]
	s_barrier
	s_add_u32 s40, s40, 0x10180
	s_addc_u32 s41, s41, 0
	s_mov_b32 m0, s53
	v_lshl_add_u64 v[104:105], s[40:41], 0, v[128:129]
	global_load_lds_dwordx4 v[104:105], off
	v_lshl_add_u64 v[4:5], s[40:41], 0, v[4:5]
	s_mov_b32 m0, s33
	s_nop 0
	global_load_lds_dwordx4 v[4:5], off
	s_waitcnt vmcnt(6)
	s_barrier
	v_mfma_f32_16x16x32_bf16 v[24:27], v[212:215], v[112:115], v[24:27]
	v_mfma_f32_16x16x32_bf16 v[28:31], v[220:223], v[112:115], v[28:31]
	v_mfma_f32_16x16x32_bf16 v[60:63], v[212:215], v[150:153], v[60:63]
	v_mfma_f32_16x16x32_bf16 v[104:107], v[220:223], v[150:153], v[116:119]
	v_mfma_f32_16x16x32_bf16 v[108:111], v[212:215], v[192:195], v[120:123]
	v_mfma_f32_16x16x32_bf16 v[112:115], v[220:223], v[192:195], v[124:127]
	v_mfma_f32_16x16x32_bf16 v[96:99], v[212:215], v[200:203], v[96:99]
	v_mfma_f32_16x16x32_bf16 v[100:103], v[220:223], v[200:203], v[100:103]
	v_mfma_f32_16x16x32_bf16 v[24:27], v[216:219], v[146:149], v[24:27]
	v_mfma_f32_16x16x32_bf16 v[28:31], v[224:227], v[146:149], v[28:31]
	v_mfma_f32_16x16x32_bf16 v[60:63], v[216:219], v[178:181], v[60:63]
	v_mfma_f32_16x16x32_bf16 v[104:107], v[224:227], v[178:181], v[104:107]
	v_mfma_f32_16x16x32_bf16 v[108:111], v[216:219], v[196:199], v[108:111]
	v_mfma_f32_16x16x32_bf16 v[112:115], v[224:227], v[196:199], v[112:115]
	v_mfma_f32_16x16x32_bf16 v[96:99], v[216:219], v[204:207], v[96:99]
	v_mfma_f32_16x16x32_bf16 v[100:103], v[224:227], v[204:207], v[100:103]
	s_add_u32 s34, s34, 0x40180
	s_addc_u32 s35, s35, 0
	s_mov_b32 m0, s78
	v_lshl_add_u64 v[0:1], s[34:35], 0, v[0:1]
	s_barrier
	ds_read_b128 v[116:119], v15
	ds_read_b128 v[120:123], v15 offset:1024
	ds_read_b128 v[124:127], v15 offset:2048
	ds_read_b128 v[138:141], v15 offset:3072
	ds_read_b128 v[142:145], v14
	ds_read_b128 v[146:149], v14 offset:1024
	ds_read_b128 v[150:153], v14 offset:2048
	ds_read_b128 v[174:177], v14 offset:3072
	ds_read_b128 v[178:181], v14 offset:4096
	ds_read_b128 v[192:195], v14 offset:5120
	ds_read_b128 v[196:199], v14 offset:6144
	ds_read_b128 v[200:203], v14 offset:7168
	global_load_lds_dwordx4 v[0:1], off
	v_lshl_add_u64 v[0:1], s[34:35], 0, v[2:3]
	s_mov_b32 m0, s75
	s_nop 0
	global_load_lds_dwordx4 v[0:1], off
	s_barrier
	s_waitcnt lgkmcnt(0)
	s_waitcnt lgkmcnt(0)
	v_mfma_f32_16x16x32_bf16 v[0:3], v[116:119], v[142:145], v[64:67]
	v_mfma_f32_16x16x32_bf16 v[64:67], v[124:127], v[142:145], v[68:71]
	v_mfma_f32_16x16x32_bf16 v[68:71], v[116:119], v[150:153], v[72:75]
	v_mfma_f32_16x16x32_bf16 v[72:75], v[124:127], v[150:153], v[76:79]
	v_mfma_f32_16x16x32_bf16 v[76:79], v[116:119], v[178:181], v[80:83]
	v_mfma_f32_16x16x32_bf16 v[80:83], v[124:127], v[178:181], v[84:87]
	v_mfma_f32_16x16x32_bf16 v[84:87], v[116:119], v[196:199], v[88:91]
	v_mfma_f32_16x16x32_bf16 v[0:3], v[120:123], v[146:149], v[0:3]
	v_mfma_f32_16x16x32_bf16 v[64:67], v[138:141], v[146:149], v[64:67]
	v_mfma_f32_16x16x32_bf16 v[68:71], v[120:123], v[174:177], v[68:71]
	v_mfma_f32_16x16x32_bf16 v[72:75], v[138:141], v[174:177], v[72:75]
	v_mfma_f32_16x16x32_bf16 v[76:79], v[120:123], v[192:195], v[76:79]
	v_mfma_f32_16x16x32_bf16 v[80:83], v[138:141], v[192:195], v[80:83]
	v_mfma_f32_16x16x32_bf16 v[88:91], v[120:123], v[200:203], v[84:87]
	v_mfma_f32_16x16x32_bf16 v[84:87], v[124:127], v[196:199], v[92:95]
	v_mfma_f32_16x16x32_bf16 v[204:207], v[138:141], v[200:203], v[84:87]
	s_barrier
	s_nop 4
	ds_read_b128 v[84:87], v134
	ds_read_b128 v[92:95], v134 offset:1024
	ds_read_b128 v[208:211], v134 offset:2048
	ds_read_b128 v[212:215], v134 offset:3072
	s_barrier
	s_waitcnt lgkmcnt(0)
	s_waitcnt lgkmcnt(0)
	v_mfma_f32_16x16x32_bf16 v[10:13], v[84:87], v[142:145], v[10:13]
	v_mfma_f32_16x16x32_bf16 v[32:35], v[208:211], v[142:145], v[32:35]
	v_mfma_f32_16x16x32_bf16 v[36:39], v[84:87], v[150:153], v[36:39]
	v_mfma_f32_16x16x32_bf16 v[40:43], v[208:211], v[150:153], v[40:43]
	v_mfma_f32_16x16x32_bf16 v[44:47], v[84:87], v[178:181], v[44:47]
	v_mfma_f32_16x16x32_bf16 v[48:51], v[208:211], v[178:181], v[48:51]
	v_mfma_f32_16x16x32_bf16 v[52:55], v[84:87], v[196:199], v[52:55]
	v_mfma_f32_16x16x32_bf16 v[56:59], v[208:211], v[196:199], v[56:59]
	v_mfma_f32_16x16x32_bf16 v[10:13], v[92:95], v[146:149], v[10:13]
	v_mfma_f32_16x16x32_bf16 v[32:35], v[212:215], v[146:149], v[32:35]
	v_mfma_f32_16x16x32_bf16 v[36:39], v[92:95], v[174:177], v[36:39]
	v_mfma_f32_16x16x32_bf16 v[40:43], v[212:215], v[174:177], v[40:43]
	v_mfma_f32_16x16x32_bf16 v[44:47], v[92:95], v[192:195], v[44:47]
	v_mfma_f32_16x16x32_bf16 v[48:51], v[212:215], v[192:195], v[48:51]
	v_mfma_f32_16x16x32_bf16 v[52:55], v[92:95], v[200:203], v[52:55]
	v_mfma_f32_16x16x32_bf16 v[56:59], v[212:215], v[200:203], v[56:59]
	s_barrier
	ds_read_b128 v[142:145], v14 offset:16384
	ds_read_b128 v[146:149], v14 offset:17408
	ds_read_b128 v[150:153], v14 offset:18432
	ds_read_b128 v[174:177], v14 offset:19456
	ds_read_b128 v[178:181], v14 offset:20480
	ds_read_b128 v[192:195], v14 offset:21504
	ds_read_b128 v[196:199], v14 offset:22528
	ds_read_b128 v[200:203], v14 offset:23552
	s_waitcnt vmcnt(4)
	s_barrier
	s_waitcnt lgkmcnt(0)
	s_waitcnt lgkmcnt(0)
	v_mfma_f32_16x16x32_bf16 v[4:7], v[116:119], v[142:145], v[6:9]
	v_mfma_f32_16x16x32_bf16 v[16:19], v[116:119], v[196:199], v[16:19]
	v_mfma_f32_16x16x32_bf16 v[20:23], v[124:127], v[196:199], v[20:23]
	v_mfma_f32_16x16x32_bf16 v[4:7], v[120:123], v[146:149], v[4:7]
	v_mfma_f32_16x16x32_bf16 v[154:157], v[124:127], v[142:145], v[154:157]
	v_mfma_f32_16x16x32_bf16 v[158:161], v[116:119], v[150:153], v[158:161]
	v_mfma_f32_16x16x32_bf16 v[162:165], v[124:127], v[150:153], v[162:165]
	v_mfma_f32_16x16x32_bf16 v[166:169], v[116:119], v[178:181], v[166:169]
	v_mfma_f32_16x16x32_bf16 v[170:173], v[124:127], v[178:181], v[170:173]
	v_mfma_f32_16x16x32_bf16 v[16:19], v[120:123], v[200:203], v[16:19]
	v_mfma_f32_16x16x32_bf16 v[20:23], v[138:141], v[200:203], v[20:23]
	v_mfma_f32_16x16x32_bf16 v[154:157], v[138:141], v[146:149], v[154:157]
	v_mfma_f32_16x16x32_bf16 v[158:161], v[120:123], v[174:177], v[158:161]
	v_mfma_f32_16x16x32_bf16 v[162:165], v[138:141], v[174:177], v[162:165]
	v_mfma_f32_16x16x32_bf16 v[166:169], v[120:123], v[192:195], v[166:169]
	v_mfma_f32_16x16x32_bf16 v[170:173], v[138:141], v[192:195], v[170:173]
	v_mfma_f32_16x16x32_bf16 v[24:27], v[84:87], v[142:145], v[24:27]
	v_mfma_f32_16x16x32_bf16 v[138:141], v[92:95], v[146:149], v[24:27]
	v_mfma_f32_16x16x32_bf16 v[24:27], v[208:211], v[142:145], v[28:31]
	v_mfma_f32_16x16x32_bf16 v[142:145], v[212:215], v[146:149], v[24:27]
	v_mfma_f32_16x16x32_bf16 v[24:27], v[84:87], v[150:153], v[60:63]
	v_mfma_f32_16x16x32_bf16 v[146:149], v[92:95], v[174:177], v[24:27]
	v_mfma_f32_16x16x32_bf16 v[24:27], v[208:211], v[150:153], v[104:107]
	v_mfma_f32_16x16x32_bf16 v[150:153], v[212:215], v[174:177], v[24:27]
	v_mfma_f32_16x16x32_bf16 v[24:27], v[84:87], v[178:181], v[108:111]
	v_mfma_f32_16x16x32_bf16 v[174:177], v[92:95], v[192:195], v[24:27]
	v_mfma_f32_16x16x32_bf16 v[24:27], v[208:211], v[178:181], v[112:115]
	v_mfma_f32_16x16x32_bf16 v[178:181], v[212:215], v[192:195], v[24:27]
	v_mfma_f32_16x16x32_bf16 v[24:27], v[84:87], v[196:199], v[96:99]
	v_mfma_f32_16x16x32_bf16 v[192:195], v[92:95], v[200:203], v[24:27]
	v_mfma_f32_16x16x32_bf16 v[24:27], v[208:211], v[196:199], v[100:103]
	v_mfma_f32_16x16x32_bf16 v[196:199], v[212:215], v[200:203], v[24:27]
	s_barrier
	ds_read_b128 v[200:203], v135
	ds_read_b128 v[208:211], v135 offset:1024
	ds_read_b128 v[212:215], v135 offset:2048
	ds_read_b128 v[216:219], v135 offset:3072
	s_nop 0
	ds_read_b128 v[24:27], v14 offset:32768
	ds_read_b128 v[28:31], v14 offset:33792
	ds_read_b128 v[60:63], v14 offset:34816
	ds_read_b128 v[96:99], v14 offset:35840
	ds_read_b128 v[220:223], v14 offset:36864
	ds_read_b128 v[224:227], v14 offset:37888
	ds_read_b128 v[228:231], v14 offset:38912
	ds_read_b128 v[232:235], v14 offset:39936
	s_waitcnt vmcnt(2)
	s_barrier
	s_waitcnt lgkmcnt(0)
	s_waitcnt lgkmcnt(0)
	v_mfma_f32_16x16x32_bf16 v[0:3], v[200:203], v[24:27], v[0:3]
	v_mfma_f32_16x16x32_bf16 v[124:127], v[208:211], v[28:31], v[0:3]
	v_mfma_f32_16x16x32_bf16 v[0:3], v[212:215], v[24:27], v[64:67]
	v_mfma_f32_16x16x32_bf16 v[116:119], v[216:219], v[28:31], v[0:3]
	v_mfma_f32_16x16x32_bf16 v[0:3], v[200:203], v[60:63], v[68:71]
	v_mfma_f32_16x16x32_bf16 v[108:111], v[208:211], v[96:99], v[0:3]
	v_mfma_f32_16x16x32_bf16 v[0:3], v[212:215], v[60:63], v[72:75]
	v_mfma_f32_16x16x32_bf16 v[100:103], v[216:219], v[96:99], v[0:3]
	v_mfma_f32_16x16x32_bf16 v[0:3], v[200:203], v[220:223], v[76:79]
	v_mfma_f32_16x16x32_bf16 v[92:95], v[208:211], v[224:227], v[0:3]
	v_mfma_f32_16x16x32_bf16 v[0:3], v[212:215], v[220:223], v[80:83]
	v_mfma_f32_16x16x32_bf16 v[84:87], v[216:219], v[224:227], v[0:3]
	v_mfma_f32_16x16x32_bf16 v[0:3], v[200:203], v[228:231], v[88:91]
	v_mfma_f32_16x16x32_bf16 v[76:79], v[208:211], v[232:235], v[0:3]
	v_mfma_f32_16x16x32_bf16 v[0:3], v[212:215], v[228:231], v[204:207]
	v_mfma_f32_16x16x32_bf16 v[68:71], v[216:219], v[232:235], v[0:3]
	s_barrier
	s_nop 4
	ds_read_b128 v[0:3], v184
	ds_read_b128 v[204:207], v184 offset:1024
	ds_read_b128 v[236:239], v184 offset:2048
	ds_read_b128 v[240:243], v184 offset:3072
	s_waitcnt vmcnt(0)
	s_barrier
	s_waitcnt lgkmcnt(0)
	s_waitcnt lgkmcnt(0)
	v_mfma_f32_16x16x32_bf16 v[8:11], v[0:3], v[24:27], v[10:13]
	v_mfma_f32_16x16x32_bf16 v[120:123], v[204:207], v[28:31], v[8:11]
	v_mfma_f32_16x16x32_bf16 v[8:11], v[236:239], v[24:27], v[32:35]
	v_mfma_f32_16x16x32_bf16 v[112:115], v[240:243], v[28:31], v[8:11]
	v_mfma_f32_16x16x32_bf16 v[8:11], v[0:3], v[60:63], v[36:39]
	v_mfma_f32_16x16x32_bf16 v[104:107], v[204:207], v[96:99], v[8:11]
	v_mfma_f32_16x16x32_bf16 v[8:11], v[236:239], v[60:63], v[40:43]
	v_mfma_f32_16x16x32_bf16 v[96:99], v[240:243], v[96:99], v[8:11]
	v_mfma_f32_16x16x32_bf16 v[8:11], v[0:3], v[220:223], v[44:47]
	v_mfma_f32_16x16x32_bf16 v[88:91], v[204:207], v[224:227], v[8:11]
	v_mfma_f32_16x16x32_bf16 v[8:11], v[236:239], v[220:223], v[48:51]
	v_mfma_f32_16x16x32_bf16 v[80:83], v[240:243], v[224:227], v[8:11]
	v_mfma_f32_16x16x32_bf16 v[8:11], v[0:3], v[228:231], v[52:55]
	v_mfma_f32_16x16x32_bf16 v[72:75], v[204:207], v[232:235], v[8:11]
	v_mfma_f32_16x16x32_bf16 v[8:11], v[236:239], v[228:231], v[56:59]
	v_mfma_f32_16x16x32_bf16 v[64:67], v[240:243], v[232:235], v[8:11]
	s_barrier
	ds_read_b128 v[32:35], v14 offset:49152
	ds_read_b128 v[36:39], v14 offset:50176
	ds_read_b128 v[220:223], v14 offset:51200
	ds_read_b128 v[224:227], v14 offset:52224
	ds_read_b128 v[228:231], v14 offset:53248
	ds_read_b128 v[232:235], v14 offset:54272
	ds_read_b128 v[244:247], v14 offset:55296
	ds_read_b128 v[248:251], v14 offset:56320
	s_barrier
	s_waitcnt lgkmcnt(0)
	s_waitcnt lgkmcnt(0)
	v_mfma_f32_16x16x32_bf16 v[4:7], v[200:203], v[32:35], v[4:7]
	v_mfma_f32_16x16x32_bf16 v[60:63], v[208:211], v[36:39], v[4:7]
	v_mfma_f32_16x16x32_bf16 v[4:7], v[212:215], v[32:35], v[154:157]
	v_mfma_f32_16x16x32_bf16 v[56:59], v[216:219], v[36:39], v[4:7]
	v_mfma_f32_16x16x32_bf16 v[4:7], v[200:203], v[220:223], v[158:161]
	v_mfma_f32_16x16x32_bf16 v[44:47], v[208:211], v[224:227], v[4:7]
	v_mfma_f32_16x16x32_bf16 v[4:7], v[212:215], v[220:223], v[162:165]
	v_mfma_f32_16x16x32_bf16 v[40:43], v[216:219], v[224:227], v[4:7]
	v_mfma_f32_16x16x32_bf16 v[4:7], v[200:203], v[228:231], v[166:169]
	v_mfma_f32_16x16x32_bf16 v[28:31], v[208:211], v[232:235], v[4:7]
	v_mfma_f32_16x16x32_bf16 v[4:7], v[212:215], v[228:231], v[170:173]
	v_mfma_f32_16x16x32_bf16 v[24:27], v[216:219], v[232:235], v[4:7]
	v_mfma_f32_16x16x32_bf16 v[4:7], v[200:203], v[244:247], v[16:19]
	v_mfma_f32_16x16x32_bf16 v[12:15], v[208:211], v[248:251], v[4:7]
	v_mfma_f32_16x16x32_bf16 v[4:7], v[212:215], v[244:247], v[20:23]
	v_mfma_f32_16x16x32_bf16 v[8:11], v[216:219], v[248:251], v[4:7]
	v_mfma_f32_16x16x32_bf16 v[4:7], v[0:3], v[32:35], v[138:141]
	v_mfma_f32_16x16x32_bf16 v[52:55], v[204:207], v[36:39], v[4:7]
	v_mfma_f32_16x16x32_bf16 v[4:7], v[236:239], v[32:35], v[142:145]
	v_mfma_f32_16x16x32_bf16 v[48:51], v[240:243], v[36:39], v[4:7]
	v_mfma_f32_16x16x32_bf16 v[4:7], v[0:3], v[220:223], v[146:149]
	v_mfma_f32_16x16x32_bf16 v[36:39], v[204:207], v[224:227], v[4:7]
	v_mfma_f32_16x16x32_bf16 v[4:7], v[236:239], v[220:223], v[150:153]
	v_mfma_f32_16x16x32_bf16 v[32:35], v[240:243], v[224:227], v[4:7]
	v_mfma_f32_16x16x32_bf16 v[4:7], v[0:3], v[228:231], v[174:177]
	v_mfma_f32_16x16x32_bf16 v[20:23], v[204:207], v[232:235], v[4:7]
	v_mfma_f32_16x16x32_bf16 v[4:7], v[236:239], v[228:231], v[178:181]
	v_mfma_f32_16x16x32_bf16 v[0:3], v[0:3], v[244:247], v[192:195]
	v_mfma_f32_16x16x32_bf16 v[16:19], v[240:243], v[232:235], v[4:7]
	v_mfma_f32_16x16x32_bf16 v[4:7], v[204:207], v[248:251], v[0:3]
	v_mfma_f32_16x16x32_bf16 v[0:3], v[236:239], v[244:247], v[196:199]
	v_mfma_f32_16x16x32_bf16 v[0:3], v[240:243], v[248:251], v[0:3]
	s_cmpk_gt_u32 s29, 0xff
	s_barrier
	s_cbranch_scc1 .LBB0_1071
	s_barrier

.LBB0_1105:
	v_and_b32_e32 v11, 15, v10
	v_and_b32_e32 v12, 48, v10
	v_lshlrev_b32_e32 v10, 2, v10
	v_lshlrev_b32_e32 v11, 6, v11
	v_and_b32_e32 v10, 32, v10
	s_lshl_b32 s34, s34, 12
	v_or_b32_e32 v13, v11, v12
	v_bitop3_b32 v11, v11, v10, v12 bitop3:0x36
	s_lshl_b32 s33, s33, 13
	s_and_b32 s34, s34, 0x3000
	s_add_i32 s68, s46, s53
	v_or_b32_e32 v12, s34, v11
	v_bitop3_b32 v13, v13, s33, v10 bitop3:0xde
	v_lshl_add_u64 v[10:11], v[6:7], 0, s[16:17]
	s_mov_b32 m0, s68
	s_add_i32 s57, s68, 0x2000
	v_lshl_add_u64 v[4:5], s[0:1], 0, v[128:129]
	s_waitcnt vmcnt(2)
	s_barrier
	global_load_lds_dwordx4 v[10:11], off
	v_lshl_add_u64 v[10:11], v[8:9], 0, s[16:17]
	s_mov_b32 m0, s57
	s_add_i32 s56, s73, 0x8000
	s_add_i32 s40, s73, 0xa000
	v_lshl_add_u64 v[2:3], s[0:1], 0, v[0:1]
	global_load_lds_dwordx4 v[10:11], off
	v_lshl_add_u64 v[10:11], v[4:5], 0, s[16:17]
	s_mov_b32 m0, s56
	s_add_u32 s76, s30, 0x10080
	v_lshl_add_u64 v[10:11], v[2:3], 0, s[16:17]
	s_mov_b32 m0, s40
	s_addc_u32 s77, s31, 0
	s_add_i32 s34, s47, s53
	v_lshl_add_u64 v[10:11], s[76:77], 0, v[128:129]
	s_mov_b32 m0, s34
	s_add_i32 s33, s34, 0x2000
	global_load_lds_dwordx4 v[10:11], off
	v_lshl_add_u64 v[10:11], s[76:77], 0, v[0:1]
	s_mov_b32 m0, s33
	v_add_u32_e32 v134, s43, v12
	global_load_lds_dwordx4 v[10:11], off
	v_add_u32_e32 v11, s42, v12
	s_waitcnt vmcnt(4)
	s_barrier
	v_add_u32_e32 v10, 0, v13
	v_add_u32_e32 v135, s46, v12
	v_add_u32_e32 v184, s47, v12
	ds_read_b128 v[12:15], v11
	ds_read_b128 v[16:19], v11 offset:1024
	ds_read_b128 v[20:23], v11 offset:2048
	ds_read_b128 v[24:27], v11 offset:3072
	s_add_i32 s72, s73, 0xc000
	v_lshl_add_u64 v[60:61], s[10:11], 0, v[128:129]
	s_mov_b32 m0, s72
	s_add_i32 s69, s73, 0xe000
	ds_read_b128 v[28:31], v10
	ds_read_b128 v[32:35], v10 offset:1024
	ds_read_b128 v[36:39], v10 offset:2048
	ds_read_b128 v[40:43], v10 offset:3072
	ds_read_b128 v[44:47], v10 offset:4096
	ds_read_b128 v[48:51], v10 offset:5120
	ds_read_b128 v[52:55], v10 offset:6144
	ds_read_b128 v[56:59], v10 offset:7168
	v_lshl_add_u64 v[60:61], s[10:11], 0, v[0:1]
	s_mov_b32 m0, s69
	s_nop 0
	s_waitcnt lgkmcnt(8)
	s_barrier
	s_waitcnt lgkmcnt(0)
	s_waitcnt lgkmcnt(0)
	v_mfma_f32_16x16x32_bf16 v[60:63], v[12:15], v[28:31], 0
	v_mfma_f32_16x16x32_bf16 v[64:67], v[20:23], v[28:31], 0
	v_mfma_f32_16x16x32_bf16 v[68:71], v[12:15], v[36:39], 0
	v_mfma_f32_16x16x32_bf16 v[72:75], v[20:23], v[36:39], 0
	v_mfma_f32_16x16x32_bf16 v[76:79], v[12:15], v[44:47], 0
	v_mfma_f32_16x16x32_bf16 v[80:83], v[20:23], v[44:47], 0
	v_mfma_f32_16x16x32_bf16 v[84:87], v[12:15], v[52:55], 0
	v_mfma_f32_16x16x32_bf16 v[88:91], v[20:23], v[52:55], 0
	v_mfma_f32_16x16x32_bf16 v[60:63], v[16:19], v[32:35], v[60:63]
	v_mfma_f32_16x16x32_bf16 v[64:67], v[24:27], v[32:35], v[64:67]
	v_mfma_f32_16x16x32_bf16 v[68:71], v[16:19], v[40:43], v[68:71]
	v_mfma_f32_16x16x32_bf16 v[72:75], v[24:27], v[40:43], v[72:75]
	v_mfma_f32_16x16x32_bf16 v[76:79], v[16:19], v[48:51], v[76:79]
	v_mfma_f32_16x16x32_bf16 v[80:83], v[24:27], v[48:51], v[80:83]
	v_mfma_f32_16x16x32_bf16 v[84:87], v[16:19], v[56:59], v[84:87]
	v_mfma_f32_16x16x32_bf16 v[88:91], v[24:27], v[56:59], v[88:91]
	s_barrier
	s_add_i32 s75, s42, s53
	v_lshl_add_u64 v[108:109], v[6:7], 0, s[18:19]
	s_mov_b32 m0, s75
	ds_read_b128 v[92:95], v134
	ds_read_b128 v[96:99], v134 offset:1024
	ds_read_b128 v[100:103], v134 offset:2048
	ds_read_b128 v[104:107], v134 offset:3072
	global_load_lds_dwordx4 v[108:109], off
	v_lshl_add_u64 v[108:109], v[8:9], 0, s[18:19]
	s_add_i32 m0, s75, 0x2000
	s_nop 0
	global_load_lds_dwordx4 v[108:109], off
	s_barrier
	s_waitcnt lgkmcnt(0)
	s_waitcnt lgkmcnt(0)
	v_mfma_f32_16x16x32_bf16 v[108:111], v[92:95], v[28:31], 0
	v_mfma_f32_16x16x32_bf16 v[28:31], v[100:103], v[28:31], 0
	v_mfma_f32_16x16x32_bf16 v[108:111], v[96:99], v[32:35], v[108:111]
	v_mfma_f32_16x16x32_bf16 v[28:31], v[104:107], v[32:35], v[28:31]
	v_mfma_f32_16x16x32_bf16 v[32:35], v[92:95], v[36:39], 0
	v_mfma_f32_16x16x32_bf16 v[36:39], v[100:103], v[36:39], 0
	v_mfma_f32_16x16x32_bf16 v[32:35], v[96:99], v[40:43], v[32:35]
	v_mfma_f32_16x16x32_bf16 v[36:39], v[104:107], v[40:43], v[36:39]
	v_mfma_f32_16x16x32_bf16 v[40:43], v[92:95], v[44:47], 0
	v_mfma_f32_16x16x32_bf16 v[44:47], v[100:103], v[44:47], 0
	v_mfma_f32_16x16x32_bf16 v[40:43], v[96:99], v[48:51], v[40:43]
	v_mfma_f32_16x16x32_bf16 v[44:47], v[104:107], v[48:51], v[44:47]
	v_mfma_f32_16x16x32_bf16 v[48:51], v[92:95], v[52:55], 0
	v_mfma_f32_16x16x32_bf16 v[52:55], v[100:103], v[52:55], 0
	v_mfma_f32_16x16x32_bf16 v[48:51], v[96:99], v[56:59], v[48:51]
	v_mfma_f32_16x16x32_bf16 v[52:55], v[104:107], v[56:59], v[52:55]
	s_mov_b32 m0, s73
	v_lshl_add_u64 v[130:131], v[4:5], 0, s[18:19]
	s_barrier
	ds_read_b128 v[56:59], v10 offset:16384
	ds_read_b128 v[112:115], v10 offset:17408
	ds_read_b128 v[116:119], v10 offset:18432
	ds_read_b128 v[120:123], v10 offset:19456
	ds_read_b128 v[124:127], v10 offset:20480
	ds_read_b128 v[138:141], v10 offset:21504
	ds_read_b128 v[142:145], v10 offset:22528
	ds_read_b128 v[146:149], v10 offset:23552
	s_bitcmp1_b32 s100, 1
	s_cbranch_scc1 .Lpv2_a
	ds_write_b64 v248, v[224:225]
	ds_write_b64 v249, v[226:227]
	ds_write_b64 v248, v[228:229] offset:2048
	ds_write_b64 v249, v[230:231] offset:2048
	ds_write_b64 v248, v[232:233] offset:4096
	ds_write_b64 v249, v[234:235] offset:4096
	ds_write_b64 v248, v[236:237] offset:6144
	ds_write_b64 v249, v[238:239] offset:6144
.Lpv2_a:
	v_lshl_add_u64 v[130:131], v[2:3], 0, s[18:19]
	s_mov_b32 m0, s74
	s_nop 0
	s_barrier
	s_waitcnt lgkmcnt(0)
	s_waitcnt lgkmcnt(0)
	v_mfma_f32_16x16x32_bf16 v[150:153], v[12:15], v[56:59], 0
	v_mfma_f32_16x16x32_bf16 v[158:161], v[12:15], v[116:119], 0
	v_mfma_f32_16x16x32_bf16 v[166:169], v[12:15], v[124:127], 0
	v_mfma_f32_16x16x32_bf16 v[12:15], v[12:15], v[142:145], 0
	v_mfma_f32_16x16x32_bf16 v[150:153], v[16:19], v[112:115], v[150:153]
	v_mfma_f32_16x16x32_bf16 v[158:161], v[16:19], v[120:123], v[158:161]
	v_mfma_f32_16x16x32_bf16 v[166:169], v[16:19], v[138:141], v[166:169]
	v_mfma_f32_16x16x32_bf16 v[12:15], v[16:19], v[146:149], v[12:15]
	v_mfma_f32_16x16x32_bf16 v[16:19], v[20:23], v[142:145], 0
	v_mfma_f32_16x16x32_bf16 v[154:157], v[20:23], v[56:59], 0
	v_mfma_f32_16x16x32_bf16 v[162:165], v[20:23], v[116:119], 0
	v_mfma_f32_16x16x32_bf16 v[170:173], v[20:23], v[124:127], 0
	v_mfma_f32_16x16x32_bf16 v[16:19], v[24:27], v[146:149], v[16:19]
	v_mfma_f32_16x16x32_bf16 v[154:157], v[24:27], v[112:115], v[154:157]
	v_mfma_f32_16x16x32_bf16 v[162:165], v[24:27], v[120:123], v[162:165]
	v_mfma_f32_16x16x32_bf16 v[170:173], v[24:27], v[138:141], v[170:173]
	s_barrier
	s_add_u32 s74, s30, 0x10100
	s_addc_u32 s75, s31, 0
	s_add_i32 s53, s43, s53
	v_lshl_add_u64 v[20:21], s[74:75], 0, v[128:129]
	s_mov_b32 m0, s53
	s_nop 0
	global_load_lds_dwordx4 v[20:21], off
	v_lshl_add_u64 v[20:21], s[74:75], 0, v[0:1]
	s_add_i32 m0, s53, 0x2000
	s_nop 0
	global_load_lds_dwordx4 v[20:21], off
	s_waitcnt vmcnt(4)
	s_barrier
	v_mfma_f32_16x16x32_bf16 v[20:23], v[92:95], v[56:59], 0
	v_mfma_f32_16x16x32_bf16 v[24:27], v[100:103], v[56:59], 0
	v_mfma_f32_16x16x32_bf16 v[20:23], v[96:99], v[112:115], v[20:23]
	v_mfma_f32_16x16x32_bf16 v[24:27], v[104:107], v[112:115], v[24:27]
	v_mfma_f32_16x16x32_bf16 v[56:59], v[92:95], v[116:119], 0
	v_mfma_f32_16x16x32_bf16 v[112:115], v[100:103], v[116:119], 0
	v_mfma_f32_16x16x32_bf16 v[116:119], v[92:95], v[124:127], 0
	v_mfma_f32_16x16x32_bf16 v[92:95], v[92:95], v[142:145], 0
	v_mfma_f32_16x16x32_bf16 v[56:59], v[96:99], v[120:123], v[56:59]
	v_mfma_f32_16x16x32_bf16 v[112:115], v[104:107], v[120:123], v[112:115]
	v_mfma_f32_16x16x32_bf16 v[116:119], v[96:99], v[138:141], v[116:119]
	v_mfma_f32_16x16x32_bf16 v[120:123], v[100:103], v[124:127], 0
	v_mfma_f32_16x16x32_bf16 v[92:95], v[96:99], v[146:149], v[92:95]
	v_mfma_f32_16x16x32_bf16 v[96:99], v[100:103], v[142:145], 0
	v_mfma_f32_16x16x32_bf16 v[120:123], v[104:107], v[138:141], v[120:123]
	v_mfma_f32_16x16x32_bf16 v[96:99], v[104:107], v[146:149], v[96:99]
	s_barrier
	ds_read_b128 v[100:103], v135
	ds_read_b128 v[104:107], v135 offset:1024
	ds_read_b128 v[124:127], v135 offset:2048
	ds_read_b128 v[138:141], v135 offset:3072
	s_mov_b32 m0, s41
	v_lshl_add_u64 v[130:131], s[12:13], 0, v[128:129]
	ds_read_b128 v[142:145], v10 offset:32768
	ds_read_b128 v[146:149], v10 offset:33792
	ds_read_b128 v[174:177], v10 offset:34816
	ds_read_b128 v[178:181], v10 offset:35840
	ds_read_b128 v[192:195], v10 offset:36864
	ds_read_b128 v[196:199], v10 offset:37888
	ds_read_b128 v[200:203], v10 offset:38912
	ds_read_b128 v[204:207], v10 offset:39936
	s_bitcmp1_b32 s100, 1
	s_cbranch_scc1 .Lpv2_b
	ds_write_b64 v248, v[208:209] offset:16384
	ds_write_b64 v249, v[210:211] offset:16384
	ds_write_b64 v248, v[212:213] offset:18432
	ds_write_b64 v249, v[214:215] offset:18432
	ds_write_b64 v248, v[216:217] offset:20480
	ds_write_b64 v249, v[218:219] offset:20480
	ds_write_b64 v248, v[220:221] offset:22528
	ds_write_b64 v249, v[222:223] offset:22528
.Lpv2_b:
	v_lshl_add_u64 v[130:131], s[12:13], 0, v[0:1]
	s_mov_b32 m0, s35
	s_nop 0
	s_waitcnt lgkmcnt(8)
	s_barrier
	s_waitcnt lgkmcnt(0)
	s_waitcnt lgkmcnt(0)
	v_mfma_f32_16x16x32_bf16 v[60:63], v[100:103], v[142:145], v[60:63]
	v_mfma_f32_16x16x32_bf16 v[64:67], v[124:127], v[142:145], v[64:67]
	v_mfma_f32_16x16x32_bf16 v[68:71], v[100:103], v[174:177], v[68:71]
	v_mfma_f32_16x16x32_bf16 v[72:75], v[124:127], v[174:177], v[72:75]
	v_mfma_f32_16x16x32_bf16 v[76:79], v[100:103], v[192:195], v[76:79]
	v_mfma_f32_16x16x32_bf16 v[80:83], v[124:127], v[192:195], v[80:83]
	v_mfma_f32_16x16x32_bf16 v[84:87], v[100:103], v[200:203], v[84:87]
	v_mfma_f32_16x16x32_bf16 v[88:91], v[124:127], v[200:203], v[88:91]
	v_mfma_f32_16x16x32_bf16 v[60:63], v[104:107], v[146:149], v[60:63]
	v_mfma_f32_16x16x32_bf16 v[64:67], v[138:141], v[146:149], v[64:67]
	v_mfma_f32_16x16x32_bf16 v[68:71], v[104:107], v[178:181], v[68:71]
	v_mfma_f32_16x16x32_bf16 v[72:75], v[138:141], v[178:181], v[72:75]
	v_mfma_f32_16x16x32_bf16 v[76:79], v[104:107], v[196:199], v[76:79]
	v_mfma_f32_16x16x32_bf16 v[80:83], v[138:141], v[196:199], v[80:83]
	v_mfma_f32_16x16x32_bf16 v[84:87], v[104:107], v[204:207], v[84:87]
	v_mfma_f32_16x16x32_bf16 v[88:91], v[138:141], v[204:207], v[88:91]
	s_barrier
	s_mov_b32 m0, s68
	v_lshl_add_u64 v[6:7], v[6:7], 0, s[20:21]
	ds_read_b128 v[208:211], v184
	ds_read_b128 v[212:215], v184 offset:1024
	ds_read_b128 v[216:219], v184 offset:2048
	ds_read_b128 v[220:223], v184 offset:3072
	global_load_lds_dwordx4 v[6:7], off
	v_lshl_add_u64 v[6:7], v[8:9], 0, s[20:21]
	s_mov_b32 m0, s57
	s_nop 0
	global_load_lds_dwordx4 v[6:7], off
	s_barrier
	s_waitcnt lgkmcnt(0)
	s_waitcnt lgkmcnt(0)
	v_mfma_f32_16x16x32_bf16 v[6:9], v[208:211], v[142:145], v[108:111]
	v_mfma_f32_16x16x32_bf16 v[28:31], v[216:219], v[142:145], v[28:31]
	v_mfma_f32_16x16x32_bf16 v[32:35], v[208:211], v[174:177], v[32:35]
	v_mfma_f32_16x16x32_bf16 v[36:39], v[216:219], v[174:177], v[36:39]
	v_mfma_f32_16x16x32_bf16 v[40:43], v[208:211], v[192:195], v[40:43]
	v_mfma_f32_16x16x32_bf16 v[44:47], v[216:219], v[192:195], v[44:47]
	v_mfma_f32_16x16x32_bf16 v[48:51], v[208:211], v[200:203], v[48:51]
	v_mfma_f32_16x16x32_bf16 v[52:55], v[216:219], v[200:203], v[52:55]
	v_mfma_f32_16x16x32_bf16 v[6:9], v[212:215], v[146:149], v[6:9]
	v_mfma_f32_16x16x32_bf16 v[28:31], v[220:223], v[146:149], v[28:31]
	v_mfma_f32_16x16x32_bf16 v[32:35], v[212:215], v[178:181], v[32:35]
	v_mfma_f32_16x16x32_bf16 v[36:39], v[220:223], v[178:181], v[36:39]
	v_mfma_f32_16x16x32_bf16 v[40:43], v[212:215], v[196:199], v[40:43]
	v_mfma_f32_16x16x32_bf16 v[44:47], v[220:223], v[196:199], v[44:47]
	v_mfma_f32_16x16x32_bf16 v[48:51], v[212:215], v[204:207], v[48:51]
	v_mfma_f32_16x16x32_bf16 v[52:55], v[220:223], v[204:207], v[52:55]
	s_mov_b32 m0, s56
	v_lshl_add_u64 v[4:5], v[4:5], 0, s[20:21]
	s_barrier
	ds_read_b128 v[108:111], v10 offset:49152
	ds_read_b128 v[142:145], v10 offset:50176
	ds_read_b128 v[146:149], v10 offset:51200
	ds_read_b128 v[174:177], v10 offset:52224
	ds_read_b128 v[178:181], v10 offset:53248
	ds_read_b128 v[192:195], v10 offset:54272
	ds_read_b128 v[196:199], v10 offset:55296
	ds_read_b128 v[200:203], v10 offset:56320
	s_bitcmp1_b32 s100, 1
	s_cbranch_scc0 .Lpv2_c
	ds_write_b64 v248, v[224:225]
	ds_write_b64 v249, v[226:227]
	ds_write_b64 v248, v[228:229] offset:2048
	ds_write_b64 v249, v[230:231] offset:2048
	ds_write_b64 v248, v[232:233] offset:4096
	ds_write_b64 v249, v[234:235] offset:4096
	ds_write_b64 v248, v[236:237] offset:6144
	ds_write_b64 v249, v[238:239] offset:6144
.Lpv2_c:
	v_lshl_add_u64 v[2:3], v[2:3], 0, s[20:21]
	s_mov_b32 m0, s40
	s_nop 0
	s_barrier
	s_waitcnt lgkmcnt(0)
	s_waitcnt lgkmcnt(0)
	v_mfma_f32_16x16x32_bf16 v[2:5], v[100:103], v[108:111], v[150:153]
	v_mfma_f32_16x16x32_bf16 v[12:15], v[100:103], v[196:199], v[12:15]
	v_mfma_f32_16x16x32_bf16 v[16:19], v[124:127], v[196:199], v[16:19]
	v_mfma_f32_16x16x32_bf16 v[2:5], v[104:107], v[142:145], v[2:5]
	v_mfma_f32_16x16x32_bf16 v[150:153], v[124:127], v[108:111], v[154:157]
	v_mfma_f32_16x16x32_bf16 v[154:157], v[100:103], v[146:149], v[158:161]
	v_mfma_f32_16x16x32_bf16 v[158:161], v[124:127], v[146:149], v[162:165]
	v_mfma_f32_16x16x32_bf16 v[162:165], v[100:103], v[178:181], v[166:169]
	v_mfma_f32_16x16x32_bf16 v[166:169], v[124:127], v[178:181], v[170:173]
	v_mfma_f32_16x16x32_bf16 v[12:15], v[104:107], v[200:203], v[12:15]
	v_mfma_f32_16x16x32_bf16 v[16:19], v[138:141], v[200:203], v[16:19]
	v_mfma_f32_16x16x32_bf16 v[150:153], v[138:141], v[142:145], v[150:153]
	v_mfma_f32_16x16x32_bf16 v[154:157], v[104:107], v[174:177], v[154:157]
	v_mfma_f32_16x16x32_bf16 v[158:161], v[138:141], v[174:177], v[158:161]
	v_mfma_f32_16x16x32_bf16 v[162:165], v[104:107], v[192:195], v[162:165]
	v_mfma_f32_16x16x32_bf16 v[166:169], v[138:141], v[192:195], v[166:169]
	s_barrier
	s_add_u32 s30, s30, 0x10180
	s_addc_u32 s31, s31, 0
	s_mov_b32 m0, s34
	v_lshl_add_u64 v[100:101], s[30:31], 0, v[128:129]
	global_load_lds_dwordx4 v[100:101], off
	v_lshl_add_u64 v[100:101], s[30:31], 0, v[0:1]
	s_mov_b32 m0, s33
	s_nop 0
	global_load_lds_dwordx4 v[100:101], off
	s_waitcnt vmcnt(4)
	s_barrier
	v_mfma_f32_16x16x32_bf16 v[20:23], v[208:211], v[108:111], v[20:23]
	v_mfma_f32_16x16x32_bf16 v[24:27], v[216:219], v[108:111], v[24:27]
	v_mfma_f32_16x16x32_bf16 v[56:59], v[208:211], v[146:149], v[56:59]
	v_mfma_f32_16x16x32_bf16 v[100:103], v[216:219], v[146:149], v[112:115]
	v_mfma_f32_16x16x32_bf16 v[104:107], v[208:211], v[178:181], v[116:119]
	v_mfma_f32_16x16x32_bf16 v[108:111], v[216:219], v[178:181], v[120:123]
	v_mfma_f32_16x16x32_bf16 v[92:95], v[208:211], v[196:199], v[92:95]
	v_mfma_f32_16x16x32_bf16 v[96:99], v[216:219], v[196:199], v[96:99]
	v_mfma_f32_16x16x32_bf16 v[20:23], v[212:215], v[142:145], v[20:23]
	v_mfma_f32_16x16x32_bf16 v[24:27], v[220:223], v[142:145], v[24:27]
	v_mfma_f32_16x16x32_bf16 v[56:59], v[212:215], v[174:177], v[56:59]
	v_mfma_f32_16x16x32_bf16 v[100:103], v[220:223], v[174:177], v[100:103]
	v_mfma_f32_16x16x32_bf16 v[104:107], v[212:215], v[192:195], v[104:107]
	v_mfma_f32_16x16x32_bf16 v[108:111], v[220:223], v[192:195], v[108:111]
	v_mfma_f32_16x16x32_bf16 v[92:95], v[212:215], v[200:203], v[92:95]
	v_mfma_f32_16x16x32_bf16 v[96:99], v[220:223], v[200:203], v[96:99]
	s_mov_b32 m0, s72
	v_lshl_add_u64 v[130:131], s[14:15], 0, v[128:129]
	s_barrier
	ds_read_b128 v[112:115], v11
	ds_read_b128 v[116:119], v11 offset:1024
	ds_read_b128 v[120:123], v11 offset:2048
	ds_read_b128 v[124:127], v11 offset:3072
	ds_read_b128 v[138:141], v10
	ds_read_b128 v[142:145], v10 offset:1024
	ds_read_b128 v[146:149], v10 offset:2048
	ds_read_b128 v[170:173], v10 offset:3072
	ds_read_b128 v[174:177], v10 offset:4096
	ds_read_b128 v[178:181], v10 offset:5120
	ds_read_b128 v[192:195], v10 offset:6144
	ds_read_b128 v[196:199], v10 offset:7168
	v_lshl_add_u64 v[0:1], s[14:15], 0, v[0:1]
	s_mov_b32 m0, s69
	s_nop 0
	s_barrier
	s_waitcnt lgkmcnt(0)
	s_waitcnt lgkmcnt(0)
	v_mfma_f32_16x16x32_bf16 v[84:87], v[112:115], v[192:195], v[84:87]
	v_mfma_f32_16x16x32_bf16 v[60:63], v[112:115], v[138:141], v[60:63]
	v_mfma_f32_16x16x32_bf16 v[64:67], v[120:123], v[138:141], v[64:67]
	v_mfma_f32_16x16x32_bf16 v[68:71], v[112:115], v[146:149], v[68:71]
	v_mfma_f32_16x16x32_bf16 v[72:75], v[120:123], v[146:149], v[72:75]
	v_mfma_f32_16x16x32_bf16 v[76:79], v[112:115], v[174:177], v[76:79]
	v_mfma_f32_16x16x32_bf16 v[80:83], v[120:123], v[174:177], v[80:83]
	v_mfma_f32_16x16x32_bf16 v[200:203], v[116:119], v[196:199], v[84:87]
	v_mfma_f32_16x16x32_bf16 v[84:87], v[120:123], v[192:195], v[88:91]
	v_mfma_f32_16x16x32_bf16 v[60:63], v[116:119], v[142:145], v[60:63]
	v_mfma_f32_16x16x32_bf16 v[64:67], v[124:127], v[142:145], v[64:67]
	v_mfma_f32_16x16x32_bf16 v[68:71], v[116:119], v[170:173], v[68:71]
	v_mfma_f32_16x16x32_bf16 v[72:75], v[124:127], v[170:173], v[72:75]
	v_mfma_f32_16x16x32_bf16 v[76:79], v[116:119], v[178:181], v[76:79]
	v_mfma_f32_16x16x32_bf16 v[80:83], v[124:127], v[178:181], v[80:83]
	v_mfma_f32_16x16x32_bf16 v[88:91], v[124:127], v[196:199], v[84:87]
	s_barrier
	s_nop 0
	ds_read_b128 v[84:87], v134
	ds_read_b128 v[204:207], v134 offset:1024
	ds_read_b128 v[208:211], v134 offset:2048
	ds_read_b128 v[212:215], v134 offset:3072
	s_barrier
	s_waitcnt lgkmcnt(0)
	s_waitcnt lgkmcnt(0)
	v_mfma_f32_16x16x32_bf16 v[6:9], v[84:87], v[138:141], v[6:9]
	v_mfma_f32_16x16x32_bf16 v[28:31], v[208:211], v[138:141], v[28:31]
	v_mfma_f32_16x16x32_bf16 v[32:35], v[84:87], v[146:149], v[32:35]
	v_mfma_f32_16x16x32_bf16 v[36:39], v[208:211], v[146:149], v[36:39]
	v_mfma_f32_16x16x32_bf16 v[40:43], v[84:87], v[174:177], v[40:43]
	v_mfma_f32_16x16x32_bf16 v[44:47], v[208:211], v[174:177], v[44:47]
	v_mfma_f32_16x16x32_bf16 v[48:51], v[84:87], v[192:195], v[48:51]
	v_mfma_f32_16x16x32_bf16 v[6:9], v[204:207], v[142:145], v[6:9]
	v_mfma_f32_16x16x32_bf16 v[28:31], v[212:215], v[142:145], v[28:31]
	v_mfma_f32_16x16x32_bf16 v[32:35], v[204:207], v[170:173], v[32:35]
	v_mfma_f32_16x16x32_bf16 v[36:39], v[212:215], v[170:173], v[36:39]
	v_mfma_f32_16x16x32_bf16 v[40:43], v[204:207], v[178:181], v[40:43]
	v_mfma_f32_16x16x32_bf16 v[44:47], v[212:215], v[178:181], v[44:47]
	v_mfma_f32_16x16x32_bf16 v[48:51], v[204:207], v[196:199], v[48:51]
	v_mfma_f32_16x16x32_bf16 v[52:55], v[208:211], v[192:195], v[52:55]
	v_mfma_f32_16x16x32_bf16 v[138:141], v[212:215], v[196:199], v[52:55]
	s_barrier
	s_nop 4
	ds_read_b128 v[52:55], v10 offset:16384
	ds_read_b128 v[142:145], v10 offset:17408
	ds_read_b128 v[146:149], v10 offset:18432
	ds_read_b128 v[170:173], v10 offset:19456
	ds_read_b128 v[174:177], v10 offset:20480
	ds_read_b128 v[178:181], v10 offset:21504
	ds_read_b128 v[192:195], v10 offset:22528
	ds_read_b128 v[196:199], v10 offset:23552
	s_waitcnt vmcnt(2)
	s_barrier
	s_waitcnt lgkmcnt(0)
	s_waitcnt lgkmcnt(0)
	v_mfma_f32_16x16x32_bf16 v[0:3], v[112:115], v[52:55], v[2:5]
	v_mfma_f32_16x16x32_bf16 v[12:15], v[112:115], v[192:195], v[12:15]
	v_mfma_f32_16x16x32_bf16 v[0:3], v[116:119], v[142:145], v[0:3]
	v_mfma_f32_16x16x32_bf16 v[150:153], v[120:123], v[52:55], v[150:153]
	v_mfma_f32_16x16x32_bf16 v[154:157], v[112:115], v[146:149], v[154:157]
	v_mfma_f32_16x16x32_bf16 v[158:161], v[120:123], v[146:149], v[158:161]
	v_mfma_f32_16x16x32_bf16 v[162:165], v[112:115], v[174:177], v[162:165]
	v_mfma_f32_16x16x32_bf16 v[166:169], v[120:123], v[174:177], v[166:169]
	v_mfma_f32_16x16x32_bf16 v[12:15], v[116:119], v[196:199], v[12:15]
	v_mfma_f32_16x16x32_bf16 v[16:19], v[120:123], v[192:195], v[16:19]
	v_mfma_f32_16x16x32_bf16 v[150:153], v[124:127], v[142:145], v[150:153]
	v_mfma_f32_16x16x32_bf16 v[154:157], v[116:119], v[170:173], v[154:157]
	v_mfma_f32_16x16x32_bf16 v[158:161], v[124:127], v[170:173], v[158:161]
	v_mfma_f32_16x16x32_bf16 v[162:165], v[116:119], v[178:181], v[162:165]
	v_mfma_f32_16x16x32_bf16 v[166:169], v[124:127], v[178:181], v[166:169]
	v_mfma_f32_16x16x32_bf16 v[216:219], v[124:127], v[196:199], v[16:19]
	v_mfma_f32_16x16x32_bf16 v[16:19], v[84:87], v[52:55], v[20:23]
	v_mfma_f32_16x16x32_bf16 v[20:23], v[204:207], v[142:145], v[16:19]
	v_mfma_f32_16x16x32_bf16 v[16:19], v[208:211], v[52:55], v[24:27]
	v_mfma_f32_16x16x32_bf16 v[142:145], v[212:215], v[142:145], v[16:19]
	v_mfma_f32_16x16x32_bf16 v[16:19], v[84:87], v[146:149], v[56:59]
	v_mfma_f32_16x16x32_bf16 v[220:223], v[204:207], v[170:173], v[16:19]
	v_mfma_f32_16x16x32_bf16 v[16:19], v[208:211], v[146:149], v[100:103]
	v_mfma_f32_16x16x32_bf16 v[146:149], v[212:215], v[170:173], v[16:19]
	v_mfma_f32_16x16x32_bf16 v[16:19], v[84:87], v[174:177], v[104:107]
	v_mfma_f32_16x16x32_bf16 v[170:173], v[204:207], v[178:181], v[16:19]
	v_mfma_f32_16x16x32_bf16 v[16:19], v[208:211], v[174:177], v[108:111]
	v_mfma_f32_16x16x32_bf16 v[174:177], v[212:215], v[178:181], v[16:19]
	v_mfma_f32_16x16x32_bf16 v[16:19], v[84:87], v[192:195], v[92:95]
	v_mfma_f32_16x16x32_bf16 v[178:181], v[204:207], v[196:199], v[16:19]
	v_mfma_f32_16x16x32_bf16 v[16:19], v[208:211], v[192:195], v[96:99]
	v_mfma_f32_16x16x32_bf16 v[192:195], v[212:215], v[196:199], v[16:19]
	s_barrier
	ds_read_b128 v[56:59], v135
	ds_read_b128 v[196:199], v135 offset:1024
	ds_read_b128 v[204:207], v135 offset:2048
	ds_read_b128 v[208:211], v135 offset:3072
	s_nop 0
	ds_read_b128 v[16:19], v10 offset:32768
	ds_read_b128 v[24:27], v10 offset:33792
	ds_read_b128 v[92:95], v10 offset:34816
	ds_read_b128 v[104:107], v10 offset:35840
	ds_read_b128 v[212:215], v10 offset:36864
	ds_read_b128 v[224:227], v10 offset:37888
	ds_read_b128 v[228:231], v10 offset:38912
	ds_read_b128 v[232:235], v10 offset:39936
	s_waitcnt vmcnt(0)
	s_barrier
	s_waitcnt lgkmcnt(0)
	s_waitcnt lgkmcnt(0)
	v_mfma_f32_16x16x32_bf16 v[52:55], v[56:59], v[16:19], v[60:63]
	v_mfma_f32_16x16x32_bf16 v[116:119], v[196:199], v[24:27], v[52:55]
	v_mfma_f32_16x16x32_bf16 v[52:55], v[204:207], v[16:19], v[64:67]
	v_mfma_f32_16x16x32_bf16 v[112:115], v[208:211], v[24:27], v[52:55]
	v_mfma_f32_16x16x32_bf16 v[52:55], v[56:59], v[92:95], v[68:71]
	v_mfma_f32_16x16x32_bf16 v[100:103], v[196:199], v[104:107], v[52:55]
	v_mfma_f32_16x16x32_bf16 v[52:55], v[204:207], v[92:95], v[72:75]
	v_mfma_f32_16x16x32_bf16 v[96:99], v[208:211], v[104:107], v[52:55]
	v_mfma_f32_16x16x32_bf16 v[52:55], v[56:59], v[212:215], v[76:79]
	v_mfma_f32_16x16x32_bf16 v[84:87], v[196:199], v[224:227], v[52:55]
	v_mfma_f32_16x16x32_bf16 v[52:55], v[204:207], v[212:215], v[80:83]
	v_mfma_f32_16x16x32_bf16 v[80:83], v[208:211], v[224:227], v[52:55]
	v_mfma_f32_16x16x32_bf16 v[52:55], v[56:59], v[228:231], v[200:203]
	v_mfma_f32_16x16x32_bf16 v[64:67], v[196:199], v[232:235], v[52:55]
	v_mfma_f32_16x16x32_bf16 v[52:55], v[204:207], v[228:231], v[88:91]
	v_mfma_f32_16x16x32_bf16 v[52:55], v[208:211], v[232:235], v[52:55]
	s_barrier
	ds_read_b128 v[200:203], v184
	ds_read_b128 v[236:239], v184 offset:1024
	ds_read_b128 v[240:243], v184 offset:2048
	ds_read_b128 v[244:247], v184 offset:3072
	s_waitcnt vmcnt(0)
	s_barrier
	s_waitcnt lgkmcnt(0)
	s_waitcnt lgkmcnt(0)
	v_mfma_f32_16x16x32_bf16 v[4:7], v[200:203], v[16:19], v[6:9]
	v_mfma_f32_16x16x32_bf16 v[124:127], v[236:239], v[24:27], v[4:7]
	v_mfma_f32_16x16x32_bf16 v[4:7], v[240:243], v[16:19], v[28:31]
	v_mfma_f32_16x16x32_bf16 v[120:123], v[244:247], v[24:27], v[4:7]
	v_mfma_f32_16x16x32_bf16 v[4:7], v[200:203], v[92:95], v[32:35]
	v_mfma_f32_16x16x32_bf16 v[108:111], v[236:239], v[104:107], v[4:7]
	v_mfma_f32_16x16x32_bf16 v[4:7], v[240:243], v[92:95], v[36:39]
	v_mfma_f32_16x16x32_bf16 v[104:107], v[244:247], v[104:107], v[4:7]
	v_mfma_f32_16x16x32_bf16 v[4:7], v[200:203], v[212:215], v[40:43]
	v_mfma_f32_16x16x32_bf16 v[92:95], v[236:239], v[224:227], v[4:7]
	v_mfma_f32_16x16x32_bf16 v[4:7], v[240:243], v[212:215], v[44:47]
	v_mfma_f32_16x16x32_bf16 v[88:91], v[244:247], v[224:227], v[4:7]
	v_mfma_f32_16x16x32_bf16 v[4:7], v[200:203], v[228:231], v[48:51]
	v_mfma_f32_16x16x32_bf16 v[76:79], v[236:239], v[232:235], v[4:7]
	v_mfma_f32_16x16x32_bf16 v[4:7], v[240:243], v[228:231], v[138:141]
	v_mfma_f32_16x16x32_bf16 v[68:71], v[244:247], v[232:235], v[4:7]
	s_barrier
	s_nop 4
	v_add_u32_e32 v10, 0x16000, v10
	ds_read_b128 v[4:7], v10 offset:49152
	ds_read_b128 v[28:31], v10 offset:50176
	ds_read_b128 v[36:39], v10 offset:51200
	ds_read_b128 v[138:141], v10 offset:52224
	ds_read_b128 v[212:215], v10 offset:53248
	ds_read_b128 v[224:227], v10 offset:54272
	ds_read_b128 v[228:231], v10 offset:55296
	ds_read_b128 v[232:235], v10 offset:56320
	s_barrier
	s_waitcnt lgkmcnt(0)
	s_waitcnt lgkmcnt(0)
	v_mfma_f32_16x16x32_bf16 v[0:3], v[56:59], v[4:7], v[0:3]
	v_mfma_f32_16x16x32_bf16 v[60:63], v[196:199], v[28:31], v[0:3]
	v_mfma_f32_16x16x32_bf16 v[0:3], v[204:207], v[4:7], v[150:153]
	v_mfma_f32_16x16x32_bf16 v[48:51], v[208:211], v[28:31], v[0:3]
	v_mfma_f32_16x16x32_bf16 v[0:3], v[56:59], v[36:39], v[154:157]
	v_mfma_f32_16x16x32_bf16 v[40:43], v[196:199], v[138:141], v[0:3]
	v_mfma_f32_16x16x32_bf16 v[0:3], v[204:207], v[36:39], v[158:161]
	v_mfma_f32_16x16x32_bf16 v[32:35], v[208:211], v[138:141], v[0:3]
	v_mfma_f32_16x16x32_bf16 v[0:3], v[56:59], v[212:215], v[162:165]
	v_mfma_f32_16x16x32_bf16 v[24:27], v[196:199], v[224:227], v[0:3]
	v_mfma_f32_16x16x32_bf16 v[0:3], v[204:207], v[212:215], v[166:169]
	v_mfma_f32_16x16x32_bf16 v[16:19], v[208:211], v[224:227], v[0:3]
	v_mfma_f32_16x16x32_bf16 v[0:3], v[56:59], v[228:231], v[12:15]
	v_mfma_f32_16x16x32_bf16 v[8:11], v[196:199], v[232:235], v[0:3]
	v_mfma_f32_16x16x32_bf16 v[0:3], v[204:207], v[228:231], v[216:219]
	v_mfma_f32_16x16x32_bf16 v[0:3], v[208:211], v[232:235], v[0:3]
	v_mfma_f32_16x16x32_bf16 v[12:15], v[200:203], v[4:7], v[20:23]
	v_mfma_f32_16x16x32_bf16 v[4:7], v[240:243], v[4:7], v[142:145]
	v_mfma_f32_16x16x32_bf16 v[56:59], v[244:247], v[28:31], v[4:7]
	v_mfma_f32_16x16x32_bf16 v[4:7], v[200:203], v[36:39], v[220:223]
	v_mfma_f32_16x16x32_bf16 v[44:47], v[236:239], v[138:141], v[4:7]
	v_mfma_f32_16x16x32_bf16 v[4:7], v[240:243], v[36:39], v[146:149]
	v_mfma_f32_16x16x32_bf16 v[36:39], v[244:247], v[138:141], v[4:7]
	v_mfma_f32_16x16x32_bf16 v[4:7], v[200:203], v[212:215], v[170:173]
	v_mfma_f32_16x16x32_bf16 v[72:75], v[236:239], v[28:31], v[12:15]
	v_mfma_f32_16x16x32_bf16 v[28:31], v[236:239], v[224:227], v[4:7]
	v_mfma_f32_16x16x32_bf16 v[4:7], v[240:243], v[212:215], v[174:177]
	v_mfma_f32_16x16x32_bf16 v[20:23], v[244:247], v[224:227], v[4:7]
	v_mfma_f32_16x16x32_bf16 v[4:7], v[200:203], v[228:231], v[178:181]
	v_mfma_f32_16x16x32_bf16 v[12:15], v[236:239], v[232:235], v[4:7]
	v_mfma_f32_16x16x32_bf16 v[4:7], v[240:243], v[228:231], v[192:195]
	v_mfma_f32_16x16x32_bf16 v[4:7], v[244:247], v[232:235], v[4:7]
	s_cmpk_gt_u32 s29, 0xff
	s_barrier
	s_cbranch_scc1 .LBB0_1066
	s_barrier
	s_branch .LBB0_1066

.LBB0_1172:
	ds_read_b128 v[148:151], v146
	ds_read_b128 v[152:155], v146 offset:1024
	ds_read_b128 v[156:159], v146 offset:2048
	ds_read_b128 v[160:163], v146 offset:3072
	v_lshl_add_u64 v[180:181], v[134:135], 0, s[24:25]
	s_mov_b32 m0, s36
	v_lshl_add_u64 v[184:185], v[180:181], 0, s[10:11]
	ds_read_b128 v[164:167], v144
	ds_read_b128 v[168:171], v144 offset:1024
	ds_read_b128 v[172:175], v144 offset:2048
	ds_read_b128 v[176:179], v144 offset:3072
	ds_read_b128 v[192:195], v144 offset:4096
	ds_read_b128 v[196:199], v144 offset:5120
	ds_read_b128 v[200:203], v144 offset:6144
	ds_read_b128 v[204:207], v144 offset:7168
	global_load_lds_dwordx4 v[184:185], off
	v_lshl_add_u64 v[184:185], v[138:139], 0, s[24:25]
	v_lshl_add_u64 v[208:209], v[184:185], 0, s[10:11]
	s_mov_b32 m0, s26
	s_nop 0
	global_load_lds_dwordx4 v[208:209], off
	s_waitcnt lgkmcnt(8)
	s_barrier
	s_waitcnt lgkmcnt(0)
	s_waitcnt lgkmcnt(0)
	v_mfma_f32_16x16x32_bf16 v[124:127], v[148:151], v[164:167], v[124:127]
	v_mfma_f32_16x16x32_bf16 v[120:123], v[156:159], v[164:167], v[120:123]
	v_mfma_f32_16x16x32_bf16 v[116:119], v[148:151], v[172:175], v[116:119]
	v_mfma_f32_16x16x32_bf16 v[112:115], v[156:159], v[172:175], v[112:115]
	v_mfma_f32_16x16x32_bf16 v[108:111], v[148:151], v[192:195], v[108:111]
	v_mfma_f32_16x16x32_bf16 v[104:107], v[156:159], v[192:195], v[104:107]
	v_mfma_f32_16x16x32_bf16 v[100:103], v[148:151], v[200:203], v[100:103]
	v_mfma_f32_16x16x32_bf16 v[96:99], v[156:159], v[200:203], v[96:99]
	v_mfma_f32_16x16x32_bf16 v[124:127], v[152:155], v[168:171], v[124:127]
	v_mfma_f32_16x16x32_bf16 v[120:123], v[160:163], v[168:171], v[120:123]
	v_mfma_f32_16x16x32_bf16 v[116:119], v[152:155], v[176:179], v[116:119]
	v_mfma_f32_16x16x32_bf16 v[112:115], v[160:163], v[176:179], v[112:115]
	v_mfma_f32_16x16x32_bf16 v[108:111], v[152:155], v[196:199], v[108:111]
	v_mfma_f32_16x16x32_bf16 v[104:107], v[160:163], v[196:199], v[104:107]
	v_mfma_f32_16x16x32_bf16 v[100:103], v[152:155], v[204:207], v[100:103]
	v_mfma_f32_16x16x32_bf16 v[96:99], v[160:163], v[204:207], v[96:99]
	s_barrier
	v_lshl_add_u64 v[224:225], v[140:141], 0, s[24:25]
	s_add_i32 s37, s42, s21
	v_lshl_add_u64 v[226:227], v[224:225], 0, s[12:13]
	s_mov_b32 m0, s37
	ds_read_b128 v[208:211], v147
	ds_read_b128 v[212:215], v147 offset:1024
	ds_read_b128 v[216:219], v147 offset:2048
	ds_read_b128 v[220:223], v147 offset:3072
	global_load_lds_dwordx4 v[226:227], off
	v_lshl_add_u64 v[226:227], v[142:143], 0, s[24:25]
	v_lshl_add_u64 v[228:229], v[226:227], 0, s[12:13]
	s_add_i32 m0, s37, 0x2000
	s_nop 0
	global_load_lds_dwordx4 v[228:229], off
	s_barrier
	s_waitcnt lgkmcnt(0)
	s_waitcnt lgkmcnt(0)
	v_mfma_f32_16x16x32_bf16 v[92:95], v[208:211], v[164:167], v[92:95]
	v_mfma_f32_16x16x32_bf16 v[88:91], v[216:219], v[164:167], v[88:91]
	v_mfma_f32_16x16x32_bf16 v[84:87], v[208:211], v[172:175], v[84:87]
	v_mfma_f32_16x16x32_bf16 v[80:83], v[216:219], v[172:175], v[80:83]
	v_mfma_f32_16x16x32_bf16 v[76:79], v[208:211], v[192:195], v[76:79]
	v_mfma_f32_16x16x32_bf16 v[72:75], v[216:219], v[192:195], v[72:75]
	v_mfma_f32_16x16x32_bf16 v[68:71], v[208:211], v[200:203], v[68:71]
	v_mfma_f32_16x16x32_bf16 v[64:67], v[216:219], v[200:203], v[64:67]
	v_mfma_f32_16x16x32_bf16 v[92:95], v[212:215], v[168:171], v[92:95]
	v_mfma_f32_16x16x32_bf16 v[88:91], v[220:223], v[168:171], v[88:91]
	v_mfma_f32_16x16x32_bf16 v[84:87], v[212:215], v[176:179], v[84:87]
	v_mfma_f32_16x16x32_bf16 v[80:83], v[220:223], v[176:179], v[80:83]
	v_mfma_f32_16x16x32_bf16 v[76:79], v[212:215], v[196:199], v[76:79]
	v_mfma_f32_16x16x32_bf16 v[72:75], v[220:223], v[196:199], v[72:75]
	v_mfma_f32_16x16x32_bf16 v[68:71], v[212:215], v[204:207], v[68:71]
	v_mfma_f32_16x16x32_bf16 v[64:67], v[220:223], v[204:207], v[64:67]
	s_mov_b32 m0, s29
	v_lshl_add_u64 v[228:229], v[180:181], 0, s[12:13]
	s_barrier
	ds_read_b128 v[164:167], v144 offset:16384
	ds_read_b128 v[168:171], v144 offset:17408
	ds_read_b128 v[172:175], v144 offset:18432
	ds_read_b128 v[176:179], v144 offset:19456
	ds_read_b128 v[192:195], v144 offset:20480
	ds_read_b128 v[196:199], v144 offset:21504
	ds_read_b128 v[200:203], v144 offset:22528
	ds_read_b128 v[204:207], v144 offset:23552
	global_load_lds_dwordx4 v[228:229], off
	v_lshl_add_u64 v[228:229], v[184:185], 0, s[12:13]
	s_mov_b32 m0, s30
	s_nop 0
	global_load_lds_dwordx4 v[228:229], off
	s_barrier
	s_waitcnt lgkmcnt(0)
	s_waitcnt lgkmcnt(0)
	v_mfma_f32_16x16x32_bf16 v[60:63], v[148:151], v[164:167], v[60:63]
	v_mfma_f32_16x16x32_bf16 v[56:59], v[156:159], v[164:167], v[56:59]
	v_mfma_f32_16x16x32_bf16 v[52:55], v[148:151], v[172:175], v[52:55]
	v_mfma_f32_16x16x32_bf16 v[48:51], v[156:159], v[172:175], v[48:51]
	v_mfma_f32_16x16x32_bf16 v[44:47], v[148:151], v[192:195], v[44:47]
	v_mfma_f32_16x16x32_bf16 v[40:43], v[156:159], v[192:195], v[40:43]
	v_mfma_f32_16x16x32_bf16 v[36:39], v[148:151], v[200:203], v[36:39]
	v_mfma_f32_16x16x32_bf16 v[32:35], v[156:159], v[200:203], v[32:35]
	v_mfma_f32_16x16x32_bf16 v[60:63], v[152:155], v[168:171], v[60:63]
	v_mfma_f32_16x16x32_bf16 v[56:59], v[160:163], v[168:171], v[56:59]
	v_mfma_f32_16x16x32_bf16 v[52:55], v[152:155], v[176:179], v[52:55]
	v_mfma_f32_16x16x32_bf16 v[48:51], v[160:163], v[176:179], v[48:51]
	v_mfma_f32_16x16x32_bf16 v[44:47], v[152:155], v[196:199], v[44:47]
	v_mfma_f32_16x16x32_bf16 v[40:43], v[160:163], v[196:199], v[40:43]
	v_mfma_f32_16x16x32_bf16 v[36:39], v[152:155], v[204:207], v[36:39]
	v_mfma_f32_16x16x32_bf16 v[32:35], v[160:163], v[204:207], v[32:35]
	s_barrier
	s_add_i32 s37, s43, s21
	v_lshl_add_u64 v[148:149], v[224:225], 0, s[14:15]
	s_mov_b32 m0, s37
	s_nop 0
	global_load_lds_dwordx4 v[148:149], off
	v_lshl_add_u64 v[148:149], v[226:227], 0, s[14:15]
	s_add_i32 m0, s37, 0x2000
	s_nop 0
	global_load_lds_dwordx4 v[148:149], off
	s_waitcnt vmcnt(6)
	s_barrier
	v_mfma_f32_16x16x32_bf16 v[28:31], v[208:211], v[164:167], v[28:31]
	v_mfma_f32_16x16x32_bf16 v[24:27], v[216:219], v[164:167], v[24:27]
	v_mfma_f32_16x16x32_bf16 v[20:23], v[208:211], v[172:175], v[20:23]
	v_mfma_f32_16x16x32_bf16 v[16:19], v[216:219], v[172:175], v[16:19]
	v_mfma_f32_16x16x32_bf16 v[12:15], v[208:211], v[192:195], v[12:15]
	v_mfma_f32_16x16x32_bf16 v[8:11], v[216:219], v[192:195], v[8:11]
	v_mfma_f32_16x16x32_bf16 v[4:7], v[208:211], v[200:203], v[4:7]
	v_mfma_f32_16x16x32_bf16 v[0:3], v[216:219], v[200:203], v[0:3]
	v_mfma_f32_16x16x32_bf16 v[28:31], v[212:215], v[168:171], v[28:31]
	v_mfma_f32_16x16x32_bf16 v[24:27], v[220:223], v[168:171], v[24:27]
	v_mfma_f32_16x16x32_bf16 v[20:23], v[212:215], v[176:179], v[20:23]
	v_mfma_f32_16x16x32_bf16 v[16:19], v[220:223], v[176:179], v[16:19]
	v_mfma_f32_16x16x32_bf16 v[12:15], v[212:215], v[196:199], v[12:15]
	v_mfma_f32_16x16x32_bf16 v[8:11], v[220:223], v[196:199], v[8:11]
	v_mfma_f32_16x16x32_bf16 v[4:7], v[212:215], v[204:207], v[4:7]
	v_mfma_f32_16x16x32_bf16 v[0:3], v[220:223], v[204:207], v[0:3]
	s_add_i32 s37, 0, 0x18000
	v_add_u32_e32 v160, s37, v145
	s_barrier
	ds_read_b128 v[148:151], v160
	ds_read_b128 v[152:155], v160 offset:1024
	ds_read_b128 v[156:159], v160 offset:2048
	ds_read_b128 v[160:163], v160 offset:3072
	s_mov_b32 m0, s31
	v_lshl_add_u64 v[208:209], v[180:181], 0, s[14:15]
	ds_read_b128 v[164:167], v144 offset:32768
	ds_read_b128 v[168:171], v144 offset:33792
	ds_read_b128 v[172:175], v144 offset:34816
	ds_read_b128 v[176:179], v144 offset:35840
	ds_read_b128 v[192:195], v144 offset:36864
	ds_read_b128 v[196:199], v144 offset:37888
	ds_read_b128 v[200:203], v144 offset:38912
	ds_read_b128 v[204:207], v144 offset:39936
	global_load_lds_dwordx4 v[208:209], off
	v_lshl_add_u64 v[208:209], v[184:185], 0, s[14:15]
	s_mov_b32 m0, s33
	s_nop 0
	global_load_lds_dwordx4 v[208:209], off
	s_waitcnt lgkmcnt(8)
	s_barrier
	s_waitcnt lgkmcnt(0)
	s_waitcnt lgkmcnt(0)
	v_mfma_f32_16x16x32_bf16 v[124:127], v[148:151], v[164:167], v[124:127]
	v_mfma_f32_16x16x32_bf16 v[120:123], v[156:159], v[164:167], v[120:123]
	v_mfma_f32_16x16x32_bf16 v[116:119], v[148:151], v[172:175], v[116:119]
	v_mfma_f32_16x16x32_bf16 v[112:115], v[156:159], v[172:175], v[112:115]
	v_mfma_f32_16x16x32_bf16 v[108:111], v[148:151], v[192:195], v[108:111]
	v_mfma_f32_16x16x32_bf16 v[104:107], v[156:159], v[192:195], v[104:107]
	v_mfma_f32_16x16x32_bf16 v[100:103], v[148:151], v[200:203], v[100:103]
	v_mfma_f32_16x16x32_bf16 v[96:99], v[156:159], v[200:203], v[96:99]
	v_mfma_f32_16x16x32_bf16 v[124:127], v[152:155], v[168:171], v[124:127]
	v_mfma_f32_16x16x32_bf16 v[120:123], v[160:163], v[168:171], v[120:123]
	v_mfma_f32_16x16x32_bf16 v[116:119], v[152:155], v[176:179], v[116:119]
	v_mfma_f32_16x16x32_bf16 v[112:115], v[160:163], v[176:179], v[112:115]
	v_mfma_f32_16x16x32_bf16 v[108:111], v[152:155], v[196:199], v[108:111]
	v_mfma_f32_16x16x32_bf16 v[104:107], v[160:163], v[196:199], v[104:107]
	v_mfma_f32_16x16x32_bf16 v[100:103], v[152:155], v[204:207], v[100:103]
	v_mfma_f32_16x16x32_bf16 v[96:99], v[160:163], v[204:207], v[96:99]
	s_barrier
	s_add_i32 s40, 0, 0x1c000
	s_add_i32 s37, s37, s21
	v_add_u32_e32 v190, s40, v145
	v_lshl_add_u64 v[228:229], v[224:225], 0, s[16:17]
	s_mov_b32 m0, s37
	ds_read_b128 v[208:211], v190
	ds_read_b128 v[212:215], v190 offset:1024
	ds_read_b128 v[216:219], v190 offset:2048
	ds_read_b128 v[220:223], v190 offset:3072
	global_load_lds_dwordx4 v[228:229], off
	v_lshl_add_u64 v[228:229], v[226:227], 0, s[16:17]
	s_add_i32 m0, s37, 0x2000
	s_nop 0
	global_load_lds_dwordx4 v[228:229], off
	s_barrier
	s_waitcnt lgkmcnt(0)
	s_waitcnt lgkmcnt(0)
	v_mfma_f32_16x16x32_bf16 v[92:95], v[208:211], v[164:167], v[92:95]
	v_mfma_f32_16x16x32_bf16 v[88:91], v[216:219], v[164:167], v[88:91]
	v_mfma_f32_16x16x32_bf16 v[84:87], v[208:211], v[172:175], v[84:87]
	v_mfma_f32_16x16x32_bf16 v[80:83], v[216:219], v[172:175], v[80:83]
	v_mfma_f32_16x16x32_bf16 v[76:79], v[208:211], v[192:195], v[76:79]
	v_mfma_f32_16x16x32_bf16 v[72:75], v[216:219], v[192:195], v[72:75]
	v_mfma_f32_16x16x32_bf16 v[68:71], v[208:211], v[200:203], v[68:71]
	v_mfma_f32_16x16x32_bf16 v[64:67], v[216:219], v[200:203], v[64:67]
	v_mfma_f32_16x16x32_bf16 v[92:95], v[212:215], v[168:171], v[92:95]
	v_mfma_f32_16x16x32_bf16 v[88:91], v[220:223], v[168:171], v[88:91]
	v_mfma_f32_16x16x32_bf16 v[84:87], v[212:215], v[176:179], v[84:87]
	v_mfma_f32_16x16x32_bf16 v[80:83], v[220:223], v[176:179], v[80:83]
	v_mfma_f32_16x16x32_bf16 v[76:79], v[212:215], v[196:199], v[76:79]
	v_mfma_f32_16x16x32_bf16 v[72:75], v[220:223], v[196:199], v[72:75]
	v_mfma_f32_16x16x32_bf16 v[68:71], v[212:215], v[204:207], v[68:71]
	v_mfma_f32_16x16x32_bf16 v[64:67], v[220:223], v[204:207], v[64:67]
	s_mov_b32 m0, s34
	v_lshl_add_u64 v[180:181], v[180:181], 0, s[16:17]
	s_barrier
	ds_read_b128 v[164:167], v144 offset:49152
	ds_read_b128 v[168:171], v144 offset:50176
	ds_read_b128 v[172:175], v144 offset:51200
	ds_read_b128 v[176:179], v144 offset:52224
	ds_read_b128 v[192:195], v144 offset:53248
	ds_read_b128 v[196:199], v144 offset:54272
	ds_read_b128 v[200:203], v144 offset:55296
	ds_read_b128 v[204:207], v144 offset:56320
	global_load_lds_dwordx4 v[180:181], off
	v_lshl_add_u64 v[180:181], v[184:185], 0, s[16:17]
	s_mov_b32 m0, s35
	s_nop 0
	global_load_lds_dwordx4 v[180:181], off
	s_barrier
	s_waitcnt lgkmcnt(0)
	s_waitcnt lgkmcnt(0)
	v_mfma_f32_16x16x32_bf16 v[60:63], v[148:151], v[164:167], v[60:63]
	v_mfma_f32_16x16x32_bf16 v[56:59], v[156:159], v[164:167], v[56:59]
	v_mfma_f32_16x16x32_bf16 v[52:55], v[148:151], v[172:175], v[52:55]
	v_mfma_f32_16x16x32_bf16 v[48:51], v[156:159], v[172:175], v[48:51]
	v_mfma_f32_16x16x32_bf16 v[44:47], v[148:151], v[192:195], v[44:47]
	v_mfma_f32_16x16x32_bf16 v[40:43], v[156:159], v[192:195], v[40:43]
	v_mfma_f32_16x16x32_bf16 v[36:39], v[148:151], v[200:203], v[36:39]
	v_mfma_f32_16x16x32_bf16 v[32:35], v[156:159], v[200:203], v[32:35]
	v_mfma_f32_16x16x32_bf16 v[60:63], v[152:155], v[168:171], v[60:63]
	v_mfma_f32_16x16x32_bf16 v[56:59], v[160:163], v[168:171], v[56:59]
	v_mfma_f32_16x16x32_bf16 v[52:55], v[152:155], v[176:179], v[52:55]
	v_mfma_f32_16x16x32_bf16 v[48:51], v[160:163], v[176:179], v[48:51]
	v_mfma_f32_16x16x32_bf16 v[44:47], v[152:155], v[196:199], v[44:47]
	v_mfma_f32_16x16x32_bf16 v[40:43], v[160:163], v[196:199], v[40:43]
	v_mfma_f32_16x16x32_bf16 v[36:39], v[152:155], v[204:207], v[36:39]
	v_mfma_f32_16x16x32_bf16 v[32:35], v[160:163], v[204:207], v[32:35]
	s_barrier
	s_add_i32 s37, s40, s21
	v_lshl_add_u64 v[148:149], v[224:225], 0, s[18:19]
	s_mov_b32 m0, s37
	s_nop 0
	global_load_lds_dwordx4 v[148:149], off
	v_lshl_add_u64 v[148:149], v[226:227], 0, s[18:19]
	s_add_i32 m0, s37, 0x2000
	s_nop 0
	global_load_lds_dwordx4 v[148:149], off
	s_waitcnt vmcnt(6)
	s_barrier
	v_mfma_f32_16x16x32_bf16 v[28:31], v[208:211], v[164:167], v[28:31]
	v_mfma_f32_16x16x32_bf16 v[24:27], v[216:219], v[164:167], v[24:27]
	v_mfma_f32_16x16x32_bf16 v[20:23], v[208:211], v[172:175], v[20:23]
	v_mfma_f32_16x16x32_bf16 v[16:19], v[216:219], v[172:175], v[16:19]
	v_mfma_f32_16x16x32_bf16 v[12:15], v[208:211], v[192:195], v[12:15]
	v_mfma_f32_16x16x32_bf16 v[8:11], v[216:219], v[192:195], v[8:11]
	v_mfma_f32_16x16x32_bf16 v[4:7], v[208:211], v[200:203], v[4:7]
	v_mfma_f32_16x16x32_bf16 v[0:3], v[216:219], v[200:203], v[0:3]
	v_mfma_f32_16x16x32_bf16 v[28:31], v[212:215], v[168:171], v[28:31]
	v_mfma_f32_16x16x32_bf16 v[24:27], v[220:223], v[168:171], v[24:27]
	v_mfma_f32_16x16x32_bf16 v[20:23], v[212:215], v[176:179], v[20:23]
	v_mfma_f32_16x16x32_bf16 v[16:19], v[220:223], v[176:179], v[16:19]
	v_mfma_f32_16x16x32_bf16 v[12:15], v[212:215], v[196:199], v[12:15]
	v_mfma_f32_16x16x32_bf16 v[8:11], v[220:223], v[196:199], v[8:11]
	v_mfma_f32_16x16x32_bf16 v[4:7], v[212:215], v[204:207], v[4:7]
	v_mfma_f32_16x16x32_bf16 v[0:3], v[220:223], v[204:207], v[0:3]
	s_add_i32 s27, s27, 2
	s_add_u32 s24, s24, 0x100
	s_addc_u32 s25, s25, 0
	s_cmp_gt_u32 s27, 11
	s_barrier
	s_cbranch_scc0 .LBB0_1172
	v_add_u32_e32 v142, 0, v145
	s_add_u32 s22, s22, 0x40780
	v_add_u32_e32 v134, 0x10000, v142
	s_addc_u32 s23, s23, 0
	s_mov_b32 m0, s36
	ds_read_b128 v[138:141], v134
	ds_read_b128 v[146:149], v134 offset:1024
	ds_read_b128 v[150:153], v134 offset:2048
	ds_read_b128 v[154:157], v134 offset:3072
	ds_read_b128 v[158:161], v144
	ds_read_b128 v[162:165], v144 offset:1024
	ds_read_b128 v[166:169], v144 offset:2048
	ds_read_b128 v[170:173], v144 offset:3072
	ds_read_b128 v[174:177], v144 offset:4096
	ds_read_b128 v[178:181], v144 offset:5120
	ds_read_b128 v[192:195], v144 offset:6144
	ds_read_b128 v[196:199], v144 offset:7168
	v_lshl_add_u64 v[134:135], s[22:23], 0, v[128:129]
	global_load_lds_dwordx4 v[134:135], off
	v_lshl_add_u64 v[130:131], s[22:23], 0, v[130:131]
	s_mov_b32 m0, s26
	s_nop 0
	global_load_lds_dwordx4 v[130:131], off
	s_barrier
	s_waitcnt lgkmcnt(0)
	s_waitcnt lgkmcnt(0)
	v_mfma_f32_16x16x32_bf16 v[124:127], v[138:141], v[158:161], v[124:127]
	v_mfma_f32_16x16x32_bf16 v[120:123], v[150:153], v[158:161], v[120:123]
	v_mfma_f32_16x16x32_bf16 v[116:119], v[138:141], v[166:169], v[116:119]
	v_mfma_f32_16x16x32_bf16 v[104:107], v[150:153], v[174:177], v[104:107]
	v_mfma_f32_16x16x32_bf16 v[100:103], v[138:141], v[192:195], v[100:103]
	v_mfma_f32_16x16x32_bf16 v[124:127], v[146:149], v[162:165], v[124:127]
	v_mfma_f32_16x16x32_bf16 v[120:123], v[154:157], v[162:165], v[120:123]
	v_mfma_f32_16x16x32_bf16 v[116:119], v[146:149], v[170:173], v[116:119]
	v_mfma_f32_16x16x32_bf16 v[112:115], v[150:153], v[166:169], v[112:115]
	v_mfma_f32_16x16x32_bf16 v[108:111], v[138:141], v[174:177], v[108:111]
	v_mfma_f32_16x16x32_bf16 v[104:107], v[154:157], v[178:181], v[104:107]
	v_mfma_f32_16x16x32_bf16 v[100:103], v[146:149], v[196:199], v[100:103]
	v_mfma_f32_16x16x32_bf16 v[96:99], v[150:153], v[192:195], v[96:99]
	v_mfma_f32_16x16x32_bf16 v[200:203], v[154:157], v[170:173], v[112:115]
	v_mfma_f32_16x16x32_bf16 v[204:207], v[146:149], v[178:181], v[108:111]
	v_mfma_f32_16x16x32_bf16 v[208:211], v[154:157], v[196:199], v[96:99]
	v_add_u32_e32 v128, 0x14000, v142
	s_barrier
	s_nop 1
	ds_read_b128 v[96:99], v128
	ds_read_b128 v[108:111], v128 offset:1024
	ds_read_b128 v[112:115], v128 offset:2048
	ds_read_b128 v[212:215], v128 offset:3072
	s_barrier
	s_waitcnt lgkmcnt(0)
	s_waitcnt lgkmcnt(0)
	v_mfma_f32_16x16x32_bf16 v[88:91], v[112:115], v[158:161], v[88:91]
	v_mfma_f32_16x16x32_bf16 v[84:87], v[96:99], v[166:169], v[84:87]
	v_mfma_f32_16x16x32_bf16 v[72:75], v[112:115], v[174:177], v[72:75]
	v_mfma_f32_16x16x32_bf16 v[68:71], v[96:99], v[192:195], v[68:71]
	v_mfma_f32_16x16x32_bf16 v[92:95], v[96:99], v[158:161], v[92:95]
	v_mfma_f32_16x16x32_bf16 v[88:91], v[212:215], v[162:165], v[88:91]
	v_mfma_f32_16x16x32_bf16 v[84:87], v[108:111], v[170:173], v[84:87]
	v_mfma_f32_16x16x32_bf16 v[80:83], v[112:115], v[166:169], v[80:83]
	v_mfma_f32_16x16x32_bf16 v[76:79], v[96:99], v[174:177], v[76:79]
	v_mfma_f32_16x16x32_bf16 v[72:75], v[212:215], v[178:181], v[72:75]
	v_mfma_f32_16x16x32_bf16 v[68:71], v[108:111], v[196:199], v[68:71]
	v_mfma_f32_16x16x32_bf16 v[64:67], v[112:115], v[192:195], v[64:67]
	v_mfma_f32_16x16x32_bf16 v[216:219], v[108:111], v[162:165], v[92:95]
	v_mfma_f32_16x16x32_bf16 v[158:161], v[212:215], v[170:173], v[80:83]
	v_mfma_f32_16x16x32_bf16 v[162:165], v[108:111], v[178:181], v[76:79]
	v_mfma_f32_16x16x32_bf16 v[166:169], v[212:215], v[196:199], v[64:67]
	s_barrier
	s_nop 1
	ds_read_b128 v[64:67], v144 offset:16384
	ds_read_b128 v[76:79], v144 offset:17408
	ds_read_b128 v[80:83], v144 offset:18432
	ds_read_b128 v[92:95], v144 offset:19456
	ds_read_b128 v[170:173], v144 offset:20480
	ds_read_b128 v[174:177], v144 offset:21504
	ds_read_b128 v[178:181], v144 offset:22528
	ds_read_b128 v[192:195], v144 offset:23552
	s_waitcnt vmcnt(4)
	s_barrier
	s_waitcnt lgkmcnt(0)
	s_waitcnt lgkmcnt(0)
	v_mfma_f32_16x16x32_bf16 v[60:63], v[138:141], v[64:67], v[60:63]
	v_mfma_f32_16x16x32_bf16 v[56:59], v[150:153], v[64:67], v[56:59]
	v_mfma_f32_16x16x32_bf16 v[52:55], v[138:141], v[80:83], v[52:55]
	v_mfma_f32_16x16x32_bf16 v[40:43], v[150:153], v[170:173], v[40:43]
	v_mfma_f32_16x16x32_bf16 v[36:39], v[138:141], v[178:181], v[36:39]
	v_mfma_f32_16x16x32_bf16 v[60:63], v[146:149], v[76:79], v[60:63]
	v_mfma_f32_16x16x32_bf16 v[56:59], v[154:157], v[76:79], v[56:59]
	v_mfma_f32_16x16x32_bf16 v[52:55], v[146:149], v[92:95], v[52:55]
	v_mfma_f32_16x16x32_bf16 v[48:51], v[150:153], v[80:83], v[48:51]
	v_mfma_f32_16x16x32_bf16 v[44:47], v[138:141], v[170:173], v[44:47]
	v_mfma_f32_16x16x32_bf16 v[40:43], v[154:157], v[174:177], v[40:43]
	v_mfma_f32_16x16x32_bf16 v[36:39], v[146:149], v[192:195], v[36:39]
	v_mfma_f32_16x16x32_bf16 v[32:35], v[150:153], v[178:181], v[32:35]
	v_mfma_f32_16x16x32_bf16 v[196:199], v[154:157], v[92:95], v[48:51]
	v_mfma_f32_16x16x32_bf16 v[220:223], v[146:149], v[174:177], v[44:47]
	v_mfma_f32_16x16x32_bf16 v[138:141], v[154:157], v[192:195], v[32:35]
	v_mfma_f32_16x16x32_bf16 v[24:27], v[112:115], v[64:67], v[24:27]
	v_mfma_f32_16x16x32_bf16 v[20:23], v[96:99], v[80:83], v[20:23]
	v_mfma_f32_16x16x32_bf16 v[8:11], v[112:115], v[170:173], v[8:11]
	v_mfma_f32_16x16x32_bf16 v[4:7], v[96:99], v[178:181], v[4:7]
	v_mfma_f32_16x16x32_bf16 v[28:31], v[96:99], v[64:67], v[28:31]
	v_mfma_f32_16x16x32_bf16 v[24:27], v[212:215], v[76:79], v[24:27]
	v_mfma_f32_16x16x32_bf16 v[20:23], v[108:111], v[92:95], v[20:23]
	v_mfma_f32_16x16x32_bf16 v[16:19], v[112:115], v[80:83], v[16:19]
	v_mfma_f32_16x16x32_bf16 v[12:15], v[96:99], v[170:173], v[12:15]
	v_mfma_f32_16x16x32_bf16 v[8:11], v[212:215], v[174:177], v[8:11]
	v_mfma_f32_16x16x32_bf16 v[4:7], v[108:111], v[192:195], v[4:7]
	v_mfma_f32_16x16x32_bf16 v[0:3], v[112:115], v[178:181], v[0:3]
	v_mfma_f32_16x16x32_bf16 v[146:149], v[108:111], v[76:79], v[28:31]
	v_mfma_f32_16x16x32_bf16 v[150:153], v[212:215], v[92:95], v[16:19]
	v_mfma_f32_16x16x32_bf16 v[154:157], v[108:111], v[174:177], v[12:15]
	v_mfma_f32_16x16x32_bf16 v[170:173], v[212:215], v[192:195], v[0:3]
	v_add_u32_e32 v16, 0x18000, v142
	s_barrier
	s_nop 0
	ds_read_b128 v[0:3], v16
	ds_read_b128 v[12:15], v16 offset:1024
	ds_read_b128 v[174:177], v16 offset:2048
	ds_read_b128 v[178:181], v16 offset:3072
	ds_read_b128 v[16:19], v144 offset:32768
	ds_read_b128 v[28:31], v144 offset:33792
	ds_read_b128 v[32:35], v144 offset:34816
	ds_read_b128 v[44:47], v144 offset:35840
	ds_read_b128 v[48:51], v144 offset:36864
	ds_read_b128 v[192:195], v144 offset:37888
	ds_read_b128 v[212:215], v144 offset:38912
	ds_read_b128 v[224:227], v144 offset:39936
	s_waitcnt vmcnt(2)
	s_barrier
	s_waitcnt lgkmcnt(0)
	s_waitcnt lgkmcnt(0)
	v_mfma_f32_16x16x32_bf16 v[64:67], v[0:3], v[16:19], v[124:127]
	v_mfma_f32_16x16x32_bf16 v[124:127], v[12:15], v[28:31], v[64:67]
	v_mfma_f32_16x16x32_bf16 v[64:67], v[174:177], v[16:19], v[120:123]
	v_mfma_f32_16x16x32_bf16 v[112:115], v[178:181], v[28:31], v[64:67]
	v_mfma_f32_16x16x32_bf16 v[64:67], v[0:3], v[32:35], v[116:119]
	v_mfma_f32_16x16x32_bf16 v[108:111], v[12:15], v[44:47], v[64:67]
	v_mfma_f32_16x16x32_bf16 v[64:67], v[174:177], v[32:35], v[200:203]
	v_mfma_f32_16x16x32_bf16 v[96:99], v[178:181], v[44:47], v[64:67]
	v_mfma_f32_16x16x32_bf16 v[64:67], v[0:3], v[48:51], v[204:207]
	v_mfma_f32_16x16x32_bf16 v[92:95], v[12:15], v[192:195], v[64:67]
	v_mfma_f32_16x16x32_bf16 v[64:67], v[174:177], v[48:51], v[104:107]
	v_mfma_f32_16x16x32_bf16 v[80:83], v[178:181], v[192:195], v[64:67]
	v_mfma_f32_16x16x32_bf16 v[64:67], v[0:3], v[212:215], v[100:103]
	v_mfma_f32_16x16x32_bf16 v[76:79], v[12:15], v[224:227], v[64:67]
	v_mfma_f32_16x16x32_bf16 v[64:67], v[174:177], v[212:215], v[208:211]
	v_mfma_f32_16x16x32_bf16 v[64:67], v[178:181], v[224:227], v[64:67]
	v_add_u32_e32 v100, 0x1c000, v142
	s_barrier
	ds_read_b128 v[200:203], v100
	ds_read_b128 v[204:207], v100 offset:1024
	ds_read_b128 v[208:211], v100 offset:2048
	ds_read_b128 v[228:231], v100 offset:3072
	s_waitcnt vmcnt(0)
	s_barrier
	s_waitcnt lgkmcnt(0)
	s_waitcnt lgkmcnt(0)
	v_mfma_f32_16x16x32_bf16 v[100:103], v[200:203], v[16:19], v[216:219]
	v_mfma_f32_16x16x32_bf16 v[16:19], v[208:211], v[16:19], v[88:91]
	v_mfma_f32_16x16x32_bf16 v[116:119], v[228:231], v[28:31], v[16:19]
	v_mfma_f32_16x16x32_bf16 v[16:19], v[200:203], v[32:35], v[84:87]
	v_mfma_f32_16x16x32_bf16 v[120:123], v[204:207], v[28:31], v[100:103]
	v_mfma_f32_16x16x32_bf16 v[100:103], v[204:207], v[44:47], v[16:19]
	v_mfma_f32_16x16x32_bf16 v[16:19], v[208:211], v[32:35], v[158:161]
	v_mfma_f32_16x16x32_bf16 v[104:107], v[228:231], v[44:47], v[16:19]
	v_mfma_f32_16x16x32_bf16 v[16:19], v[200:203], v[48:51], v[162:165]
	v_mfma_f32_16x16x32_bf16 v[84:87], v[204:207], v[192:195], v[16:19]
	v_mfma_f32_16x16x32_bf16 v[16:19], v[208:211], v[48:51], v[72:75]
	v_mfma_f32_16x16x32_bf16 v[88:91], v[228:231], v[192:195], v[16:19]
	v_mfma_f32_16x16x32_bf16 v[16:19], v[200:203], v[212:215], v[68:71]
	v_mfma_f32_16x16x32_bf16 v[68:71], v[204:207], v[224:227], v[16:19]
	v_mfma_f32_16x16x32_bf16 v[16:19], v[208:211], v[212:215], v[166:169]
	v_mfma_f32_16x16x32_bf16 v[72:75], v[228:231], v[224:227], v[16:19]
	s_barrier
	ds_read_b128 v[158:161], v144 offset:49152
	ds_read_b128 v[162:165], v144 offset:50176
	ds_read_b128 v[166:169], v144 offset:51200
	ds_read_b128 v[192:195], v144 offset:52224
	ds_read_b128 v[212:215], v144 offset:53248
	ds_read_b128 v[216:219], v144 offset:54272
	ds_read_b128 v[224:227], v144 offset:55296
	ds_read_b128 v[142:145], v144 offset:56320
	s_barrier
	s_waitcnt lgkmcnt(0)
	s_waitcnt lgkmcnt(0)
	v_mfma_f32_16x16x32_bf16 v[16:19], v[0:3], v[158:161], v[60:63]
	v_mfma_f32_16x16x32_bf16 v[60:63], v[12:15], v[162:165], v[16:19]
	v_mfma_f32_16x16x32_bf16 v[16:19], v[174:177], v[158:161], v[56:59]
	v_mfma_f32_16x16x32_bf16 v[48:51], v[178:181], v[162:165], v[16:19]
	v_mfma_f32_16x16x32_bf16 v[16:19], v[0:3], v[166:169], v[52:55]
	v_mfma_f32_16x16x32_bf16 v[44:47], v[12:15], v[192:195], v[16:19]
	v_mfma_f32_16x16x32_bf16 v[16:19], v[174:177], v[166:169], v[196:199]
	v_mfma_f32_16x16x32_bf16 v[32:35], v[178:181], v[192:195], v[16:19]
	v_mfma_f32_16x16x32_bf16 v[16:19], v[0:3], v[212:215], v[220:223]
	v_mfma_f32_16x16x32_bf16 v[0:3], v[0:3], v[224:227], v[36:39]
	v_mfma_f32_16x16x32_bf16 v[28:31], v[12:15], v[216:219], v[16:19]
	v_mfma_f32_16x16x32_bf16 v[16:19], v[174:177], v[212:215], v[40:43]
	v_mfma_f32_16x16x32_bf16 v[12:15], v[12:15], v[142:145], v[0:3]
	v_mfma_f32_16x16x32_bf16 v[0:3], v[174:177], v[224:227], v[138:141]
	v_mfma_f32_16x16x32_bf16 v[16:19], v[178:181], v[216:219], v[16:19]
	v_mfma_f32_16x16x32_bf16 v[0:3], v[178:181], v[142:145], v[0:3]
	v_mfma_f32_16x16x32_bf16 v[36:39], v[200:203], v[158:161], v[146:149]
	v_mfma_f32_16x16x32_bf16 v[20:23], v[200:203], v[166:169], v[20:23]
	v_mfma_f32_16x16x32_bf16 v[52:55], v[204:207], v[162:165], v[36:39]
	v_mfma_f32_16x16x32_bf16 v[24:27], v[208:211], v[158:161], v[24:27]
	v_mfma_f32_16x16x32_bf16 v[36:39], v[204:207], v[192:195], v[20:23]
	v_mfma_f32_16x16x32_bf16 v[20:23], v[208:211], v[166:169], v[150:153]
	v_mfma_f32_16x16x32_bf16 v[8:11], v[208:211], v[212:215], v[8:11]
	v_mfma_f32_16x16x32_bf16 v[56:59], v[228:231], v[162:165], v[24:27]
	v_mfma_f32_16x16x32_bf16 v[40:43], v[228:231], v[192:195], v[20:23]
	v_mfma_f32_16x16x32_bf16 v[20:23], v[200:203], v[212:215], v[154:157]
	v_mfma_f32_16x16x32_bf16 v[24:27], v[228:231], v[216:219], v[8:11]
	v_mfma_f32_16x16x32_bf16 v[4:7], v[200:203], v[224:227], v[4:7]
	v_mfma_f32_16x16x32_bf16 v[8:11], v[208:211], v[224:227], v[170:173]
	v_mfma_f32_16x16x32_bf16 v[20:23], v[204:207], v[216:219], v[20:23]
	v_mfma_f32_16x16x32_bf16 v[4:7], v[204:207], v[142:145], v[4:7]
	v_mfma_f32_16x16x32_bf16 v[8:11], v[228:231], v[142:145], v[8:11]
	s_cmpk_lt_u32 s1, 0x100
	s_barrier
	s_cbranch_scc0 .LBB0_1175
	s_barrier

.LBB0_1317:
	v_add_u32_e32 v158, s42, v145
	ds_read_b128 v[146:149], v158
	ds_read_b128 v[150:153], v158 offset:1024
	ds_read_b128 v[154:157], v158 offset:2048
	ds_read_b128 v[158:161], v158 offset:3072
	v_lshl_add_u64 v[184:185], v[134:135], 0, s[40:41]
	s_add_i32 s61, s47, 0xc000
	v_lshl_add_u64 v[204:205], v[184:185], 0, s[8:9]
	s_mov_b32 m0, s61
	v_lshl_add_u64 v[220:221], v[138:139], 0, s[40:41]
	s_add_i32 s60, s47, 0xe000
	ds_read_b128 v[162:165], v144
	ds_read_b128 v[166:169], v144 offset:1024
	ds_read_b128 v[170:173], v144 offset:2048
	ds_read_b128 v[174:177], v144 offset:3072
	ds_read_b128 v[178:181], v144 offset:4096
	ds_read_b128 v[192:195], v144 offset:5120
	ds_read_b128 v[196:199], v144 offset:6144
	ds_read_b128 v[200:203], v144 offset:7168
	global_load_lds_dwordx4 v[204:205], off
	v_lshl_add_u64 v[204:205], v[220:221], 0, s[8:9]
	s_mov_b32 m0, s60
	s_nop 0
	global_load_lds_dwordx4 v[204:205], off
	s_waitcnt lgkmcnt(8)
	s_barrier
	s_waitcnt lgkmcnt(0)
	s_waitcnt lgkmcnt(0)
	v_mfma_f32_16x16x32_bf16 v[124:127], v[146:149], v[162:165], v[124:127]
	v_mfma_f32_16x16x32_bf16 v[120:123], v[154:157], v[162:165], v[120:123]
	v_mfma_f32_16x16x32_bf16 v[116:119], v[146:149], v[170:173], v[116:119]
	v_mfma_f32_16x16x32_bf16 v[112:115], v[154:157], v[170:173], v[112:115]
	v_mfma_f32_16x16x32_bf16 v[108:111], v[146:149], v[178:181], v[108:111]
	v_mfma_f32_16x16x32_bf16 v[104:107], v[154:157], v[178:181], v[104:107]
	v_mfma_f32_16x16x32_bf16 v[100:103], v[146:149], v[196:199], v[100:103]
	v_mfma_f32_16x16x32_bf16 v[96:99], v[154:157], v[196:199], v[96:99]
	v_mfma_f32_16x16x32_bf16 v[124:127], v[150:153], v[166:169], v[124:127]
	v_mfma_f32_16x16x32_bf16 v[120:123], v[158:161], v[166:169], v[120:123]
	v_mfma_f32_16x16x32_bf16 v[116:119], v[150:153], v[174:177], v[116:119]
	v_mfma_f32_16x16x32_bf16 v[112:115], v[158:161], v[174:177], v[112:115]
	v_mfma_f32_16x16x32_bf16 v[108:111], v[150:153], v[192:195], v[108:111]
	v_mfma_f32_16x16x32_bf16 v[104:107], v[158:161], v[192:195], v[104:107]
	v_mfma_f32_16x16x32_bf16 v[100:103], v[150:153], v[200:203], v[100:103]
	v_mfma_f32_16x16x32_bf16 v[96:99], v[158:161], v[200:203], v[96:99]
	s_barrier
	v_lshl_add_u64 v[222:223], v[140:141], 0, s[40:41]
	s_add_i32 s62, s42, s33
	v_add_u32_e32 v190, s43, v145
	v_lshl_add_u64 v[224:225], v[222:223], 0, s[10:11]
	s_mov_b32 m0, s62
	ds_read_b128 v[204:207], v190
	ds_read_b128 v[208:211], v190 offset:1024
	ds_read_b128 v[212:215], v190 offset:2048
	ds_read_b128 v[216:219], v190 offset:3072
	global_load_lds_dwordx4 v[224:225], off
	v_lshl_add_u64 v[224:225], v[142:143], 0, s[40:41]
	v_lshl_add_u64 v[226:227], v[224:225], 0, s[10:11]
	s_add_i32 m0, s62, 0x2000
	s_nop 0
	global_load_lds_dwordx4 v[226:227], off
	s_barrier
	s_waitcnt lgkmcnt(0)
	s_waitcnt lgkmcnt(0)
	v_mfma_f32_16x16x32_bf16 v[92:95], v[204:207], v[162:165], v[92:95]
	v_mfma_f32_16x16x32_bf16 v[88:91], v[212:215], v[162:165], v[88:91]
	v_mfma_f32_16x16x32_bf16 v[84:87], v[204:207], v[170:173], v[84:87]
	v_mfma_f32_16x16x32_bf16 v[80:83], v[212:215], v[170:173], v[80:83]
	v_mfma_f32_16x16x32_bf16 v[76:79], v[204:207], v[178:181], v[76:79]
	v_mfma_f32_16x16x32_bf16 v[72:75], v[212:215], v[178:181], v[72:75]
	v_mfma_f32_16x16x32_bf16 v[68:71], v[204:207], v[196:199], v[68:71]
	v_mfma_f32_16x16x32_bf16 v[64:67], v[212:215], v[196:199], v[64:67]
	v_mfma_f32_16x16x32_bf16 v[92:95], v[208:211], v[166:169], v[92:95]
	v_mfma_f32_16x16x32_bf16 v[88:91], v[216:219], v[166:169], v[88:91]
	v_mfma_f32_16x16x32_bf16 v[84:87], v[208:211], v[174:177], v[84:87]
	v_mfma_f32_16x16x32_bf16 v[80:83], v[216:219], v[174:177], v[80:83]
	v_mfma_f32_16x16x32_bf16 v[76:79], v[208:211], v[192:195], v[76:79]
	v_mfma_f32_16x16x32_bf16 v[72:75], v[216:219], v[192:195], v[72:75]
	v_mfma_f32_16x16x32_bf16 v[68:71], v[208:211], v[200:203], v[68:71]
	v_mfma_f32_16x16x32_bf16 v[64:67], v[216:219], v[200:203], v[64:67]
	s_mov_b32 m0, s47
	v_lshl_add_u64 v[226:227], v[184:185], 0, s[10:11]
	s_barrier
	ds_read_b128 v[162:165], v144 offset:16384
	ds_read_b128 v[166:169], v144 offset:17408
	ds_read_b128 v[170:173], v144 offset:18432
	ds_read_b128 v[174:177], v144 offset:19456
	ds_read_b128 v[178:181], v144 offset:20480
	ds_read_b128 v[192:195], v144 offset:21504
	ds_read_b128 v[196:199], v144 offset:22528
	ds_read_b128 v[200:203], v144 offset:23552
	global_load_lds_dwordx4 v[226:227], off
	v_lshl_add_u64 v[226:227], v[220:221], 0, s[10:11]
	s_mov_b32 m0, s50
	s_nop 0
	global_load_lds_dwordx4 v[226:227], off
	s_barrier
	s_waitcnt lgkmcnt(0)
	s_waitcnt lgkmcnt(0)
	v_mfma_f32_16x16x32_bf16 v[60:63], v[146:149], v[162:165], v[60:63]
	v_mfma_f32_16x16x32_bf16 v[56:59], v[154:157], v[162:165], v[56:59]
	v_mfma_f32_16x16x32_bf16 v[52:55], v[146:149], v[170:173], v[52:55]
	v_mfma_f32_16x16x32_bf16 v[48:51], v[154:157], v[170:173], v[48:51]
	v_mfma_f32_16x16x32_bf16 v[44:47], v[146:149], v[178:181], v[44:47]
	v_mfma_f32_16x16x32_bf16 v[40:43], v[154:157], v[178:181], v[40:43]
	v_mfma_f32_16x16x32_bf16 v[36:39], v[146:149], v[196:199], v[36:39]
	v_mfma_f32_16x16x32_bf16 v[32:35], v[154:157], v[196:199], v[32:35]
	v_mfma_f32_16x16x32_bf16 v[60:63], v[150:153], v[166:169], v[60:63]
	v_mfma_f32_16x16x32_bf16 v[56:59], v[158:161], v[166:169], v[56:59]
	v_mfma_f32_16x16x32_bf16 v[52:55], v[150:153], v[174:177], v[52:55]
	v_mfma_f32_16x16x32_bf16 v[48:51], v[158:161], v[174:177], v[48:51]
	v_mfma_f32_16x16x32_bf16 v[44:47], v[150:153], v[192:195], v[44:47]
	v_mfma_f32_16x16x32_bf16 v[40:43], v[158:161], v[192:195], v[40:43]
	v_mfma_f32_16x16x32_bf16 v[36:39], v[150:153], v[200:203], v[36:39]
	v_mfma_f32_16x16x32_bf16 v[32:35], v[158:161], v[200:203], v[32:35]
	s_barrier
	s_add_i32 s62, s43, s33
	v_lshl_add_u64 v[146:147], v[222:223], 0, s[12:13]
	s_mov_b32 m0, s62
	s_nop 0
	global_load_lds_dwordx4 v[146:147], off
	v_lshl_add_u64 v[146:147], v[224:225], 0, s[12:13]
	s_add_i32 m0, s62, 0x2000
	s_nop 0
	global_load_lds_dwordx4 v[146:147], off
	s_waitcnt vmcnt(6)
	s_barrier
	v_mfma_f32_16x16x32_bf16 v[28:31], v[204:207], v[162:165], v[28:31]
	v_mfma_f32_16x16x32_bf16 v[24:27], v[212:215], v[162:165], v[24:27]
	v_mfma_f32_16x16x32_bf16 v[20:23], v[204:207], v[170:173], v[20:23]
	v_mfma_f32_16x16x32_bf16 v[16:19], v[212:215], v[170:173], v[16:19]
	v_mfma_f32_16x16x32_bf16 v[12:15], v[204:207], v[178:181], v[12:15]
	v_mfma_f32_16x16x32_bf16 v[8:11], v[212:215], v[178:181], v[8:11]
	v_mfma_f32_16x16x32_bf16 v[4:7], v[204:207], v[196:199], v[4:7]
	v_mfma_f32_16x16x32_bf16 v[0:3], v[212:215], v[196:199], v[0:3]
	v_mfma_f32_16x16x32_bf16 v[28:31], v[208:211], v[166:169], v[28:31]
	v_mfma_f32_16x16x32_bf16 v[24:27], v[216:219], v[166:169], v[24:27]
	v_mfma_f32_16x16x32_bf16 v[20:23], v[208:211], v[174:177], v[20:23]
	v_mfma_f32_16x16x32_bf16 v[16:19], v[216:219], v[174:177], v[16:19]
	v_mfma_f32_16x16x32_bf16 v[12:15], v[208:211], v[192:195], v[12:15]
	v_mfma_f32_16x16x32_bf16 v[8:11], v[216:219], v[192:195], v[8:11]
	v_mfma_f32_16x16x32_bf16 v[4:7], v[208:211], v[200:203], v[4:7]
	v_mfma_f32_16x16x32_bf16 v[0:3], v[216:219], v[200:203], v[0:3]
	s_add_i32 s62, 0, 0x18000
	v_add_u32_e32 v158, s62, v145
	s_barrier
	ds_read_b128 v[146:149], v158
	ds_read_b128 v[150:153], v158 offset:1024
	ds_read_b128 v[154:157], v158 offset:2048
	ds_read_b128 v[158:161], v158 offset:3072
	s_mov_b32 m0, s51
	v_lshl_add_u64 v[204:205], v[184:185], 0, s[12:13]
	ds_read_b128 v[162:165], v144 offset:32768
	ds_read_b128 v[166:169], v144 offset:33792
	ds_read_b128 v[170:173], v144 offset:34816
	ds_read_b128 v[174:177], v144 offset:35840
	ds_read_b128 v[178:181], v144 offset:36864
	ds_read_b128 v[192:195], v144 offset:37888
	ds_read_b128 v[196:199], v144 offset:38912
	ds_read_b128 v[200:203], v144 offset:39936
	global_load_lds_dwordx4 v[204:205], off
	v_lshl_add_u64 v[204:205], v[220:221], 0, s[12:13]
	s_mov_b32 m0, s52
	s_nop 0
	global_load_lds_dwordx4 v[204:205], off
	s_waitcnt lgkmcnt(8)
	s_barrier
	s_waitcnt lgkmcnt(0)
	s_waitcnt lgkmcnt(0)
	v_mfma_f32_16x16x32_bf16 v[124:127], v[146:149], v[162:165], v[124:127]
	v_mfma_f32_16x16x32_bf16 v[120:123], v[154:157], v[162:165], v[120:123]
	v_mfma_f32_16x16x32_bf16 v[116:119], v[146:149], v[170:173], v[116:119]
	v_mfma_f32_16x16x32_bf16 v[112:115], v[154:157], v[170:173], v[112:115]
	v_mfma_f32_16x16x32_bf16 v[108:111], v[146:149], v[178:181], v[108:111]
	v_mfma_f32_16x16x32_bf16 v[104:107], v[154:157], v[178:181], v[104:107]
	v_mfma_f32_16x16x32_bf16 v[100:103], v[146:149], v[196:199], v[100:103]
	v_mfma_f32_16x16x32_bf16 v[96:99], v[154:157], v[196:199], v[96:99]
	v_mfma_f32_16x16x32_bf16 v[124:127], v[150:153], v[166:169], v[124:127]
	v_mfma_f32_16x16x32_bf16 v[120:123], v[158:161], v[166:169], v[120:123]
	v_mfma_f32_16x16x32_bf16 v[116:119], v[150:153], v[174:177], v[116:119]
	v_mfma_f32_16x16x32_bf16 v[112:115], v[158:161], v[174:177], v[112:115]
	v_mfma_f32_16x16x32_bf16 v[108:111], v[150:153], v[192:195], v[108:111]
	v_mfma_f32_16x16x32_bf16 v[104:107], v[158:161], v[192:195], v[104:107]
	v_mfma_f32_16x16x32_bf16 v[100:103], v[150:153], v[200:203], v[100:103]
	v_mfma_f32_16x16x32_bf16 v[96:99], v[158:161], v[200:203], v[96:99]
	s_barrier
	s_add_i32 s63, 0, 0x1c000
	s_add_i32 s62, s62, s33
	v_add_u32_e32 v190, s63, v145
	v_lshl_add_u64 v[226:227], v[222:223], 0, s[14:15]
	s_mov_b32 m0, s62
	ds_read_b128 v[204:207], v190
	ds_read_b128 v[208:211], v190 offset:1024
	ds_read_b128 v[212:215], v190 offset:2048
	ds_read_b128 v[216:219], v190 offset:3072
	global_load_lds_dwordx4 v[226:227], off
	v_lshl_add_u64 v[226:227], v[224:225], 0, s[14:15]
	s_add_i32 m0, s62, 0x2000
	s_nop 0
	global_load_lds_dwordx4 v[226:227], off
	s_barrier
	s_waitcnt lgkmcnt(0)
	s_waitcnt lgkmcnt(0)
	v_mfma_f32_16x16x32_bf16 v[92:95], v[204:207], v[162:165], v[92:95]
	v_mfma_f32_16x16x32_bf16 v[88:91], v[212:215], v[162:165], v[88:91]
	v_mfma_f32_16x16x32_bf16 v[84:87], v[204:207], v[170:173], v[84:87]
	v_mfma_f32_16x16x32_bf16 v[80:83], v[212:215], v[170:173], v[80:83]
	v_mfma_f32_16x16x32_bf16 v[76:79], v[204:207], v[178:181], v[76:79]
	v_mfma_f32_16x16x32_bf16 v[72:75], v[212:215], v[178:181], v[72:75]
	v_mfma_f32_16x16x32_bf16 v[68:71], v[204:207], v[196:199], v[68:71]
	v_mfma_f32_16x16x32_bf16 v[64:67], v[212:215], v[196:199], v[64:67]
	v_mfma_f32_16x16x32_bf16 v[92:95], v[208:211], v[166:169], v[92:95]
	v_mfma_f32_16x16x32_bf16 v[88:91], v[216:219], v[166:169], v[88:91]
	v_mfma_f32_16x16x32_bf16 v[84:87], v[208:211], v[174:177], v[84:87]
	v_mfma_f32_16x16x32_bf16 v[80:83], v[216:219], v[174:177], v[80:83]
	v_mfma_f32_16x16x32_bf16 v[76:79], v[208:211], v[192:195], v[76:79]
	v_mfma_f32_16x16x32_bf16 v[72:75], v[216:219], v[192:195], v[72:75]
	v_mfma_f32_16x16x32_bf16 v[68:71], v[208:211], v[200:203], v[68:71]
	v_mfma_f32_16x16x32_bf16 v[64:67], v[216:219], v[200:203], v[64:67]
	s_mov_b32 m0, s53
	v_lshl_add_u64 v[184:185], v[184:185], 0, s[14:15]
	s_barrier
	ds_read_b128 v[162:165], v144 offset:49152
	ds_read_b128 v[166:169], v144 offset:50176
	ds_read_b128 v[170:173], v144 offset:51200
	ds_read_b128 v[174:177], v144 offset:52224
	ds_read_b128 v[178:181], v144 offset:53248
	ds_read_b128 v[192:195], v144 offset:54272
	ds_read_b128 v[196:199], v144 offset:55296
	ds_read_b128 v[200:203], v144 offset:56320
	global_load_lds_dwordx4 v[184:185], off
	v_lshl_add_u64 v[184:185], v[220:221], 0, s[14:15]
	s_mov_b32 m0, s56
	s_nop 0
	global_load_lds_dwordx4 v[184:185], off
	s_barrier
	s_waitcnt lgkmcnt(0)
	s_waitcnt lgkmcnt(0)
	v_mfma_f32_16x16x32_bf16 v[60:63], v[146:149], v[162:165], v[60:63]
	v_mfma_f32_16x16x32_bf16 v[56:59], v[154:157], v[162:165], v[56:59]
	v_mfma_f32_16x16x32_bf16 v[52:55], v[146:149], v[170:173], v[52:55]
	v_mfma_f32_16x16x32_bf16 v[48:51], v[154:157], v[170:173], v[48:51]
	v_mfma_f32_16x16x32_bf16 v[44:47], v[146:149], v[178:181], v[44:47]
	v_mfma_f32_16x16x32_bf16 v[40:43], v[154:157], v[178:181], v[40:43]
	v_mfma_f32_16x16x32_bf16 v[36:39], v[146:149], v[196:199], v[36:39]
	v_mfma_f32_16x16x32_bf16 v[32:35], v[154:157], v[196:199], v[32:35]
	v_mfma_f32_16x16x32_bf16 v[60:63], v[150:153], v[166:169], v[60:63]
	v_mfma_f32_16x16x32_bf16 v[56:59], v[158:161], v[166:169], v[56:59]
	v_mfma_f32_16x16x32_bf16 v[52:55], v[150:153], v[174:177], v[52:55]
	v_mfma_f32_16x16x32_bf16 v[48:51], v[158:161], v[174:177], v[48:51]
	v_mfma_f32_16x16x32_bf16 v[44:47], v[150:153], v[192:195], v[44:47]
	v_mfma_f32_16x16x32_bf16 v[40:43], v[158:161], v[192:195], v[40:43]
	v_mfma_f32_16x16x32_bf16 v[36:39], v[150:153], v[200:203], v[36:39]
	v_mfma_f32_16x16x32_bf16 v[32:35], v[158:161], v[200:203], v[32:35]
	s_barrier
	s_add_i32 s62, s63, s33
	v_lshl_add_u64 v[146:147], v[222:223], 0, s[16:17]
	s_mov_b32 m0, s62
	s_nop 0
	global_load_lds_dwordx4 v[146:147], off
	v_lshl_add_u64 v[146:147], v[224:225], 0, s[16:17]
	s_add_i32 m0, s62, 0x2000
	s_nop 0
	global_load_lds_dwordx4 v[146:147], off
	s_waitcnt vmcnt(6)
	s_barrier
	v_mfma_f32_16x16x32_bf16 v[28:31], v[204:207], v[162:165], v[28:31]
	v_mfma_f32_16x16x32_bf16 v[24:27], v[212:215], v[162:165], v[24:27]
	v_mfma_f32_16x16x32_bf16 v[20:23], v[204:207], v[170:173], v[20:23]
	v_mfma_f32_16x16x32_bf16 v[16:19], v[212:215], v[170:173], v[16:19]
	v_mfma_f32_16x16x32_bf16 v[12:15], v[204:207], v[178:181], v[12:15]
	v_mfma_f32_16x16x32_bf16 v[8:11], v[212:215], v[178:181], v[8:11]
	v_mfma_f32_16x16x32_bf16 v[4:7], v[204:207], v[196:199], v[4:7]
	v_mfma_f32_16x16x32_bf16 v[0:3], v[212:215], v[196:199], v[0:3]
	v_mfma_f32_16x16x32_bf16 v[28:31], v[208:211], v[166:169], v[28:31]
	v_mfma_f32_16x16x32_bf16 v[24:27], v[216:219], v[166:169], v[24:27]
	v_mfma_f32_16x16x32_bf16 v[20:23], v[208:211], v[174:177], v[20:23]
	v_mfma_f32_16x16x32_bf16 v[16:19], v[216:219], v[174:177], v[16:19]
	v_mfma_f32_16x16x32_bf16 v[12:15], v[208:211], v[192:195], v[12:15]
	v_mfma_f32_16x16x32_bf16 v[8:11], v[216:219], v[192:195], v[8:11]
	v_mfma_f32_16x16x32_bf16 v[4:7], v[208:211], v[200:203], v[4:7]
	v_mfma_f32_16x16x32_bf16 v[0:3], v[216:219], v[200:203], v[0:3]
	s_add_i32 s57, s57, 2
	s_add_u32 s40, s40, 0x100
	s_addc_u32 s41, s41, 0
	s_cmp_gt_u32 s57, 11
	s_barrier
	s_cbranch_scc0 .LBB0_1317
	v_add_u32_e32 v142, 0, v145
	s_add_u32 s40, s28, 0x40780
	v_add_u32_e32 v134, 0x10000, v142
	s_addc_u32 s41, s29, 0
	s_mov_b32 m0, s61
	ds_read_b128 v[138:141], v134
	ds_read_b128 v[146:149], v134 offset:1024
	ds_read_b128 v[150:153], v134 offset:2048
	ds_read_b128 v[154:157], v134 offset:3072
	ds_read_b128 v[158:161], v144
	ds_read_b128 v[162:165], v144 offset:1024
	ds_read_b128 v[166:169], v144 offset:2048
	ds_read_b128 v[170:173], v144 offset:3072
	ds_read_b128 v[174:177], v144 offset:4096
	ds_read_b128 v[178:181], v144 offset:5120
	ds_read_b128 v[192:195], v144 offset:6144
	ds_read_b128 v[196:199], v144 offset:7168
	v_lshl_add_u64 v[134:135], s[40:41], 0, v[128:129]
	global_load_lds_dwordx4 v[134:135], off
	v_lshl_add_u64 v[130:131], s[40:41], 0, v[130:131]
	s_mov_b32 m0, s60
	s_nop 0
	global_load_lds_dwordx4 v[130:131], off
	s_barrier
	s_waitcnt lgkmcnt(0)
	s_waitcnt lgkmcnt(0)
	v_mfma_f32_16x16x32_bf16 v[124:127], v[138:141], v[158:161], v[124:127]
	v_mfma_f32_16x16x32_bf16 v[120:123], v[150:153], v[158:161], v[120:123]
	v_mfma_f32_16x16x32_bf16 v[108:111], v[138:141], v[174:177], v[108:111]
	v_mfma_f32_16x16x32_bf16 v[104:107], v[150:153], v[174:177], v[104:107]
	v_mfma_f32_16x16x32_bf16 v[124:127], v[146:149], v[162:165], v[124:127]
	v_mfma_f32_16x16x32_bf16 v[120:123], v[154:157], v[162:165], v[120:123]
	v_mfma_f32_16x16x32_bf16 v[116:119], v[138:141], v[166:169], v[116:119]
	v_mfma_f32_16x16x32_bf16 v[112:115], v[150:153], v[166:169], v[112:115]
	v_mfma_f32_16x16x32_bf16 v[108:111], v[146:149], v[178:181], v[108:111]
	v_mfma_f32_16x16x32_bf16 v[104:107], v[154:157], v[178:181], v[104:107]
	v_mfma_f32_16x16x32_bf16 v[100:103], v[138:141], v[192:195], v[100:103]
	v_mfma_f32_16x16x32_bf16 v[96:99], v[150:153], v[192:195], v[96:99]
	v_mfma_f32_16x16x32_bf16 v[200:203], v[146:149], v[170:173], v[116:119]
	v_mfma_f32_16x16x32_bf16 v[204:207], v[154:157], v[170:173], v[112:115]
	v_mfma_f32_16x16x32_bf16 v[208:211], v[146:149], v[196:199], v[100:103]
	v_mfma_f32_16x16x32_bf16 v[212:215], v[154:157], v[196:199], v[96:99]
	v_add_u32_e32 v116, 0x14000, v142
	s_barrier
	s_nop 0
	ds_read_b128 v[96:99], v116
	ds_read_b128 v[100:103], v116 offset:1024
	ds_read_b128 v[112:115], v116 offset:2048
	ds_read_b128 v[116:119], v116 offset:3072
	s_barrier
	s_waitcnt lgkmcnt(0)
	s_waitcnt lgkmcnt(0)
	v_mfma_f32_16x16x32_bf16 v[92:95], v[96:99], v[158:161], v[92:95]
	v_mfma_f32_16x16x32_bf16 v[88:91], v[112:115], v[158:161], v[88:91]
	v_mfma_f32_16x16x32_bf16 v[76:79], v[96:99], v[174:177], v[76:79]
	v_mfma_f32_16x16x32_bf16 v[72:75], v[112:115], v[174:177], v[72:75]
	v_mfma_f32_16x16x32_bf16 v[92:95], v[100:103], v[162:165], v[92:95]
	v_mfma_f32_16x16x32_bf16 v[88:91], v[116:119], v[162:165], v[88:91]
	v_mfma_f32_16x16x32_bf16 v[84:87], v[96:99], v[166:169], v[84:87]
	v_mfma_f32_16x16x32_bf16 v[80:83], v[112:115], v[166:169], v[80:83]
	v_mfma_f32_16x16x32_bf16 v[76:79], v[100:103], v[178:181], v[76:79]
	v_mfma_f32_16x16x32_bf16 v[72:75], v[116:119], v[178:181], v[72:75]
	v_mfma_f32_16x16x32_bf16 v[68:71], v[96:99], v[192:195], v[68:71]
	v_mfma_f32_16x16x32_bf16 v[64:67], v[112:115], v[192:195], v[64:67]
	v_mfma_f32_16x16x32_bf16 v[158:161], v[100:103], v[170:173], v[84:87]
	v_mfma_f32_16x16x32_bf16 v[162:165], v[116:119], v[170:173], v[80:83]
	v_mfma_f32_16x16x32_bf16 v[166:169], v[100:103], v[196:199], v[68:71]
	v_mfma_f32_16x16x32_bf16 v[170:173], v[116:119], v[196:199], v[64:67]
	s_barrier
	s_nop 1
	ds_read_b128 v[64:67], v144 offset:16384
	ds_read_b128 v[68:71], v144 offset:17408
	ds_read_b128 v[80:83], v144 offset:18432
	ds_read_b128 v[84:87], v144 offset:19456
	ds_read_b128 v[174:177], v144 offset:20480
	ds_read_b128 v[178:181], v144 offset:21504
	ds_read_b128 v[192:195], v144 offset:22528
	ds_read_b128 v[196:199], v144 offset:23552
	s_waitcnt vmcnt(4)
	s_barrier
	s_waitcnt lgkmcnt(0)
	s_waitcnt lgkmcnt(0)
	v_mfma_f32_16x16x32_bf16 v[60:63], v[138:141], v[64:67], v[60:63]
	v_mfma_f32_16x16x32_bf16 v[56:59], v[150:153], v[64:67], v[56:59]
	v_mfma_f32_16x16x32_bf16 v[44:47], v[138:141], v[174:177], v[44:47]
	v_mfma_f32_16x16x32_bf16 v[40:43], v[150:153], v[174:177], v[40:43]
	v_mfma_f32_16x16x32_bf16 v[60:63], v[146:149], v[68:71], v[60:63]
	v_mfma_f32_16x16x32_bf16 v[56:59], v[154:157], v[68:71], v[56:59]
	v_mfma_f32_16x16x32_bf16 v[52:55], v[138:141], v[80:83], v[52:55]
	v_mfma_f32_16x16x32_bf16 v[48:51], v[150:153], v[80:83], v[48:51]
	v_mfma_f32_16x16x32_bf16 v[44:47], v[146:149], v[178:181], v[44:47]
	v_mfma_f32_16x16x32_bf16 v[40:43], v[154:157], v[178:181], v[40:43]
	v_mfma_f32_16x16x32_bf16 v[36:39], v[138:141], v[192:195], v[36:39]
	v_mfma_f32_16x16x32_bf16 v[32:35], v[150:153], v[192:195], v[32:35]
	v_mfma_f32_16x16x32_bf16 v[216:219], v[146:149], v[84:87], v[52:55]
	v_mfma_f32_16x16x32_bf16 v[220:223], v[154:157], v[84:87], v[48:51]
	v_mfma_f32_16x16x32_bf16 v[138:141], v[146:149], v[196:199], v[36:39]
	v_mfma_f32_16x16x32_bf16 v[146:149], v[154:157], v[196:199], v[32:35]
	v_mfma_f32_16x16x32_bf16 v[28:31], v[96:99], v[64:67], v[28:31]
	v_mfma_f32_16x16x32_bf16 v[24:27], v[112:115], v[64:67], v[24:27]
	v_mfma_f32_16x16x32_bf16 v[12:15], v[96:99], v[174:177], v[12:15]
	v_mfma_f32_16x16x32_bf16 v[8:11], v[112:115], v[174:177], v[8:11]
	v_mfma_f32_16x16x32_bf16 v[28:31], v[100:103], v[68:71], v[28:31]
	v_mfma_f32_16x16x32_bf16 v[24:27], v[116:119], v[68:71], v[24:27]
	v_mfma_f32_16x16x32_bf16 v[20:23], v[96:99], v[80:83], v[20:23]
	v_mfma_f32_16x16x32_bf16 v[16:19], v[112:115], v[80:83], v[16:19]
	v_mfma_f32_16x16x32_bf16 v[12:15], v[100:103], v[178:181], v[12:15]
	v_mfma_f32_16x16x32_bf16 v[8:11], v[116:119], v[178:181], v[8:11]
	v_mfma_f32_16x16x32_bf16 v[4:7], v[96:99], v[192:195], v[4:7]
	v_mfma_f32_16x16x32_bf16 v[0:3], v[112:115], v[192:195], v[0:3]
	v_mfma_f32_16x16x32_bf16 v[150:153], v[100:103], v[84:87], v[20:23]
	v_mfma_f32_16x16x32_bf16 v[154:157], v[116:119], v[84:87], v[16:19]
	v_mfma_f32_16x16x32_bf16 v[174:177], v[100:103], v[196:199], v[4:7]
	v_mfma_f32_16x16x32_bf16 v[178:181], v[116:119], v[196:199], v[0:3]
	v_add_u32_e32 v16, 0x18000, v142
	s_barrier
	s_nop 0
	ds_read_b128 v[0:3], v16
	ds_read_b128 v[4:7], v16 offset:1024
	ds_read_b128 v[192:195], v16 offset:2048
	ds_read_b128 v[196:199], v16 offset:3072
	ds_read_b128 v[16:19], v144 offset:32768
	ds_read_b128 v[20:23], v144 offset:33792
	ds_read_b128 v[32:35], v144 offset:34816
	ds_read_b128 v[36:39], v144 offset:35840
	ds_read_b128 v[48:51], v144 offset:36864
	ds_read_b128 v[52:55], v144 offset:37888
	ds_read_b128 v[224:227], v144 offset:38912
	ds_read_b128 v[228:231], v144 offset:39936
	s_waitcnt vmcnt(2)
	s_barrier
	s_waitcnt lgkmcnt(0)
	s_waitcnt lgkmcnt(0)
	v_mfma_f32_16x16x32_bf16 v[64:67], v[0:3], v[16:19], v[124:127]
	v_mfma_f32_16x16x32_bf16 v[116:119], v[4:7], v[20:23], v[64:67]
	v_mfma_f32_16x16x32_bf16 v[64:67], v[192:195], v[16:19], v[120:123]
	v_mfma_f32_16x16x32_bf16 v[112:115], v[196:199], v[20:23], v[64:67]
	v_mfma_f32_16x16x32_bf16 v[64:67], v[0:3], v[32:35], v[200:203]
	v_mfma_f32_16x16x32_bf16 v[100:103], v[4:7], v[36:39], v[64:67]
	v_mfma_f32_16x16x32_bf16 v[64:67], v[192:195], v[32:35], v[204:207]
	v_mfma_f32_16x16x32_bf16 v[96:99], v[196:199], v[36:39], v[64:67]
	v_mfma_f32_16x16x32_bf16 v[64:67], v[0:3], v[48:51], v[108:111]
	v_mfma_f32_16x16x32_bf16 v[84:87], v[4:7], v[52:55], v[64:67]
	v_mfma_f32_16x16x32_bf16 v[64:67], v[192:195], v[48:51], v[104:107]
	v_mfma_f32_16x16x32_bf16 v[80:83], v[196:199], v[52:55], v[64:67]
	v_mfma_f32_16x16x32_bf16 v[64:67], v[0:3], v[224:227], v[208:211]
	v_mfma_f32_16x16x32_bf16 v[68:71], v[4:7], v[228:231], v[64:67]
	v_mfma_f32_16x16x32_bf16 v[64:67], v[192:195], v[224:227], v[212:215]
	v_mfma_f32_16x16x32_bf16 v[64:67], v[196:199], v[228:231], v[64:67]
	v_add_u32_e32 v104, 0x1c000, v142
	s_barrier
	ds_read_b128 v[200:203], v104
	ds_read_b128 v[204:207], v104 offset:1024
	ds_read_b128 v[208:211], v104 offset:2048
	ds_read_b128 v[212:215], v104 offset:3072
	s_waitcnt vmcnt(0)
	s_barrier
	s_waitcnt lgkmcnt(0)
	s_waitcnt lgkmcnt(0)
	v_mfma_f32_16x16x32_bf16 v[92:95], v[200:203], v[16:19], v[92:95]
	v_mfma_f32_16x16x32_bf16 v[16:19], v[208:211], v[16:19], v[88:91]
	v_mfma_f32_16x16x32_bf16 v[120:123], v[212:215], v[20:23], v[16:19]
	v_mfma_f32_16x16x32_bf16 v[16:19], v[200:203], v[32:35], v[158:161]
	v_mfma_f32_16x16x32_bf16 v[108:111], v[204:207], v[36:39], v[16:19]
	v_mfma_f32_16x16x32_bf16 v[16:19], v[208:211], v[32:35], v[162:165]
	v_mfma_f32_16x16x32_bf16 v[104:107], v[212:215], v[36:39], v[16:19]
	v_mfma_f32_16x16x32_bf16 v[16:19], v[200:203], v[48:51], v[76:79]
	v_mfma_f32_16x16x32_bf16 v[124:127], v[204:207], v[20:23], v[92:95]
	v_mfma_f32_16x16x32_bf16 v[92:95], v[204:207], v[52:55], v[16:19]
	v_mfma_f32_16x16x32_bf16 v[16:19], v[208:211], v[48:51], v[72:75]
	v_mfma_f32_16x16x32_bf16 v[88:91], v[212:215], v[52:55], v[16:19]
	v_mfma_f32_16x16x32_bf16 v[16:19], v[200:203], v[224:227], v[166:169]
	v_mfma_f32_16x16x32_bf16 v[76:79], v[204:207], v[228:231], v[16:19]
	v_mfma_f32_16x16x32_bf16 v[16:19], v[208:211], v[224:227], v[170:173]
	v_mfma_f32_16x16x32_bf16 v[72:75], v[212:215], v[228:231], v[16:19]
	s_barrier
	ds_read_b128 v[158:161], v144 offset:49152
	ds_read_b128 v[162:165], v144 offset:50176
	ds_read_b128 v[166:169], v144 offset:51200
	ds_read_b128 v[170:173], v144 offset:52224
	ds_read_b128 v[224:227], v144 offset:53248
	ds_read_b128 v[228:231], v144 offset:54272
	ds_read_b128 v[232:235], v144 offset:55296
	ds_read_b128 v[142:145], v144 offset:56320
	s_barrier
	s_waitcnt lgkmcnt(0)
	s_waitcnt lgkmcnt(0)
	v_mfma_f32_16x16x32_bf16 v[16:19], v[0:3], v[158:161], v[60:63]
	v_mfma_f32_16x16x32_bf16 v[52:55], v[4:7], v[162:165], v[16:19]
	v_mfma_f32_16x16x32_bf16 v[16:19], v[192:195], v[158:161], v[56:59]
	v_mfma_f32_16x16x32_bf16 v[48:51], v[196:199], v[162:165], v[16:19]
	v_mfma_f32_16x16x32_bf16 v[16:19], v[0:3], v[166:169], v[216:219]
	v_mfma_f32_16x16x32_bf16 v[36:39], v[4:7], v[170:173], v[16:19]
	v_mfma_f32_16x16x32_bf16 v[16:19], v[192:195], v[166:169], v[220:223]
	v_mfma_f32_16x16x32_bf16 v[32:35], v[196:199], v[170:173], v[16:19]
	v_mfma_f32_16x16x32_bf16 v[16:19], v[0:3], v[224:227], v[44:47]
	v_mfma_f32_16x16x32_bf16 v[0:3], v[0:3], v[232:235], v[138:141]
	v_mfma_f32_16x16x32_bf16 v[20:23], v[4:7], v[228:231], v[16:19]
	v_mfma_f32_16x16x32_bf16 v[16:19], v[192:195], v[224:227], v[40:43]
	v_mfma_f32_16x16x32_bf16 v[4:7], v[4:7], v[142:145], v[0:3]
	v_mfma_f32_16x16x32_bf16 v[0:3], v[192:195], v[232:235], v[146:149]
	v_mfma_f32_16x16x32_bf16 v[16:19], v[196:199], v[228:231], v[16:19]
	v_mfma_f32_16x16x32_bf16 v[0:3], v[196:199], v[142:145], v[0:3]
	v_mfma_f32_16x16x32_bf16 v[24:27], v[208:211], v[158:161], v[24:27]
	v_mfma_f32_16x16x32_bf16 v[56:59], v[212:215], v[162:165], v[24:27]
	v_mfma_f32_16x16x32_bf16 v[24:27], v[200:203], v[166:169], v[150:153]
	v_mfma_f32_16x16x32_bf16 v[44:47], v[204:207], v[170:173], v[24:27]
	v_mfma_f32_16x16x32_bf16 v[24:27], v[208:211], v[166:169], v[154:157]
	v_mfma_f32_16x16x32_bf16 v[8:11], v[208:211], v[224:227], v[8:11]
	v_mfma_f32_16x16x32_bf16 v[28:31], v[200:203], v[158:161], v[28:31]
	v_mfma_f32_16x16x32_bf16 v[40:43], v[212:215], v[170:173], v[24:27]
	v_mfma_f32_16x16x32_bf16 v[12:15], v[200:203], v[224:227], v[12:15]
	v_mfma_f32_16x16x32_bf16 v[24:27], v[212:215], v[228:231], v[8:11]
	v_mfma_f32_16x16x32_bf16 v[8:11], v[200:203], v[232:235], v[174:177]
	v_mfma_f32_16x16x32_bf16 v[60:63], v[204:207], v[162:165], v[28:31]
	v_mfma_f32_16x16x32_bf16 v[28:31], v[204:207], v[228:231], v[12:15]
	v_mfma_f32_16x16x32_bf16 v[12:15], v[204:207], v[142:145], v[8:11]
	v_mfma_f32_16x16x32_bf16 v[8:11], v[208:211], v[232:235], v[178:181]
	v_mfma_f32_16x16x32_bf16 v[8:11], v[212:215], v[142:145], v[8:11]
	s_cmpk_lt_u32 s27, 0x100
	s_barrier
	s_cbranch_scc0 .LBB0_1320
	s_barrier

.LBB0_1327:
	v_add_u32_e32 v158, s42, v145
	ds_read_b128 v[146:149], v158
	ds_read_b128 v[150:153], v158 offset:1024
	ds_read_b128 v[154:157], v158 offset:2048
	ds_read_b128 v[158:161], v158 offset:3072
	v_lshl_add_u64 v[184:185], v[134:135], 0, s[30:31]
	s_add_i32 s35, s40, 0xc000
	v_lshl_add_u64 v[204:205], v[184:185], 0, s[8:9]
	s_mov_b32 m0, s35
	v_lshl_add_u64 v[220:221], v[138:139], 0, s[30:31]
	s_add_i32 s34, s40, 0xe000
	ds_read_b128 v[162:165], v144
	ds_read_b128 v[166:169], v144 offset:1024
	ds_read_b128 v[170:173], v144 offset:2048
	ds_read_b128 v[174:177], v144 offset:3072
	ds_read_b128 v[178:181], v144 offset:4096
	ds_read_b128 v[192:195], v144 offset:5120
	ds_read_b128 v[196:199], v144 offset:6144
	ds_read_b128 v[200:203], v144 offset:7168
	global_load_lds_dwordx4 v[204:205], off
	v_lshl_add_u64 v[204:205], v[220:221], 0, s[8:9]
	s_mov_b32 m0, s34
	s_nop 0
	global_load_lds_dwordx4 v[204:205], off
	s_waitcnt lgkmcnt(8)
	s_barrier
	s_waitcnt lgkmcnt(0)
	s_waitcnt lgkmcnt(0)
	v_mfma_f32_16x16x32_bf16 v[124:127], v[146:149], v[162:165], v[124:127]
	v_mfma_f32_16x16x32_bf16 v[120:123], v[154:157], v[162:165], v[120:123]
	v_mfma_f32_16x16x32_bf16 v[116:119], v[146:149], v[170:173], v[116:119]
	v_mfma_f32_16x16x32_bf16 v[112:115], v[154:157], v[170:173], v[112:115]
	v_mfma_f32_16x16x32_bf16 v[108:111], v[146:149], v[178:181], v[108:111]
	v_mfma_f32_16x16x32_bf16 v[104:107], v[154:157], v[178:181], v[104:107]
	v_mfma_f32_16x16x32_bf16 v[100:103], v[146:149], v[196:199], v[100:103]
	v_mfma_f32_16x16x32_bf16 v[96:99], v[154:157], v[196:199], v[96:99]
	v_mfma_f32_16x16x32_bf16 v[124:127], v[150:153], v[166:169], v[124:127]
	v_mfma_f32_16x16x32_bf16 v[120:123], v[158:161], v[166:169], v[120:123]
	v_mfma_f32_16x16x32_bf16 v[116:119], v[150:153], v[174:177], v[116:119]
	v_mfma_f32_16x16x32_bf16 v[112:115], v[158:161], v[174:177], v[112:115]
	v_mfma_f32_16x16x32_bf16 v[108:111], v[150:153], v[192:195], v[108:111]
	v_mfma_f32_16x16x32_bf16 v[104:107], v[158:161], v[192:195], v[104:107]
	v_mfma_f32_16x16x32_bf16 v[100:103], v[150:153], v[200:203], v[100:103]
	v_mfma_f32_16x16x32_bf16 v[96:99], v[158:161], v[200:203], v[96:99]
	s_barrier
	v_lshl_add_u64 v[222:223], v[140:141], 0, s[30:31]
	s_add_i32 s46, s42, s33
	v_add_u32_e32 v190, s43, v145
	v_lshl_add_u64 v[224:225], v[222:223], 0, s[10:11]
	s_mov_b32 m0, s46
	ds_read_b128 v[204:207], v190
	ds_read_b128 v[208:211], v190 offset:1024
	ds_read_b128 v[212:215], v190 offset:2048
	ds_read_b128 v[216:219], v190 offset:3072
	global_load_lds_dwordx4 v[224:225], off
	v_lshl_add_u64 v[224:225], v[142:143], 0, s[30:31]
	v_lshl_add_u64 v[226:227], v[224:225], 0, s[10:11]
	s_add_i32 m0, s46, 0x2000
	s_nop 0
	global_load_lds_dwordx4 v[226:227], off
	s_barrier
	s_waitcnt lgkmcnt(0)
	s_waitcnt lgkmcnt(0)
	v_mfma_f32_16x16x32_bf16 v[92:95], v[204:207], v[162:165], v[92:95]
	v_mfma_f32_16x16x32_bf16 v[88:91], v[212:215], v[162:165], v[88:91]
	v_mfma_f32_16x16x32_bf16 v[84:87], v[204:207], v[170:173], v[84:87]
	v_mfma_f32_16x16x32_bf16 v[80:83], v[212:215], v[170:173], v[80:83]
	v_mfma_f32_16x16x32_bf16 v[76:79], v[204:207], v[178:181], v[76:79]
	v_mfma_f32_16x16x32_bf16 v[72:75], v[212:215], v[178:181], v[72:75]
	v_mfma_f32_16x16x32_bf16 v[68:71], v[204:207], v[196:199], v[68:71]
	v_mfma_f32_16x16x32_bf16 v[64:67], v[212:215], v[196:199], v[64:67]
	v_mfma_f32_16x16x32_bf16 v[92:95], v[208:211], v[166:169], v[92:95]
	v_mfma_f32_16x16x32_bf16 v[88:91], v[216:219], v[166:169], v[88:91]
	v_mfma_f32_16x16x32_bf16 v[84:87], v[208:211], v[174:177], v[84:87]
	v_mfma_f32_16x16x32_bf16 v[80:83], v[216:219], v[174:177], v[80:83]
	v_mfma_f32_16x16x32_bf16 v[76:79], v[208:211], v[192:195], v[76:79]
	v_mfma_f32_16x16x32_bf16 v[72:75], v[216:219], v[192:195], v[72:75]
	v_mfma_f32_16x16x32_bf16 v[68:71], v[208:211], v[200:203], v[68:71]
	v_mfma_f32_16x16x32_bf16 v[64:67], v[216:219], v[200:203], v[64:67]
	s_mov_b32 m0, s40
	v_lshl_add_u64 v[226:227], v[184:185], 0, s[10:11]
	s_barrier
	ds_read_b128 v[162:165], v144 offset:16384
	ds_read_b128 v[166:169], v144 offset:17408
	ds_read_b128 v[170:173], v144 offset:18432
	ds_read_b128 v[174:177], v144 offset:19456
	ds_read_b128 v[178:181], v144 offset:20480
	ds_read_b128 v[192:195], v144 offset:21504
	ds_read_b128 v[196:199], v144 offset:22528
	ds_read_b128 v[200:203], v144 offset:23552
	global_load_lds_dwordx4 v[226:227], off
	v_lshl_add_u64 v[226:227], v[220:221], 0, s[10:11]
	s_add_i32 m0, s40, 0x2000
	s_nop 0
	global_load_lds_dwordx4 v[226:227], off
	s_barrier
	s_waitcnt lgkmcnt(0)
	s_waitcnt lgkmcnt(0)
	v_mfma_f32_16x16x32_bf16 v[60:63], v[146:149], v[162:165], v[60:63]
	v_mfma_f32_16x16x32_bf16 v[56:59], v[154:157], v[162:165], v[56:59]
	v_mfma_f32_16x16x32_bf16 v[52:55], v[146:149], v[170:173], v[52:55]
	v_mfma_f32_16x16x32_bf16 v[48:51], v[154:157], v[170:173], v[48:51]
	v_mfma_f32_16x16x32_bf16 v[44:47], v[146:149], v[178:181], v[44:47]
	v_mfma_f32_16x16x32_bf16 v[40:43], v[154:157], v[178:181], v[40:43]
	v_mfma_f32_16x16x32_bf16 v[36:39], v[146:149], v[196:199], v[36:39]
	v_mfma_f32_16x16x32_bf16 v[32:35], v[154:157], v[196:199], v[32:35]
	v_mfma_f32_16x16x32_bf16 v[60:63], v[150:153], v[166:169], v[60:63]
	v_mfma_f32_16x16x32_bf16 v[56:59], v[158:161], v[166:169], v[56:59]
	v_mfma_f32_16x16x32_bf16 v[52:55], v[150:153], v[174:177], v[52:55]
	v_mfma_f32_16x16x32_bf16 v[48:51], v[158:161], v[174:177], v[48:51]
	v_mfma_f32_16x16x32_bf16 v[44:47], v[150:153], v[192:195], v[44:47]
	v_mfma_f32_16x16x32_bf16 v[40:43], v[158:161], v[192:195], v[40:43]
	v_mfma_f32_16x16x32_bf16 v[36:39], v[150:153], v[200:203], v[36:39]
	v_mfma_f32_16x16x32_bf16 v[32:35], v[158:161], v[200:203], v[32:35]
	s_barrier
	s_add_i32 s46, s43, s33
	v_lshl_add_u64 v[146:147], v[222:223], 0, s[12:13]
	s_mov_b32 m0, s46
	s_nop 0
	global_load_lds_dwordx4 v[146:147], off
	v_lshl_add_u64 v[146:147], v[224:225], 0, s[12:13]
	s_add_i32 m0, s46, 0x2000
	s_nop 0
	global_load_lds_dwordx4 v[146:147], off
	s_waitcnt vmcnt(6)
	s_barrier
	v_mfma_f32_16x16x32_bf16 v[28:31], v[204:207], v[162:165], v[28:31]
	v_mfma_f32_16x16x32_bf16 v[24:27], v[212:215], v[162:165], v[24:27]
	v_mfma_f32_16x16x32_bf16 v[20:23], v[204:207], v[170:173], v[20:23]
	v_mfma_f32_16x16x32_bf16 v[16:19], v[212:215], v[170:173], v[16:19]
	v_mfma_f32_16x16x32_bf16 v[12:15], v[204:207], v[178:181], v[12:15]
	v_mfma_f32_16x16x32_bf16 v[8:11], v[212:215], v[178:181], v[8:11]
	v_mfma_f32_16x16x32_bf16 v[4:7], v[204:207], v[196:199], v[4:7]
	v_mfma_f32_16x16x32_bf16 v[0:3], v[212:215], v[196:199], v[0:3]
	v_mfma_f32_16x16x32_bf16 v[28:31], v[208:211], v[166:169], v[28:31]
	v_mfma_f32_16x16x32_bf16 v[24:27], v[216:219], v[166:169], v[24:27]
	v_mfma_f32_16x16x32_bf16 v[20:23], v[208:211], v[174:177], v[20:23]
	v_mfma_f32_16x16x32_bf16 v[16:19], v[216:219], v[174:177], v[16:19]
	v_mfma_f32_16x16x32_bf16 v[12:15], v[208:211], v[192:195], v[12:15]
	v_mfma_f32_16x16x32_bf16 v[8:11], v[216:219], v[192:195], v[8:11]
	v_mfma_f32_16x16x32_bf16 v[4:7], v[208:211], v[200:203], v[4:7]
	v_mfma_f32_16x16x32_bf16 v[0:3], v[216:219], v[200:203], v[0:3]
	s_add_i32 s46, 0, 0x18000
	v_add_u32_e32 v158, s46, v145
	s_barrier
	ds_read_b128 v[146:149], v158
	ds_read_b128 v[150:153], v158 offset:1024
	ds_read_b128 v[154:157], v158 offset:2048
	ds_read_b128 v[158:161], v158 offset:3072
	v_lshl_add_u64 v[204:205], v[184:185], 0, s[12:13]
	s_add_i32 m0, s40, 0x4000
	ds_read_b128 v[162:165], v144 offset:32768
	ds_read_b128 v[166:169], v144 offset:33792
	ds_read_b128 v[170:173], v144 offset:34816
	ds_read_b128 v[174:177], v144 offset:35840
	ds_read_b128 v[178:181], v144 offset:36864
	ds_read_b128 v[192:195], v144 offset:37888
	ds_read_b128 v[196:199], v144 offset:38912
	ds_read_b128 v[200:203], v144 offset:39936
	global_load_lds_dwordx4 v[204:205], off
	v_lshl_add_u64 v[204:205], v[220:221], 0, s[12:13]
	s_add_i32 m0, s40, 0x6000
	s_nop 0
	global_load_lds_dwordx4 v[204:205], off
	s_waitcnt lgkmcnt(8)
	s_barrier
	s_waitcnt lgkmcnt(0)
	s_waitcnt lgkmcnt(0)
	v_mfma_f32_16x16x32_bf16 v[124:127], v[146:149], v[162:165], v[124:127]
	v_mfma_f32_16x16x32_bf16 v[120:123], v[154:157], v[162:165], v[120:123]
	v_mfma_f32_16x16x32_bf16 v[116:119], v[146:149], v[170:173], v[116:119]
	v_mfma_f32_16x16x32_bf16 v[112:115], v[154:157], v[170:173], v[112:115]
	v_mfma_f32_16x16x32_bf16 v[108:111], v[146:149], v[178:181], v[108:111]
	v_mfma_f32_16x16x32_bf16 v[104:107], v[154:157], v[178:181], v[104:107]
	v_mfma_f32_16x16x32_bf16 v[100:103], v[146:149], v[196:199], v[100:103]
	v_mfma_f32_16x16x32_bf16 v[96:99], v[154:157], v[196:199], v[96:99]
	v_mfma_f32_16x16x32_bf16 v[124:127], v[150:153], v[166:169], v[124:127]
	v_mfma_f32_16x16x32_bf16 v[120:123], v[158:161], v[166:169], v[120:123]
	v_mfma_f32_16x16x32_bf16 v[116:119], v[150:153], v[174:177], v[116:119]
	v_mfma_f32_16x16x32_bf16 v[112:115], v[158:161], v[174:177], v[112:115]
	v_mfma_f32_16x16x32_bf16 v[108:111], v[150:153], v[192:195], v[108:111]
	v_mfma_f32_16x16x32_bf16 v[104:107], v[158:161], v[192:195], v[104:107]
	v_mfma_f32_16x16x32_bf16 v[100:103], v[150:153], v[200:203], v[100:103]
	v_mfma_f32_16x16x32_bf16 v[96:99], v[158:161], v[200:203], v[96:99]
	s_barrier
	s_add_i32 s50, 0, 0x1c000
	s_add_i32 s46, s46, s33
	v_add_u32_e32 v190, s50, v145
	v_lshl_add_u64 v[226:227], v[222:223], 0, s[14:15]
	s_mov_b32 m0, s46
	ds_read_b128 v[204:207], v190
	ds_read_b128 v[208:211], v190 offset:1024
	ds_read_b128 v[212:215], v190 offset:2048
	ds_read_b128 v[216:219], v190 offset:3072
	global_load_lds_dwordx4 v[226:227], off
	v_lshl_add_u64 v[226:227], v[224:225], 0, s[14:15]
	s_add_i32 m0, s46, 0x2000
	s_nop 0
	global_load_lds_dwordx4 v[226:227], off
	s_barrier
	s_waitcnt lgkmcnt(0)
	s_waitcnt lgkmcnt(0)
	v_mfma_f32_16x16x32_bf16 v[92:95], v[204:207], v[162:165], v[92:95]
	v_mfma_f32_16x16x32_bf16 v[88:91], v[212:215], v[162:165], v[88:91]
	v_mfma_f32_16x16x32_bf16 v[84:87], v[204:207], v[170:173], v[84:87]
	v_mfma_f32_16x16x32_bf16 v[80:83], v[212:215], v[170:173], v[80:83]
	v_mfma_f32_16x16x32_bf16 v[76:79], v[204:207], v[178:181], v[76:79]
	v_mfma_f32_16x16x32_bf16 v[72:75], v[212:215], v[178:181], v[72:75]
	v_mfma_f32_16x16x32_bf16 v[68:71], v[204:207], v[196:199], v[68:71]
	v_mfma_f32_16x16x32_bf16 v[64:67], v[212:215], v[196:199], v[64:67]
	v_mfma_f32_16x16x32_bf16 v[92:95], v[208:211], v[166:169], v[92:95]
	v_mfma_f32_16x16x32_bf16 v[88:91], v[216:219], v[166:169], v[88:91]
	v_mfma_f32_16x16x32_bf16 v[84:87], v[208:211], v[174:177], v[84:87]
	v_mfma_f32_16x16x32_bf16 v[80:83], v[216:219], v[174:177], v[80:83]
	v_mfma_f32_16x16x32_bf16 v[76:79], v[208:211], v[192:195], v[76:79]
	v_mfma_f32_16x16x32_bf16 v[72:75], v[216:219], v[192:195], v[72:75]
	v_mfma_f32_16x16x32_bf16 v[68:71], v[208:211], v[200:203], v[68:71]
	v_mfma_f32_16x16x32_bf16 v[64:67], v[216:219], v[200:203], v[64:67]
	s_mov_b32 m0, s41
	v_lshl_add_u64 v[184:185], v[184:185], 0, s[14:15]
	s_barrier
	ds_read_b128 v[162:165], v144 offset:49152
	ds_read_b128 v[166:169], v144 offset:50176
	ds_read_b128 v[170:173], v144 offset:51200
	ds_read_b128 v[174:177], v144 offset:52224
	ds_read_b128 v[178:181], v144 offset:53248
	ds_read_b128 v[192:195], v144 offset:54272
	ds_read_b128 v[196:199], v144 offset:55296
	ds_read_b128 v[200:203], v144 offset:56320
	global_load_lds_dwordx4 v[184:185], off
	v_lshl_add_u64 v[184:185], v[220:221], 0, s[14:15]
	s_mov_b32 m0, s47
	s_nop 0
	global_load_lds_dwordx4 v[184:185], off
	s_barrier
	s_waitcnt lgkmcnt(0)
	s_waitcnt lgkmcnt(0)
	v_mfma_f32_16x16x32_bf16 v[60:63], v[146:149], v[162:165], v[60:63]
	v_mfma_f32_16x16x32_bf16 v[56:59], v[154:157], v[162:165], v[56:59]
	v_mfma_f32_16x16x32_bf16 v[52:55], v[146:149], v[170:173], v[52:55]
	v_mfma_f32_16x16x32_bf16 v[48:51], v[154:157], v[170:173], v[48:51]
	v_mfma_f32_16x16x32_bf16 v[44:47], v[146:149], v[178:181], v[44:47]
	v_mfma_f32_16x16x32_bf16 v[40:43], v[154:157], v[178:181], v[40:43]
	v_mfma_f32_16x16x32_bf16 v[36:39], v[146:149], v[196:199], v[36:39]
	v_mfma_f32_16x16x32_bf16 v[32:35], v[154:157], v[196:199], v[32:35]
	v_mfma_f32_16x16x32_bf16 v[60:63], v[150:153], v[166:169], v[60:63]
	v_mfma_f32_16x16x32_bf16 v[56:59], v[158:161], v[166:169], v[56:59]
	v_mfma_f32_16x16x32_bf16 v[52:55], v[150:153], v[174:177], v[52:55]
	v_mfma_f32_16x16x32_bf16 v[48:51], v[158:161], v[174:177], v[48:51]
	v_mfma_f32_16x16x32_bf16 v[44:47], v[150:153], v[192:195], v[44:47]
	v_mfma_f32_16x16x32_bf16 v[40:43], v[158:161], v[192:195], v[40:43]
	v_mfma_f32_16x16x32_bf16 v[36:39], v[150:153], v[200:203], v[36:39]
	v_mfma_f32_16x16x32_bf16 v[32:35], v[158:161], v[200:203], v[32:35]
	s_barrier
	s_add_i32 s46, s50, s33
	v_lshl_add_u64 v[146:147], v[222:223], 0, s[16:17]
	s_mov_b32 m0, s46
	s_nop 0
	global_load_lds_dwordx4 v[146:147], off
	v_lshl_add_u64 v[146:147], v[224:225], 0, s[16:17]
	s_add_i32 m0, s46, 0x2000
	s_nop 0
	global_load_lds_dwordx4 v[146:147], off
	s_waitcnt vmcnt(6)
	s_barrier
	v_mfma_f32_16x16x32_bf16 v[28:31], v[204:207], v[162:165], v[28:31]
	v_mfma_f32_16x16x32_bf16 v[24:27], v[212:215], v[162:165], v[24:27]
	v_mfma_f32_16x16x32_bf16 v[20:23], v[204:207], v[170:173], v[20:23]
	v_mfma_f32_16x16x32_bf16 v[16:19], v[212:215], v[170:173], v[16:19]
	v_mfma_f32_16x16x32_bf16 v[12:15], v[204:207], v[178:181], v[12:15]
	v_mfma_f32_16x16x32_bf16 v[8:11], v[212:215], v[178:181], v[8:11]
	v_mfma_f32_16x16x32_bf16 v[4:7], v[204:207], v[196:199], v[4:7]
	v_mfma_f32_16x16x32_bf16 v[0:3], v[212:215], v[196:199], v[0:3]
	v_mfma_f32_16x16x32_bf16 v[28:31], v[208:211], v[166:169], v[28:31]
	v_mfma_f32_16x16x32_bf16 v[24:27], v[216:219], v[166:169], v[24:27]
	v_mfma_f32_16x16x32_bf16 v[20:23], v[208:211], v[174:177], v[20:23]
	v_mfma_f32_16x16x32_bf16 v[16:19], v[216:219], v[174:177], v[16:19]
	v_mfma_f32_16x16x32_bf16 v[12:15], v[208:211], v[192:195], v[12:15]
	v_mfma_f32_16x16x32_bf16 v[8:11], v[216:219], v[192:195], v[8:11]
	v_mfma_f32_16x16x32_bf16 v[4:7], v[208:211], v[200:203], v[4:7]
	v_mfma_f32_16x16x32_bf16 v[0:3], v[216:219], v[200:203], v[0:3]
	s_add_i32 s21, s21, 2
	s_add_u32 s30, s30, 0x100
	s_addc_u32 s31, s31, 0
	s_cmp_gt_u32 s21, 11
	s_barrier
	s_cbranch_scc0 .LBB0_1327
	v_add_u32_e32 v142, 0, v145
	s_add_u32 s28, s28, 0x40780
	v_add_u32_e32 v134, 0x10000, v142
	s_addc_u32 s29, s29, 0
	s_mov_b32 m0, s35
	ds_read_b128 v[138:141], v134
	ds_read_b128 v[146:149], v134 offset:1024
	ds_read_b128 v[150:153], v134 offset:2048
	ds_read_b128 v[154:157], v134 offset:3072
	ds_read_b128 v[158:161], v144
	ds_read_b128 v[162:165], v144 offset:1024
	ds_read_b128 v[166:169], v144 offset:2048
	ds_read_b128 v[170:173], v144 offset:3072
	ds_read_b128 v[174:177], v144 offset:4096
	ds_read_b128 v[178:181], v144 offset:5120
	ds_read_b128 v[192:195], v144 offset:6144
	ds_read_b128 v[196:199], v144 offset:7168
	v_lshl_add_u64 v[134:135], s[28:29], 0, v[128:129]
	global_load_lds_dwordx4 v[134:135], off
	v_lshl_add_u64 v[130:131], s[28:29], 0, v[130:131]
	s_mov_b32 m0, s34
	s_nop 0
	global_load_lds_dwordx4 v[130:131], off
	s_barrier
	s_waitcnt lgkmcnt(0)
	s_waitcnt lgkmcnt(0)
	v_mfma_f32_16x16x32_bf16 v[124:127], v[138:141], v[158:161], v[124:127]
	v_mfma_f32_16x16x32_bf16 v[120:123], v[150:153], v[158:161], v[120:123]
	v_mfma_f32_16x16x32_bf16 v[108:111], v[138:141], v[174:177], v[108:111]
	v_mfma_f32_16x16x32_bf16 v[104:107], v[150:153], v[174:177], v[104:107]
	v_mfma_f32_16x16x32_bf16 v[124:127], v[146:149], v[162:165], v[124:127]
	v_mfma_f32_16x16x32_bf16 v[120:123], v[154:157], v[162:165], v[120:123]
	v_mfma_f32_16x16x32_bf16 v[116:119], v[138:141], v[166:169], v[116:119]
	v_mfma_f32_16x16x32_bf16 v[112:115], v[150:153], v[166:169], v[112:115]
	v_mfma_f32_16x16x32_bf16 v[108:111], v[146:149], v[178:181], v[108:111]
	v_mfma_f32_16x16x32_bf16 v[104:107], v[154:157], v[178:181], v[104:107]
	v_mfma_f32_16x16x32_bf16 v[100:103], v[138:141], v[192:195], v[100:103]
	v_mfma_f32_16x16x32_bf16 v[96:99], v[150:153], v[192:195], v[96:99]
	v_mfma_f32_16x16x32_bf16 v[200:203], v[146:149], v[170:173], v[116:119]
	v_mfma_f32_16x16x32_bf16 v[204:207], v[154:157], v[170:173], v[112:115]
	v_mfma_f32_16x16x32_bf16 v[208:211], v[146:149], v[196:199], v[100:103]
	v_mfma_f32_16x16x32_bf16 v[212:215], v[154:157], v[196:199], v[96:99]
	v_add_u32_e32 v116, 0x14000, v142
	s_barrier
	s_nop 0
	ds_read_b128 v[96:99], v116
	ds_read_b128 v[100:103], v116 offset:1024
	ds_read_b128 v[112:115], v116 offset:2048
	ds_read_b128 v[116:119], v116 offset:3072
	s_barrier
	s_waitcnt lgkmcnt(0)
	s_waitcnt lgkmcnt(0)
	v_mfma_f32_16x16x32_bf16 v[92:95], v[96:99], v[158:161], v[92:95]
	v_mfma_f32_16x16x32_bf16 v[88:91], v[112:115], v[158:161], v[88:91]
	v_mfma_f32_16x16x32_bf16 v[76:79], v[96:99], v[174:177], v[76:79]
	v_mfma_f32_16x16x32_bf16 v[72:75], v[112:115], v[174:177], v[72:75]
	v_mfma_f32_16x16x32_bf16 v[92:95], v[100:103], v[162:165], v[92:95]
	v_mfma_f32_16x16x32_bf16 v[88:91], v[116:119], v[162:165], v[88:91]
	v_mfma_f32_16x16x32_bf16 v[84:87], v[96:99], v[166:169], v[84:87]
	v_mfma_f32_16x16x32_bf16 v[80:83], v[112:115], v[166:169], v[80:83]
	v_mfma_f32_16x16x32_bf16 v[76:79], v[100:103], v[178:181], v[76:79]
	v_mfma_f32_16x16x32_bf16 v[72:75], v[116:119], v[178:181], v[72:75]
	v_mfma_f32_16x16x32_bf16 v[68:71], v[96:99], v[192:195], v[68:71]
	v_mfma_f32_16x16x32_bf16 v[64:67], v[112:115], v[192:195], v[64:67]
	v_mfma_f32_16x16x32_bf16 v[158:161], v[100:103], v[170:173], v[84:87]
	v_mfma_f32_16x16x32_bf16 v[162:165], v[116:119], v[170:173], v[80:83]
	v_mfma_f32_16x16x32_bf16 v[166:169], v[100:103], v[196:199], v[68:71]
	v_mfma_f32_16x16x32_bf16 v[170:173], v[116:119], v[196:199], v[64:67]
	s_barrier
	s_nop 1
	ds_read_b128 v[64:67], v144 offset:16384
	ds_read_b128 v[68:71], v144 offset:17408
	ds_read_b128 v[80:83], v144 offset:18432
	ds_read_b128 v[84:87], v144 offset:19456
	ds_read_b128 v[174:177], v144 offset:20480
	ds_read_b128 v[178:181], v144 offset:21504
	ds_read_b128 v[192:195], v144 offset:22528
	ds_read_b128 v[196:199], v144 offset:23552
	s_waitcnt vmcnt(4)
	s_barrier
	s_waitcnt lgkmcnt(0)
	s_waitcnt lgkmcnt(0)
	v_mfma_f32_16x16x32_bf16 v[60:63], v[138:141], v[64:67], v[60:63]
	v_mfma_f32_16x16x32_bf16 v[56:59], v[150:153], v[64:67], v[56:59]
	v_mfma_f32_16x16x32_bf16 v[44:47], v[138:141], v[174:177], v[44:47]
	v_mfma_f32_16x16x32_bf16 v[40:43], v[150:153], v[174:177], v[40:43]
	v_mfma_f32_16x16x32_bf16 v[60:63], v[146:149], v[68:71], v[60:63]
	v_mfma_f32_16x16x32_bf16 v[56:59], v[154:157], v[68:71], v[56:59]
	v_mfma_f32_16x16x32_bf16 v[52:55], v[138:141], v[80:83], v[52:55]
	v_mfma_f32_16x16x32_bf16 v[48:51], v[150:153], v[80:83], v[48:51]
	v_mfma_f32_16x16x32_bf16 v[44:47], v[146:149], v[178:181], v[44:47]
	v_mfma_f32_16x16x32_bf16 v[40:43], v[154:157], v[178:181], v[40:43]
	v_mfma_f32_16x16x32_bf16 v[36:39], v[138:141], v[192:195], v[36:39]
	v_mfma_f32_16x16x32_bf16 v[32:35], v[150:153], v[192:195], v[32:35]
	v_mfma_f32_16x16x32_bf16 v[216:219], v[146:149], v[84:87], v[52:55]
	v_mfma_f32_16x16x32_bf16 v[220:223], v[154:157], v[84:87], v[48:51]
	v_mfma_f32_16x16x32_bf16 v[138:141], v[146:149], v[196:199], v[36:39]
	v_mfma_f32_16x16x32_bf16 v[146:149], v[154:157], v[196:199], v[32:35]
	v_mfma_f32_16x16x32_bf16 v[28:31], v[96:99], v[64:67], v[28:31]
	v_mfma_f32_16x16x32_bf16 v[24:27], v[112:115], v[64:67], v[24:27]
	v_mfma_f32_16x16x32_bf16 v[12:15], v[96:99], v[174:177], v[12:15]
	v_mfma_f32_16x16x32_bf16 v[8:11], v[112:115], v[174:177], v[8:11]
	v_mfma_f32_16x16x32_bf16 v[28:31], v[100:103], v[68:71], v[28:31]
	v_mfma_f32_16x16x32_bf16 v[24:27], v[116:119], v[68:71], v[24:27]
	v_mfma_f32_16x16x32_bf16 v[20:23], v[96:99], v[80:83], v[20:23]
	v_mfma_f32_16x16x32_bf16 v[16:19], v[112:115], v[80:83], v[16:19]
	v_mfma_f32_16x16x32_bf16 v[12:15], v[100:103], v[178:181], v[12:15]
	v_mfma_f32_16x16x32_bf16 v[8:11], v[116:119], v[178:181], v[8:11]
	v_mfma_f32_16x16x32_bf16 v[4:7], v[96:99], v[192:195], v[4:7]
	v_mfma_f32_16x16x32_bf16 v[0:3], v[112:115], v[192:195], v[0:3]
	v_mfma_f32_16x16x32_bf16 v[150:153], v[100:103], v[84:87], v[20:23]
	v_mfma_f32_16x16x32_bf16 v[154:157], v[116:119], v[84:87], v[16:19]
	v_mfma_f32_16x16x32_bf16 v[174:177], v[100:103], v[196:199], v[4:7]
	v_mfma_f32_16x16x32_bf16 v[178:181], v[116:119], v[196:199], v[0:3]
	v_add_u32_e32 v16, 0x18000, v142
	s_barrier
	s_nop 0
	ds_read_b128 v[0:3], v16
	ds_read_b128 v[4:7], v16 offset:1024
	ds_read_b128 v[192:195], v16 offset:2048
	ds_read_b128 v[196:199], v16 offset:3072
	ds_read_b128 v[16:19], v144 offset:32768
	ds_read_b128 v[20:23], v144 offset:33792
	ds_read_b128 v[32:35], v144 offset:34816
	ds_read_b128 v[36:39], v144 offset:35840
	ds_read_b128 v[48:51], v144 offset:36864
	ds_read_b128 v[52:55], v144 offset:37888
	ds_read_b128 v[224:227], v144 offset:38912
	ds_read_b128 v[228:231], v144 offset:39936
	s_waitcnt vmcnt(2)
	s_barrier
	s_waitcnt lgkmcnt(0)
	s_waitcnt lgkmcnt(0)
	v_mfma_f32_16x16x32_bf16 v[64:67], v[0:3], v[16:19], v[124:127]
	v_mfma_f32_16x16x32_bf16 v[116:119], v[4:7], v[20:23], v[64:67]
	v_mfma_f32_16x16x32_bf16 v[64:67], v[192:195], v[16:19], v[120:123]
	v_mfma_f32_16x16x32_bf16 v[112:115], v[196:199], v[20:23], v[64:67]
	v_mfma_f32_16x16x32_bf16 v[64:67], v[0:3], v[32:35], v[200:203]
	v_mfma_f32_16x16x32_bf16 v[100:103], v[4:7], v[36:39], v[64:67]
	v_mfma_f32_16x16x32_bf16 v[64:67], v[192:195], v[32:35], v[204:207]
	v_mfma_f32_16x16x32_bf16 v[96:99], v[196:199], v[36:39], v[64:67]
	v_mfma_f32_16x16x32_bf16 v[64:67], v[0:3], v[48:51], v[108:111]
	v_mfma_f32_16x16x32_bf16 v[84:87], v[4:7], v[52:55], v[64:67]
	v_mfma_f32_16x16x32_bf16 v[64:67], v[192:195], v[48:51], v[104:107]
	v_mfma_f32_16x16x32_bf16 v[80:83], v[196:199], v[52:55], v[64:67]
	v_mfma_f32_16x16x32_bf16 v[64:67], v[0:3], v[224:227], v[208:211]
	v_mfma_f32_16x16x32_bf16 v[68:71], v[4:7], v[228:231], v[64:67]
	v_mfma_f32_16x16x32_bf16 v[64:67], v[192:195], v[224:227], v[212:215]
	v_mfma_f32_16x16x32_bf16 v[64:67], v[196:199], v[228:231], v[64:67]
	v_add_u32_e32 v104, 0x1c000, v142
	s_barrier
	ds_read_b128 v[200:203], v104
	ds_read_b128 v[204:207], v104 offset:1024
	ds_read_b128 v[208:211], v104 offset:2048
	ds_read_b128 v[212:215], v104 offset:3072
	s_waitcnt vmcnt(0)
	s_barrier
	s_waitcnt lgkmcnt(0)
	s_waitcnt lgkmcnt(0)
	v_mfma_f32_16x16x32_bf16 v[92:95], v[200:203], v[16:19], v[92:95]
	v_mfma_f32_16x16x32_bf16 v[16:19], v[208:211], v[16:19], v[88:91]
	v_mfma_f32_16x16x32_bf16 v[120:123], v[212:215], v[20:23], v[16:19]
	v_mfma_f32_16x16x32_bf16 v[16:19], v[200:203], v[32:35], v[158:161]
	v_mfma_f32_16x16x32_bf16 v[108:111], v[204:207], v[36:39], v[16:19]
	v_mfma_f32_16x16x32_bf16 v[16:19], v[208:211], v[32:35], v[162:165]
	v_mfma_f32_16x16x32_bf16 v[104:107], v[212:215], v[36:39], v[16:19]
	v_mfma_f32_16x16x32_bf16 v[16:19], v[200:203], v[48:51], v[76:79]
	v_mfma_f32_16x16x32_bf16 v[124:127], v[204:207], v[20:23], v[92:95]
	v_mfma_f32_16x16x32_bf16 v[92:95], v[204:207], v[52:55], v[16:19]
	v_mfma_f32_16x16x32_bf16 v[16:19], v[208:211], v[48:51], v[72:75]
	v_mfma_f32_16x16x32_bf16 v[88:91], v[212:215], v[52:55], v[16:19]
	v_mfma_f32_16x16x32_bf16 v[16:19], v[200:203], v[224:227], v[166:169]
	v_mfma_f32_16x16x32_bf16 v[76:79], v[204:207], v[228:231], v[16:19]
	v_mfma_f32_16x16x32_bf16 v[16:19], v[208:211], v[224:227], v[170:173]
	v_mfma_f32_16x16x32_bf16 v[72:75], v[212:215], v[228:231], v[16:19]
	s_barrier
	ds_read_b128 v[158:161], v144 offset:49152
	ds_read_b128 v[162:165], v144 offset:50176
	ds_read_b128 v[166:169], v144 offset:51200
	ds_read_b128 v[170:173], v144 offset:52224
	ds_read_b128 v[224:227], v144 offset:53248
	ds_read_b128 v[228:231], v144 offset:54272
	ds_read_b128 v[232:235], v144 offset:55296
	ds_read_b128 v[142:145], v144 offset:56320
	s_barrier
	s_waitcnt lgkmcnt(0)
	s_waitcnt lgkmcnt(0)
	v_mfma_f32_16x16x32_bf16 v[16:19], v[0:3], v[158:161], v[60:63]
	v_mfma_f32_16x16x32_bf16 v[52:55], v[4:7], v[162:165], v[16:19]
	v_mfma_f32_16x16x32_bf16 v[16:19], v[192:195], v[158:161], v[56:59]
	v_mfma_f32_16x16x32_bf16 v[48:51], v[196:199], v[162:165], v[16:19]
	v_mfma_f32_16x16x32_bf16 v[16:19], v[0:3], v[166:169], v[216:219]
	v_mfma_f32_16x16x32_bf16 v[36:39], v[4:7], v[170:173], v[16:19]
	v_mfma_f32_16x16x32_bf16 v[16:19], v[192:195], v[166:169], v[220:223]
	v_mfma_f32_16x16x32_bf16 v[32:35], v[196:199], v[170:173], v[16:19]
	v_mfma_f32_16x16x32_bf16 v[16:19], v[0:3], v[224:227], v[44:47]
	v_mfma_f32_16x16x32_bf16 v[0:3], v[0:3], v[232:235], v[138:141]
	v_mfma_f32_16x16x32_bf16 v[20:23], v[4:7], v[228:231], v[16:19]
	v_mfma_f32_16x16x32_bf16 v[16:19], v[192:195], v[224:227], v[40:43]
	v_mfma_f32_16x16x32_bf16 v[4:7], v[4:7], v[142:145], v[0:3]
	v_mfma_f32_16x16x32_bf16 v[0:3], v[192:195], v[232:235], v[146:149]
	v_mfma_f32_16x16x32_bf16 v[16:19], v[196:199], v[228:231], v[16:19]
	v_mfma_f32_16x16x32_bf16 v[0:3], v[196:199], v[142:145], v[0:3]
	v_mfma_f32_16x16x32_bf16 v[24:27], v[208:211], v[158:161], v[24:27]
	v_mfma_f32_16x16x32_bf16 v[56:59], v[212:215], v[162:165], v[24:27]
	v_mfma_f32_16x16x32_bf16 v[24:27], v[200:203], v[166:169], v[150:153]
	v_mfma_f32_16x16x32_bf16 v[44:47], v[204:207], v[170:173], v[24:27]
	v_mfma_f32_16x16x32_bf16 v[24:27], v[208:211], v[166:169], v[154:157]
	v_mfma_f32_16x16x32_bf16 v[8:11], v[208:211], v[224:227], v[8:11]
	v_mfma_f32_16x16x32_bf16 v[28:31], v[200:203], v[158:161], v[28:31]
	v_mfma_f32_16x16x32_bf16 v[40:43], v[212:215], v[170:173], v[24:27]
	v_mfma_f32_16x16x32_bf16 v[12:15], v[200:203], v[224:227], v[12:15]
	v_mfma_f32_16x16x32_bf16 v[24:27], v[212:215], v[228:231], v[8:11]
	v_mfma_f32_16x16x32_bf16 v[8:11], v[200:203], v[232:235], v[174:177]
	v_mfma_f32_16x16x32_bf16 v[60:63], v[204:207], v[162:165], v[28:31]
	v_mfma_f32_16x16x32_bf16 v[28:31], v[204:207], v[228:231], v[12:15]
	v_mfma_f32_16x16x32_bf16 v[12:15], v[204:207], v[142:145], v[8:11]
	v_mfma_f32_16x16x32_bf16 v[8:11], v[208:211], v[232:235], v[178:181]
	v_mfma_f32_16x16x32_bf16 v[8:11], v[212:215], v[142:145], v[8:11]
	s_cmpk_lt_u32 s27, 0x100
	s_barrier
	s_cbranch_scc0 .LBB0_1330
	s_barrier

.LBB0_1397:
	v_add_u32_e32 v145, s42, v144
	ds_read_b128 v[146:149], v145
	ds_read_b128 v[150:153], v145 offset:1024
	ds_read_b128 v[154:157], v145 offset:2048
	ds_read_b128 v[158:161], v145 offset:3072
	v_lshl_add_u64 v[210:211], v[132:133], 0, s[18:19]
	s_add_i32 s35, s26, 0xc000
	v_lshl_add_u64 v[194:195], v[210:211], 0, s[8:9]
	s_mov_b32 m0, s35
	v_lshl_add_u64 v[212:213], v[134:135], 0, s[18:19]
	s_add_i32 s34, s26, 0xe000
	ds_read_b128 v[162:165], v143
	ds_read_b128 v[166:169], v143 offset:1024
	ds_read_b128 v[170:173], v143 offset:2048
	ds_read_b128 v[174:177], v143 offset:3072
	ds_read_b128 v[178:181], v143 offset:4096
	ds_read_b128 v[182:185], v143 offset:5120
	ds_read_b128 v[186:189], v143 offset:6144
	ds_read_b128 v[190:193], v143 offset:7168
	global_load_lds_dwordx4 v[194:195], off
	v_lshl_add_u64 v[194:195], v[212:213], 0, s[8:9]
	s_mov_b32 m0, s34
	s_nop 0
	global_load_lds_dwordx4 v[194:195], off
	s_waitcnt lgkmcnt(8)
	s_barrier
	s_waitcnt lgkmcnt(0)
	s_waitcnt lgkmcnt(0)
	v_mfma_f32_16x16x32_bf16 v[124:127], v[146:149], v[162:165], v[124:127]
	v_mfma_f32_16x16x32_bf16 v[120:123], v[154:157], v[162:165], v[120:123]
	v_mfma_f32_16x16x32_bf16 v[116:119], v[146:149], v[170:173], v[116:119]
	v_mfma_f32_16x16x32_bf16 v[112:115], v[154:157], v[170:173], v[112:115]
	v_mfma_f32_16x16x32_bf16 v[108:111], v[146:149], v[178:181], v[108:111]
	v_mfma_f32_16x16x32_bf16 v[104:107], v[154:157], v[178:181], v[104:107]
	v_mfma_f32_16x16x32_bf16 v[100:103], v[146:149], v[186:189], v[100:103]
	v_mfma_f32_16x16x32_bf16 v[96:99], v[154:157], v[186:189], v[96:99]
	v_mfma_f32_16x16x32_bf16 v[124:127], v[150:153], v[166:169], v[124:127]
	v_mfma_f32_16x16x32_bf16 v[120:123], v[158:161], v[166:169], v[120:123]
	v_mfma_f32_16x16x32_bf16 v[116:119], v[150:153], v[174:177], v[116:119]
	v_mfma_f32_16x16x32_bf16 v[112:115], v[158:161], v[174:177], v[112:115]
	v_mfma_f32_16x16x32_bf16 v[108:111], v[150:153], v[182:185], v[108:111]
	v_mfma_f32_16x16x32_bf16 v[104:107], v[158:161], v[182:185], v[104:107]
	v_mfma_f32_16x16x32_bf16 v[100:103], v[150:153], v[190:193], v[100:103]
	v_mfma_f32_16x16x32_bf16 v[96:99], v[158:161], v[190:193], v[96:99]
	s_barrier
	v_lshl_add_u64 v[214:215], v[138:139], 0, s[18:19]
	s_add_i32 s36, s42, s25
	v_add_u32_e32 v145, s43, v144
	v_lshl_add_u64 v[216:217], v[214:215], 0, s[10:11]
	s_mov_b32 m0, s36
	ds_read_b128 v[194:197], v145
	ds_read_b128 v[198:201], v145 offset:1024
	ds_read_b128 v[202:205], v145 offset:2048
	ds_read_b128 v[206:209], v145 offset:3072
	global_load_lds_dwordx4 v[216:217], off
	v_lshl_add_u64 v[216:217], v[140:141], 0, s[18:19]
	v_lshl_add_u64 v[218:219], v[216:217], 0, s[10:11]
	s_add_i32 m0, s36, 0x2000
	s_nop 0
	global_load_lds_dwordx4 v[218:219], off
	s_barrier
	s_waitcnt lgkmcnt(0)
	s_waitcnt lgkmcnt(0)
	v_mfma_f32_16x16x32_bf16 v[92:95], v[194:197], v[162:165], v[92:95]
	v_mfma_f32_16x16x32_bf16 v[88:91], v[202:205], v[162:165], v[88:91]
	v_mfma_f32_16x16x32_bf16 v[84:87], v[194:197], v[170:173], v[84:87]
	v_mfma_f32_16x16x32_bf16 v[80:83], v[202:205], v[170:173], v[80:83]
	v_mfma_f32_16x16x32_bf16 v[76:79], v[194:197], v[178:181], v[76:79]
	v_mfma_f32_16x16x32_bf16 v[72:75], v[202:205], v[178:181], v[72:75]
	v_mfma_f32_16x16x32_bf16 v[68:71], v[194:197], v[186:189], v[68:71]
	v_mfma_f32_16x16x32_bf16 v[64:67], v[202:205], v[186:189], v[64:67]
	v_mfma_f32_16x16x32_bf16 v[92:95], v[198:201], v[166:169], v[92:95]
	v_mfma_f32_16x16x32_bf16 v[88:91], v[206:209], v[166:169], v[88:91]
	v_mfma_f32_16x16x32_bf16 v[84:87], v[198:201], v[174:177], v[84:87]
	v_mfma_f32_16x16x32_bf16 v[80:83], v[206:209], v[174:177], v[80:83]
	v_mfma_f32_16x16x32_bf16 v[76:79], v[198:201], v[182:185], v[76:79]
	v_mfma_f32_16x16x32_bf16 v[72:75], v[206:209], v[182:185], v[72:75]
	v_mfma_f32_16x16x32_bf16 v[68:71], v[198:201], v[190:193], v[68:71]
	v_mfma_f32_16x16x32_bf16 v[64:67], v[206:209], v[190:193], v[64:67]
	s_mov_b32 m0, s26
	v_lshl_add_u64 v[218:219], v[210:211], 0, s[10:11]
	s_barrier
	ds_read_b128 v[162:165], v143 offset:16384
	ds_read_b128 v[166:169], v143 offset:17408
	ds_read_b128 v[170:173], v143 offset:18432
	ds_read_b128 v[174:177], v143 offset:19456
	ds_read_b128 v[178:181], v143 offset:20480
	ds_read_b128 v[182:185], v143 offset:21504
	ds_read_b128 v[186:189], v143 offset:22528
	ds_read_b128 v[190:193], v143 offset:23552
	global_load_lds_dwordx4 v[218:219], off
	v_lshl_add_u64 v[218:219], v[212:213], 0, s[10:11]
	s_mov_b32 m0, s27
	s_nop 0
	global_load_lds_dwordx4 v[218:219], off
	s_barrier
	s_waitcnt lgkmcnt(0)
	s_waitcnt lgkmcnt(0)
	v_mfma_f32_16x16x32_bf16 v[60:63], v[146:149], v[162:165], v[60:63]
	v_mfma_f32_16x16x32_bf16 v[56:59], v[154:157], v[162:165], v[56:59]
	v_mfma_f32_16x16x32_bf16 v[52:55], v[146:149], v[170:173], v[52:55]
	v_mfma_f32_16x16x32_bf16 v[48:51], v[154:157], v[170:173], v[48:51]
	v_mfma_f32_16x16x32_bf16 v[44:47], v[146:149], v[178:181], v[44:47]
	v_mfma_f32_16x16x32_bf16 v[40:43], v[154:157], v[178:181], v[40:43]
	v_mfma_f32_16x16x32_bf16 v[36:39], v[146:149], v[186:189], v[36:39]
	v_mfma_f32_16x16x32_bf16 v[32:35], v[154:157], v[186:189], v[32:35]
	v_mfma_f32_16x16x32_bf16 v[60:63], v[150:153], v[166:169], v[60:63]
	v_mfma_f32_16x16x32_bf16 v[56:59], v[158:161], v[166:169], v[56:59]
	v_mfma_f32_16x16x32_bf16 v[52:55], v[150:153], v[174:177], v[52:55]
	v_mfma_f32_16x16x32_bf16 v[48:51], v[158:161], v[174:177], v[48:51]
	v_mfma_f32_16x16x32_bf16 v[44:47], v[150:153], v[182:185], v[44:47]
	v_mfma_f32_16x16x32_bf16 v[40:43], v[158:161], v[182:185], v[40:43]
	v_mfma_f32_16x16x32_bf16 v[36:39], v[150:153], v[190:193], v[36:39]
	v_mfma_f32_16x16x32_bf16 v[32:35], v[158:161], v[190:193], v[32:35]
	s_barrier
	s_add_i32 s36, s43, s25
	v_lshl_add_u64 v[146:147], v[214:215], 0, s[12:13]
	s_mov_b32 m0, s36
	s_nop 0
	global_load_lds_dwordx4 v[146:147], off
	v_lshl_add_u64 v[146:147], v[216:217], 0, s[12:13]
	s_add_i32 m0, s36, 0x2000
	s_nop 0
	global_load_lds_dwordx4 v[146:147], off
	s_waitcnt vmcnt(6)
	s_barrier
	v_mfma_f32_16x16x32_bf16 v[28:31], v[194:197], v[162:165], v[28:31]
	v_mfma_f32_16x16x32_bf16 v[24:27], v[202:205], v[162:165], v[24:27]
	v_mfma_f32_16x16x32_bf16 v[20:23], v[194:197], v[170:173], v[20:23]
	v_mfma_f32_16x16x32_bf16 v[16:19], v[202:205], v[170:173], v[16:19]
	v_mfma_f32_16x16x32_bf16 v[12:15], v[194:197], v[178:181], v[12:15]
	v_mfma_f32_16x16x32_bf16 v[8:11], v[202:205], v[178:181], v[8:11]
	v_mfma_f32_16x16x32_bf16 v[4:7], v[194:197], v[186:189], v[4:7]
	v_mfma_f32_16x16x32_bf16 v[0:3], v[202:205], v[186:189], v[0:3]
	v_mfma_f32_16x16x32_bf16 v[28:31], v[198:201], v[166:169], v[28:31]
	v_mfma_f32_16x16x32_bf16 v[24:27], v[206:209], v[166:169], v[24:27]
	v_mfma_f32_16x16x32_bf16 v[20:23], v[198:201], v[174:177], v[20:23]
	v_mfma_f32_16x16x32_bf16 v[16:19], v[206:209], v[174:177], v[16:19]
	v_mfma_f32_16x16x32_bf16 v[12:15], v[198:201], v[182:185], v[12:15]
	v_mfma_f32_16x16x32_bf16 v[8:11], v[206:209], v[182:185], v[8:11]
	v_mfma_f32_16x16x32_bf16 v[4:7], v[198:201], v[190:193], v[4:7]
	v_mfma_f32_16x16x32_bf16 v[0:3], v[206:209], v[190:193], v[0:3]
	s_add_i32 s36, 0, 0x18000
	v_add_u32_e32 v145, s36, v144
	s_barrier
	ds_read_b128 v[146:149], v145
	ds_read_b128 v[150:153], v145 offset:1024
	ds_read_b128 v[154:157], v145 offset:2048
	ds_read_b128 v[158:161], v145 offset:3072
	s_mov_b32 m0, s28
	v_lshl_add_u64 v[194:195], v[210:211], 0, s[12:13]
	ds_read_b128 v[162:165], v143 offset:32768
	ds_read_b128 v[166:169], v143 offset:33792
	ds_read_b128 v[170:173], v143 offset:34816
	ds_read_b128 v[174:177], v143 offset:35840
	ds_read_b128 v[178:181], v143 offset:36864
	ds_read_b128 v[182:185], v143 offset:37888
	ds_read_b128 v[186:189], v143 offset:38912
	ds_read_b128 v[190:193], v143 offset:39936
	global_load_lds_dwordx4 v[194:195], off
	v_lshl_add_u64 v[194:195], v[212:213], 0, s[12:13]
	s_mov_b32 m0, s29
	s_nop 0
	global_load_lds_dwordx4 v[194:195], off
	s_waitcnt lgkmcnt(8)
	s_barrier
	s_waitcnt lgkmcnt(0)
	s_waitcnt lgkmcnt(0)
	v_mfma_f32_16x16x32_bf16 v[124:127], v[146:149], v[162:165], v[124:127]
	v_mfma_f32_16x16x32_bf16 v[120:123], v[154:157], v[162:165], v[120:123]
	v_mfma_f32_16x16x32_bf16 v[116:119], v[146:149], v[170:173], v[116:119]
	v_mfma_f32_16x16x32_bf16 v[112:115], v[154:157], v[170:173], v[112:115]
	v_mfma_f32_16x16x32_bf16 v[108:111], v[146:149], v[178:181], v[108:111]
	v_mfma_f32_16x16x32_bf16 v[104:107], v[154:157], v[178:181], v[104:107]
	v_mfma_f32_16x16x32_bf16 v[100:103], v[146:149], v[186:189], v[100:103]
	v_mfma_f32_16x16x32_bf16 v[96:99], v[154:157], v[186:189], v[96:99]
	v_mfma_f32_16x16x32_bf16 v[124:127], v[150:153], v[166:169], v[124:127]
	v_mfma_f32_16x16x32_bf16 v[120:123], v[158:161], v[166:169], v[120:123]
	v_mfma_f32_16x16x32_bf16 v[116:119], v[150:153], v[174:177], v[116:119]
	v_mfma_f32_16x16x32_bf16 v[112:115], v[158:161], v[174:177], v[112:115]
	v_mfma_f32_16x16x32_bf16 v[108:111], v[150:153], v[182:185], v[108:111]
	v_mfma_f32_16x16x32_bf16 v[104:107], v[158:161], v[182:185], v[104:107]
	v_mfma_f32_16x16x32_bf16 v[100:103], v[150:153], v[190:193], v[100:103]
	v_mfma_f32_16x16x32_bf16 v[96:99], v[158:161], v[190:193], v[96:99]
	s_barrier
	s_add_i32 s37, 0, 0x1c000
	s_add_i32 s36, s36, s25
	v_add_u32_e32 v145, s37, v144
	v_lshl_add_u64 v[218:219], v[214:215], 0, s[14:15]
	s_mov_b32 m0, s36
	ds_read_b128 v[194:197], v145
	ds_read_b128 v[198:201], v145 offset:1024
	ds_read_b128 v[202:205], v145 offset:2048
	ds_read_b128 v[206:209], v145 offset:3072
	global_load_lds_dwordx4 v[218:219], off
	v_lshl_add_u64 v[218:219], v[216:217], 0, s[14:15]
	s_add_i32 m0, s36, 0x2000
	s_nop 0
	global_load_lds_dwordx4 v[218:219], off
	s_barrier
	s_waitcnt lgkmcnt(0)
	s_waitcnt lgkmcnt(0)
	v_mfma_f32_16x16x32_bf16 v[92:95], v[194:197], v[162:165], v[92:95]
	v_mfma_f32_16x16x32_bf16 v[88:91], v[202:205], v[162:165], v[88:91]
	v_mfma_f32_16x16x32_bf16 v[84:87], v[194:197], v[170:173], v[84:87]
	v_mfma_f32_16x16x32_bf16 v[80:83], v[202:205], v[170:173], v[80:83]
	v_mfma_f32_16x16x32_bf16 v[76:79], v[194:197], v[178:181], v[76:79]
	v_mfma_f32_16x16x32_bf16 v[72:75], v[202:205], v[178:181], v[72:75]
	v_mfma_f32_16x16x32_bf16 v[68:71], v[194:197], v[186:189], v[68:71]
	v_mfma_f32_16x16x32_bf16 v[64:67], v[202:205], v[186:189], v[64:67]
	v_mfma_f32_16x16x32_bf16 v[92:95], v[198:201], v[166:169], v[92:95]
	v_mfma_f32_16x16x32_bf16 v[88:91], v[206:209], v[166:169], v[88:91]
	v_mfma_f32_16x16x32_bf16 v[84:87], v[198:201], v[174:177], v[84:87]
	v_mfma_f32_16x16x32_bf16 v[80:83], v[206:209], v[174:177], v[80:83]
	v_mfma_f32_16x16x32_bf16 v[76:79], v[198:201], v[182:185], v[76:79]
	v_mfma_f32_16x16x32_bf16 v[72:75], v[206:209], v[182:185], v[72:75]
	v_mfma_f32_16x16x32_bf16 v[68:71], v[198:201], v[190:193], v[68:71]
	v_mfma_f32_16x16x32_bf16 v[64:67], v[206:209], v[190:193], v[64:67]
	s_mov_b32 m0, s30
	v_lshl_add_u64 v[210:211], v[210:211], 0, s[14:15]
	s_barrier
	ds_read_b128 v[162:165], v143 offset:49152
	ds_read_b128 v[166:169], v143 offset:50176
	ds_read_b128 v[170:173], v143 offset:51200
	ds_read_b128 v[174:177], v143 offset:52224
	ds_read_b128 v[178:181], v143 offset:53248
	ds_read_b128 v[182:185], v143 offset:54272
	ds_read_b128 v[186:189], v143 offset:55296
	ds_read_b128 v[190:193], v143 offset:56320
	global_load_lds_dwordx4 v[210:211], off
	v_lshl_add_u64 v[210:211], v[212:213], 0, s[14:15]
	s_mov_b32 m0, s31
	s_nop 0
	global_load_lds_dwordx4 v[210:211], off
	s_barrier
	s_waitcnt lgkmcnt(0)
	s_waitcnt lgkmcnt(0)
	v_mfma_f32_16x16x32_bf16 v[60:63], v[146:149], v[162:165], v[60:63]
	v_mfma_f32_16x16x32_bf16 v[56:59], v[154:157], v[162:165], v[56:59]
	v_mfma_f32_16x16x32_bf16 v[52:55], v[146:149], v[170:173], v[52:55]
	v_mfma_f32_16x16x32_bf16 v[48:51], v[154:157], v[170:173], v[48:51]
	v_mfma_f32_16x16x32_bf16 v[44:47], v[146:149], v[178:181], v[44:47]
	v_mfma_f32_16x16x32_bf16 v[40:43], v[154:157], v[178:181], v[40:43]
	v_mfma_f32_16x16x32_bf16 v[36:39], v[146:149], v[186:189], v[36:39]
	v_mfma_f32_16x16x32_bf16 v[32:35], v[154:157], v[186:189], v[32:35]
	v_mfma_f32_16x16x32_bf16 v[60:63], v[150:153], v[166:169], v[60:63]
	v_mfma_f32_16x16x32_bf16 v[56:59], v[158:161], v[166:169], v[56:59]
	v_mfma_f32_16x16x32_bf16 v[52:55], v[150:153], v[174:177], v[52:55]
	v_mfma_f32_16x16x32_bf16 v[48:51], v[158:161], v[174:177], v[48:51]
	v_mfma_f32_16x16x32_bf16 v[44:47], v[150:153], v[182:185], v[44:47]
	v_mfma_f32_16x16x32_bf16 v[40:43], v[158:161], v[182:185], v[40:43]
	v_mfma_f32_16x16x32_bf16 v[36:39], v[150:153], v[190:193], v[36:39]
	v_mfma_f32_16x16x32_bf16 v[32:35], v[158:161], v[190:193], v[32:35]
	s_barrier
	s_add_i32 s36, s37, s25
	v_lshl_add_u64 v[146:147], v[214:215], 0, s[16:17]
	s_mov_b32 m0, s36
	s_nop 0
	global_load_lds_dwordx4 v[146:147], off
	v_lshl_add_u64 v[146:147], v[216:217], 0, s[16:17]
	s_add_i32 m0, s36, 0x2000
	s_nop 0
	global_load_lds_dwordx4 v[146:147], off
	s_waitcnt vmcnt(6)
	s_barrier
	v_mfma_f32_16x16x32_bf16 v[28:31], v[194:197], v[162:165], v[28:31]
	v_mfma_f32_16x16x32_bf16 v[24:27], v[202:205], v[162:165], v[24:27]
	v_mfma_f32_16x16x32_bf16 v[20:23], v[194:197], v[170:173], v[20:23]
	v_mfma_f32_16x16x32_bf16 v[16:19], v[202:205], v[170:173], v[16:19]
	v_mfma_f32_16x16x32_bf16 v[12:15], v[194:197], v[178:181], v[12:15]
	v_mfma_f32_16x16x32_bf16 v[8:11], v[202:205], v[178:181], v[8:11]
	v_mfma_f32_16x16x32_bf16 v[4:7], v[194:197], v[186:189], v[4:7]
	v_mfma_f32_16x16x32_bf16 v[0:3], v[202:205], v[186:189], v[0:3]
	v_mfma_f32_16x16x32_bf16 v[28:31], v[198:201], v[166:169], v[28:31]
	v_mfma_f32_16x16x32_bf16 v[24:27], v[206:209], v[166:169], v[24:27]
	v_mfma_f32_16x16x32_bf16 v[20:23], v[198:201], v[174:177], v[20:23]
	v_mfma_f32_16x16x32_bf16 v[16:19], v[206:209], v[174:177], v[16:19]
	v_mfma_f32_16x16x32_bf16 v[12:15], v[198:201], v[182:185], v[12:15]
	v_mfma_f32_16x16x32_bf16 v[8:11], v[206:209], v[182:185], v[8:11]
	v_mfma_f32_16x16x32_bf16 v[4:7], v[198:201], v[190:193], v[4:7]
	v_mfma_f32_16x16x32_bf16 v[0:3], v[206:209], v[190:193], v[0:3]
	s_add_i32 s33, s33, 2
	s_add_u32 s18, s18, 0x100
	s_addc_u32 s19, s19, 0
	s_cmp_gt_u32 s33, 39
	s_barrier
	s_cbranch_scc0 .LBB0_1397
	s_add_u32 s0, s0, 0xb1580
	v_add_u32_e32 v212, 0, v144
	s_addc_u32 s1, s1, 0
	s_mov_b32 m0, s35
	v_add_u32_e32 v148, 0x10000, v212
	v_lshl_add_u64 v[184:185], s[0:1], 0, v[128:129]
	ds_read_b128 v[132:135], v148
	ds_read_b128 v[138:141], v148 offset:1024
	ds_read_b128 v[144:147], v148 offset:2048
	ds_read_b128 v[148:151], v148 offset:3072
	ds_read_b128 v[152:155], v143
	ds_read_b128 v[156:159], v143 offset:1024
	ds_read_b128 v[160:163], v143 offset:2048
	ds_read_b128 v[164:167], v143 offset:3072
	ds_read_b128 v[168:171], v143 offset:4096
	ds_read_b128 v[172:175], v143 offset:5120
	ds_read_b128 v[176:179], v143 offset:6144
	ds_read_b128 v[180:183], v143 offset:7168
	global_load_lds_dwordx4 v[184:185], off
	v_lshl_add_u64 v[130:131], s[0:1], 0, v[130:131]
	s_mov_b32 m0, s34
	s_nop 0
	global_load_lds_dwordx4 v[130:131], off
	s_barrier
	s_waitcnt lgkmcnt(0)
	s_waitcnt lgkmcnt(0)
	v_mfma_f32_16x16x32_bf16 v[124:127], v[132:135], v[152:155], v[124:127]
	v_mfma_f32_16x16x32_bf16 v[120:123], v[144:147], v[152:155], v[120:123]
	v_mfma_f32_16x16x32_bf16 v[116:119], v[132:135], v[160:163], v[116:119]
	v_mfma_f32_16x16x32_bf16 v[104:107], v[144:147], v[168:171], v[104:107]
	v_mfma_f32_16x16x32_bf16 v[100:103], v[132:135], v[176:179], v[100:103]
	v_mfma_f32_16x16x32_bf16 v[124:127], v[138:141], v[156:159], v[124:127]
	v_mfma_f32_16x16x32_bf16 v[120:123], v[148:151], v[156:159], v[120:123]
	v_mfma_f32_16x16x32_bf16 v[116:119], v[138:141], v[164:167], v[116:119]
	v_mfma_f32_16x16x32_bf16 v[112:115], v[144:147], v[160:163], v[112:115]
	v_mfma_f32_16x16x32_bf16 v[108:111], v[132:135], v[168:171], v[108:111]
	v_mfma_f32_16x16x32_bf16 v[104:107], v[148:151], v[172:175], v[104:107]
	v_mfma_f32_16x16x32_bf16 v[100:103], v[138:141], v[180:183], v[100:103]
	v_mfma_f32_16x16x32_bf16 v[96:99], v[144:147], v[176:179], v[96:99]
	v_mfma_f32_16x16x32_bf16 v[184:187], v[148:151], v[164:167], v[112:115]
	v_mfma_f32_16x16x32_bf16 v[188:191], v[138:141], v[172:175], v[108:111]
	v_mfma_f32_16x16x32_bf16 v[192:195], v[148:151], v[180:183], v[96:99]
	v_add_u32_e32 v128, 0x14000, v212
	s_barrier
	s_nop 1
	ds_read_b128 v[96:99], v128
	ds_read_b128 v[108:111], v128 offset:1024
	ds_read_b128 v[112:115], v128 offset:2048
	ds_read_b128 v[196:199], v128 offset:3072
	s_barrier
	s_waitcnt lgkmcnt(0)
	s_waitcnt lgkmcnt(0)
	v_mfma_f32_16x16x32_bf16 v[88:91], v[112:115], v[152:155], v[88:91]
	v_mfma_f32_16x16x32_bf16 v[84:87], v[96:99], v[160:163], v[84:87]
	v_mfma_f32_16x16x32_bf16 v[72:75], v[112:115], v[168:171], v[72:75]
	v_mfma_f32_16x16x32_bf16 v[68:71], v[96:99], v[176:179], v[68:71]
	v_mfma_f32_16x16x32_bf16 v[92:95], v[96:99], v[152:155], v[92:95]
	v_mfma_f32_16x16x32_bf16 v[88:91], v[196:199], v[156:159], v[88:91]
	v_mfma_f32_16x16x32_bf16 v[84:87], v[108:111], v[164:167], v[84:87]
	v_mfma_f32_16x16x32_bf16 v[80:83], v[112:115], v[160:163], v[80:83]
	v_mfma_f32_16x16x32_bf16 v[76:79], v[96:99], v[168:171], v[76:79]
	v_mfma_f32_16x16x32_bf16 v[72:75], v[196:199], v[172:175], v[72:75]
	v_mfma_f32_16x16x32_bf16 v[68:71], v[108:111], v[180:183], v[68:71]
	v_mfma_f32_16x16x32_bf16 v[64:67], v[112:115], v[176:179], v[64:67]
	v_mfma_f32_16x16x32_bf16 v[200:203], v[108:111], v[156:159], v[92:95]
	v_mfma_f32_16x16x32_bf16 v[152:155], v[196:199], v[164:167], v[80:83]
	v_mfma_f32_16x16x32_bf16 v[156:159], v[108:111], v[172:175], v[76:79]
	v_mfma_f32_16x16x32_bf16 v[160:163], v[196:199], v[180:183], v[64:67]
	s_barrier
	s_nop 1
	ds_read_b128 v[64:67], v143 offset:16384
	ds_read_b128 v[76:79], v143 offset:17408
	ds_read_b128 v[80:83], v143 offset:18432
	ds_read_b128 v[92:95], v143 offset:19456
	ds_read_b128 v[164:167], v143 offset:20480
	ds_read_b128 v[168:171], v143 offset:21504
	ds_read_b128 v[172:175], v143 offset:22528
	ds_read_b128 v[176:179], v143 offset:23552
	s_waitcnt vmcnt(4)
	s_barrier
	s_waitcnt lgkmcnt(0)
	s_waitcnt lgkmcnt(0)
	v_mfma_f32_16x16x32_bf16 v[60:63], v[132:135], v[64:67], v[60:63]
	v_mfma_f32_16x16x32_bf16 v[56:59], v[144:147], v[64:67], v[56:59]
	v_mfma_f32_16x16x32_bf16 v[52:55], v[132:135], v[80:83], v[52:55]
	v_mfma_f32_16x16x32_bf16 v[40:43], v[144:147], v[164:167], v[40:43]
	v_mfma_f32_16x16x32_bf16 v[36:39], v[132:135], v[172:175], v[36:39]
	v_mfma_f32_16x16x32_bf16 v[60:63], v[138:141], v[76:79], v[60:63]
	v_mfma_f32_16x16x32_bf16 v[56:59], v[148:151], v[76:79], v[56:59]
	v_mfma_f32_16x16x32_bf16 v[52:55], v[138:141], v[92:95], v[52:55]
	v_mfma_f32_16x16x32_bf16 v[48:51], v[144:147], v[80:83], v[48:51]
	v_mfma_f32_16x16x32_bf16 v[44:47], v[132:135], v[164:167], v[44:47]
	v_mfma_f32_16x16x32_bf16 v[40:43], v[148:151], v[168:171], v[40:43]
	v_mfma_f32_16x16x32_bf16 v[36:39], v[138:141], v[176:179], v[36:39]
	v_mfma_f32_16x16x32_bf16 v[32:35], v[144:147], v[172:175], v[32:35]
	v_mfma_f32_16x16x32_bf16 v[180:183], v[148:151], v[92:95], v[48:51]
	v_mfma_f32_16x16x32_bf16 v[204:207], v[138:141], v[168:171], v[44:47]
	v_mfma_f32_16x16x32_bf16 v[130:133], v[148:151], v[176:179], v[32:35]
	v_mfma_f32_16x16x32_bf16 v[24:27], v[112:115], v[64:67], v[24:27]
	v_mfma_f32_16x16x32_bf16 v[20:23], v[96:99], v[80:83], v[20:23]
	v_mfma_f32_16x16x32_bf16 v[8:11], v[112:115], v[164:167], v[8:11]
	v_mfma_f32_16x16x32_bf16 v[4:7], v[96:99], v[172:175], v[4:7]
	v_mfma_f32_16x16x32_bf16 v[28:31], v[96:99], v[64:67], v[28:31]
	v_mfma_f32_16x16x32_bf16 v[24:27], v[196:199], v[76:79], v[24:27]
	v_mfma_f32_16x16x32_bf16 v[20:23], v[108:111], v[92:95], v[20:23]
	v_mfma_f32_16x16x32_bf16 v[16:19], v[112:115], v[80:83], v[16:19]
	v_mfma_f32_16x16x32_bf16 v[12:15], v[96:99], v[164:167], v[12:15]
	v_mfma_f32_16x16x32_bf16 v[8:11], v[196:199], v[168:171], v[8:11]
	v_mfma_f32_16x16x32_bf16 v[4:7], v[108:111], v[176:179], v[4:7]
	v_mfma_f32_16x16x32_bf16 v[0:3], v[112:115], v[172:175], v[0:3]
	v_mfma_f32_16x16x32_bf16 v[138:141], v[108:111], v[76:79], v[28:31]
	v_mfma_f32_16x16x32_bf16 v[144:147], v[196:199], v[92:95], v[16:19]
	v_mfma_f32_16x16x32_bf16 v[148:151], v[108:111], v[168:171], v[12:15]
	v_mfma_f32_16x16x32_bf16 v[164:167], v[196:199], v[176:179], v[0:3]
	v_add_u32_e32 v16, 0x18000, v212
	s_barrier
	s_nop 0
	ds_read_b128 v[0:3], v16
	ds_read_b128 v[12:15], v16 offset:1024
	ds_read_b128 v[168:171], v16 offset:2048
	ds_read_b128 v[172:175], v16 offset:3072
	ds_read_b128 v[16:19], v143 offset:32768
	ds_read_b128 v[28:31], v143 offset:33792
	ds_read_b128 v[32:35], v143 offset:34816
	ds_read_b128 v[44:47], v143 offset:35840
	ds_read_b128 v[48:51], v143 offset:36864
	ds_read_b128 v[176:179], v143 offset:37888
	ds_read_b128 v[196:199], v143 offset:38912
	ds_read_b128 v[208:211], v143 offset:39936
	s_waitcnt vmcnt(2)
	s_barrier
	s_waitcnt lgkmcnt(0)
	s_waitcnt lgkmcnt(0)
	v_mfma_f32_16x16x32_bf16 v[64:67], v[0:3], v[16:19], v[124:127]
	v_mfma_f32_16x16x32_bf16 v[124:127], v[12:15], v[28:31], v[64:67]
	v_mfma_f32_16x16x32_bf16 v[64:67], v[168:171], v[16:19], v[120:123]
	v_mfma_f32_16x16x32_bf16 v[112:115], v[172:175], v[28:31], v[64:67]
	v_mfma_f32_16x16x32_bf16 v[64:67], v[0:3], v[32:35], v[116:119]
	v_mfma_f32_16x16x32_bf16 v[108:111], v[12:15], v[44:47], v[64:67]
	v_mfma_f32_16x16x32_bf16 v[64:67], v[168:171], v[32:35], v[184:187]
	v_mfma_f32_16x16x32_bf16 v[96:99], v[172:175], v[44:47], v[64:67]
	v_mfma_f32_16x16x32_bf16 v[64:67], v[0:3], v[48:51], v[188:191]
	v_mfma_f32_16x16x32_bf16 v[92:95], v[12:15], v[176:179], v[64:67]
	v_mfma_f32_16x16x32_bf16 v[64:67], v[168:171], v[48:51], v[104:107]
	v_mfma_f32_16x16x32_bf16 v[80:83], v[172:175], v[176:179], v[64:67]
	v_mfma_f32_16x16x32_bf16 v[64:67], v[0:3], v[196:199], v[100:103]
	v_mfma_f32_16x16x32_bf16 v[76:79], v[12:15], v[208:211], v[64:67]
	v_mfma_f32_16x16x32_bf16 v[64:67], v[168:171], v[196:199], v[192:195]
	v_mfma_f32_16x16x32_bf16 v[64:67], v[172:175], v[208:211], v[64:67]
	v_add_u32_e32 v100, 0x1c000, v212
	s_barrier
	ds_read_b128 v[184:187], v100
	ds_read_b128 v[188:191], v100 offset:1024
	ds_read_b128 v[192:195], v100 offset:2048
	ds_read_b128 v[212:215], v100 offset:3072
	s_waitcnt vmcnt(0)
	s_barrier
	s_waitcnt lgkmcnt(0)
	s_waitcnt lgkmcnt(0)
	v_mfma_f32_16x16x32_bf16 v[100:103], v[184:187], v[16:19], v[200:203]
	v_mfma_f32_16x16x32_bf16 v[16:19], v[192:195], v[16:19], v[88:91]
	v_mfma_f32_16x16x32_bf16 v[116:119], v[212:215], v[28:31], v[16:19]
	v_mfma_f32_16x16x32_bf16 v[16:19], v[184:187], v[32:35], v[84:87]
	v_mfma_f32_16x16x32_bf16 v[120:123], v[188:191], v[28:31], v[100:103]
	v_mfma_f32_16x16x32_bf16 v[100:103], v[188:191], v[44:47], v[16:19]
	v_mfma_f32_16x16x32_bf16 v[16:19], v[192:195], v[32:35], v[152:155]
	v_mfma_f32_16x16x32_bf16 v[104:107], v[212:215], v[44:47], v[16:19]
	v_mfma_f32_16x16x32_bf16 v[16:19], v[184:187], v[48:51], v[156:159]
	v_mfma_f32_16x16x32_bf16 v[84:87], v[188:191], v[176:179], v[16:19]
	v_mfma_f32_16x16x32_bf16 v[16:19], v[192:195], v[48:51], v[72:75]
	v_mfma_f32_16x16x32_bf16 v[88:91], v[212:215], v[176:179], v[16:19]
	v_mfma_f32_16x16x32_bf16 v[16:19], v[184:187], v[196:199], v[68:71]
	v_mfma_f32_16x16x32_bf16 v[68:71], v[188:191], v[208:211], v[16:19]
	v_mfma_f32_16x16x32_bf16 v[16:19], v[192:195], v[196:199], v[160:163]
	v_mfma_f32_16x16x32_bf16 v[72:75], v[212:215], v[208:211], v[16:19]
	s_barrier
	ds_read_b128 v[152:155], v143 offset:49152
	ds_read_b128 v[156:159], v143 offset:50176
	ds_read_b128 v[160:163], v143 offset:51200
	ds_read_b128 v[176:179], v143 offset:52224
	ds_read_b128 v[196:199], v143 offset:53248
	ds_read_b128 v[200:203], v143 offset:54272
	ds_read_b128 v[208:211], v143 offset:55296
	ds_read_b128 v[216:219], v143 offset:56320
	s_barrier
	s_waitcnt lgkmcnt(0)
	s_waitcnt lgkmcnt(0)
	v_mfma_f32_16x16x32_bf16 v[16:19], v[0:3], v[152:155], v[60:63]
	v_mfma_f32_16x16x32_bf16 v[60:63], v[12:15], v[156:159], v[16:19]
	v_mfma_f32_16x16x32_bf16 v[16:19], v[168:171], v[152:155], v[56:59]
	v_mfma_f32_16x16x32_bf16 v[48:51], v[172:175], v[156:159], v[16:19]
	v_mfma_f32_16x16x32_bf16 v[16:19], v[0:3], v[160:163], v[52:55]
	v_mfma_f32_16x16x32_bf16 v[44:47], v[12:15], v[176:179], v[16:19]
	v_mfma_f32_16x16x32_bf16 v[16:19], v[168:171], v[160:163], v[180:183]
	v_mfma_f32_16x16x32_bf16 v[32:35], v[172:175], v[176:179], v[16:19]
	v_mfma_f32_16x16x32_bf16 v[16:19], v[0:3], v[196:199], v[204:207]
	v_mfma_f32_16x16x32_bf16 v[0:3], v[0:3], v[208:211], v[36:39]
	v_mfma_f32_16x16x32_bf16 v[28:31], v[12:15], v[200:203], v[16:19]
	v_mfma_f32_16x16x32_bf16 v[16:19], v[168:171], v[196:199], v[40:43]
	v_mfma_f32_16x16x32_bf16 v[12:15], v[12:15], v[216:219], v[0:3]
	v_mfma_f32_16x16x32_bf16 v[0:3], v[168:171], v[208:211], v[130:133]
	v_mfma_f32_16x16x32_bf16 v[16:19], v[172:175], v[200:203], v[16:19]
	v_mfma_f32_16x16x32_bf16 v[0:3], v[172:175], v[216:219], v[0:3]
	v_mfma_f32_16x16x32_bf16 v[36:39], v[184:187], v[152:155], v[138:141]
	v_mfma_f32_16x16x32_bf16 v[20:23], v[184:187], v[160:163], v[20:23]
	v_mfma_f32_16x16x32_bf16 v[52:55], v[188:191], v[156:159], v[36:39]
	v_mfma_f32_16x16x32_bf16 v[24:27], v[192:195], v[152:155], v[24:27]
	v_mfma_f32_16x16x32_bf16 v[36:39], v[188:191], v[176:179], v[20:23]
	v_mfma_f32_16x16x32_bf16 v[20:23], v[192:195], v[160:163], v[144:147]
	v_mfma_f32_16x16x32_bf16 v[8:11], v[192:195], v[196:199], v[8:11]
	v_mfma_f32_16x16x32_bf16 v[56:59], v[212:215], v[156:159], v[24:27]
	v_mfma_f32_16x16x32_bf16 v[40:43], v[212:215], v[176:179], v[20:23]
	v_mfma_f32_16x16x32_bf16 v[20:23], v[184:187], v[196:199], v[148:151]
	v_mfma_f32_16x16x32_bf16 v[24:27], v[212:215], v[200:203], v[8:11]
	v_mfma_f32_16x16x32_bf16 v[4:7], v[184:187], v[208:211], v[4:7]
	v_mfma_f32_16x16x32_bf16 v[8:11], v[192:195], v[208:211], v[164:167]
	v_mfma_f32_16x16x32_bf16 v[20:23], v[188:191], v[200:203], v[20:23]
	v_mfma_f32_16x16x32_bf16 v[4:7], v[188:191], v[216:219], v[4:7]
	v_mfma_f32_16x16x32_bf16 v[8:11], v[212:215], v[216:219], v[8:11]
	s_cmpk_lt_u32 s24, 0x100
	s_barrier
	s_cbranch_scc0 .LBB0_1400
	s_barrier
